# write-through sc1 16-byte stores for W_in outputs and attention O (consumers on other XCDs): less dirty L2 at the next full barrier
# baseline (speedup 1.0000x reference)
; __device__ __forceinline__ float row_rstd(const float* ssq, int row, int fq) {
;     const f32x4 v = *(const f32x4*)(ssq + (size_t)row * 16 + fq * 4);
;     float s = (v[0] + v[1]) + (v[2] + v[3]);
;     s += __shfl_xor(s, 16); s += __shfl_xor(s, 32);
;     return __builtin_amdgcn_rsqf(s * (1.f / DM) + EPS);
; }
; __device__ __forceinline__ void row_rstd4(const float* ssq, int row0, int fq, float (&rs)[4]) {
;     f32x4 v[4];
; #pragma unroll
;     for (int m = 0; m < 4; ++m) v[m] = *(const f32x4*)(ssq + (size_t)(row0 + m * 16) * 16 + fq * 4);
; #pragma unroll
;     for (int m = 0; m < 4; ++m) { float t = (v[m][0] + v[m][1]) + (v[m][2] + v[m][3]); t += __shfl_xor(t, 16); t += __shfl_xor(t, 32); rs[m] = __builtin_amdgcn_rsqf(t * (1.f / DM) + EPS); }
; }
; __device__ __forceinline__ v4u pack8(const f32x4 a, const f32x4 b) { v4u w; w.x = cvt_pk_bf16(a[0], a[1]); w.y = cvt_pk_bf16(a[2], a[3]); w.z = cvt_pk_bf16(b[0], b[1]); w.w = cvt_pk_bf16(b[2], b[3]); return w; }
;     __device__ __forceinline__ void operator()(const f32x4 (&acc)[2][2][4][2], const pg8::Unit& u, int wr, int wc, int fr, int fq) const {
;     ...
;         const int grp = pn >> 1, cb = (pn & 1) * 256 + cw;
;     ...
;         if (grp == 0) { WIN_LOOP( _Pragma("unroll") for (int i = 0; i < 4; ++i) { a[i] = silu_f(a[i]); b[i] = silu_f(b[i]); } *(v4u*)(QO + (size_t)row * DM + c) = pack8(a, b); ) }
;         else if (grp == 3) { WIN_LOOP( _Pragma("unroll") for (int i = 0; i < 4; ++i) { a[i] = silu_f(a[i]); b[i] = silu_f(b[i]); } *(v4u*)(GH + (size_t)row * 512 + c) = pack8(a, b); ) }
;         else if (grp == 1) {
;             f32x4 l0[2], l1[2];
; #pragma unroll
;             for (int bj = 0; bj < 2; ++bj) { l0[bj] = *(const f32x4*)(lb + cb + bj * 128); l1[bj] = *(const f32x4*)(lb + cb + bj * 128 + 4); }
;             WIN_LOOP( _Pragma("unroll") for (int i = 0; i < 4; ++i) { const float s0 = fminf(a[i], 0.f) - __logf(1.f + __expf(-fabsf(a[i]))), s1 = fminf(b[i], 0.f) - __logf(1.f + __expf(-fabsf(b[i]))); const float la = l0[bj][i], lbv = l1[bj][i];
;                     a[i] = la > 0.f ? __logf(la + (1.f - la) * __expf(s0)) : s0; b[i] = lbv > 0.f ? __logf(lbv + (1.f - lbv) * __expf(s1)) : s1; }
;                 *(f32x4*)(LF + (size_t)row * 512 + c) = a; *(f32x4*)(LF + (size_t)row * 512 + c + 4) = b; __builtin_amdgcn_sched_barrier(0); ) }
.LBB0_394:
	s_lshl_b32 s8, s2, 8
	s_and_b32 s8, s8, 0x100
	v_or_b32_e32 v176, s8, v174
	s_cmp_gt_u32 s2, 1
	s_mov_b64 s[8:9], -1
	s_cbranch_scc0 .LBB0_417
	s_ashr_i32 s14, s2, 1
	s_mov_b64 s[12:13], -1
	s_mov_b64 s[8:9], 0
	s_cmp_lt_i32 s14, 3
	s_mov_b64 s[10:11], 0
	s_cbranch_scc1 .LBB0_407
	s_cmp_gt_i32 s14, 3
	s_cbranch_scc0 .LBB0_404
	s_cmp_gt_i32 s14, 4
	s_cbranch_scc0 .LBB0_401
	s_cmp_eq_u32 s14, 5
	s_mov_b64 s[10:11], -1
	s_cbranch_scc0 .LBB0_400
	v_and_b32_e32 v129, 64, v215
	v_xor_b32_e32 v128, 16, v215
	v_add_u32_e32 v129, 64, v129
	v_cmp_lt_i32_e32 vcc, v128, v129
	v_ashrrev_i32_e32 v167, 31, v166
	v_readlane_b32 s10, v255, 41
	v_cndmask_b32_e32 v128, v215, v128, vcc
	v_lshlrev_b32_e32 v130, 2, v128
	v_xor_b32_e32 v128, 32, v215
	v_cmp_lt_i32_e32 vcc, v128, v129
	v_readlane_b32 s11, v255, 42
	v_lshlrev_b32_e32 v192, 1, v176
	v_cndmask_b32_e32 v128, v215, v128, vcc
	v_lshlrev_b32_e32 v131, 2, v128
	v_lshlrev_b64 v[128:129], 6, v[166:167]
	v_lshl_add_u64 v[128:129], v[160:161], 0, v[128:129]
	flat_load_dwordx4 v[132:135], v[128:129]
	s_waitcnt vmcnt(0) lgkmcnt(0)
	v_mov_b32_e32 v128, v133
	v_mov_b32_e32 v129, v134
	v_mov_b32_e32 v133, v135
	v_pk_add_f32 v[128:129], v[128:129], v[132:133]
	v_lshlrev_b64 v[132:133], 10, v[166:167]
	v_add_f32_e32 v128, v128, v129
	ds_bpermute_b32 v129, v130, v128
	v_lshl_add_u64 v[136:137], s[10:11], 0, v[132:133]
	v_lshl_add_u64 v[136:137], v[136:137], 0, v[192:193]
	s_waitcnt lgkmcnt(0)
	v_add_f32_e32 v128, v128, v129
	ds_bpermute_b32 v129, v131, v128
	s_waitcnt lgkmcnt(0)
	v_add_f32_e32 v128, v128, v129
	v_fmamk_f32 v128, v128, 0x3a800000, v212
	v_rsq_f32_e32 v128, v128
	s_nop 0
	v_pk_mul_f32 v[134:135], v[62:63], v[128:129] op_sel_hi:[1,0]
	v_pk_mul_f32 v[132:133], v[60:61], v[128:129] op_sel_hi:[1,0]
	v_pk_mul_f32 v[138:139], v[58:59], v[128:129] op_sel_hi:[1,0]
	v_pk_mul_f32 v[140:141], v[56:57], v[128:129] op_sel_hi:[1,0]
	v_cvt_pk_bf16_f32 v132, v132, v133
	v_cvt_pk_bf16_f32 v133, v134, v135
	v_cvt_pk_bf16_f32 v134, v140, v141
	v_cvt_pk_bf16_f32 v135, v138, v139
	flat_store_dwordx4 v[136:137], v[132:135] sc1
	v_pk_mul_f32 v[138:139], v[122:123], v[128:129] op_sel_hi:[1,0]
	s_nop 0
	v_pk_mul_f32 v[134:135], v[126:127], v[128:129] op_sel_hi:[1,0]
	v_pk_mul_f32 v[132:133], v[124:125], v[128:129] op_sel_hi:[1,0]
	v_pk_mul_f32 v[128:129], v[120:121], v[128:129] op_sel_hi:[1,0]
	v_cvt_pk_bf16_f32 v132, v132, v133
	v_cvt_pk_bf16_f32 v133, v134, v135
	v_cvt_pk_bf16_f32 v134, v128, v129
	v_or_b32_e32 v128, 16, v166
	v_cvt_pk_bf16_f32 v135, v138, v139
	v_ashrrev_i32_e32 v129, 31, v128
	flat_store_dwordx4 v[136:137], v[132:135] offset:256 sc1
	s_nop 1
	v_lshlrev_b64 v[132:133], 6, v[128:129]
	v_lshl_add_u64 v[132:133], v[160:161], 0, v[132:133]
	flat_load_dwordx4 v[132:135], v[132:133]
	v_lshlrev_b64 v[128:129], 10, v[128:129]
	v_lshl_add_u64 v[128:129], s[10:11], 0, v[128:129]
	v_lshl_add_u64 v[128:129], v[128:129], 0, v[192:193]
	s_waitcnt vmcnt(0) lgkmcnt(0)
	v_mov_b32_e32 v136, v133
	v_mov_b32_e32 v137, v134
	v_mov_b32_e32 v133, v135
	v_pk_add_f32 v[132:133], v[136:137], v[132:133]
	s_nop 0
	v_add_f32_e32 v132, v132, v133
	ds_bpermute_b32 v133, v130, v132
	s_waitcnt lgkmcnt(0)
	v_add_f32_e32 v132, v132, v133
	ds_bpermute_b32 v133, v131, v132
	s_waitcnt lgkmcnt(0)
	v_add_f32_e32 v132, v132, v133
	v_fmamk_f32 v132, v132, 0x3a800000, v212
	v_rsq_f32_e32 v136, v132
	s_nop 0
	v_pk_mul_f32 v[134:135], v[54:55], v[136:137] op_sel_hi:[1,0]
	v_pk_mul_f32 v[132:133], v[52:53], v[136:137] op_sel_hi:[1,0]
	v_pk_mul_f32 v[138:139], v[50:51], v[136:137] op_sel_hi:[1,0]
	v_pk_mul_f32 v[140:141], v[48:49], v[136:137] op_sel_hi:[1,0]
	v_cvt_pk_bf16_f32 v132, v132, v133
	v_cvt_pk_bf16_f32 v133, v134, v135
	v_cvt_pk_bf16_f32 v134, v140, v141
	v_cvt_pk_bf16_f32 v135, v138, v139
	flat_store_dwordx4 v[128:129], v[132:135] sc1
	v_pk_mul_f32 v[138:139], v[114:115], v[136:137] op_sel_hi:[1,0]
	s_nop 0
	v_pk_mul_f32 v[134:135], v[118:119], v[136:137] op_sel_hi:[1,0]
	v_pk_mul_f32 v[132:133], v[116:117], v[136:137] op_sel_hi:[1,0]
	v_pk_mul_f32 v[136:137], v[112:113], v[136:137] op_sel_hi:[1,0]
	v_cvt_pk_bf16_f32 v132, v132, v133
	v_cvt_pk_bf16_f32 v133, v134, v135
	v_cvt_pk_bf16_f32 v134, v136, v137
	v_cvt_pk_bf16_f32 v135, v138, v139
	flat_store_dwordx4 v[128:129], v[132:135] offset:256 sc1
	v_or_b32_e32 v128, 32, v166
	v_ashrrev_i32_e32 v129, 31, v128
	v_lshlrev_b64 v[132:133], 6, v[128:129]
	v_lshl_add_u64 v[132:133], v[160:161], 0, v[132:133]
	flat_load_dwordx4 v[132:135], v[132:133]
	v_lshlrev_b64 v[128:129], 10, v[128:129]
	v_lshl_add_u64 v[128:129], s[10:11], 0, v[128:129]
	v_lshl_add_u64 v[128:129], v[128:129], 0, v[192:193]
	s_waitcnt vmcnt(0) lgkmcnt(0)
	v_mov_b32_e32 v136, v133
	v_mov_b32_e32 v137, v134
	v_mov_b32_e32 v133, v135
	v_pk_add_f32 v[132:133], v[136:137], v[132:133]
	s_nop 0
	v_add_f32_e32 v132, v132, v133
	ds_bpermute_b32 v133, v130, v132
	s_waitcnt lgkmcnt(0)
	v_add_f32_e32 v132, v132, v133
	ds_bpermute_b32 v133, v131, v132
	s_waitcnt lgkmcnt(0)
; __device__ __forceinline__ float silu_f(float x) { return x * __builtin_amdgcn_rcpf(1.f + __expf(-x)); }
; __device__ __forceinline__ v4u pack8(const f32x4 a, const f32x4 b) { v4u w; w.x = cvt_pk_bf16(a[0], a[1]); w.y = cvt_pk_bf16(a[2], a[3]); w.z = cvt_pk_bf16(b[0], b[1]); w.w = cvt_pk_bf16(b[2], b[3]); return w; }
; __device__ __forceinline__ float row_rstd(const float* ssq, int row, int fq) {
;     const f32x4 v = *(const f32x4*)(ssq + (size_t)row * 16 + fq * 4);
;     float s = (v[0] + v[1]) + (v[2] + v[3]);
;     s += __shfl_xor(s, 16); s += __shfl_xor(s, 32);
;     return __builtin_amdgcn_rsqf(s * (1.f / DM) + EPS);
; }
;     __device__ __forceinline__ void operator()(const f32x4 (&acc)[2][2][4][2], const pg8::Unit& u, int wr, int wc, int fr, int fq) const {
;     ...
;         if (grp == 0) { WIN_LOOP( _Pragma("unroll") for (int i = 0; i < 4; ++i) { a[i] = silu_f(a[i]); b[i] = silu_f(b[i]); } *(v4u*)(QO + (size_t)row * DM + c) = pack8(a, b); ) }
;         else if (grp == 3) { WIN_LOOP( _Pragma("unroll") for (int i = 0; i < 4; ++i) { a[i] = silu_f(a[i]); b[i] = silu_f(b[i]); } *(v4u*)(GH + (size_t)row * 512 + c) = pack8(a, b); ) }
;         else if (grp == 1) {
;             f32x4 l0[2], l1[2];
; #pragma unroll
;             for (int bj = 0; bj < 2; ++bj) { l0[bj] = *(const f32x4*)(lb + cb + bj * 128); l1[bj] = *(const f32x4*)(lb + cb + bj * 128 + 4); }
;             WIN_LOOP( _Pragma("unroll") for (int i = 0; i < 4; ++i) { const float s0 = fminf(a[i], 0.f) - __logf(1.f + __expf(-fabsf(a[i]))), s1 = fminf(b[i], 0.f) - __logf(1.f + __expf(-fabsf(b[i]))); const float la = l0[bj][i], lbv = l1[bj][i];
;                     a[i] = la > 0.f ? __logf(la + (1.f - la) * __expf(s0)) : s0; b[i] = lbv > 0.f ? __logf(lbv + (1.f - lbv) * __expf(s1)) : s1; }
;                 *(f32x4*)(LF + (size_t)row * 512 + c) = a; *(f32x4*)(LF + (size_t)row * 512 + c + 4) = b; __builtin_amdgcn_sched_barrier(0); ) }
;         else if (grp == 2) { WIN_LOOP( *(v4u*)(VH + (size_t)row * 512 + c) = pack8(a, b); ) }
;         else if (grp == 4) { WIN_LOOP( *(v4u*)(QO + (size_t)row * DM + 512 + c) = pack8(a * C2Q, b * C2Q); ) }
;         else if (grp == 5) { WIN_LOOP( *(v4u*)(FK + (size_t)row * 512 + c) = pack8(a, b); ) }
	v_add_f32_e32 v132, v132, v133
	v_fmamk_f32 v132, v132, 0x3a800000, v212
	v_rsq_f32_e32 v136, v132
	s_nop 0
	v_pk_mul_f32 v[134:135], v[46:47], v[136:137] op_sel_hi:[1,0]
	v_pk_mul_f32 v[132:133], v[44:45], v[136:137] op_sel_hi:[1,0]
	v_pk_mul_f32 v[138:139], v[42:43], v[136:137] op_sel_hi:[1,0]
	v_pk_mul_f32 v[140:141], v[40:41], v[136:137] op_sel_hi:[1,0]
	v_cvt_pk_bf16_f32 v132, v132, v133
	v_cvt_pk_bf16_f32 v133, v134, v135
	v_cvt_pk_bf16_f32 v134, v140, v141
	v_cvt_pk_bf16_f32 v135, v138, v139
	flat_store_dwordx4 v[128:129], v[132:135] sc1
	v_pk_mul_f32 v[138:139], v[106:107], v[136:137] op_sel_hi:[1,0]
	s_nop 0
	v_pk_mul_f32 v[134:135], v[110:111], v[136:137] op_sel_hi:[1,0]
	v_pk_mul_f32 v[132:133], v[108:109], v[136:137] op_sel_hi:[1,0]
	v_pk_mul_f32 v[136:137], v[104:105], v[136:137] op_sel_hi:[1,0]
	v_cvt_pk_bf16_f32 v132, v132, v133
	v_cvt_pk_bf16_f32 v133, v134, v135
	v_cvt_pk_bf16_f32 v134, v136, v137
	v_cvt_pk_bf16_f32 v135, v138, v139
	flat_store_dwordx4 v[128:129], v[132:135] offset:256 sc1
	v_or_b32_e32 v128, 48, v166
	v_ashrrev_i32_e32 v129, 31, v128
	v_lshlrev_b64 v[132:133], 6, v[128:129]
	v_lshl_add_u64 v[132:133], v[160:161], 0, v[132:133]
	flat_load_dwordx4 v[132:135], v[132:133]
	v_lshlrev_b64 v[128:129], 10, v[128:129]
	v_lshl_add_u64 v[128:129], s[10:11], 0, v[128:129]
	v_lshl_add_u64 v[128:129], v[128:129], 0, v[192:193]
	s_waitcnt vmcnt(0) lgkmcnt(0)
	v_mov_b32_e32 v136, v133
	v_mov_b32_e32 v137, v134
	v_mov_b32_e32 v133, v135
	v_pk_add_f32 v[132:133], v[136:137], v[132:133]
	s_nop 0
	v_add_f32_e32 v132, v132, v133
	ds_bpermute_b32 v133, v130, v132
	s_waitcnt lgkmcnt(0)
	v_add_f32_e32 v132, v132, v133
	ds_bpermute_b32 v133, v131, v132
	s_waitcnt lgkmcnt(0)
	v_add_f32_e32 v132, v132, v133
	v_fmamk_f32 v132, v132, 0x3a800000, v212
	v_rsq_f32_e32 v136, v132
	s_nop 0
	v_pk_mul_f32 v[134:135], v[38:39], v[136:137] op_sel_hi:[1,0]
	v_pk_mul_f32 v[132:133], v[36:37], v[136:137] op_sel_hi:[1,0]
	v_pk_mul_f32 v[138:139], v[34:35], v[136:137] op_sel_hi:[1,0]
	v_pk_mul_f32 v[140:141], v[32:33], v[136:137] op_sel_hi:[1,0]
	v_cvt_pk_bf16_f32 v132, v132, v133
	v_cvt_pk_bf16_f32 v133, v134, v135
	v_cvt_pk_bf16_f32 v134, v140, v141
	v_cvt_pk_bf16_f32 v135, v138, v139
	flat_store_dwordx4 v[128:129], v[132:135] sc1
	v_pk_mul_f32 v[138:139], v[98:99], v[136:137] op_sel_hi:[1,0]
	s_nop 0
	v_pk_mul_f32 v[134:135], v[102:103], v[136:137] op_sel_hi:[1,0]
	v_pk_mul_f32 v[132:133], v[100:101], v[136:137] op_sel_hi:[1,0]
	v_pk_mul_f32 v[136:137], v[96:97], v[136:137] op_sel_hi:[1,0]
	v_cvt_pk_bf16_f32 v132, v132, v133
	v_cvt_pk_bf16_f32 v133, v134, v135
	v_cvt_pk_bf16_f32 v134, v136, v137
	v_cvt_pk_bf16_f32 v135, v138, v139
	flat_store_dwordx4 v[128:129], v[132:135] offset:256 sc1
	v_add_u32_e32 v128, 0x80, v166
	v_ashrrev_i32_e32 v129, 31, v128
	v_lshlrev_b64 v[132:133], 6, v[128:129]
	v_lshl_add_u64 v[132:133], v[160:161], 0, v[132:133]
	flat_load_dwordx4 v[132:135], v[132:133]
	v_lshlrev_b64 v[128:129], 10, v[128:129]
	v_lshl_add_u64 v[128:129], s[10:11], 0, v[128:129]
	v_lshl_add_u64 v[128:129], v[128:129], 0, v[192:193]
	s_waitcnt vmcnt(0) lgkmcnt(0)
	v_mov_b32_e32 v136, v133
	v_mov_b32_e32 v137, v134
	v_mov_b32_e32 v133, v135
	v_pk_add_f32 v[132:133], v[136:137], v[132:133]
	s_nop 0
	v_add_f32_e32 v132, v132, v133
	ds_bpermute_b32 v133, v130, v132
	s_waitcnt lgkmcnt(0)
	v_add_f32_e32 v132, v132, v133
	ds_bpermute_b32 v133, v131, v132
	s_waitcnt lgkmcnt(0)
	v_add_f32_e32 v132, v132, v133
	v_fmamk_f32 v132, v132, 0x3a800000, v212
	v_rsq_f32_e32 v136, v132
	s_nop 0
	v_pk_mul_f32 v[134:135], v[30:31], v[136:137] op_sel_hi:[1,0]
	v_pk_mul_f32 v[132:133], v[28:29], v[136:137] op_sel_hi:[1,0]
	v_pk_mul_f32 v[138:139], v[26:27], v[136:137] op_sel_hi:[1,0]
	v_pk_mul_f32 v[140:141], v[24:25], v[136:137] op_sel_hi:[1,0]
	v_cvt_pk_bf16_f32 v132, v132, v133
	v_cvt_pk_bf16_f32 v133, v134, v135
	v_cvt_pk_bf16_f32 v134, v140, v141
	v_cvt_pk_bf16_f32 v135, v138, v139
	flat_store_dwordx4 v[128:129], v[132:135] sc1
	v_pk_mul_f32 v[138:139], v[90:91], v[136:137] op_sel_hi:[1,0]
	s_nop 0
	v_pk_mul_f32 v[134:135], v[94:95], v[136:137] op_sel_hi:[1,0]
	v_pk_mul_f32 v[132:133], v[92:93], v[136:137] op_sel_hi:[1,0]
	v_pk_mul_f32 v[136:137], v[88:89], v[136:137] op_sel_hi:[1,0]
	v_cvt_pk_bf16_f32 v132, v132, v133
	v_cvt_pk_bf16_f32 v133, v134, v135
	v_cvt_pk_bf16_f32 v134, v136, v137
	v_cvt_pk_bf16_f32 v135, v138, v139
	flat_store_dwordx4 v[128:129], v[132:135] offset:256 sc1
	v_add_u32_e32 v128, 0x90, v166
	v_ashrrev_i32_e32 v129, 31, v128
	v_lshlrev_b64 v[132:133], 6, v[128:129]
	v_lshl_add_u64 v[132:133], v[160:161], 0, v[132:133]
	flat_load_dwordx4 v[132:135], v[132:133]
	v_lshlrev_b64 v[128:129], 10, v[128:129]
	v_lshl_add_u64 v[128:129], s[10:11], 0, v[128:129]
	v_lshl_add_u64 v[128:129], v[128:129], 0, v[192:193]
	s_waitcnt vmcnt(0) lgkmcnt(0)
; __device__ __forceinline__ float silu_f(float x) { return x * __builtin_amdgcn_rcpf(1.f + __expf(-x)); }
; __device__ __forceinline__ v4u pack8(const f32x4 a, const f32x4 b) { v4u w; w.x = cvt_pk_bf16(a[0], a[1]); w.y = cvt_pk_bf16(a[2], a[3]); w.z = cvt_pk_bf16(b[0], b[1]); w.w = cvt_pk_bf16(b[2], b[3]); return w; }
; __device__ __forceinline__ float row_rstd(const float* ssq, int row, int fq) {
;     const f32x4 v = *(const f32x4*)(ssq + (size_t)row * 16 + fq * 4);
;     float s = (v[0] + v[1]) + (v[2] + v[3]);
;     s += __shfl_xor(s, 16); s += __shfl_xor(s, 32);
;     return __builtin_amdgcn_rsqf(s * (1.f / DM) + EPS);
; }
;     __device__ __forceinline__ void operator()(const f32x4 (&acc)[2][2][4][2], const pg8::Unit& u, int wr, int wc, int fr, int fq) const {
;     ...
;         if (grp == 0) { WIN_LOOP( _Pragma("unroll") for (int i = 0; i < 4; ++i) { a[i] = silu_f(a[i]); b[i] = silu_f(b[i]); } *(v4u*)(QO + (size_t)row * DM + c) = pack8(a, b); ) }
;         else if (grp == 3) { WIN_LOOP( _Pragma("unroll") for (int i = 0; i < 4; ++i) { a[i] = silu_f(a[i]); b[i] = silu_f(b[i]); } *(v4u*)(GH + (size_t)row * 512 + c) = pack8(a, b); ) }
;         else if (grp == 1) {
;             f32x4 l0[2], l1[2];
; #pragma unroll
;             for (int bj = 0; bj < 2; ++bj) { l0[bj] = *(const f32x4*)(lb + cb + bj * 128); l1[bj] = *(const f32x4*)(lb + cb + bj * 128 + 4); }
;             WIN_LOOP( _Pragma("unroll") for (int i = 0; i < 4; ++i) { const float s0 = fminf(a[i], 0.f) - __logf(1.f + __expf(-fabsf(a[i]))), s1 = fminf(b[i], 0.f) - __logf(1.f + __expf(-fabsf(b[i]))); const float la = l0[bj][i], lbv = l1[bj][i];
;                     a[i] = la > 0.f ? __logf(la + (1.f - la) * __expf(s0)) : s0; b[i] = lbv > 0.f ? __logf(lbv + (1.f - lbv) * __expf(s1)) : s1; }
;                 *(f32x4*)(LF + (size_t)row * 512 + c) = a; *(f32x4*)(LF + (size_t)row * 512 + c + 4) = b; __builtin_amdgcn_sched_barrier(0); ) }
;         else if (grp == 2) { WIN_LOOP( *(v4u*)(VH + (size_t)row * 512 + c) = pack8(a, b); ) }
;         else if (grp == 4) { WIN_LOOP( *(v4u*)(QO + (size_t)row * DM + 512 + c) = pack8(a * C2Q, b * C2Q); ) }
;         else if (grp == 5) { WIN_LOOP( *(v4u*)(FK + (size_t)row * 512 + c) = pack8(a, b); ) }
	v_mov_b32_e32 v136, v133
	v_mov_b32_e32 v137, v134
	v_mov_b32_e32 v133, v135
	v_pk_add_f32 v[132:133], v[136:137], v[132:133]
	s_nop 0
	v_add_f32_e32 v132, v132, v133
	ds_bpermute_b32 v133, v130, v132
	s_waitcnt lgkmcnt(0)
	v_add_f32_e32 v132, v132, v133
	ds_bpermute_b32 v133, v131, v132
	s_waitcnt lgkmcnt(0)
	v_add_f32_e32 v132, v132, v133
	v_fmamk_f32 v132, v132, 0x3a800000, v212
	v_rsq_f32_e32 v136, v132
	s_nop 0
	v_pk_mul_f32 v[134:135], v[22:23], v[136:137] op_sel_hi:[1,0]
	v_pk_mul_f32 v[132:133], v[20:21], v[136:137] op_sel_hi:[1,0]
	v_pk_mul_f32 v[138:139], v[18:19], v[136:137] op_sel_hi:[1,0]
	v_pk_mul_f32 v[140:141], v[16:17], v[136:137] op_sel_hi:[1,0]
	v_cvt_pk_bf16_f32 v132, v132, v133
	v_cvt_pk_bf16_f32 v133, v134, v135
	v_cvt_pk_bf16_f32 v134, v140, v141
	v_cvt_pk_bf16_f32 v135, v138, v139
	flat_store_dwordx4 v[128:129], v[132:135] sc1
	v_pk_mul_f32 v[138:139], v[82:83], v[136:137] op_sel_hi:[1,0]
	s_nop 0
	v_pk_mul_f32 v[134:135], v[86:87], v[136:137] op_sel_hi:[1,0]
	v_pk_mul_f32 v[132:133], v[84:85], v[136:137] op_sel_hi:[1,0]
	v_pk_mul_f32 v[136:137], v[80:81], v[136:137] op_sel_hi:[1,0]
	v_cvt_pk_bf16_f32 v132, v132, v133
	v_cvt_pk_bf16_f32 v133, v134, v135
	v_cvt_pk_bf16_f32 v134, v136, v137
	v_cvt_pk_bf16_f32 v135, v138, v139
	flat_store_dwordx4 v[128:129], v[132:135] offset:256 sc1
	v_add_u32_e32 v128, 0xa0, v166
	v_ashrrev_i32_e32 v129, 31, v128
	v_lshlrev_b64 v[132:133], 6, v[128:129]
	v_lshl_add_u64 v[132:133], v[160:161], 0, v[132:133]
	flat_load_dwordx4 v[132:135], v[132:133]
	v_lshlrev_b64 v[128:129], 10, v[128:129]
	v_lshl_add_u64 v[128:129], s[10:11], 0, v[128:129]
	v_lshl_add_u64 v[128:129], v[128:129], 0, v[192:193]
	s_waitcnt vmcnt(0) lgkmcnt(0)
	v_mov_b32_e32 v136, v133
	v_mov_b32_e32 v137, v134
	v_mov_b32_e32 v133, v135
	v_pk_add_f32 v[132:133], v[136:137], v[132:133]
	s_nop 0
	v_add_f32_e32 v132, v132, v133
	ds_bpermute_b32 v133, v130, v132
	s_waitcnt lgkmcnt(0)
	v_add_f32_e32 v132, v132, v133
	ds_bpermute_b32 v133, v131, v132
	s_waitcnt lgkmcnt(0)
	v_add_f32_e32 v132, v132, v133
	v_fmamk_f32 v132, v132, 0x3a800000, v212
	v_rsq_f32_e32 v136, v132
	s_nop 0
	v_pk_mul_f32 v[134:135], v[14:15], v[136:137] op_sel_hi:[1,0]
	v_pk_mul_f32 v[132:133], v[12:13], v[136:137] op_sel_hi:[1,0]
	v_pk_mul_f32 v[138:139], v[10:11], v[136:137] op_sel_hi:[1,0]
	v_pk_mul_f32 v[140:141], v[8:9], v[136:137] op_sel_hi:[1,0]
	v_cvt_pk_bf16_f32 v132, v132, v133
	v_cvt_pk_bf16_f32 v133, v134, v135
	v_cvt_pk_bf16_f32 v134, v140, v141
	v_cvt_pk_bf16_f32 v135, v138, v139
	flat_store_dwordx4 v[128:129], v[132:135] sc1
	v_pk_mul_f32 v[138:139], v[74:75], v[136:137] op_sel_hi:[1,0]
	s_nop 0
	v_pk_mul_f32 v[134:135], v[78:79], v[136:137] op_sel_hi:[1,0]
	v_pk_mul_f32 v[132:133], v[76:77], v[136:137] op_sel_hi:[1,0]
	v_pk_mul_f32 v[136:137], v[72:73], v[136:137] op_sel_hi:[1,0]
	v_cvt_pk_bf16_f32 v132, v132, v133
	v_cvt_pk_bf16_f32 v133, v134, v135
	v_cvt_pk_bf16_f32 v134, v136, v137
	v_cvt_pk_bf16_f32 v135, v138, v139
	flat_store_dwordx4 v[128:129], v[132:135] offset:256 sc1
	v_add_u32_e32 v128, 0xb0, v166
	v_ashrrev_i32_e32 v129, 31, v128
	v_lshlrev_b64 v[132:133], 6, v[128:129]
	v_lshl_add_u64 v[132:133], v[160:161], 0, v[132:133]
	flat_load_dwordx4 v[132:135], v[132:133]
	v_lshlrev_b64 v[128:129], 10, v[128:129]
	s_waitcnt vmcnt(0) lgkmcnt(0)
	v_mov_b32_e32 v136, v133
	v_mov_b32_e32 v137, v134
	v_mov_b32_e32 v133, v135
	v_pk_add_f32 v[132:133], v[136:137], v[132:133]
	v_lshl_add_u64 v[134:135], s[10:11], 0, v[128:129]
	v_add_f32_e32 v132, v132, v133
	ds_bpermute_b32 v130, v130, v132
	v_lshl_add_u64 v[134:135], v[134:135], 0, v[192:193]
	s_mov_b64 s[10:11], 0
	s_waitcnt lgkmcnt(0)
	v_add_f32_e32 v130, v132, v130
	ds_bpermute_b32 v131, v131, v130
	s_waitcnt lgkmcnt(0)
	v_add_f32_e32 v130, v130, v131
	v_fmamk_f32 v130, v130, 0x3a800000, v212
	v_rsq_f32_e32 v132, v130
	s_nop 0
	v_pk_mul_f32 v[130:131], v[6:7], v[132:133] op_sel_hi:[1,0]
	v_pk_mul_f32 v[128:129], v[4:5], v[132:133] op_sel_hi:[1,0]
	v_pk_mul_f32 v[136:137], v[2:3], v[132:133] op_sel_hi:[1,0]
	v_pk_mul_f32 v[138:139], v[0:1], v[132:133] op_sel_hi:[1,0]
	v_cvt_pk_bf16_f32 v128, v128, v129
	v_cvt_pk_bf16_f32 v129, v130, v131
	v_cvt_pk_bf16_f32 v130, v138, v139
	v_cvt_pk_bf16_f32 v131, v136, v137
	flat_store_dwordx4 v[134:135], v[128:131] sc1
	v_pk_mul_f32 v[136:137], v[66:67], v[132:133] op_sel_hi:[1,0]
	s_nop 0
	v_pk_mul_f32 v[130:131], v[70:71], v[132:133] op_sel_hi:[1,0]
	v_pk_mul_f32 v[128:129], v[68:69], v[132:133] op_sel_hi:[1,0]
	v_pk_mul_f32 v[132:133], v[64:65], v[132:133] op_sel_hi:[1,0]
	v_cvt_pk_bf16_f32 v128, v128, v129
	v_cvt_pk_bf16_f32 v129, v130, v131
	v_cvt_pk_bf16_f32 v130, v132, v133
	v_cvt_pk_bf16_f32 v131, v136, v137
	flat_store_dwordx4 v[134:135], v[128:131] offset:256 sc1

; __device__ __forceinline__ float silu_f(float x) { return x * __builtin_amdgcn_rcpf(1.f + __expf(-x)); }
; __device__ __forceinline__ v4u pack8(const f32x4 a, const f32x4 b) { v4u w; w.x = cvt_pk_bf16(a[0], a[1]); w.y = cvt_pk_bf16(a[2], a[3]); w.z = cvt_pk_bf16(b[0], b[1]); w.w = cvt_pk_bf16(b[2], b[3]); return w; }
; __device__ __forceinline__ float row_rstd(const float* ssq, int row, int fq) {
;     const f32x4 v = *(const f32x4*)(ssq + (size_t)row * 16 + fq * 4);
;     float s = (v[0] + v[1]) + (v[2] + v[3]);
;     s += __shfl_xor(s, 16); s += __shfl_xor(s, 32);
;     return __builtin_amdgcn_rsqf(s * (1.f / DM) + EPS);
; }
;     __device__ __forceinline__ void operator()(const f32x4 (&acc)[2][2][4][2], const pg8::Unit& u, int wr, int wc, int fr, int fq) const {
;     ...
;         if (grp == 0) { WIN_LOOP( _Pragma("unroll") for (int i = 0; i < 4; ++i) { a[i] = silu_f(a[i]); b[i] = silu_f(b[i]); } *(v4u*)(QO + (size_t)row * DM + c) = pack8(a, b); ) }
;         else if (grp == 3) { WIN_LOOP( _Pragma("unroll") for (int i = 0; i < 4; ++i) { a[i] = silu_f(a[i]); b[i] = silu_f(b[i]); } *(v4u*)(GH + (size_t)row * 512 + c) = pack8(a, b); ) }
;         else if (grp == 1) {
;             f32x4 l0[2], l1[2];
; #pragma unroll
;             for (int bj = 0; bj < 2; ++bj) { l0[bj] = *(const f32x4*)(lb + cb + bj * 128); l1[bj] = *(const f32x4*)(lb + cb + bj * 128 + 4); }
;             WIN_LOOP( _Pragma("unroll") for (int i = 0; i < 4; ++i) { const float s0 = fminf(a[i], 0.f) - __logf(1.f + __expf(-fabsf(a[i]))), s1 = fminf(b[i], 0.f) - __logf(1.f + __expf(-fabsf(b[i]))); const float la = l0[bj][i], lbv = l1[bj][i];
;                     a[i] = la > 0.f ? __logf(la + (1.f - la) * __expf(s0)) : s0; b[i] = lbv > 0.f ? __logf(lbv + (1.f - lbv) * __expf(s1)) : s1; }
;                 *(f32x4*)(LF + (size_t)row * 512 + c) = a; *(f32x4*)(LF + (size_t)row * 512 + c + 4) = b; __builtin_amdgcn_sched_barrier(0); ) }
;         else if (grp == 2) { WIN_LOOP( *(v4u*)(VH + (size_t)row * 512 + c) = pack8(a, b); ) }
;         else if (grp == 4) { WIN_LOOP( *(v4u*)(QO + (size_t)row * DM + 512 + c) = pack8(a * C2Q, b * C2Q); ) }
.LBB0_401:
	s_and_b64 vcc, exec, s[12:13]
	s_cbranch_vccz .LBB0_403
	v_and_b32_e32 v129, 64, v215
	v_xor_b32_e32 v128, 16, v215
	v_add_u32_e32 v129, 64, v129
	v_cmp_lt_i32_e32 vcc, v128, v129
	v_ashrrev_i32_e32 v167, 31, v166
	s_mov_b32 s2, 0x3e38aa3b
	v_cndmask_b32_e32 v128, v215, v128, vcc
	v_lshlrev_b32_e32 v132, 2, v128
	v_xor_b32_e32 v128, 32, v215
	v_cmp_lt_i32_e32 vcc, v128, v129
	v_lshlrev_b32_e32 v192, 1, v176
	s_nop 0
	v_cndmask_b32_e32 v128, v215, v128, vcc
	v_lshlrev_b32_e32 v133, 2, v128
	v_lshlrev_b64 v[128:129], 6, v[166:167]
	v_lshl_add_u64 v[128:129], v[160:161], 0, v[128:129]
	flat_load_dwordx4 v[128:131], v[128:129]
	s_waitcnt vmcnt(0) lgkmcnt(0)
	v_mov_b32_e32 v134, v129
	v_mov_b32_e32 v135, v130
	v_mov_b32_e32 v129, v131
	v_pk_add_f32 v[128:129], v[134:135], v[128:129]
	s_nop 0
	v_add_f32_e32 v128, v128, v129
	ds_bpermute_b32 v129, v132, v128
	s_waitcnt lgkmcnt(0)
	v_add_f32_e32 v128, v128, v129
	ds_bpermute_b32 v129, v133, v128
	s_waitcnt lgkmcnt(0)
	v_add_f32_e32 v128, v128, v129
	v_fmamk_f32 v128, v128, 0x3a800000, v212
	v_rsq_f32_e32 v134, v128
	v_lshlrev_b64 v[128:129], 11, v[166:167]
	v_lshl_add_u64 v[136:137], s[44:45], 0, v[128:129]
	v_lshl_add_u64 v[136:137], v[136:137], 0, v[192:193]
	v_pk_mul_f32 v[128:129], v[60:61], v[134:135] op_sel_hi:[1,0]
	v_pk_mul_f32 v[130:131], v[62:63], v[134:135] op_sel_hi:[1,0]
	v_pk_mul_f32 v[138:139], v[56:57], v[134:135] op_sel_hi:[1,0]
	v_pk_mul_f32 v[140:141], v[58:59], v[134:135] op_sel_hi:[1,0]
	v_pk_mul_f32 v[130:131], v[130:131], s[2:3] op_sel_hi:[1,0]
	v_pk_mul_f32 v[128:129], v[128:129], s[2:3] op_sel_hi:[1,0]
	v_pk_mul_f32 v[140:141], v[140:141], s[2:3] op_sel_hi:[1,0]
	v_pk_mul_f32 v[138:139], v[138:139], s[2:3] op_sel_hi:[1,0]
	v_cvt_pk_bf16_f32 v128, v128, v129
	v_cvt_pk_bf16_f32 v129, v130, v131
	v_cvt_pk_bf16_f32 v130, v138, v139
	v_cvt_pk_bf16_f32 v131, v140, v141
	flat_store_dwordx4 v[136:137], v[128:131] offset:1024 sc1
	v_pk_mul_f32 v[138:139], v[120:121], v[134:135] op_sel_hi:[1,0]
	s_nop 0
	v_pk_mul_f32 v[128:129], v[124:125], v[134:135] op_sel_hi:[1,0]
	v_pk_mul_f32 v[130:131], v[126:127], v[134:135] op_sel_hi:[1,0]
	v_pk_mul_f32 v[134:135], v[122:123], v[134:135] op_sel_hi:[1,0]
	v_pk_mul_f32 v[130:131], v[130:131], s[2:3] op_sel_hi:[1,0]
	v_pk_mul_f32 v[128:129], v[128:129], s[2:3] op_sel_hi:[1,0]
	v_pk_mul_f32 v[134:135], v[134:135], s[2:3] op_sel_hi:[1,0]
	v_pk_mul_f32 v[138:139], v[138:139], s[2:3] op_sel_hi:[1,0]
	v_cvt_pk_bf16_f32 v128, v128, v129
	v_cvt_pk_bf16_f32 v129, v130, v131
	v_cvt_pk_bf16_f32 v131, v134, v135
	v_or_b32_e32 v134, 16, v166
	v_cvt_pk_bf16_f32 v130, v138, v139
	v_ashrrev_i32_e32 v135, 31, v134
	flat_store_dwordx4 v[136:137], v[128:131] offset:1280 sc1
	s_nop 1
	v_lshlrev_b64 v[128:129], 6, v[134:135]
	v_lshl_add_u64 v[128:129], v[160:161], 0, v[128:129]
	flat_load_dwordx4 v[128:131], v[128:129]
	s_waitcnt vmcnt(0) lgkmcnt(0)
	v_mov_b32_e32 v136, v129
	v_mov_b32_e32 v137, v130
	v_mov_b32_e32 v129, v131
	v_pk_add_f32 v[128:129], v[136:137], v[128:129]
	s_nop 0
	v_add_f32_e32 v128, v128, v129
	ds_bpermute_b32 v129, v132, v128
	s_waitcnt lgkmcnt(0)
	v_add_f32_e32 v128, v128, v129
	ds_bpermute_b32 v129, v133, v128
	s_waitcnt lgkmcnt(0)
	v_add_f32_e32 v128, v128, v129
	v_fmamk_f32 v128, v128, 0x3a800000, v212
	v_rsq_f32_e32 v136, v128
	v_lshlrev_b64 v[128:129], 11, v[134:135]
	v_lshl_add_u64 v[134:135], s[44:45], 0, v[128:129]
	v_lshl_add_u64 v[134:135], v[134:135], 0, v[192:193]
	v_pk_mul_f32 v[128:129], v[52:53], v[136:137] op_sel_hi:[1,0]
	v_pk_mul_f32 v[130:131], v[54:55], v[136:137] op_sel_hi:[1,0]
	v_pk_mul_f32 v[138:139], v[48:49], v[136:137] op_sel_hi:[1,0]
	v_pk_mul_f32 v[140:141], v[50:51], v[136:137] op_sel_hi:[1,0]
	v_pk_mul_f32 v[130:131], v[130:131], s[2:3] op_sel_hi:[1,0]
	v_pk_mul_f32 v[128:129], v[128:129], s[2:3] op_sel_hi:[1,0]
	v_pk_mul_f32 v[140:141], v[140:141], s[2:3] op_sel_hi:[1,0]
	v_pk_mul_f32 v[138:139], v[138:139], s[2:3] op_sel_hi:[1,0]
	v_cvt_pk_bf16_f32 v128, v128, v129
	v_cvt_pk_bf16_f32 v129, v130, v131
	v_cvt_pk_bf16_f32 v130, v138, v139
	v_cvt_pk_bf16_f32 v131, v140, v141
	flat_store_dwordx4 v[134:135], v[128:131] offset:1024 sc1
	v_pk_mul_f32 v[138:139], v[112:113], v[136:137] op_sel_hi:[1,0]
	s_nop 0
	v_pk_mul_f32 v[128:129], v[116:117], v[136:137] op_sel_hi:[1,0]
	v_pk_mul_f32 v[130:131], v[118:119], v[136:137] op_sel_hi:[1,0]
	v_pk_mul_f32 v[136:137], v[114:115], v[136:137] op_sel_hi:[1,0]
	v_pk_mul_f32 v[130:131], v[130:131], s[2:3] op_sel_hi:[1,0]
	v_pk_mul_f32 v[128:129], v[128:129], s[2:3] op_sel_hi:[1,0]
	v_pk_mul_f32 v[136:137], v[136:137], s[2:3] op_sel_hi:[1,0]
	v_pk_mul_f32 v[138:139], v[138:139], s[2:3] op_sel_hi:[1,0]
	v_cvt_pk_bf16_f32 v128, v128, v129
	v_cvt_pk_bf16_f32 v129, v130, v131
	v_cvt_pk_bf16_f32 v130, v138, v139
	v_cvt_pk_bf16_f32 v131, v136, v137
	flat_store_dwordx4 v[134:135], v[128:131] offset:1280 sc1
	v_or_b32_e32 v134, 32, v166
	v_ashrrev_i32_e32 v135, 31, v134
	v_lshlrev_b64 v[128:129], 6, v[134:135]
	v_lshl_add_u64 v[128:129], v[160:161], 0, v[128:129]
	flat_load_dwordx4 v[128:131], v[128:129]
	s_waitcnt vmcnt(0) lgkmcnt(0)
	v_mov_b32_e32 v136, v129
	v_mov_b32_e32 v137, v130
	v_mov_b32_e32 v129, v131
	v_pk_add_f32 v[128:129], v[136:137], v[128:129]
	s_nop 0
	v_add_f32_e32 v128, v128, v129
	ds_bpermute_b32 v129, v132, v128
	s_waitcnt lgkmcnt(0)
	v_add_f32_e32 v128, v128, v129
	ds_bpermute_b32 v129, v133, v128
	s_waitcnt lgkmcnt(0)
; __device__ __forceinline__ float silu_f(float x) { return x * __builtin_amdgcn_rcpf(1.f + __expf(-x)); }
; __device__ __forceinline__ v4u pack8(const f32x4 a, const f32x4 b) { v4u w; w.x = cvt_pk_bf16(a[0], a[1]); w.y = cvt_pk_bf16(a[2], a[3]); w.z = cvt_pk_bf16(b[0], b[1]); w.w = cvt_pk_bf16(b[2], b[3]); return w; }
; __device__ __forceinline__ float row_rstd(const float* ssq, int row, int fq) {
;     const f32x4 v = *(const f32x4*)(ssq + (size_t)row * 16 + fq * 4);
;     float s = (v[0] + v[1]) + (v[2] + v[3]);
;     s += __shfl_xor(s, 16); s += __shfl_xor(s, 32);
;     return __builtin_amdgcn_rsqf(s * (1.f / DM) + EPS);
; }
;     __device__ __forceinline__ void operator()(const f32x4 (&acc)[2][2][4][2], const pg8::Unit& u, int wr, int wc, int fr, int fq) const {
;     ...
;         if (grp == 0) { WIN_LOOP( _Pragma("unroll") for (int i = 0; i < 4; ++i) { a[i] = silu_f(a[i]); b[i] = silu_f(b[i]); } *(v4u*)(QO + (size_t)row * DM + c) = pack8(a, b); ) }
;         else if (grp == 3) { WIN_LOOP( _Pragma("unroll") for (int i = 0; i < 4; ++i) { a[i] = silu_f(a[i]); b[i] = silu_f(b[i]); } *(v4u*)(GH + (size_t)row * 512 + c) = pack8(a, b); ) }
;         else if (grp == 1) {
;             f32x4 l0[2], l1[2];
; #pragma unroll
;             for (int bj = 0; bj < 2; ++bj) { l0[bj] = *(const f32x4*)(lb + cb + bj * 128); l1[bj] = *(const f32x4*)(lb + cb + bj * 128 + 4); }
;             WIN_LOOP( _Pragma("unroll") for (int i = 0; i < 4; ++i) { const float s0 = fminf(a[i], 0.f) - __logf(1.f + __expf(-fabsf(a[i]))), s1 = fminf(b[i], 0.f) - __logf(1.f + __expf(-fabsf(b[i]))); const float la = l0[bj][i], lbv = l1[bj][i];
;                     a[i] = la > 0.f ? __logf(la + (1.f - la) * __expf(s0)) : s0; b[i] = lbv > 0.f ? __logf(lbv + (1.f - lbv) * __expf(s1)) : s1; }
;                 *(f32x4*)(LF + (size_t)row * 512 + c) = a; *(f32x4*)(LF + (size_t)row * 512 + c + 4) = b; __builtin_amdgcn_sched_barrier(0); ) }
;         else if (grp == 2) { WIN_LOOP( *(v4u*)(VH + (size_t)row * 512 + c) = pack8(a, b); ) }
;         else if (grp == 4) { WIN_LOOP( *(v4u*)(QO + (size_t)row * DM + 512 + c) = pack8(a * C2Q, b * C2Q); ) }
	v_add_f32_e32 v128, v128, v129
	v_fmamk_f32 v128, v128, 0x3a800000, v212
	v_rsq_f32_e32 v136, v128
	v_lshlrev_b64 v[128:129], 11, v[134:135]
	v_lshl_add_u64 v[134:135], s[44:45], 0, v[128:129]
	v_lshl_add_u64 v[134:135], v[134:135], 0, v[192:193]
	v_pk_mul_f32 v[128:129], v[44:45], v[136:137] op_sel_hi:[1,0]
	v_pk_mul_f32 v[130:131], v[46:47], v[136:137] op_sel_hi:[1,0]
	v_pk_mul_f32 v[138:139], v[40:41], v[136:137] op_sel_hi:[1,0]
	v_pk_mul_f32 v[140:141], v[42:43], v[136:137] op_sel_hi:[1,0]
	v_pk_mul_f32 v[130:131], v[130:131], s[2:3] op_sel_hi:[1,0]
	v_pk_mul_f32 v[128:129], v[128:129], s[2:3] op_sel_hi:[1,0]
	v_pk_mul_f32 v[140:141], v[140:141], s[2:3] op_sel_hi:[1,0]
	v_pk_mul_f32 v[138:139], v[138:139], s[2:3] op_sel_hi:[1,0]
	v_cvt_pk_bf16_f32 v128, v128, v129
	v_cvt_pk_bf16_f32 v129, v130, v131
	v_cvt_pk_bf16_f32 v130, v138, v139
	v_cvt_pk_bf16_f32 v131, v140, v141
	flat_store_dwordx4 v[134:135], v[128:131] offset:1024 sc1
	v_pk_mul_f32 v[138:139], v[104:105], v[136:137] op_sel_hi:[1,0]
	s_nop 0
	v_pk_mul_f32 v[128:129], v[108:109], v[136:137] op_sel_hi:[1,0]
	v_pk_mul_f32 v[130:131], v[110:111], v[136:137] op_sel_hi:[1,0]
	v_pk_mul_f32 v[136:137], v[106:107], v[136:137] op_sel_hi:[1,0]
	v_pk_mul_f32 v[130:131], v[130:131], s[2:3] op_sel_hi:[1,0]
	v_pk_mul_f32 v[128:129], v[128:129], s[2:3] op_sel_hi:[1,0]
	v_pk_mul_f32 v[136:137], v[136:137], s[2:3] op_sel_hi:[1,0]
	v_pk_mul_f32 v[138:139], v[138:139], s[2:3] op_sel_hi:[1,0]
	v_cvt_pk_bf16_f32 v128, v128, v129
	v_cvt_pk_bf16_f32 v129, v130, v131
	v_cvt_pk_bf16_f32 v130, v138, v139
	v_cvt_pk_bf16_f32 v131, v136, v137
	flat_store_dwordx4 v[134:135], v[128:131] offset:1280 sc1
	v_or_b32_e32 v134, 48, v166
	v_ashrrev_i32_e32 v135, 31, v134
	v_lshlrev_b64 v[128:129], 6, v[134:135]
	v_lshl_add_u64 v[128:129], v[160:161], 0, v[128:129]
	flat_load_dwordx4 v[128:131], v[128:129]
	s_waitcnt vmcnt(0) lgkmcnt(0)
	v_mov_b32_e32 v136, v129
	v_mov_b32_e32 v137, v130
	v_mov_b32_e32 v129, v131
	v_pk_add_f32 v[128:129], v[136:137], v[128:129]
	s_nop 0
	v_add_f32_e32 v128, v128, v129
	ds_bpermute_b32 v129, v132, v128
	s_waitcnt lgkmcnt(0)
	v_add_f32_e32 v128, v128, v129
	ds_bpermute_b32 v129, v133, v128
	s_waitcnt lgkmcnt(0)
	v_add_f32_e32 v128, v128, v129
	v_fmamk_f32 v128, v128, 0x3a800000, v212
	v_rsq_f32_e32 v136, v128
	v_lshlrev_b64 v[128:129], 11, v[134:135]
	v_lshl_add_u64 v[134:135], s[44:45], 0, v[128:129]
	v_lshl_add_u64 v[134:135], v[134:135], 0, v[192:193]
	v_pk_mul_f32 v[128:129], v[36:37], v[136:137] op_sel_hi:[1,0]
	v_pk_mul_f32 v[130:131], v[38:39], v[136:137] op_sel_hi:[1,0]
	v_pk_mul_f32 v[138:139], v[32:33], v[136:137] op_sel_hi:[1,0]
	v_pk_mul_f32 v[140:141], v[34:35], v[136:137] op_sel_hi:[1,0]
	v_pk_mul_f32 v[130:131], v[130:131], s[2:3] op_sel_hi:[1,0]
	v_pk_mul_f32 v[128:129], v[128:129], s[2:3] op_sel_hi:[1,0]
	v_pk_mul_f32 v[140:141], v[140:141], s[2:3] op_sel_hi:[1,0]
	v_pk_mul_f32 v[138:139], v[138:139], s[2:3] op_sel_hi:[1,0]
	v_cvt_pk_bf16_f32 v128, v128, v129
	v_cvt_pk_bf16_f32 v129, v130, v131
	v_cvt_pk_bf16_f32 v130, v138, v139
	v_cvt_pk_bf16_f32 v131, v140, v141
	flat_store_dwordx4 v[134:135], v[128:131] offset:1024 sc1
	v_pk_mul_f32 v[138:139], v[96:97], v[136:137] op_sel_hi:[1,0]
	s_nop 0
	v_pk_mul_f32 v[128:129], v[100:101], v[136:137] op_sel_hi:[1,0]
	v_pk_mul_f32 v[130:131], v[102:103], v[136:137] op_sel_hi:[1,0]
	v_pk_mul_f32 v[136:137], v[98:99], v[136:137] op_sel_hi:[1,0]
	v_pk_mul_f32 v[130:131], v[130:131], s[2:3] op_sel_hi:[1,0]
	v_pk_mul_f32 v[128:129], v[128:129], s[2:3] op_sel_hi:[1,0]
	v_pk_mul_f32 v[136:137], v[136:137], s[2:3] op_sel_hi:[1,0]
	v_pk_mul_f32 v[138:139], v[138:139], s[2:3] op_sel_hi:[1,0]
	v_cvt_pk_bf16_f32 v128, v128, v129
	v_cvt_pk_bf16_f32 v129, v130, v131
	v_cvt_pk_bf16_f32 v130, v138, v139
	v_cvt_pk_bf16_f32 v131, v136, v137
	flat_store_dwordx4 v[134:135], v[128:131] offset:1280 sc1
	s_nop 1
	v_add_u32_e32 v128, 0x80, v166
	v_ashrrev_i32_e32 v129, 31, v128
	v_lshlrev_b64 v[130:131], 6, v[128:129]
	v_lshl_add_u64 v[130:131], v[160:161], 0, v[130:131]
	flat_load_dwordx4 v[134:137], v[130:131]
	v_lshlrev_b64 v[128:129], 11, v[128:129]
	s_waitcnt vmcnt(0) lgkmcnt(0)
	v_mov_b32_e32 v130, v135
	v_mov_b32_e32 v131, v136
	v_mov_b32_e32 v135, v137
	v_pk_add_f32 v[130:131], v[130:131], v[134:135]
	v_lshl_add_u64 v[136:137], s[44:45], 0, v[128:129]
	v_add_f32_e32 v130, v130, v131
	ds_bpermute_b32 v131, v132, v130
	v_lshl_add_u64 v[136:137], v[136:137], 0, v[192:193]
	s_waitcnt lgkmcnt(0)
	v_add_f32_e32 v130, v130, v131
	ds_bpermute_b32 v131, v133, v130
	s_waitcnt lgkmcnt(0)
	v_add_f32_e32 v130, v130, v131
	v_fmamk_f32 v130, v130, 0x3a800000, v212
	v_rsq_f32_e32 v134, v130
	s_nop 0
	v_pk_mul_f32 v[128:129], v[28:29], v[134:135] op_sel_hi:[1,0]
	v_pk_mul_f32 v[130:131], v[30:31], v[134:135] op_sel_hi:[1,0]
	v_pk_mul_f32 v[138:139], v[24:25], v[134:135] op_sel_hi:[1,0]
	v_pk_mul_f32 v[140:141], v[26:27], v[134:135] op_sel_hi:[1,0]
	v_pk_mul_f32 v[130:131], v[130:131], s[2:3] op_sel_hi:[1,0]
	v_pk_mul_f32 v[128:129], v[128:129], s[2:3] op_sel_hi:[1,0]
	v_pk_mul_f32 v[140:141], v[140:141], s[2:3] op_sel_hi:[1,0]
	v_pk_mul_f32 v[138:139], v[138:139], s[2:3] op_sel_hi:[1,0]
	v_cvt_pk_bf16_f32 v128, v128, v129
	v_cvt_pk_bf16_f32 v129, v130, v131
	v_cvt_pk_bf16_f32 v130, v138, v139
	v_cvt_pk_bf16_f32 v131, v140, v141
	flat_store_dwordx4 v[136:137], v[128:131] offset:1024 sc1
	v_pk_mul_f32 v[138:139], v[88:89], v[134:135] op_sel_hi:[1,0]
	s_nop 0
	v_pk_mul_f32 v[128:129], v[92:93], v[134:135] op_sel_hi:[1,0]
	v_pk_mul_f32 v[130:131], v[94:95], v[134:135] op_sel_hi:[1,0]
	v_pk_mul_f32 v[134:135], v[90:91], v[134:135] op_sel_hi:[1,0]
	v_pk_mul_f32 v[130:131], v[130:131], s[2:3] op_sel_hi:[1,0]
	v_pk_mul_f32 v[128:129], v[128:129], s[2:3] op_sel_hi:[1,0]
	v_pk_mul_f32 v[134:135], v[134:135], s[2:3] op_sel_hi:[1,0]
	v_pk_mul_f32 v[138:139], v[138:139], s[2:3] op_sel_hi:[1,0]
	v_cvt_pk_bf16_f32 v128, v128, v129
	v_cvt_pk_bf16_f32 v129, v130, v131
	v_cvt_pk_bf16_f32 v131, v134, v135
	v_add_u32_e32 v134, 0x90, v166
	v_cvt_pk_bf16_f32 v130, v138, v139
	v_ashrrev_i32_e32 v135, 31, v134
	flat_store_dwordx4 v[136:137], v[128:131] offset:1280 sc1
	s_nop 1
	v_lshlrev_b64 v[128:129], 6, v[134:135]
	v_lshl_add_u64 v[128:129], v[160:161], 0, v[128:129]
	flat_load_dwordx4 v[128:131], v[128:129]
	s_waitcnt vmcnt(0) lgkmcnt(0)
; __device__ __forceinline__ float silu_f(float x) { return x * __builtin_amdgcn_rcpf(1.f + __expf(-x)); }
; __device__ __forceinline__ v4u pack8(const f32x4 a, const f32x4 b) { v4u w; w.x = cvt_pk_bf16(a[0], a[1]); w.y = cvt_pk_bf16(a[2], a[3]); w.z = cvt_pk_bf16(b[0], b[1]); w.w = cvt_pk_bf16(b[2], b[3]); return w; }
; __device__ __forceinline__ float row_rstd(const float* ssq, int row, int fq) {
;     const f32x4 v = *(const f32x4*)(ssq + (size_t)row * 16 + fq * 4);
;     float s = (v[0] + v[1]) + (v[2] + v[3]);
;     s += __shfl_xor(s, 16); s += __shfl_xor(s, 32);
;     return __builtin_amdgcn_rsqf(s * (1.f / DM) + EPS);
; }
;     __device__ __forceinline__ void operator()(const f32x4 (&acc)[2][2][4][2], const pg8::Unit& u, int wr, int wc, int fr, int fq) const {
;     ...
;         if (grp == 0) { WIN_LOOP( _Pragma("unroll") for (int i = 0; i < 4; ++i) { a[i] = silu_f(a[i]); b[i] = silu_f(b[i]); } *(v4u*)(QO + (size_t)row * DM + c) = pack8(a, b); ) }
;         else if (grp == 3) { WIN_LOOP( _Pragma("unroll") for (int i = 0; i < 4; ++i) { a[i] = silu_f(a[i]); b[i] = silu_f(b[i]); } *(v4u*)(GH + (size_t)row * 512 + c) = pack8(a, b); ) }
;         else if (grp == 1) {
;             f32x4 l0[2], l1[2];
; #pragma unroll
;             for (int bj = 0; bj < 2; ++bj) { l0[bj] = *(const f32x4*)(lb + cb + bj * 128); l1[bj] = *(const f32x4*)(lb + cb + bj * 128 + 4); }
;             WIN_LOOP( _Pragma("unroll") for (int i = 0; i < 4; ++i) { const float s0 = fminf(a[i], 0.f) - __logf(1.f + __expf(-fabsf(a[i]))), s1 = fminf(b[i], 0.f) - __logf(1.f + __expf(-fabsf(b[i]))); const float la = l0[bj][i], lbv = l1[bj][i];
;                     a[i] = la > 0.f ? __logf(la + (1.f - la) * __expf(s0)) : s0; b[i] = lbv > 0.f ? __logf(lbv + (1.f - lbv) * __expf(s1)) : s1; }
;                 *(f32x4*)(LF + (size_t)row * 512 + c) = a; *(f32x4*)(LF + (size_t)row * 512 + c + 4) = b; __builtin_amdgcn_sched_barrier(0); ) }
;         else if (grp == 2) { WIN_LOOP( *(v4u*)(VH + (size_t)row * 512 + c) = pack8(a, b); ) }
;         else if (grp == 4) { WIN_LOOP( *(v4u*)(QO + (size_t)row * DM + 512 + c) = pack8(a * C2Q, b * C2Q); ) }
	v_mov_b32_e32 v136, v129
	v_mov_b32_e32 v137, v130
	v_mov_b32_e32 v129, v131
	v_pk_add_f32 v[128:129], v[136:137], v[128:129]
	s_nop 0
	v_add_f32_e32 v128, v128, v129
	ds_bpermute_b32 v129, v132, v128
	s_waitcnt lgkmcnt(0)
	v_add_f32_e32 v128, v128, v129
	ds_bpermute_b32 v129, v133, v128
	s_waitcnt lgkmcnt(0)
	v_add_f32_e32 v128, v128, v129
	v_fmamk_f32 v128, v128, 0x3a800000, v212
	v_rsq_f32_e32 v136, v128
	v_lshlrev_b64 v[128:129], 11, v[134:135]
	v_lshl_add_u64 v[134:135], s[44:45], 0, v[128:129]
	v_lshl_add_u64 v[134:135], v[134:135], 0, v[192:193]
	v_pk_mul_f32 v[128:129], v[20:21], v[136:137] op_sel_hi:[1,0]
	v_pk_mul_f32 v[130:131], v[22:23], v[136:137] op_sel_hi:[1,0]
	v_pk_mul_f32 v[138:139], v[16:17], v[136:137] op_sel_hi:[1,0]
	v_pk_mul_f32 v[140:141], v[18:19], v[136:137] op_sel_hi:[1,0]
	v_pk_mul_f32 v[130:131], v[130:131], s[2:3] op_sel_hi:[1,0]
	v_pk_mul_f32 v[128:129], v[128:129], s[2:3] op_sel_hi:[1,0]
	v_pk_mul_f32 v[140:141], v[140:141], s[2:3] op_sel_hi:[1,0]
	v_pk_mul_f32 v[138:139], v[138:139], s[2:3] op_sel_hi:[1,0]
	v_cvt_pk_bf16_f32 v128, v128, v129
	v_cvt_pk_bf16_f32 v129, v130, v131
	v_cvt_pk_bf16_f32 v130, v138, v139
	v_cvt_pk_bf16_f32 v131, v140, v141
	flat_store_dwordx4 v[134:135], v[128:131] offset:1024 sc1
	v_pk_mul_f32 v[138:139], v[80:81], v[136:137] op_sel_hi:[1,0]
	s_nop 0
	v_pk_mul_f32 v[128:129], v[84:85], v[136:137] op_sel_hi:[1,0]
	v_pk_mul_f32 v[130:131], v[86:87], v[136:137] op_sel_hi:[1,0]
	v_pk_mul_f32 v[136:137], v[82:83], v[136:137] op_sel_hi:[1,0]
	v_pk_mul_f32 v[130:131], v[130:131], s[2:3] op_sel_hi:[1,0]
	v_pk_mul_f32 v[128:129], v[128:129], s[2:3] op_sel_hi:[1,0]
	v_pk_mul_f32 v[136:137], v[136:137], s[2:3] op_sel_hi:[1,0]
	v_pk_mul_f32 v[138:139], v[138:139], s[2:3] op_sel_hi:[1,0]
	v_cvt_pk_bf16_f32 v128, v128, v129
	v_cvt_pk_bf16_f32 v129, v130, v131
	v_cvt_pk_bf16_f32 v130, v138, v139
	v_cvt_pk_bf16_f32 v131, v136, v137
	flat_store_dwordx4 v[134:135], v[128:131] offset:1280 sc1
	v_add_u32_e32 v134, 0xa0, v166
	v_ashrrev_i32_e32 v135, 31, v134
	v_lshlrev_b64 v[128:129], 6, v[134:135]
	v_lshl_add_u64 v[128:129], v[160:161], 0, v[128:129]
	flat_load_dwordx4 v[128:131], v[128:129]
	s_waitcnt vmcnt(0) lgkmcnt(0)
	v_mov_b32_e32 v136, v129
	v_mov_b32_e32 v137, v130
	v_mov_b32_e32 v129, v131
	v_pk_add_f32 v[128:129], v[136:137], v[128:129]
	s_nop 0
	v_add_f32_e32 v128, v128, v129
	ds_bpermute_b32 v129, v132, v128
	s_waitcnt lgkmcnt(0)
	v_add_f32_e32 v128, v128, v129
	ds_bpermute_b32 v129, v133, v128
	s_waitcnt lgkmcnt(0)
	v_add_f32_e32 v128, v128, v129
	v_fmamk_f32 v128, v128, 0x3a800000, v212
	v_rsq_f32_e32 v136, v128
	v_lshlrev_b64 v[128:129], 11, v[134:135]
	v_lshl_add_u64 v[134:135], s[44:45], 0, v[128:129]
	v_lshl_add_u64 v[134:135], v[134:135], 0, v[192:193]
	v_pk_mul_f32 v[128:129], v[12:13], v[136:137] op_sel_hi:[1,0]
	v_pk_mul_f32 v[130:131], v[14:15], v[136:137] op_sel_hi:[1,0]
	v_pk_mul_f32 v[138:139], v[8:9], v[136:137] op_sel_hi:[1,0]
	v_pk_mul_f32 v[140:141], v[10:11], v[136:137] op_sel_hi:[1,0]
	v_pk_mul_f32 v[130:131], v[130:131], s[2:3] op_sel_hi:[1,0]
	v_pk_mul_f32 v[128:129], v[128:129], s[2:3] op_sel_hi:[1,0]
	v_pk_mul_f32 v[140:141], v[140:141], s[2:3] op_sel_hi:[1,0]
	v_pk_mul_f32 v[138:139], v[138:139], s[2:3] op_sel_hi:[1,0]
	v_cvt_pk_bf16_f32 v128, v128, v129
	v_cvt_pk_bf16_f32 v129, v130, v131
	v_cvt_pk_bf16_f32 v130, v138, v139
	v_cvt_pk_bf16_f32 v131, v140, v141
	flat_store_dwordx4 v[134:135], v[128:131] offset:1024 sc1
	v_pk_mul_f32 v[138:139], v[72:73], v[136:137] op_sel_hi:[1,0]
	s_nop 0
	v_pk_mul_f32 v[128:129], v[76:77], v[136:137] op_sel_hi:[1,0]
	v_pk_mul_f32 v[130:131], v[78:79], v[136:137] op_sel_hi:[1,0]
	v_pk_mul_f32 v[136:137], v[74:75], v[136:137] op_sel_hi:[1,0]
	v_pk_mul_f32 v[130:131], v[130:131], s[2:3] op_sel_hi:[1,0]
	v_pk_mul_f32 v[128:129], v[128:129], s[2:3] op_sel_hi:[1,0]
	v_pk_mul_f32 v[136:137], v[136:137], s[2:3] op_sel_hi:[1,0]
	v_pk_mul_f32 v[138:139], v[138:139], s[2:3] op_sel_hi:[1,0]
	v_cvt_pk_bf16_f32 v128, v128, v129
	v_cvt_pk_bf16_f32 v129, v130, v131
	v_cvt_pk_bf16_f32 v130, v138, v139
	v_cvt_pk_bf16_f32 v131, v136, v137
	flat_store_dwordx4 v[134:135], v[128:131] offset:1280 sc1
	v_add_u32_e32 v134, 0xb0, v166
	v_ashrrev_i32_e32 v135, 31, v134
	v_lshlrev_b64 v[128:129], 6, v[134:135]
	v_lshl_add_u64 v[128:129], v[160:161], 0, v[128:129]
	flat_load_dwordx4 v[128:131], v[128:129]
	s_waitcnt vmcnt(0) lgkmcnt(0)
	v_mov_b32_e32 v136, v129
	v_mov_b32_e32 v137, v130
	v_mov_b32_e32 v129, v131
	v_pk_add_f32 v[128:129], v[136:137], v[128:129]
	s_nop 0
	v_add_f32_e32 v128, v128, v129
	ds_bpermute_b32 v129, v132, v128
	s_waitcnt lgkmcnt(0)
	v_add_f32_e32 v128, v128, v129
	ds_bpermute_b32 v129, v133, v128
	s_waitcnt lgkmcnt(0)
	v_add_f32_e32 v128, v128, v129
	v_fmamk_f32 v128, v128, 0x3a800000, v212
	v_rsq_f32_e32 v132, v128
	v_lshlrev_b64 v[128:129], 11, v[134:135]
	v_lshl_add_u64 v[134:135], s[44:45], 0, v[128:129]
	v_lshl_add_u64 v[134:135], v[134:135], 0, v[192:193]
	v_pk_mul_f32 v[128:129], v[4:5], v[132:133] op_sel_hi:[1,0]
	v_pk_mul_f32 v[130:131], v[6:7], v[132:133] op_sel_hi:[1,0]
	v_pk_mul_f32 v[136:137], v[0:1], v[132:133] op_sel_hi:[1,0]
	v_pk_mul_f32 v[138:139], v[2:3], v[132:133] op_sel_hi:[1,0]
	v_pk_mul_f32 v[130:131], v[130:131], s[2:3] op_sel_hi:[1,0]
	v_pk_mul_f32 v[128:129], v[128:129], s[2:3] op_sel_hi:[1,0]
	v_pk_mul_f32 v[138:139], v[138:139], s[2:3] op_sel_hi:[1,0]
	v_pk_mul_f32 v[136:137], v[136:137], s[2:3] op_sel_hi:[1,0]
	v_cvt_pk_bf16_f32 v128, v128, v129
	v_cvt_pk_bf16_f32 v129, v130, v131
	v_cvt_pk_bf16_f32 v130, v136, v137
	v_cvt_pk_bf16_f32 v131, v138, v139
	flat_store_dwordx4 v[134:135], v[128:131] offset:1024 sc1
	v_pk_mul_f32 v[136:137], v[64:65], v[132:133] op_sel_hi:[1,0]
	s_nop 0
	v_pk_mul_f32 v[128:129], v[68:69], v[132:133] op_sel_hi:[1,0]
	v_pk_mul_f32 v[130:131], v[70:71], v[132:133] op_sel_hi:[1,0]
	v_pk_mul_f32 v[132:133], v[66:67], v[132:133] op_sel_hi:[1,0]
	v_pk_mul_f32 v[130:131], v[130:131], s[2:3] op_sel_hi:[1,0]
	v_pk_mul_f32 v[128:129], v[128:129], s[2:3] op_sel_hi:[1,0]
	v_pk_mul_f32 v[132:133], v[132:133], s[2:3] op_sel_hi:[1,0]
	v_pk_mul_f32 v[136:137], v[136:137], s[2:3] op_sel_hi:[1,0]
	v_cvt_pk_bf16_f32 v128, v128, v129
	v_cvt_pk_bf16_f32 v129, v130, v131
	v_cvt_pk_bf16_f32 v130, v136, v137
	v_cvt_pk_bf16_f32 v131, v132, v133
	flat_store_dwordx4 v[134:135], v[128:131] offset:1280 sc1

; __device__ __forceinline__ v4u pack8(const f32x4 a, const f32x4 b) { v4u w; w.x = cvt_pk_bf16(a[0], a[1]); w.y = cvt_pk_bf16(a[2], a[3]); w.z = cvt_pk_bf16(b[0], b[1]); w.w = cvt_pk_bf16(b[2], b[3]); return w; }
; __device__ __forceinline__ float silu_f(float x) { return x * __builtin_amdgcn_rcpf(1.f + __expf(-x)); }
; __device__ __forceinline__ float logsig_f(float x) { return fminf(x, 0.f) - __logf(1.f + __expf(-fabsf(x))); }
; __device__ __forceinline__ float row_rstd(const float* ssq, int row, int fq) {
;     const f32x4 v = *(const f32x4*)(ssq + (size_t)row * 16 + fq * 4);
;     float s = (v[0] + v[1]) + (v[2] + v[3]);
;     s += __shfl_xor(s, 16); s += __shfl_xor(s, 32);
;     return __builtin_amdgcn_rsqf(s * (1.f / DM) + EPS);
; }
;     __device__ __forceinline__ void operator()(const f32x4 (&acc)[2][2][4][2], const pg8::Unit& u, int wr, int wc, int fr, int fq) const {
;     ...
;         if (grp == 0) { WIN_LOOP( _Pragma("unroll") for (int i = 0; i < 4; ++i) { a[i] = silu_f(a[i]); b[i] = silu_f(b[i]); } *(v4u*)(QO + (size_t)row * DM + c) = pack8(a, b); ) }
;         else if (grp == 3) { WIN_LOOP( _Pragma("unroll") for (int i = 0; i < 4; ++i) { a[i] = silu_f(a[i]); b[i] = silu_f(b[i]); } *(v4u*)(GH + (size_t)row * 512 + c) = pack8(a, b); ) }
.LBB0_404:
	s_and_b64 vcc, exec, s[12:13]
	s_cbranch_vccz .LBB0_406
	v_and_b32_e32 v129, 64, v215
	v_xor_b32_e32 v128, 16, v215
	v_add_u32_e32 v129, 64, v129
	v_cmp_lt_i32_e32 vcc, v128, v129
	v_ashrrev_i32_e32 v167, 31, v166
	v_readlane_b32 s12, v255, 39
	v_cndmask_b32_e32 v128, v215, v128, vcc
	v_lshlrev_b32_e32 v140, 2, v128
	v_xor_b32_e32 v128, 32, v215
	v_cmp_lt_i32_e32 vcc, v128, v129
	v_readlane_b32 s13, v255, 40
	v_lshlrev_b32_e32 v192, 1, v176
	v_cndmask_b32_e32 v128, v215, v128, vcc
	v_lshlrev_b32_e32 v141, 2, v128
	v_lshlrev_b64 v[128:129], 6, v[166:167]
	v_lshl_add_u64 v[128:129], v[160:161], 0, v[128:129]
	flat_load_dwordx4 v[128:131], v[128:129]
	s_waitcnt vmcnt(0) lgkmcnt(0)
	v_mov_b32_e32 v132, v129
	v_mov_b32_e32 v133, v130
	v_mov_b32_e32 v129, v131
	v_pk_add_f32 v[128:129], v[132:133], v[128:129]
	s_nop 0
	v_add_f32_e32 v128, v128, v129
	ds_bpermute_b32 v129, v140, v128
	s_waitcnt lgkmcnt(0)
	v_add_f32_e32 v128, v128, v129
	ds_bpermute_b32 v129, v141, v128
	s_waitcnt lgkmcnt(0)
	v_add_f32_e32 v128, v128, v129
	v_fmamk_f32 v128, v128, 0x3a800000, v212
	v_rsq_f32_e32 v132, v128
	v_lshlrev_b64 v[128:129], 10, v[166:167]
	v_lshl_add_u64 v[134:135], s[12:13], 0, v[128:129]
	v_lshl_add_u64 v[134:135], v[134:135], 0, v[192:193]
	v_pk_mul_f32 v[130:131], v[60:61], v[132:133] op_sel_hi:[1,0]
	v_pk_mul_f32 v[128:129], v[62:63], v[132:133] op_sel_hi:[1,0]
	v_pk_mul_f32 v[136:137], v[58:59], v[132:133] op_sel_hi:[1,0]
	v_pk_mul_f32 v[138:139], v[56:57], v[132:133] op_sel_hi:[1,0]
	v_mul_f32_e32 v133, 0xbfb8aa3b, v130
	v_exp_f32_e32 v133, v133
	s_nop 0
	v_add_f32_e32 v133, 1.0, v133
	v_rcp_f32_e32 v142, v133
	v_mul_f32_e32 v133, 0xbfb8aa3b, v138
	v_exp_f32_e32 v133, v133
	s_nop 0
	v_add_f32_e32 v133, 1.0, v133
	v_rcp_f32_e32 v144, v133
	v_mul_f32_e32 v133, 0xbfb8aa3b, v131
	v_exp_f32_e32 v133, v133
	s_nop 0
	v_add_f32_e32 v133, 1.0, v133
	v_rcp_f32_e32 v143, v133
	v_mul_f32_e32 v133, 0xbfb8aa3b, v139
	v_exp_f32_e32 v133, v133
	v_pk_mul_f32 v[130:131], v[130:131], v[142:143]
	v_add_f32_e32 v133, 1.0, v133
	v_rcp_f32_e32 v145, v133
	v_mul_f32_e32 v133, 0xbfb8aa3b, v128
	v_exp_f32_e32 v133, v133
	v_pk_mul_f32 v[138:139], v[138:139], v[144:145]
	v_add_f32_e32 v133, 1.0, v133
	v_rcp_f32_e32 v142, v133
	v_mul_f32_e32 v133, 0xbfb8aa3b, v136
	v_exp_f32_e32 v133, v133
	s_nop 0
	v_add_f32_e32 v133, 1.0, v133
	v_rcp_f32_e32 v144, v133
	v_mul_f32_e32 v133, 0xbfb8aa3b, v129
	v_exp_f32_e32 v133, v133
	s_nop 0
	v_add_f32_e32 v133, 1.0, v133
	v_rcp_f32_e32 v143, v133
	s_nop 0
	v_pk_mul_f32 v[142:143], v[128:129], v[142:143]
	v_mul_f32_e32 v128, 0xbfb8aa3b, v137
	v_exp_f32_e32 v128, v128
	v_cvt_pk_bf16_f32 v129, v142, v143
	v_add_f32_e32 v128, 1.0, v128
	v_rcp_f32_e32 v145, v128
	v_cvt_pk_bf16_f32 v128, v130, v131
	v_cvt_pk_bf16_f32 v130, v138, v139
	v_pk_mul_f32 v[136:137], v[136:137], v[144:145]
	s_nop 0
	v_cvt_pk_bf16_f32 v131, v136, v137
	flat_store_dwordx4 v[134:135], v[128:131] sc1
	v_pk_mul_f32 v[136:137], v[122:123], v[132:133] op_sel_hi:[1,0]
	s_nop 0
	v_pk_mul_f32 v[128:129], v[126:127], v[132:133] op_sel_hi:[1,0]
	v_pk_mul_f32 v[130:131], v[124:125], v[132:133] op_sel_hi:[1,0]
	v_pk_mul_f32 v[132:133], v[120:121], v[132:133] op_sel_hi:[1,0]
	v_mul_f32_e32 v138, 0xbfb8aa3b, v130
	v_mul_f32_e32 v139, 0xbfb8aa3b, v132
	v_exp_f32_e32 v139, v139
	v_exp_f32_e32 v138, v138
	v_add_f32_e32 v139, 1.0, v139
	v_rcp_f32_e32 v142, v139
	v_mul_f32_e32 v139, 0xbfb8aa3b, v131
	v_exp_f32_e32 v139, v139
	v_add_f32_e32 v138, 1.0, v138
	v_rcp_f32_e32 v138, v138
	v_add_f32_e32 v139, 1.0, v139
	v_rcp_f32_e32 v139, v139
	s_nop 0
	v_pk_mul_f32 v[130:131], v[130:131], v[138:139]
	v_mul_f32_e32 v138, 0xbfb8aa3b, v133
	v_exp_f32_e32 v138, v138
	v_mul_f32_e32 v139, 0xbfb8aa3b, v136
	v_exp_f32_e32 v139, v139
	v_add_f32_e32 v138, 1.0, v138
	v_rcp_f32_e32 v143, v138
	v_add_f32_e32 v139, 1.0, v139
	v_mul_f32_e32 v138, 0xbfb8aa3b, v128
	v_exp_f32_e32 v138, v138
	v_pk_mul_f32 v[132:133], v[132:133], v[142:143]
	v_rcp_f32_e32 v142, v139
	v_mul_f32_e32 v139, 0xbfb8aa3b, v129
	v_exp_f32_e32 v139, v139
	v_add_f32_e32 v138, 1.0, v138
	v_rcp_f32_e32 v138, v138
	v_add_f32_e32 v139, 1.0, v139
	v_rcp_f32_e32 v139, v139
	s_nop 0
	v_pk_mul_f32 v[138:139], v[128:129], v[138:139]
	v_mul_f32_e32 v128, 0xbfb8aa3b, v137
	v_exp_f32_e32 v128, v128
	v_cvt_pk_bf16_f32 v129, v138, v139
	v_add_f32_e32 v128, 1.0, v128
	v_rcp_f32_e32 v143, v128
	v_cvt_pk_bf16_f32 v128, v130, v131
	v_cvt_pk_bf16_f32 v130, v132, v133
	v_pk_mul_f32 v[136:137], v[136:137], v[142:143]
	s_nop 0
	v_cvt_pk_bf16_f32 v131, v136, v137
	flat_store_dwordx4 v[134:135], v[128:131] offset:256 sc1
	v_or_b32_e32 v134, 16, v166
	v_ashrrev_i32_e32 v135, 31, v134
	v_lshlrev_b64 v[128:129], 6, v[134:135]
	v_lshl_add_u64 v[128:129], v[160:161], 0, v[128:129]
	flat_load_dwordx4 v[128:131], v[128:129]
	s_waitcnt vmcnt(0) lgkmcnt(0)
	v_mov_b32_e32 v132, v129
	v_mov_b32_e32 v133, v130
	v_mov_b32_e32 v129, v131
	v_pk_add_f32 v[128:129], v[132:133], v[128:129]
	s_nop 0
	v_add_f32_e32 v128, v128, v129
	ds_bpermute_b32 v129, v140, v128
	s_waitcnt lgkmcnt(0)
	v_add_f32_e32 v128, v128, v129
	ds_bpermute_b32 v129, v141, v128
	s_waitcnt lgkmcnt(0)
; __device__ __forceinline__ v4u pack8(const f32x4 a, const f32x4 b) { v4u w; w.x = cvt_pk_bf16(a[0], a[1]); w.y = cvt_pk_bf16(a[2], a[3]); w.z = cvt_pk_bf16(b[0], b[1]); w.w = cvt_pk_bf16(b[2], b[3]); return w; }
; __device__ __forceinline__ float silu_f(float x) { return x * __builtin_amdgcn_rcpf(1.f + __expf(-x)); }
; __device__ __forceinline__ float logsig_f(float x) { return fminf(x, 0.f) - __logf(1.f + __expf(-fabsf(x))); }
; __device__ __forceinline__ float row_rstd(const float* ssq, int row, int fq) {
;     const f32x4 v = *(const f32x4*)(ssq + (size_t)row * 16 + fq * 4);
;     float s = (v[0] + v[1]) + (v[2] + v[3]);
;     s += __shfl_xor(s, 16); s += __shfl_xor(s, 32);
;     return __builtin_amdgcn_rsqf(s * (1.f / DM) + EPS);
; }
;     __device__ __forceinline__ void operator()(const f32x4 (&acc)[2][2][4][2], const pg8::Unit& u, int wr, int wc, int fr, int fq) const {
;     ...
;         if (grp == 0) { WIN_LOOP( _Pragma("unroll") for (int i = 0; i < 4; ++i) { a[i] = silu_f(a[i]); b[i] = silu_f(b[i]); } *(v4u*)(QO + (size_t)row * DM + c) = pack8(a, b); ) }
;         else if (grp == 3) { WIN_LOOP( _Pragma("unroll") for (int i = 0; i < 4; ++i) { a[i] = silu_f(a[i]); b[i] = silu_f(b[i]); } *(v4u*)(GH + (size_t)row * 512 + c) = pack8(a, b); ) }
	v_add_f32_e32 v128, v128, v129
	v_fmamk_f32 v128, v128, 0x3a800000, v212
	v_rsq_f32_e32 v132, v128
	v_lshlrev_b64 v[128:129], 10, v[134:135]
	v_lshl_add_u64 v[128:129], s[12:13], 0, v[128:129]
	v_lshl_add_u64 v[128:129], v[128:129], 0, v[192:193]
	v_pk_mul_f32 v[134:135], v[52:53], v[132:133] op_sel_hi:[1,0]
	v_pk_mul_f32 v[130:131], v[54:55], v[132:133] op_sel_hi:[1,0]
	v_pk_mul_f32 v[136:137], v[50:51], v[132:133] op_sel_hi:[1,0]
	v_pk_mul_f32 v[138:139], v[48:49], v[132:133] op_sel_hi:[1,0]
	v_mul_f32_e32 v133, 0xbfb8aa3b, v134
	v_exp_f32_e32 v133, v133
	s_nop 0
	v_add_f32_e32 v133, 1.0, v133
	v_rcp_f32_e32 v142, v133
	v_mul_f32_e32 v133, 0xbfb8aa3b, v138
	v_exp_f32_e32 v133, v133
	s_nop 0
	v_add_f32_e32 v133, 1.0, v133
	v_rcp_f32_e32 v144, v133
	v_mul_f32_e32 v133, 0xbfb8aa3b, v135
	v_exp_f32_e32 v133, v133
	s_nop 0
	v_add_f32_e32 v133, 1.0, v133
	v_rcp_f32_e32 v143, v133
	v_mul_f32_e32 v133, 0xbfb8aa3b, v139
	v_exp_f32_e32 v133, v133
	v_pk_mul_f32 v[134:135], v[134:135], v[142:143]
	s_nop 0
	v_cvt_pk_bf16_f32 v134, v134, v135
	v_add_f32_e32 v133, 1.0, v133
	v_rcp_f32_e32 v145, v133
	v_mul_f32_e32 v133, 0xbfb8aa3b, v130
	v_exp_f32_e32 v133, v133
	v_pk_mul_f32 v[138:139], v[138:139], v[144:145]
	v_add_f32_e32 v133, 1.0, v133
	v_rcp_f32_e32 v142, v133
	v_mul_f32_e32 v133, 0xbfb8aa3b, v136
	v_exp_f32_e32 v133, v133
	s_nop 0
	v_add_f32_e32 v133, 1.0, v133
	v_rcp_f32_e32 v144, v133
	v_mul_f32_e32 v133, 0xbfb8aa3b, v131
	v_exp_f32_e32 v133, v133
	s_nop 0
	v_add_f32_e32 v133, 1.0, v133
	v_rcp_f32_e32 v143, v133
	v_mul_f32_e32 v133, 0xbfb8aa3b, v137
	v_exp_f32_e32 v133, v133
	v_pk_mul_f32 v[130:131], v[130:131], v[142:143]
	s_nop 0
	v_cvt_pk_bf16_f32 v135, v130, v131
	v_add_f32_e32 v133, 1.0, v133
	v_rcp_f32_e32 v145, v133
	v_pk_mul_f32 v[130:131], v[114:115], v[132:133] op_sel_hi:[1,0]
	v_pk_mul_f32 v[142:143], v[136:137], v[144:145]
	v_cvt_pk_bf16_f32 v136, v138, v139
	v_cvt_pk_bf16_f32 v137, v142, v143
	flat_store_dwordx4 v[128:129], v[134:137] sc1
	v_pk_mul_f32 v[138:139], v[118:119], v[132:133] op_sel_hi:[1,0]
	s_nop 0
	v_pk_mul_f32 v[136:137], v[112:113], v[132:133] op_sel_hi:[1,0]
	v_pk_mul_f32 v[134:135], v[116:117], v[132:133] op_sel_hi:[1,0]
	v_mul_f32_e32 v133, 0xbfb8aa3b, v136
	v_exp_f32_e32 v133, v133
	v_mul_f32_e32 v132, 0xbfb8aa3b, v134
	v_exp_f32_e32 v132, v132
	v_add_f32_e32 v133, 1.0, v133
	v_rcp_f32_e32 v142, v133
	v_mul_f32_e32 v133, 0xbfb8aa3b, v135
	v_exp_f32_e32 v133, v133
	v_add_f32_e32 v132, 1.0, v132
	v_rcp_f32_e32 v132, v132
	v_add_f32_e32 v133, 1.0, v133
	v_rcp_f32_e32 v133, v133
	s_nop 0
	v_pk_mul_f32 v[132:133], v[134:135], v[132:133]
	v_mul_f32_e32 v134, 0xbfb8aa3b, v137
	v_exp_f32_e32 v134, v134
	s_nop 0
	v_add_f32_e32 v134, 1.0, v134
	v_rcp_f32_e32 v143, v134
	s_nop 0
	v_pk_mul_f32 v[134:135], v[136:137], v[142:143]
	v_mul_f32_e32 v136, 0xbfb8aa3b, v138
	v_mul_f32_e32 v137, 0xbfb8aa3b, v139
	v_exp_f32_e32 v136, v136
	v_exp_f32_e32 v137, v137
	v_add_f32_e32 v136, 1.0, v136
	v_add_f32_e32 v137, 1.0, v137
	v_rcp_f32_e32 v142, v136
	v_mul_f32_e32 v136, 0xbfb8aa3b, v130
	v_rcp_f32_e32 v143, v137
	v_mul_f32_e32 v137, 0xbfb8aa3b, v131
	v_exp_f32_e32 v136, v136
	v_exp_f32_e32 v137, v137
	v_pk_mul_f32 v[138:139], v[138:139], v[142:143]
	v_add_f32_e32 v136, 1.0, v136
	v_add_f32_e32 v137, 1.0, v137
	v_rcp_f32_e32 v136, v136
	v_rcp_f32_e32 v137, v137
	s_nop 0
	v_pk_mul_f32 v[136:137], v[130:131], v[136:137]
	v_cvt_pk_bf16_f32 v130, v132, v133
	v_cvt_pk_bf16_f32 v131, v138, v139
	v_cvt_pk_bf16_f32 v132, v134, v135
	v_cvt_pk_bf16_f32 v133, v136, v137
	flat_store_dwordx4 v[128:129], v[130:133] offset:256 sc1
	s_nop 1
	v_or_b32_e32 v132, 32, v166
	v_ashrrev_i32_e32 v133, 31, v132
	v_lshlrev_b64 v[128:129], 6, v[132:133]
	v_lshl_add_u64 v[128:129], v[160:161], 0, v[128:129]
	flat_load_dwordx4 v[128:131], v[128:129]
	s_waitcnt vmcnt(0) lgkmcnt(0)
	v_mov_b32_e32 v134, v129
	v_mov_b32_e32 v135, v130
	v_mov_b32_e32 v129, v131
	v_pk_add_f32 v[128:129], v[134:135], v[128:129]
	s_nop 0
	v_add_f32_e32 v128, v128, v129
	ds_bpermute_b32 v129, v140, v128
	s_waitcnt lgkmcnt(0)
	v_add_f32_e32 v128, v128, v129
	ds_bpermute_b32 v129, v141, v128
	s_waitcnt lgkmcnt(0)
	v_add_f32_e32 v128, v128, v129
	v_fmamk_f32 v128, v128, 0x3a800000, v212
	v_rsq_f32_e32 v134, v128
	v_lshlrev_b64 v[128:129], 10, v[132:133]
	v_lshl_add_u64 v[128:129], s[12:13], 0, v[128:129]
	v_lshl_add_u64 v[128:129], v[128:129], 0, v[192:193]
	v_pk_mul_f32 v[132:133], v[44:45], v[134:135] op_sel_hi:[1,0]
	v_pk_mul_f32 v[130:131], v[46:47], v[134:135] op_sel_hi:[1,0]
	v_pk_mul_f32 v[136:137], v[42:43], v[134:135] op_sel_hi:[1,0]
	v_pk_mul_f32 v[138:139], v[40:41], v[134:135] op_sel_hi:[1,0]
	v_mul_f32_e32 v135, 0xbfb8aa3b, v132
	v_exp_f32_e32 v135, v135
	s_nop 0
	v_add_f32_e32 v135, 1.0, v135
	v_rcp_f32_e32 v142, v135
	v_mul_f32_e32 v135, 0xbfb8aa3b, v138
	v_exp_f32_e32 v135, v135
	s_nop 0
	v_add_f32_e32 v135, 1.0, v135
	v_rcp_f32_e32 v144, v135
	v_mul_f32_e32 v135, 0xbfb8aa3b, v133
	v_exp_f32_e32 v135, v135
	s_nop 0
	v_add_f32_e32 v135, 1.0, v135
	v_rcp_f32_e32 v143, v135
	v_mul_f32_e32 v135, 0xbfb8aa3b, v139
	v_exp_f32_e32 v135, v135
	v_pk_mul_f32 v[132:133], v[132:133], v[142:143]
	v_add_f32_e32 v135, 1.0, v135
	v_rcp_f32_e32 v145, v135
	v_mul_f32_e32 v135, 0xbfb8aa3b, v130
	v_exp_f32_e32 v135, v135
	v_pk_mul_f32 v[138:139], v[138:139], v[144:145]
	v_add_f32_e32 v135, 1.0, v135
	v_rcp_f32_e32 v142, v135
	v_mul_f32_e32 v135, 0xbfb8aa3b, v136
	v_exp_f32_e32 v135, v135
	s_nop 0
	v_add_f32_e32 v135, 1.0, v135
	v_rcp_f32_e32 v144, v135
	v_mul_f32_e32 v135, 0xbfb8aa3b, v131
	v_exp_f32_e32 v135, v135
	s_nop 0
	v_add_f32_e32 v135, 1.0, v135
	v_rcp_f32_e32 v143, v135
	s_nop 0
; __device__ __forceinline__ v4u pack8(const f32x4 a, const f32x4 b) { v4u w; w.x = cvt_pk_bf16(a[0], a[1]); w.y = cvt_pk_bf16(a[2], a[3]); w.z = cvt_pk_bf16(b[0], b[1]); w.w = cvt_pk_bf16(b[2], b[3]); return w; }
; __device__ __forceinline__ float silu_f(float x) { return x * __builtin_amdgcn_rcpf(1.f + __expf(-x)); }
; __device__ __forceinline__ float logsig_f(float x) { return fminf(x, 0.f) - __logf(1.f + __expf(-fabsf(x))); }
; __device__ __forceinline__ float row_rstd(const float* ssq, int row, int fq) {
;     const f32x4 v = *(const f32x4*)(ssq + (size_t)row * 16 + fq * 4);
;     float s = (v[0] + v[1]) + (v[2] + v[3]);
;     s += __shfl_xor(s, 16); s += __shfl_xor(s, 32);
;     return __builtin_amdgcn_rsqf(s * (1.f / DM) + EPS);
; }
;     __device__ __forceinline__ void operator()(const f32x4 (&acc)[2][2][4][2], const pg8::Unit& u, int wr, int wc, int fr, int fq) const {
;     ...
;         if (grp == 0) { WIN_LOOP( _Pragma("unroll") for (int i = 0; i < 4; ++i) { a[i] = silu_f(a[i]); b[i] = silu_f(b[i]); } *(v4u*)(QO + (size_t)row * DM + c) = pack8(a, b); ) }
;         else if (grp == 3) { WIN_LOOP( _Pragma("unroll") for (int i = 0; i < 4; ++i) { a[i] = silu_f(a[i]); b[i] = silu_f(b[i]); } *(v4u*)(GH + (size_t)row * 512 + c) = pack8(a, b); ) }
	v_pk_mul_f32 v[142:143], v[130:131], v[142:143]
	v_mul_f32_e32 v130, 0xbfb8aa3b, v137
	v_exp_f32_e32 v130, v130
	v_cvt_pk_bf16_f32 v131, v142, v143
	v_add_f32_e32 v130, 1.0, v130
	v_rcp_f32_e32 v145, v130
	v_cvt_pk_bf16_f32 v130, v132, v133
	v_cvt_pk_bf16_f32 v132, v138, v139
	v_pk_mul_f32 v[138:139], v[104:105], v[134:135] op_sel_hi:[1,0]
	v_pk_mul_f32 v[136:137], v[136:137], v[144:145]
	s_nop 0
	v_cvt_pk_bf16_f32 v133, v136, v137
	flat_store_dwordx4 v[128:129], v[130:133] sc1
	v_pk_mul_f32 v[136:137], v[108:109], v[134:135] op_sel_hi:[1,0]
	s_nop 0
	v_pk_mul_f32 v[132:133], v[110:111], v[134:135] op_sel_hi:[1,0]
	v_pk_mul_f32 v[130:131], v[106:107], v[134:135] op_sel_hi:[1,0]
	v_mul_f32_e32 v135, 0xbfb8aa3b, v138
	v_exp_f32_e32 v135, v135
	v_mul_f32_e32 v134, 0xbfb8aa3b, v136
	v_exp_f32_e32 v134, v134
	v_add_f32_e32 v135, 1.0, v135
	v_rcp_f32_e32 v142, v135
	v_mul_f32_e32 v135, 0xbfb8aa3b, v137
	v_exp_f32_e32 v135, v135
	v_add_f32_e32 v134, 1.0, v134
	v_rcp_f32_e32 v134, v134
	v_add_f32_e32 v135, 1.0, v135
	v_rcp_f32_e32 v135, v135
	s_nop 0
	v_pk_mul_f32 v[134:135], v[136:137], v[134:135]
	v_mul_f32_e32 v136, 0xbfb8aa3b, v139
	v_exp_f32_e32 v136, v136
	s_nop 0
	v_add_f32_e32 v136, 1.0, v136
	v_rcp_f32_e32 v143, v136
	s_nop 0
	v_pk_mul_f32 v[136:137], v[138:139], v[142:143]
	v_mul_f32_e32 v138, 0xbfb8aa3b, v132
	v_mul_f32_e32 v139, 0xbfb8aa3b, v133
	v_exp_f32_e32 v138, v138
	v_exp_f32_e32 v139, v139
	v_add_f32_e32 v138, 1.0, v138
	v_add_f32_e32 v139, 1.0, v139
	v_rcp_f32_e32 v142, v138
	v_mul_f32_e32 v138, 0xbfb8aa3b, v130
	v_rcp_f32_e32 v143, v139
	v_mul_f32_e32 v139, 0xbfb8aa3b, v131
	v_exp_f32_e32 v138, v138
	v_exp_f32_e32 v139, v139
	v_pk_mul_f32 v[132:133], v[132:133], v[142:143]
	v_add_f32_e32 v138, 1.0, v138
	v_add_f32_e32 v139, 1.0, v139
	v_rcp_f32_e32 v138, v138
	v_rcp_f32_e32 v139, v139
	s_nop 0
	v_pk_mul_f32 v[138:139], v[130:131], v[138:139]
	v_cvt_pk_bf16_f32 v130, v134, v135
	v_cvt_pk_bf16_f32 v131, v132, v133
	v_cvt_pk_bf16_f32 v132, v136, v137
	v_cvt_pk_bf16_f32 v133, v138, v139
	flat_store_dwordx4 v[128:129], v[130:133] offset:256 sc1
	s_nop 1
	v_or_b32_e32 v132, 48, v166
	v_ashrrev_i32_e32 v133, 31, v132
	v_lshlrev_b64 v[128:129], 6, v[132:133]
	v_lshl_add_u64 v[128:129], v[160:161], 0, v[128:129]
	flat_load_dwordx4 v[128:131], v[128:129]
	s_waitcnt vmcnt(0) lgkmcnt(0)
	v_mov_b32_e32 v134, v129
	v_mov_b32_e32 v135, v130
	v_mov_b32_e32 v129, v131
	v_pk_add_f32 v[128:129], v[134:135], v[128:129]
	s_nop 0
	v_add_f32_e32 v128, v128, v129
	ds_bpermute_b32 v129, v140, v128
	s_waitcnt lgkmcnt(0)
	v_add_f32_e32 v128, v128, v129
	ds_bpermute_b32 v129, v141, v128
	s_waitcnt lgkmcnt(0)
	v_add_f32_e32 v128, v128, v129
	v_fmamk_f32 v128, v128, 0x3a800000, v212
	v_rsq_f32_e32 v134, v128
	v_lshlrev_b64 v[128:129], 10, v[132:133]
	v_lshl_add_u64 v[132:133], s[12:13], 0, v[128:129]
	v_lshl_add_u64 v[132:133], v[132:133], 0, v[192:193]
	v_pk_mul_f32 v[130:131], v[36:37], v[134:135] op_sel_hi:[1,0]
	v_pk_mul_f32 v[128:129], v[38:39], v[134:135] op_sel_hi:[1,0]
	v_pk_mul_f32 v[136:137], v[34:35], v[134:135] op_sel_hi:[1,0]
	v_pk_mul_f32 v[138:139], v[32:33], v[134:135] op_sel_hi:[1,0]
	v_mul_f32_e32 v135, 0xbfb8aa3b, v130
	v_exp_f32_e32 v135, v135
	s_nop 0
	v_add_f32_e32 v135, 1.0, v135
	v_rcp_f32_e32 v142, v135
	v_mul_f32_e32 v135, 0xbfb8aa3b, v138
	v_exp_f32_e32 v135, v135
	s_nop 0
	v_add_f32_e32 v135, 1.0, v135
	v_rcp_f32_e32 v144, v135
	v_mul_f32_e32 v135, 0xbfb8aa3b, v131
	v_exp_f32_e32 v135, v135
	s_nop 0
	v_add_f32_e32 v135, 1.0, v135
	v_rcp_f32_e32 v143, v135
	v_mul_f32_e32 v135, 0xbfb8aa3b, v139
	v_exp_f32_e32 v135, v135
	v_pk_mul_f32 v[130:131], v[130:131], v[142:143]
	v_add_f32_e32 v135, 1.0, v135
	v_rcp_f32_e32 v145, v135
	v_mul_f32_e32 v135, 0xbfb8aa3b, v128
	v_exp_f32_e32 v135, v135
	v_pk_mul_f32 v[138:139], v[138:139], v[144:145]
	v_add_f32_e32 v135, 1.0, v135
	v_rcp_f32_e32 v142, v135
	v_mul_f32_e32 v135, 0xbfb8aa3b, v136
	v_exp_f32_e32 v135, v135
	s_nop 0
	v_add_f32_e32 v135, 1.0, v135
	v_rcp_f32_e32 v144, v135
	v_mul_f32_e32 v135, 0xbfb8aa3b, v129
	v_exp_f32_e32 v135, v135
	s_nop 0
	v_add_f32_e32 v135, 1.0, v135
	v_rcp_f32_e32 v143, v135
	s_nop 0
	v_pk_mul_f32 v[142:143], v[128:129], v[142:143]
	v_mul_f32_e32 v128, 0xbfb8aa3b, v137
	v_exp_f32_e32 v128, v128
	v_cvt_pk_bf16_f32 v129, v142, v143
	v_add_f32_e32 v128, 1.0, v128
	v_rcp_f32_e32 v145, v128
	v_cvt_pk_bf16_f32 v128, v130, v131
	v_cvt_pk_bf16_f32 v130, v138, v139
	v_pk_mul_f32 v[136:137], v[136:137], v[144:145]
	s_nop 0
	v_cvt_pk_bf16_f32 v131, v136, v137
	flat_store_dwordx4 v[132:133], v[128:131] sc1
	v_pk_mul_f32 v[136:137], v[98:99], v[134:135] op_sel_hi:[1,0]
	s_nop 0
	v_pk_mul_f32 v[128:129], v[102:103], v[134:135] op_sel_hi:[1,0]
	v_pk_mul_f32 v[130:131], v[100:101], v[134:135] op_sel_hi:[1,0]
	v_pk_mul_f32 v[134:135], v[96:97], v[134:135] op_sel_hi:[1,0]
	v_mul_f32_e32 v138, 0xbfb8aa3b, v130
	v_mul_f32_e32 v139, 0xbfb8aa3b, v134
	v_exp_f32_e32 v139, v139
	v_exp_f32_e32 v138, v138
	v_add_f32_e32 v139, 1.0, v139
	v_rcp_f32_e32 v142, v139
	v_mul_f32_e32 v139, 0xbfb8aa3b, v131
	v_exp_f32_e32 v139, v139
	v_add_f32_e32 v138, 1.0, v138
	v_rcp_f32_e32 v138, v138
	v_add_f32_e32 v139, 1.0, v139
	v_rcp_f32_e32 v139, v139
	s_nop 0
	v_pk_mul_f32 v[130:131], v[130:131], v[138:139]
	v_mul_f32_e32 v138, 0xbfb8aa3b, v135
	v_exp_f32_e32 v138, v138
	v_mul_f32_e32 v139, 0xbfb8aa3b, v136
	v_exp_f32_e32 v139, v139
	v_add_f32_e32 v138, 1.0, v138
	v_rcp_f32_e32 v143, v138
	v_add_f32_e32 v139, 1.0, v139
	v_mul_f32_e32 v138, 0xbfb8aa3b, v128
	v_exp_f32_e32 v138, v138
	v_pk_mul_f32 v[134:135], v[134:135], v[142:143]
	v_rcp_f32_e32 v142, v139
	v_mul_f32_e32 v139, 0xbfb8aa3b, v129
	v_exp_f32_e32 v139, v139
	v_add_f32_e32 v138, 1.0, v138
	v_rcp_f32_e32 v138, v138
	v_add_f32_e32 v139, 1.0, v139
	v_rcp_f32_e32 v139, v139
	s_nop 0
	v_pk_mul_f32 v[138:139], v[128:129], v[138:139]
	v_mul_f32_e32 v128, 0xbfb8aa3b, v137
	v_exp_f32_e32 v128, v128
	v_cvt_pk_bf16_f32 v129, v138, v139
	v_add_f32_e32 v128, 1.0, v128
	v_rcp_f32_e32 v143, v128
	v_cvt_pk_bf16_f32 v128, v130, v131
	v_cvt_pk_bf16_f32 v130, v134, v135
	v_pk_mul_f32 v[136:137], v[136:137], v[142:143]
	s_nop 0
	v_cvt_pk_bf16_f32 v131, v136, v137
	flat_store_dwordx4 v[132:133], v[128:131] offset:256 sc1
	v_add_u32_e32 v132, 0x80, v166
	v_ashrrev_i32_e32 v133, 31, v132
	v_lshlrev_b64 v[128:129], 6, v[132:133]
	v_lshl_add_u64 v[128:129], v[160:161], 0, v[128:129]
	flat_load_dwordx4 v[128:131], v[128:129]
	s_waitcnt vmcnt(0) lgkmcnt(0)
; __device__ __forceinline__ v4u pack8(const f32x4 a, const f32x4 b) { v4u w; w.x = cvt_pk_bf16(a[0], a[1]); w.y = cvt_pk_bf16(a[2], a[3]); w.z = cvt_pk_bf16(b[0], b[1]); w.w = cvt_pk_bf16(b[2], b[3]); return w; }
; __device__ __forceinline__ float silu_f(float x) { return x * __builtin_amdgcn_rcpf(1.f + __expf(-x)); }
; __device__ __forceinline__ float logsig_f(float x) { return fminf(x, 0.f) - __logf(1.f + __expf(-fabsf(x))); }
; __device__ __forceinline__ float row_rstd(const float* ssq, int row, int fq) {
;     const f32x4 v = *(const f32x4*)(ssq + (size_t)row * 16 + fq * 4);
;     float s = (v[0] + v[1]) + (v[2] + v[3]);
;     s += __shfl_xor(s, 16); s += __shfl_xor(s, 32);
;     return __builtin_amdgcn_rsqf(s * (1.f / DM) + EPS);
; }
;     __device__ __forceinline__ void operator()(const f32x4 (&acc)[2][2][4][2], const pg8::Unit& u, int wr, int wc, int fr, int fq) const {
;     ...
;         if (grp == 0) { WIN_LOOP( _Pragma("unroll") for (int i = 0; i < 4; ++i) { a[i] = silu_f(a[i]); b[i] = silu_f(b[i]); } *(v4u*)(QO + (size_t)row * DM + c) = pack8(a, b); ) }
;         else if (grp == 3) { WIN_LOOP( _Pragma("unroll") for (int i = 0; i < 4; ++i) { a[i] = silu_f(a[i]); b[i] = silu_f(b[i]); } *(v4u*)(GH + (size_t)row * 512 + c) = pack8(a, b); ) }
	v_mov_b32_e32 v134, v129
	v_mov_b32_e32 v135, v130
	v_mov_b32_e32 v129, v131
	v_pk_add_f32 v[128:129], v[134:135], v[128:129]
	s_nop 0
	v_add_f32_e32 v128, v128, v129
	ds_bpermute_b32 v129, v140, v128
	s_waitcnt lgkmcnt(0)
	v_add_f32_e32 v128, v128, v129
	ds_bpermute_b32 v129, v141, v128
	s_waitcnt lgkmcnt(0)
	v_add_f32_e32 v128, v128, v129
	v_fmamk_f32 v128, v128, 0x3a800000, v212
	v_rsq_f32_e32 v134, v128
	v_lshlrev_b64 v[128:129], 10, v[132:133]
	v_lshl_add_u64 v[132:133], s[12:13], 0, v[128:129]
	v_lshl_add_u64 v[132:133], v[132:133], 0, v[192:193]
	v_pk_mul_f32 v[130:131], v[28:29], v[134:135] op_sel_hi:[1,0]
	v_pk_mul_f32 v[128:129], v[30:31], v[134:135] op_sel_hi:[1,0]
	v_pk_mul_f32 v[136:137], v[26:27], v[134:135] op_sel_hi:[1,0]
	v_pk_mul_f32 v[138:139], v[24:25], v[134:135] op_sel_hi:[1,0]
	v_mul_f32_e32 v135, 0xbfb8aa3b, v130
	v_exp_f32_e32 v135, v135
	s_nop 0
	v_add_f32_e32 v135, 1.0, v135
	v_rcp_f32_e32 v142, v135
	v_mul_f32_e32 v135, 0xbfb8aa3b, v138
	v_exp_f32_e32 v135, v135
	s_nop 0
	v_add_f32_e32 v135, 1.0, v135
	v_rcp_f32_e32 v144, v135
	v_mul_f32_e32 v135, 0xbfb8aa3b, v131
	v_exp_f32_e32 v135, v135
	s_nop 0
	v_add_f32_e32 v135, 1.0, v135
	v_rcp_f32_e32 v143, v135
	v_mul_f32_e32 v135, 0xbfb8aa3b, v139
	v_exp_f32_e32 v135, v135
	v_pk_mul_f32 v[130:131], v[130:131], v[142:143]
	v_add_f32_e32 v135, 1.0, v135
	v_rcp_f32_e32 v145, v135
	v_mul_f32_e32 v135, 0xbfb8aa3b, v128
	v_exp_f32_e32 v135, v135
	v_pk_mul_f32 v[138:139], v[138:139], v[144:145]
	v_add_f32_e32 v135, 1.0, v135
	v_rcp_f32_e32 v142, v135
	v_mul_f32_e32 v135, 0xbfb8aa3b, v136
	v_exp_f32_e32 v135, v135
	s_nop 0
	v_add_f32_e32 v135, 1.0, v135
	v_rcp_f32_e32 v144, v135
	v_mul_f32_e32 v135, 0xbfb8aa3b, v129
	v_exp_f32_e32 v135, v135
	s_nop 0
	v_add_f32_e32 v135, 1.0, v135
	v_rcp_f32_e32 v143, v135
	s_nop 0
	v_pk_mul_f32 v[142:143], v[128:129], v[142:143]
	v_mul_f32_e32 v128, 0xbfb8aa3b, v137
	v_exp_f32_e32 v128, v128
	v_cvt_pk_bf16_f32 v129, v142, v143
	v_add_f32_e32 v128, 1.0, v128
	v_rcp_f32_e32 v145, v128
	v_cvt_pk_bf16_f32 v128, v130, v131
	v_cvt_pk_bf16_f32 v130, v138, v139
	v_pk_mul_f32 v[136:137], v[136:137], v[144:145]
	s_nop 0
	v_cvt_pk_bf16_f32 v131, v136, v137
	flat_store_dwordx4 v[132:133], v[128:131] sc1
	v_pk_mul_f32 v[136:137], v[90:91], v[134:135] op_sel_hi:[1,0]
	s_nop 0
	v_pk_mul_f32 v[128:129], v[94:95], v[134:135] op_sel_hi:[1,0]
	v_pk_mul_f32 v[130:131], v[92:93], v[134:135] op_sel_hi:[1,0]
	v_pk_mul_f32 v[134:135], v[88:89], v[134:135] op_sel_hi:[1,0]
	v_mul_f32_e32 v138, 0xbfb8aa3b, v130
	v_mul_f32_e32 v139, 0xbfb8aa3b, v134
	v_exp_f32_e32 v139, v139
	v_exp_f32_e32 v138, v138
	v_add_f32_e32 v139, 1.0, v139
	v_rcp_f32_e32 v142, v139
	v_mul_f32_e32 v139, 0xbfb8aa3b, v131
	v_exp_f32_e32 v139, v139
	v_add_f32_e32 v138, 1.0, v138
	v_rcp_f32_e32 v138, v138
	v_add_f32_e32 v139, 1.0, v139
	v_rcp_f32_e32 v139, v139
	s_nop 0
	v_pk_mul_f32 v[130:131], v[130:131], v[138:139]
	v_mul_f32_e32 v138, 0xbfb8aa3b, v135
	v_exp_f32_e32 v138, v138
	v_mul_f32_e32 v139, 0xbfb8aa3b, v136
	v_exp_f32_e32 v139, v139
	v_add_f32_e32 v138, 1.0, v138
	v_rcp_f32_e32 v143, v138
	v_add_f32_e32 v139, 1.0, v139
	v_mul_f32_e32 v138, 0xbfb8aa3b, v128
	v_exp_f32_e32 v138, v138
	v_pk_mul_f32 v[134:135], v[134:135], v[142:143]
	v_rcp_f32_e32 v142, v139
	v_mul_f32_e32 v139, 0xbfb8aa3b, v129
	v_exp_f32_e32 v139, v139
	v_add_f32_e32 v138, 1.0, v138
	v_rcp_f32_e32 v138, v138
	v_add_f32_e32 v139, 1.0, v139
	v_rcp_f32_e32 v139, v139
	s_nop 0
	v_pk_mul_f32 v[138:139], v[128:129], v[138:139]
	v_mul_f32_e32 v128, 0xbfb8aa3b, v137
	v_exp_f32_e32 v128, v128
	v_cvt_pk_bf16_f32 v129, v138, v139
	v_add_f32_e32 v128, 1.0, v128
	v_rcp_f32_e32 v143, v128
	v_cvt_pk_bf16_f32 v128, v130, v131
	v_cvt_pk_bf16_f32 v130, v134, v135
	v_pk_mul_f32 v[136:137], v[136:137], v[142:143]
	s_nop 0
	v_cvt_pk_bf16_f32 v131, v136, v137
	flat_store_dwordx4 v[132:133], v[128:131] offset:256 sc1
	v_add_u32_e32 v132, 0x90, v166
	v_ashrrev_i32_e32 v133, 31, v132
	v_lshlrev_b64 v[128:129], 6, v[132:133]
	v_lshl_add_u64 v[128:129], v[160:161], 0, v[128:129]
	flat_load_dwordx4 v[128:131], v[128:129]
	s_waitcnt vmcnt(0) lgkmcnt(0)
	v_mov_b32_e32 v134, v129
	v_mov_b32_e32 v135, v130
	v_mov_b32_e32 v129, v131
	v_pk_add_f32 v[128:129], v[134:135], v[128:129]
	s_nop 0
	v_add_f32_e32 v128, v128, v129
	ds_bpermute_b32 v129, v140, v128
	s_waitcnt lgkmcnt(0)
	v_add_f32_e32 v128, v128, v129
	ds_bpermute_b32 v129, v141, v128
	s_waitcnt lgkmcnt(0)
; __device__ __forceinline__ v4u pack8(const f32x4 a, const f32x4 b) { v4u w; w.x = cvt_pk_bf16(a[0], a[1]); w.y = cvt_pk_bf16(a[2], a[3]); w.z = cvt_pk_bf16(b[0], b[1]); w.w = cvt_pk_bf16(b[2], b[3]); return w; }
; __device__ __forceinline__ float silu_f(float x) { return x * __builtin_amdgcn_rcpf(1.f + __expf(-x)); }
; __device__ __forceinline__ float logsig_f(float x) { return fminf(x, 0.f) - __logf(1.f + __expf(-fabsf(x))); }
; __device__ __forceinline__ float row_rstd(const float* ssq, int row, int fq) {
;     const f32x4 v = *(const f32x4*)(ssq + (size_t)row * 16 + fq * 4);
;     float s = (v[0] + v[1]) + (v[2] + v[3]);
;     s += __shfl_xor(s, 16); s += __shfl_xor(s, 32);
;     return __builtin_amdgcn_rsqf(s * (1.f / DM) + EPS);
; }
;     __device__ __forceinline__ void operator()(const f32x4 (&acc)[2][2][4][2], const pg8::Unit& u, int wr, int wc, int fr, int fq) const {
;     ...
;         if (grp == 0) { WIN_LOOP( _Pragma("unroll") for (int i = 0; i < 4; ++i) { a[i] = silu_f(a[i]); b[i] = silu_f(b[i]); } *(v4u*)(QO + (size_t)row * DM + c) = pack8(a, b); ) }
;         else if (grp == 3) { WIN_LOOP( _Pragma("unroll") for (int i = 0; i < 4; ++i) { a[i] = silu_f(a[i]); b[i] = silu_f(b[i]); } *(v4u*)(GH + (size_t)row * 512 + c) = pack8(a, b); ) }
	v_add_f32_e32 v128, v128, v129
	v_fmamk_f32 v128, v128, 0x3a800000, v212
	v_rsq_f32_e32 v134, v128
	v_lshlrev_b64 v[128:129], 10, v[132:133]
	v_lshl_add_u64 v[132:133], s[12:13], 0, v[128:129]
	v_lshl_add_u64 v[132:133], v[132:133], 0, v[192:193]
	v_pk_mul_f32 v[130:131], v[20:21], v[134:135] op_sel_hi:[1,0]
	v_pk_mul_f32 v[128:129], v[22:23], v[134:135] op_sel_hi:[1,0]
	v_pk_mul_f32 v[136:137], v[18:19], v[134:135] op_sel_hi:[1,0]
	v_pk_mul_f32 v[138:139], v[16:17], v[134:135] op_sel_hi:[1,0]
	v_mul_f32_e32 v135, 0xbfb8aa3b, v130
	v_exp_f32_e32 v135, v135
	s_nop 0
	v_add_f32_e32 v135, 1.0, v135
	v_rcp_f32_e32 v142, v135
	v_mul_f32_e32 v135, 0xbfb8aa3b, v138
	v_exp_f32_e32 v135, v135
	s_nop 0
	v_add_f32_e32 v135, 1.0, v135
	v_rcp_f32_e32 v144, v135
	v_mul_f32_e32 v135, 0xbfb8aa3b, v131
	v_exp_f32_e32 v135, v135
	s_nop 0
	v_add_f32_e32 v135, 1.0, v135
	v_rcp_f32_e32 v143, v135
	v_mul_f32_e32 v135, 0xbfb8aa3b, v139
	v_exp_f32_e32 v135, v135
	v_pk_mul_f32 v[130:131], v[130:131], v[142:143]
	v_add_f32_e32 v135, 1.0, v135
	v_rcp_f32_e32 v145, v135
	v_mul_f32_e32 v135, 0xbfb8aa3b, v128
	v_exp_f32_e32 v135, v135
	v_pk_mul_f32 v[138:139], v[138:139], v[144:145]
	v_add_f32_e32 v135, 1.0, v135
	v_rcp_f32_e32 v142, v135
	v_mul_f32_e32 v135, 0xbfb8aa3b, v136
	v_exp_f32_e32 v135, v135
	s_nop 0
	v_add_f32_e32 v135, 1.0, v135
	v_rcp_f32_e32 v144, v135
	v_mul_f32_e32 v135, 0xbfb8aa3b, v129
	v_exp_f32_e32 v135, v135
	s_nop 0
	v_add_f32_e32 v135, 1.0, v135
	v_rcp_f32_e32 v143, v135
	s_nop 0
	v_pk_mul_f32 v[142:143], v[128:129], v[142:143]
	v_mul_f32_e32 v128, 0xbfb8aa3b, v137
	v_exp_f32_e32 v128, v128
	v_cvt_pk_bf16_f32 v129, v142, v143
	v_add_f32_e32 v128, 1.0, v128
	v_rcp_f32_e32 v145, v128
	v_cvt_pk_bf16_f32 v128, v130, v131
	v_cvt_pk_bf16_f32 v130, v138, v139
	v_pk_mul_f32 v[136:137], v[136:137], v[144:145]
	s_nop 0
	v_cvt_pk_bf16_f32 v131, v136, v137
	flat_store_dwordx4 v[132:133], v[128:131] sc1
	v_pk_mul_f32 v[136:137], v[82:83], v[134:135] op_sel_hi:[1,0]
	s_nop 0
	v_pk_mul_f32 v[128:129], v[86:87], v[134:135] op_sel_hi:[1,0]
	v_pk_mul_f32 v[130:131], v[84:85], v[134:135] op_sel_hi:[1,0]
	v_pk_mul_f32 v[134:135], v[80:81], v[134:135] op_sel_hi:[1,0]
	v_mul_f32_e32 v138, 0xbfb8aa3b, v130
	v_mul_f32_e32 v139, 0xbfb8aa3b, v134
	v_exp_f32_e32 v139, v139
	v_exp_f32_e32 v138, v138
	v_add_f32_e32 v139, 1.0, v139
	v_rcp_f32_e32 v142, v139
	v_mul_f32_e32 v139, 0xbfb8aa3b, v131
	v_exp_f32_e32 v139, v139
	v_add_f32_e32 v138, 1.0, v138
	v_rcp_f32_e32 v138, v138
	v_add_f32_e32 v139, 1.0, v139
	v_rcp_f32_e32 v139, v139
	s_nop 0
	v_pk_mul_f32 v[130:131], v[130:131], v[138:139]
	v_mul_f32_e32 v138, 0xbfb8aa3b, v135
	v_exp_f32_e32 v138, v138
	v_mul_f32_e32 v139, 0xbfb8aa3b, v136
	v_exp_f32_e32 v139, v139
	v_add_f32_e32 v138, 1.0, v138
	v_rcp_f32_e32 v143, v138
	v_add_f32_e32 v139, 1.0, v139
	v_mul_f32_e32 v138, 0xbfb8aa3b, v128
	v_exp_f32_e32 v138, v138
	v_pk_mul_f32 v[134:135], v[134:135], v[142:143]
	v_rcp_f32_e32 v142, v139
	v_mul_f32_e32 v139, 0xbfb8aa3b, v129
	v_exp_f32_e32 v139, v139
	v_add_f32_e32 v138, 1.0, v138
	v_rcp_f32_e32 v138, v138
	v_add_f32_e32 v139, 1.0, v139
	v_rcp_f32_e32 v139, v139
	s_nop 0
	v_pk_mul_f32 v[138:139], v[128:129], v[138:139]
	v_mul_f32_e32 v128, 0xbfb8aa3b, v137
	v_exp_f32_e32 v128, v128
	v_cvt_pk_bf16_f32 v129, v138, v139
	v_add_f32_e32 v128, 1.0, v128
	v_rcp_f32_e32 v143, v128
	v_cvt_pk_bf16_f32 v128, v130, v131
	v_cvt_pk_bf16_f32 v130, v134, v135
	v_pk_mul_f32 v[136:137], v[136:137], v[142:143]
	s_nop 0
	v_cvt_pk_bf16_f32 v131, v136, v137
	flat_store_dwordx4 v[132:133], v[128:131] offset:256 sc1
	v_add_u32_e32 v132, 0xa0, v166
	v_ashrrev_i32_e32 v133, 31, v132
	v_lshlrev_b64 v[128:129], 6, v[132:133]
	v_lshl_add_u64 v[128:129], v[160:161], 0, v[128:129]
	flat_load_dwordx4 v[128:131], v[128:129]
	s_waitcnt vmcnt(0) lgkmcnt(0)
	v_mov_b32_e32 v134, v129
	v_mov_b32_e32 v135, v130
	v_mov_b32_e32 v129, v131
	v_pk_add_f32 v[128:129], v[134:135], v[128:129]
	s_nop 0
	v_add_f32_e32 v128, v128, v129
	ds_bpermute_b32 v129, v140, v128
	s_waitcnt lgkmcnt(0)
	v_add_f32_e32 v128, v128, v129
	ds_bpermute_b32 v129, v141, v128
	s_waitcnt lgkmcnt(0)
	v_add_f32_e32 v128, v128, v129
	v_fmamk_f32 v128, v128, 0x3a800000, v212
	v_rsq_f32_e32 v134, v128
	v_lshlrev_b64 v[128:129], 10, v[132:133]
	v_lshl_add_u64 v[132:133], s[12:13], 0, v[128:129]
	v_lshl_add_u64 v[132:133], v[132:133], 0, v[192:193]
	v_pk_mul_f32 v[130:131], v[12:13], v[134:135] op_sel_hi:[1,0]
	v_pk_mul_f32 v[128:129], v[14:15], v[134:135] op_sel_hi:[1,0]
	v_pk_mul_f32 v[136:137], v[10:11], v[134:135] op_sel_hi:[1,0]
	v_pk_mul_f32 v[138:139], v[8:9], v[134:135] op_sel_hi:[1,0]
	v_mul_f32_e32 v135, 0xbfb8aa3b, v130
	v_exp_f32_e32 v135, v135
	s_nop 0
	v_add_f32_e32 v135, 1.0, v135
	v_rcp_f32_e32 v142, v135
	v_mul_f32_e32 v135, 0xbfb8aa3b, v138
	v_exp_f32_e32 v135, v135
	s_nop 0
	v_add_f32_e32 v135, 1.0, v135
	v_rcp_f32_e32 v144, v135
	v_mul_f32_e32 v135, 0xbfb8aa3b, v131
	v_exp_f32_e32 v135, v135
	s_nop 0
	v_add_f32_e32 v135, 1.0, v135
	v_rcp_f32_e32 v143, v135
	v_mul_f32_e32 v135, 0xbfb8aa3b, v139
	v_exp_f32_e32 v135, v135
	v_pk_mul_f32 v[130:131], v[130:131], v[142:143]
	v_add_f32_e32 v135, 1.0, v135
	v_rcp_f32_e32 v145, v135
	v_mul_f32_e32 v135, 0xbfb8aa3b, v128
	v_exp_f32_e32 v135, v135
	v_pk_mul_f32 v[138:139], v[138:139], v[144:145]
	v_add_f32_e32 v135, 1.0, v135
	v_rcp_f32_e32 v142, v135
	v_mul_f32_e32 v135, 0xbfb8aa3b, v136
	v_exp_f32_e32 v135, v135
	s_nop 0
	v_add_f32_e32 v135, 1.0, v135
	v_rcp_f32_e32 v144, v135
	v_mul_f32_e32 v135, 0xbfb8aa3b, v129
	v_exp_f32_e32 v135, v135
	s_nop 0
	v_add_f32_e32 v135, 1.0, v135
	v_rcp_f32_e32 v143, v135
	s_nop 0
	v_pk_mul_f32 v[142:143], v[128:129], v[142:143]
; __device__ __forceinline__ v4u pack8(const f32x4 a, const f32x4 b) { v4u w; w.x = cvt_pk_bf16(a[0], a[1]); w.y = cvt_pk_bf16(a[2], a[3]); w.z = cvt_pk_bf16(b[0], b[1]); w.w = cvt_pk_bf16(b[2], b[3]); return w; }
; __device__ __forceinline__ float silu_f(float x) { return x * __builtin_amdgcn_rcpf(1.f + __expf(-x)); }
; __device__ __forceinline__ float logsig_f(float x) { return fminf(x, 0.f) - __logf(1.f + __expf(-fabsf(x))); }
; __device__ __forceinline__ float row_rstd(const float* ssq, int row, int fq) {
;     const f32x4 v = *(const f32x4*)(ssq + (size_t)row * 16 + fq * 4);
;     float s = (v[0] + v[1]) + (v[2] + v[3]);
;     s += __shfl_xor(s, 16); s += __shfl_xor(s, 32);
;     return __builtin_amdgcn_rsqf(s * (1.f / DM) + EPS);
; }
;     __device__ __forceinline__ void operator()(const f32x4 (&acc)[2][2][4][2], const pg8::Unit& u, int wr, int wc, int fr, int fq) const {
;     ...
;         if (grp == 0) { WIN_LOOP( _Pragma("unroll") for (int i = 0; i < 4; ++i) { a[i] = silu_f(a[i]); b[i] = silu_f(b[i]); } *(v4u*)(QO + (size_t)row * DM + c) = pack8(a, b); ) }
;         else if (grp == 3) { WIN_LOOP( _Pragma("unroll") for (int i = 0; i < 4; ++i) { a[i] = silu_f(a[i]); b[i] = silu_f(b[i]); } *(v4u*)(GH + (size_t)row * 512 + c) = pack8(a, b); ) }
	v_mul_f32_e32 v128, 0xbfb8aa3b, v137
	v_exp_f32_e32 v128, v128
	v_cvt_pk_bf16_f32 v129, v142, v143
	v_add_f32_e32 v128, 1.0, v128
	v_rcp_f32_e32 v145, v128
	v_cvt_pk_bf16_f32 v128, v130, v131
	v_cvt_pk_bf16_f32 v130, v138, v139
	v_pk_mul_f32 v[136:137], v[136:137], v[144:145]
	s_nop 0
	v_cvt_pk_bf16_f32 v131, v136, v137
	flat_store_dwordx4 v[132:133], v[128:131] sc1
	v_pk_mul_f32 v[136:137], v[74:75], v[134:135] op_sel_hi:[1,0]
	s_nop 0
	v_pk_mul_f32 v[128:129], v[78:79], v[134:135] op_sel_hi:[1,0]
	v_pk_mul_f32 v[130:131], v[76:77], v[134:135] op_sel_hi:[1,0]
	v_pk_mul_f32 v[134:135], v[72:73], v[134:135] op_sel_hi:[1,0]
	v_mul_f32_e32 v138, 0xbfb8aa3b, v130
	v_mul_f32_e32 v139, 0xbfb8aa3b, v134
	v_exp_f32_e32 v139, v139
	v_exp_f32_e32 v138, v138
	v_add_f32_e32 v139, 1.0, v139
	v_rcp_f32_e32 v142, v139
	v_mul_f32_e32 v139, 0xbfb8aa3b, v131
	v_exp_f32_e32 v139, v139
	v_add_f32_e32 v138, 1.0, v138
	v_rcp_f32_e32 v138, v138
	v_add_f32_e32 v139, 1.0, v139
	v_rcp_f32_e32 v139, v139
	s_nop 0
	v_pk_mul_f32 v[130:131], v[130:131], v[138:139]
	v_mul_f32_e32 v138, 0xbfb8aa3b, v135
	v_exp_f32_e32 v138, v138
	v_mul_f32_e32 v139, 0xbfb8aa3b, v136
	v_exp_f32_e32 v139, v139
	v_add_f32_e32 v138, 1.0, v138
	v_rcp_f32_e32 v143, v138
	v_add_f32_e32 v139, 1.0, v139
	v_mul_f32_e32 v138, 0xbfb8aa3b, v128
	v_exp_f32_e32 v138, v138
	v_pk_mul_f32 v[134:135], v[134:135], v[142:143]
	v_rcp_f32_e32 v142, v139
	v_mul_f32_e32 v139, 0xbfb8aa3b, v129
	v_exp_f32_e32 v139, v139
	v_add_f32_e32 v138, 1.0, v138
	v_rcp_f32_e32 v138, v138
	v_add_f32_e32 v139, 1.0, v139
	v_rcp_f32_e32 v139, v139
	s_nop 0
	v_pk_mul_f32 v[138:139], v[128:129], v[138:139]
	v_mul_f32_e32 v128, 0xbfb8aa3b, v137
	v_exp_f32_e32 v128, v128
	v_cvt_pk_bf16_f32 v129, v138, v139
	v_add_f32_e32 v128, 1.0, v128
	v_rcp_f32_e32 v143, v128
	v_cvt_pk_bf16_f32 v128, v130, v131
	v_cvt_pk_bf16_f32 v130, v134, v135
	v_pk_mul_f32 v[136:137], v[136:137], v[142:143]
	s_nop 0
	v_cvt_pk_bf16_f32 v131, v136, v137
	flat_store_dwordx4 v[132:133], v[128:131] offset:256 sc1
	v_add_u32_e32 v132, 0xb0, v166
	v_ashrrev_i32_e32 v133, 31, v132
	v_lshlrev_b64 v[128:129], 6, v[132:133]
	v_lshl_add_u64 v[128:129], v[160:161], 0, v[128:129]
	flat_load_dwordx4 v[128:131], v[128:129]
	s_waitcnt vmcnt(0) lgkmcnt(0)
	v_mov_b32_e32 v134, v129
	v_mov_b32_e32 v135, v130
	v_mov_b32_e32 v129, v131
	v_pk_add_f32 v[128:129], v[134:135], v[128:129]
	s_nop 0
	v_add_f32_e32 v128, v128, v129
	ds_bpermute_b32 v129, v140, v128
	s_waitcnt lgkmcnt(0)
	v_add_f32_e32 v128, v128, v129
	ds_bpermute_b32 v129, v141, v128
	s_waitcnt lgkmcnt(0)
	v_add_f32_e32 v128, v128, v129
	v_fmamk_f32 v128, v128, 0x3a800000, v212
	v_rsq_f32_e32 v134, v128
	v_lshlrev_b64 v[128:129], 10, v[132:133]
	v_lshl_add_u64 v[132:133], s[12:13], 0, v[128:129]
	v_lshl_add_u64 v[132:133], v[132:133], 0, v[192:193]
	v_pk_mul_f32 v[130:131], v[4:5], v[134:135] op_sel_hi:[1,0]
	v_pk_mul_f32 v[128:129], v[6:7], v[134:135] op_sel_hi:[1,0]
	v_pk_mul_f32 v[136:137], v[2:3], v[134:135] op_sel_hi:[1,0]
	v_pk_mul_f32 v[138:139], v[0:1], v[134:135] op_sel_hi:[1,0]
	v_mul_f32_e32 v135, 0xbfb8aa3b, v130
	v_exp_f32_e32 v135, v135
	s_nop 0
	v_add_f32_e32 v135, 1.0, v135
	v_rcp_f32_e32 v140, v135
	v_mul_f32_e32 v135, 0xbfb8aa3b, v138
	v_exp_f32_e32 v135, v135
	s_nop 0
	v_add_f32_e32 v135, 1.0, v135
	v_rcp_f32_e32 v142, v135
	v_mul_f32_e32 v135, 0xbfb8aa3b, v131
	v_exp_f32_e32 v135, v135
	s_nop 0
	v_add_f32_e32 v135, 1.0, v135
	v_rcp_f32_e32 v141, v135
	v_mul_f32_e32 v135, 0xbfb8aa3b, v139
	v_exp_f32_e32 v135, v135
	v_pk_mul_f32 v[130:131], v[130:131], v[140:141]
	v_add_f32_e32 v135, 1.0, v135
	v_rcp_f32_e32 v143, v135
	v_mul_f32_e32 v135, 0xbfb8aa3b, v128
	v_exp_f32_e32 v135, v135
	v_pk_mul_f32 v[138:139], v[138:139], v[142:143]
	v_add_f32_e32 v135, 1.0, v135
	v_rcp_f32_e32 v140, v135
	v_mul_f32_e32 v135, 0xbfb8aa3b, v136
	v_exp_f32_e32 v135, v135
	s_nop 0
	v_add_f32_e32 v135, 1.0, v135
	v_rcp_f32_e32 v142, v135
	v_mul_f32_e32 v135, 0xbfb8aa3b, v129
	v_exp_f32_e32 v135, v135
	s_nop 0
	v_add_f32_e32 v135, 1.0, v135
	v_rcp_f32_e32 v141, v135
	s_nop 0
	v_pk_mul_f32 v[140:141], v[128:129], v[140:141]
	v_mul_f32_e32 v128, 0xbfb8aa3b, v137
	v_exp_f32_e32 v128, v128
	v_cvt_pk_bf16_f32 v129, v140, v141
	v_add_f32_e32 v128, 1.0, v128
	v_rcp_f32_e32 v143, v128
	v_cvt_pk_bf16_f32 v128, v130, v131
	v_cvt_pk_bf16_f32 v130, v138, v139
	v_pk_mul_f32 v[136:137], v[136:137], v[142:143]
	s_nop 0
	v_cvt_pk_bf16_f32 v131, v136, v137
	flat_store_dwordx4 v[132:133], v[128:131] sc1
	v_pk_mul_f32 v[136:137], v[66:67], v[134:135] op_sel_hi:[1,0]
	s_nop 0
	v_pk_mul_f32 v[128:129], v[70:71], v[134:135] op_sel_hi:[1,0]
	v_pk_mul_f32 v[130:131], v[68:69], v[134:135] op_sel_hi:[1,0]
	v_pk_mul_f32 v[134:135], v[64:65], v[134:135] op_sel_hi:[1,0]
	v_mul_f32_e32 v138, 0xbfb8aa3b, v130
	v_mul_f32_e32 v139, 0xbfb8aa3b, v134
	v_exp_f32_e32 v139, v139
	v_exp_f32_e32 v138, v138
	v_add_f32_e32 v139, 1.0, v139
	v_rcp_f32_e32 v140, v139
	v_mul_f32_e32 v139, 0xbfb8aa3b, v131
	v_exp_f32_e32 v139, v139
	v_add_f32_e32 v138, 1.0, v138
	v_rcp_f32_e32 v138, v138
	v_add_f32_e32 v139, 1.0, v139
	v_rcp_f32_e32 v139, v139
	s_nop 0
	v_pk_mul_f32 v[130:131], v[130:131], v[138:139]
	v_mul_f32_e32 v138, 0xbfb8aa3b, v135
	v_exp_f32_e32 v138, v138
	v_mul_f32_e32 v139, 0xbfb8aa3b, v136
	v_exp_f32_e32 v139, v139
	v_add_f32_e32 v138, 1.0, v138
	v_rcp_f32_e32 v141, v138
	v_add_f32_e32 v139, 1.0, v139
	v_mul_f32_e32 v138, 0xbfb8aa3b, v128
	v_exp_f32_e32 v138, v138
	v_pk_mul_f32 v[134:135], v[134:135], v[140:141]
	v_rcp_f32_e32 v140, v139
	v_mul_f32_e32 v139, 0xbfb8aa3b, v129
	v_exp_f32_e32 v139, v139
	v_add_f32_e32 v138, 1.0, v138
	v_rcp_f32_e32 v138, v138
	v_add_f32_e32 v139, 1.0, v139
	v_rcp_f32_e32 v139, v139
	s_nop 0
	v_pk_mul_f32 v[138:139], v[128:129], v[138:139]
	v_mul_f32_e32 v128, 0xbfb8aa3b, v137
	v_exp_f32_e32 v128, v128
	v_cvt_pk_bf16_f32 v129, v138, v139
	v_add_f32_e32 v128, 1.0, v128
	v_rcp_f32_e32 v141, v128
	v_cvt_pk_bf16_f32 v128, v130, v131
	v_cvt_pk_bf16_f32 v130, v134, v135
	v_pk_mul_f32 v[136:137], v[136:137], v[140:141]
	s_nop 0
	v_cvt_pk_bf16_f32 v131, v136, v137
	flat_store_dwordx4 v[132:133], v[128:131] offset:256 sc1

; __device__ __forceinline__ float silu_f(float x) { return x * __builtin_amdgcn_rcpf(1.f + __expf(-x)); }
; __device__ __forceinline__ v4u pack8(const f32x4 a, const f32x4 b) { v4u w; w.x = cvt_pk_bf16(a[0], a[1]); w.y = cvt_pk_bf16(a[2], a[3]); w.z = cvt_pk_bf16(b[0], b[1]); w.w = cvt_pk_bf16(b[2], b[3]); return w; }
; __device__ __forceinline__ float row_rstd(const float* ssq, int row, int fq) {
;     const f32x4 v = *(const f32x4*)(ssq + (size_t)row * 16 + fq * 4);
;     float s = (v[0] + v[1]) + (v[2] + v[3]);
;     s += __shfl_xor(s, 16); s += __shfl_xor(s, 32);
;     return __builtin_amdgcn_rsqf(s * (1.f / DM) + EPS);
; }
;     __device__ __forceinline__ void operator()(const f32x4 (&acc)[2][2][4][2], const pg8::Unit& u, int wr, int wc, int fr, int fq) const {
;     ...
;         if (grp == 0) { WIN_LOOP( _Pragma("unroll") for (int i = 0; i < 4; ++i) { a[i] = silu_f(a[i]); b[i] = silu_f(b[i]); } *(v4u*)(QO + (size_t)row * DM + c) = pack8(a, b); ) }
;         else if (grp == 3) { WIN_LOOP( _Pragma("unroll") for (int i = 0; i < 4; ++i) { a[i] = silu_f(a[i]); b[i] = silu_f(b[i]); } *(v4u*)(GH + (size_t)row * 512 + c) = pack8(a, b); ) }
;         else if (grp == 1) {
;             f32x4 l0[2], l1[2];
; #pragma unroll
;             for (int bj = 0; bj < 2; ++bj) { l0[bj] = *(const f32x4*)(lb + cb + bj * 128); l1[bj] = *(const f32x4*)(lb + cb + bj * 128 + 4); }
;             WIN_LOOP( _Pragma("unroll") for (int i = 0; i < 4; ++i) { const float s0 = fminf(a[i], 0.f) - __logf(1.f + __expf(-fabsf(a[i]))), s1 = fminf(b[i], 0.f) - __logf(1.f + __expf(-fabsf(b[i]))); const float la = l0[bj][i], lbv = l1[bj][i];
;                     a[i] = la > 0.f ? __logf(la + (1.f - la) * __expf(s0)) : s0; b[i] = lbv > 0.f ? __logf(lbv + (1.f - lbv) * __expf(s1)) : s1; }
;                 *(f32x4*)(LF + (size_t)row * 512 + c) = a; *(f32x4*)(LF + (size_t)row * 512 + c + 4) = b; __builtin_amdgcn_sched_barrier(0); ) }
;         else if (grp == 2) { WIN_LOOP( *(v4u*)(VH + (size_t)row * 512 + c) = pack8(a, b); ) }
.LBB0_407:
	s_and_b64 vcc, exec, s[12:13]
	s_cbranch_vccz .LBB0_412
	s_cmp_gt_i32 s14, 1
	s_mov_b64 s[8:9], -1
	s_cbranch_scc0 .LBB0_410
	v_and_b32_e32 v129, 64, v215
	v_xor_b32_e32 v128, 16, v215
	v_add_u32_e32 v129, 64, v129
	v_cmp_lt_i32_e32 vcc, v128, v129
	v_ashrrev_i32_e32 v167, 31, v166
	v_readlane_b32 s8, v255, 37
	v_cndmask_b32_e32 v128, v215, v128, vcc
	v_lshlrev_b32_e32 v130, 2, v128
	v_xor_b32_e32 v128, 32, v215
	v_cmp_lt_i32_e32 vcc, v128, v129
	v_readlane_b32 s9, v255, 38
	v_lshlrev_b32_e32 v192, 1, v176
	v_cndmask_b32_e32 v128, v215, v128, vcc
	v_lshlrev_b32_e32 v131, 2, v128
	v_lshlrev_b64 v[128:129], 6, v[166:167]
	v_lshl_add_u64 v[128:129], v[160:161], 0, v[128:129]
	flat_load_dwordx4 v[132:135], v[128:129]
	s_waitcnt vmcnt(0) lgkmcnt(0)
	v_mov_b32_e32 v128, v133
	v_mov_b32_e32 v129, v134
	v_mov_b32_e32 v133, v135
	v_pk_add_f32 v[128:129], v[128:129], v[132:133]
	v_lshlrev_b64 v[132:133], 10, v[166:167]
	v_add_f32_e32 v128, v128, v129
	ds_bpermute_b32 v129, v130, v128
	v_lshl_add_u64 v[136:137], s[8:9], 0, v[132:133]
	v_lshl_add_u64 v[136:137], v[136:137], 0, v[192:193]
	s_waitcnt lgkmcnt(0)
	v_add_f32_e32 v128, v128, v129
	ds_bpermute_b32 v129, v131, v128
	s_waitcnt lgkmcnt(0)
	v_add_f32_e32 v128, v128, v129
	v_fmamk_f32 v128, v128, 0x3a800000, v212
	v_rsq_f32_e32 v128, v128
	s_nop 0
	v_pk_mul_f32 v[134:135], v[62:63], v[128:129] op_sel_hi:[1,0]
	v_pk_mul_f32 v[132:133], v[60:61], v[128:129] op_sel_hi:[1,0]
	v_pk_mul_f32 v[138:139], v[58:59], v[128:129] op_sel_hi:[1,0]
	v_pk_mul_f32 v[140:141], v[56:57], v[128:129] op_sel_hi:[1,0]
	v_cvt_pk_bf16_f32 v132, v132, v133
	v_cvt_pk_bf16_f32 v133, v134, v135
	v_cvt_pk_bf16_f32 v134, v140, v141
	v_cvt_pk_bf16_f32 v135, v138, v139
	flat_store_dwordx4 v[136:137], v[132:135] sc1
	v_pk_mul_f32 v[138:139], v[122:123], v[128:129] op_sel_hi:[1,0]
	s_nop 0
	v_pk_mul_f32 v[134:135], v[126:127], v[128:129] op_sel_hi:[1,0]
	v_pk_mul_f32 v[132:133], v[124:125], v[128:129] op_sel_hi:[1,0]
	v_pk_mul_f32 v[128:129], v[120:121], v[128:129] op_sel_hi:[1,0]
	v_cvt_pk_bf16_f32 v132, v132, v133
	v_cvt_pk_bf16_f32 v133, v134, v135
	v_cvt_pk_bf16_f32 v134, v128, v129
	v_or_b32_e32 v128, 16, v166
	v_cvt_pk_bf16_f32 v135, v138, v139
	v_ashrrev_i32_e32 v129, 31, v128
	flat_store_dwordx4 v[136:137], v[132:135] offset:256 sc1
	s_nop 1
	v_lshlrev_b64 v[132:133], 6, v[128:129]
	v_lshl_add_u64 v[132:133], v[160:161], 0, v[132:133]
	flat_load_dwordx4 v[132:135], v[132:133]
	v_lshlrev_b64 v[128:129], 10, v[128:129]
	v_lshl_add_u64 v[128:129], s[8:9], 0, v[128:129]
	v_lshl_add_u64 v[128:129], v[128:129], 0, v[192:193]
	s_waitcnt vmcnt(0) lgkmcnt(0)
	v_mov_b32_e32 v136, v133
	v_mov_b32_e32 v137, v134
	v_mov_b32_e32 v133, v135
	v_pk_add_f32 v[132:133], v[136:137], v[132:133]
	s_nop 0
	v_add_f32_e32 v132, v132, v133
	ds_bpermute_b32 v133, v130, v132
	s_waitcnt lgkmcnt(0)
	v_add_f32_e32 v132, v132, v133
	ds_bpermute_b32 v133, v131, v132
	s_waitcnt lgkmcnt(0)
	v_add_f32_e32 v132, v132, v133
	v_fmamk_f32 v132, v132, 0x3a800000, v212
	v_rsq_f32_e32 v136, v132
	s_nop 0
	v_pk_mul_f32 v[134:135], v[54:55], v[136:137] op_sel_hi:[1,0]
	v_pk_mul_f32 v[132:133], v[52:53], v[136:137] op_sel_hi:[1,0]
	v_pk_mul_f32 v[138:139], v[50:51], v[136:137] op_sel_hi:[1,0]
	v_pk_mul_f32 v[140:141], v[48:49], v[136:137] op_sel_hi:[1,0]
	v_cvt_pk_bf16_f32 v132, v132, v133
	v_cvt_pk_bf16_f32 v133, v134, v135
	v_cvt_pk_bf16_f32 v134, v140, v141
	v_cvt_pk_bf16_f32 v135, v138, v139
	flat_store_dwordx4 v[128:129], v[132:135] sc1
	v_pk_mul_f32 v[138:139], v[114:115], v[136:137] op_sel_hi:[1,0]
	s_nop 0
	v_pk_mul_f32 v[134:135], v[118:119], v[136:137] op_sel_hi:[1,0]
	v_pk_mul_f32 v[132:133], v[116:117], v[136:137] op_sel_hi:[1,0]
	v_pk_mul_f32 v[136:137], v[112:113], v[136:137] op_sel_hi:[1,0]
	v_cvt_pk_bf16_f32 v132, v132, v133
	v_cvt_pk_bf16_f32 v133, v134, v135
	v_cvt_pk_bf16_f32 v134, v136, v137
	v_cvt_pk_bf16_f32 v135, v138, v139
	flat_store_dwordx4 v[128:129], v[132:135] offset:256 sc1
	v_or_b32_e32 v128, 32, v166
	v_ashrrev_i32_e32 v129, 31, v128
	v_lshlrev_b64 v[132:133], 6, v[128:129]
	v_lshl_add_u64 v[132:133], v[160:161], 0, v[132:133]
	flat_load_dwordx4 v[132:135], v[132:133]
	v_lshlrev_b64 v[128:129], 10, v[128:129]
	v_lshl_add_u64 v[128:129], s[8:9], 0, v[128:129]
	v_lshl_add_u64 v[128:129], v[128:129], 0, v[192:193]
	s_waitcnt vmcnt(0) lgkmcnt(0)
	v_mov_b32_e32 v136, v133
	v_mov_b32_e32 v137, v134
	v_mov_b32_e32 v133, v135
	v_pk_add_f32 v[132:133], v[136:137], v[132:133]
	s_nop 0
	v_add_f32_e32 v132, v132, v133
	ds_bpermute_b32 v133, v130, v132
	s_waitcnt lgkmcnt(0)
	v_add_f32_e32 v132, v132, v133
	ds_bpermute_b32 v133, v131, v132
	s_waitcnt lgkmcnt(0)
	v_add_f32_e32 v132, v132, v133
	v_fmamk_f32 v132, v132, 0x3a800000, v212
	v_rsq_f32_e32 v136, v132
	s_nop 0
	v_pk_mul_f32 v[134:135], v[46:47], v[136:137] op_sel_hi:[1,0]
	v_pk_mul_f32 v[132:133], v[44:45], v[136:137] op_sel_hi:[1,0]
	v_pk_mul_f32 v[138:139], v[42:43], v[136:137] op_sel_hi:[1,0]
	v_pk_mul_f32 v[140:141], v[40:41], v[136:137] op_sel_hi:[1,0]
	v_cvt_pk_bf16_f32 v132, v132, v133
	v_cvt_pk_bf16_f32 v133, v134, v135
	v_cvt_pk_bf16_f32 v134, v140, v141
	v_cvt_pk_bf16_f32 v135, v138, v139
	flat_store_dwordx4 v[128:129], v[132:135] sc1
	v_pk_mul_f32 v[138:139], v[106:107], v[136:137] op_sel_hi:[1,0]
	s_nop 0
	v_pk_mul_f32 v[134:135], v[110:111], v[136:137] op_sel_hi:[1,0]
	v_pk_mul_f32 v[132:133], v[108:109], v[136:137] op_sel_hi:[1,0]
	v_pk_mul_f32 v[136:137], v[104:105], v[136:137] op_sel_hi:[1,0]
	v_cvt_pk_bf16_f32 v132, v132, v133
	v_cvt_pk_bf16_f32 v133, v134, v135
	v_cvt_pk_bf16_f32 v134, v136, v137
	v_cvt_pk_bf16_f32 v135, v138, v139
	flat_store_dwordx4 v[128:129], v[132:135] offset:256 sc1
	v_or_b32_e32 v128, 48, v166
	v_ashrrev_i32_e32 v129, 31, v128
	v_lshlrev_b64 v[132:133], 6, v[128:129]
	v_lshl_add_u64 v[132:133], v[160:161], 0, v[132:133]
	flat_load_dwordx4 v[132:135], v[132:133]
	v_lshlrev_b64 v[128:129], 10, v[128:129]
	v_lshl_add_u64 v[128:129], s[8:9], 0, v[128:129]
	v_lshl_add_u64 v[128:129], v[128:129], 0, v[192:193]
	s_waitcnt vmcnt(0) lgkmcnt(0)
; __device__ __forceinline__ float silu_f(float x) { return x * __builtin_amdgcn_rcpf(1.f + __expf(-x)); }
; __device__ __forceinline__ v4u pack8(const f32x4 a, const f32x4 b) { v4u w; w.x = cvt_pk_bf16(a[0], a[1]); w.y = cvt_pk_bf16(a[2], a[3]); w.z = cvt_pk_bf16(b[0], b[1]); w.w = cvt_pk_bf16(b[2], b[3]); return w; }
; __device__ __forceinline__ float row_rstd(const float* ssq, int row, int fq) {
;     const f32x4 v = *(const f32x4*)(ssq + (size_t)row * 16 + fq * 4);
;     float s = (v[0] + v[1]) + (v[2] + v[3]);
;     s += __shfl_xor(s, 16); s += __shfl_xor(s, 32);
;     return __builtin_amdgcn_rsqf(s * (1.f / DM) + EPS);
; }
;     __device__ __forceinline__ void operator()(const f32x4 (&acc)[2][2][4][2], const pg8::Unit& u, int wr, int wc, int fr, int fq) const {
;     ...
;         if (grp == 0) { WIN_LOOP( _Pragma("unroll") for (int i = 0; i < 4; ++i) { a[i] = silu_f(a[i]); b[i] = silu_f(b[i]); } *(v4u*)(QO + (size_t)row * DM + c) = pack8(a, b); ) }
;         else if (grp == 3) { WIN_LOOP( _Pragma("unroll") for (int i = 0; i < 4; ++i) { a[i] = silu_f(a[i]); b[i] = silu_f(b[i]); } *(v4u*)(GH + (size_t)row * 512 + c) = pack8(a, b); ) }
;         else if (grp == 1) {
;             f32x4 l0[2], l1[2];
; #pragma unroll
;             for (int bj = 0; bj < 2; ++bj) { l0[bj] = *(const f32x4*)(lb + cb + bj * 128); l1[bj] = *(const f32x4*)(lb + cb + bj * 128 + 4); }
;             WIN_LOOP( _Pragma("unroll") for (int i = 0; i < 4; ++i) { const float s0 = fminf(a[i], 0.f) - __logf(1.f + __expf(-fabsf(a[i]))), s1 = fminf(b[i], 0.f) - __logf(1.f + __expf(-fabsf(b[i]))); const float la = l0[bj][i], lbv = l1[bj][i];
;                     a[i] = la > 0.f ? __logf(la + (1.f - la) * __expf(s0)) : s0; b[i] = lbv > 0.f ? __logf(lbv + (1.f - lbv) * __expf(s1)) : s1; }
;                 *(f32x4*)(LF + (size_t)row * 512 + c) = a; *(f32x4*)(LF + (size_t)row * 512 + c + 4) = b; __builtin_amdgcn_sched_barrier(0); ) }
;         else if (grp == 2) { WIN_LOOP( *(v4u*)(VH + (size_t)row * 512 + c) = pack8(a, b); ) }
	v_mov_b32_e32 v136, v133
	v_mov_b32_e32 v137, v134
	v_mov_b32_e32 v133, v135
	v_pk_add_f32 v[132:133], v[136:137], v[132:133]
	s_nop 0
	v_add_f32_e32 v132, v132, v133
	ds_bpermute_b32 v133, v130, v132
	s_waitcnt lgkmcnt(0)
	v_add_f32_e32 v132, v132, v133
	ds_bpermute_b32 v133, v131, v132
	s_waitcnt lgkmcnt(0)
	v_add_f32_e32 v132, v132, v133
	v_fmamk_f32 v132, v132, 0x3a800000, v212
	v_rsq_f32_e32 v136, v132
	s_nop 0
	v_pk_mul_f32 v[134:135], v[38:39], v[136:137] op_sel_hi:[1,0]
	v_pk_mul_f32 v[132:133], v[36:37], v[136:137] op_sel_hi:[1,0]
	v_pk_mul_f32 v[138:139], v[34:35], v[136:137] op_sel_hi:[1,0]
	v_pk_mul_f32 v[140:141], v[32:33], v[136:137] op_sel_hi:[1,0]
	v_cvt_pk_bf16_f32 v132, v132, v133
	v_cvt_pk_bf16_f32 v133, v134, v135
	v_cvt_pk_bf16_f32 v134, v140, v141
	v_cvt_pk_bf16_f32 v135, v138, v139
	flat_store_dwordx4 v[128:129], v[132:135] sc1
	v_pk_mul_f32 v[138:139], v[98:99], v[136:137] op_sel_hi:[1,0]
	s_nop 0
	v_pk_mul_f32 v[134:135], v[102:103], v[136:137] op_sel_hi:[1,0]
	v_pk_mul_f32 v[132:133], v[100:101], v[136:137] op_sel_hi:[1,0]
	v_pk_mul_f32 v[136:137], v[96:97], v[136:137] op_sel_hi:[1,0]
	v_cvt_pk_bf16_f32 v132, v132, v133
	v_cvt_pk_bf16_f32 v133, v134, v135
	v_cvt_pk_bf16_f32 v134, v136, v137
	v_cvt_pk_bf16_f32 v135, v138, v139
	flat_store_dwordx4 v[128:129], v[132:135] offset:256 sc1
	v_add_u32_e32 v128, 0x80, v166
	v_ashrrev_i32_e32 v129, 31, v128
	v_lshlrev_b64 v[132:133], 6, v[128:129]
	v_lshl_add_u64 v[132:133], v[160:161], 0, v[132:133]
	flat_load_dwordx4 v[132:135], v[132:133]
	v_lshlrev_b64 v[128:129], 10, v[128:129]
	v_lshl_add_u64 v[128:129], s[8:9], 0, v[128:129]
	v_lshl_add_u64 v[128:129], v[128:129], 0, v[192:193]
	s_waitcnt vmcnt(0) lgkmcnt(0)
	v_mov_b32_e32 v136, v133
	v_mov_b32_e32 v137, v134
	v_mov_b32_e32 v133, v135
	v_pk_add_f32 v[132:133], v[136:137], v[132:133]
	s_nop 0
	v_add_f32_e32 v132, v132, v133
	ds_bpermute_b32 v133, v130, v132
	s_waitcnt lgkmcnt(0)
	v_add_f32_e32 v132, v132, v133
	ds_bpermute_b32 v133, v131, v132
	s_waitcnt lgkmcnt(0)
	v_add_f32_e32 v132, v132, v133
	v_fmamk_f32 v132, v132, 0x3a800000, v212
	v_rsq_f32_e32 v136, v132
	s_nop 0
	v_pk_mul_f32 v[134:135], v[30:31], v[136:137] op_sel_hi:[1,0]
	v_pk_mul_f32 v[132:133], v[28:29], v[136:137] op_sel_hi:[1,0]
	v_pk_mul_f32 v[138:139], v[26:27], v[136:137] op_sel_hi:[1,0]
	v_pk_mul_f32 v[140:141], v[24:25], v[136:137] op_sel_hi:[1,0]
	v_cvt_pk_bf16_f32 v132, v132, v133
	v_cvt_pk_bf16_f32 v133, v134, v135
	v_cvt_pk_bf16_f32 v134, v140, v141
	v_cvt_pk_bf16_f32 v135, v138, v139
	flat_store_dwordx4 v[128:129], v[132:135] sc1
	v_pk_mul_f32 v[138:139], v[90:91], v[136:137] op_sel_hi:[1,0]
	s_nop 0
	v_pk_mul_f32 v[134:135], v[94:95], v[136:137] op_sel_hi:[1,0]
	v_pk_mul_f32 v[132:133], v[92:93], v[136:137] op_sel_hi:[1,0]
	v_pk_mul_f32 v[136:137], v[88:89], v[136:137] op_sel_hi:[1,0]
	v_cvt_pk_bf16_f32 v132, v132, v133
	v_cvt_pk_bf16_f32 v133, v134, v135
	v_cvt_pk_bf16_f32 v134, v136, v137
	v_cvt_pk_bf16_f32 v135, v138, v139
	flat_store_dwordx4 v[128:129], v[132:135] offset:256 sc1
	v_add_u32_e32 v128, 0x90, v166
	v_ashrrev_i32_e32 v129, 31, v128
	v_lshlrev_b64 v[132:133], 6, v[128:129]
	v_lshl_add_u64 v[132:133], v[160:161], 0, v[132:133]
	flat_load_dwordx4 v[132:135], v[132:133]
	v_lshlrev_b64 v[128:129], 10, v[128:129]
	v_lshl_add_u64 v[128:129], s[8:9], 0, v[128:129]
	v_lshl_add_u64 v[128:129], v[128:129], 0, v[192:193]
	s_waitcnt vmcnt(0) lgkmcnt(0)
	v_mov_b32_e32 v136, v133
	v_mov_b32_e32 v137, v134
	v_mov_b32_e32 v133, v135
	v_pk_add_f32 v[132:133], v[136:137], v[132:133]
	s_nop 0
	v_add_f32_e32 v132, v132, v133
	ds_bpermute_b32 v133, v130, v132
	s_waitcnt lgkmcnt(0)
	v_add_f32_e32 v132, v132, v133
	ds_bpermute_b32 v133, v131, v132
	s_waitcnt lgkmcnt(0)
; __device__ __forceinline__ float silu_f(float x) { return x * __builtin_amdgcn_rcpf(1.f + __expf(-x)); }
; __device__ __forceinline__ v4u pack8(const f32x4 a, const f32x4 b) { v4u w; w.x = cvt_pk_bf16(a[0], a[1]); w.y = cvt_pk_bf16(a[2], a[3]); w.z = cvt_pk_bf16(b[0], b[1]); w.w = cvt_pk_bf16(b[2], b[3]); return w; }
; __device__ __forceinline__ float row_rstd(const float* ssq, int row, int fq) {
;     const f32x4 v = *(const f32x4*)(ssq + (size_t)row * 16 + fq * 4);
;     float s = (v[0] + v[1]) + (v[2] + v[3]);
;     s += __shfl_xor(s, 16); s += __shfl_xor(s, 32);
;     return __builtin_amdgcn_rsqf(s * (1.f / DM) + EPS);
; }
;     __device__ __forceinline__ void operator()(const f32x4 (&acc)[2][2][4][2], const pg8::Unit& u, int wr, int wc, int fr, int fq) const {
;     ...
;         if (grp == 0) { WIN_LOOP( _Pragma("unroll") for (int i = 0; i < 4; ++i) { a[i] = silu_f(a[i]); b[i] = silu_f(b[i]); } *(v4u*)(QO + (size_t)row * DM + c) = pack8(a, b); ) }
;         else if (grp == 3) { WIN_LOOP( _Pragma("unroll") for (int i = 0; i < 4; ++i) { a[i] = silu_f(a[i]); b[i] = silu_f(b[i]); } *(v4u*)(GH + (size_t)row * 512 + c) = pack8(a, b); ) }
;         else if (grp == 1) {
;             f32x4 l0[2], l1[2];
; #pragma unroll
;             for (int bj = 0; bj < 2; ++bj) { l0[bj] = *(const f32x4*)(lb + cb + bj * 128); l1[bj] = *(const f32x4*)(lb + cb + bj * 128 + 4); }
;             WIN_LOOP( _Pragma("unroll") for (int i = 0; i < 4; ++i) { const float s0 = fminf(a[i], 0.f) - __logf(1.f + __expf(-fabsf(a[i]))), s1 = fminf(b[i], 0.f) - __logf(1.f + __expf(-fabsf(b[i]))); const float la = l0[bj][i], lbv = l1[bj][i];
;                     a[i] = la > 0.f ? __logf(la + (1.f - la) * __expf(s0)) : s0; b[i] = lbv > 0.f ? __logf(lbv + (1.f - lbv) * __expf(s1)) : s1; }
;                 *(f32x4*)(LF + (size_t)row * 512 + c) = a; *(f32x4*)(LF + (size_t)row * 512 + c + 4) = b; __builtin_amdgcn_sched_barrier(0); ) }
;         else if (grp == 2) { WIN_LOOP( *(v4u*)(VH + (size_t)row * 512 + c) = pack8(a, b); ) }
	v_add_f32_e32 v132, v132, v133
	v_fmamk_f32 v132, v132, 0x3a800000, v212
	v_rsq_f32_e32 v136, v132
	s_nop 0
	v_pk_mul_f32 v[134:135], v[22:23], v[136:137] op_sel_hi:[1,0]
	v_pk_mul_f32 v[132:133], v[20:21], v[136:137] op_sel_hi:[1,0]
	v_pk_mul_f32 v[138:139], v[18:19], v[136:137] op_sel_hi:[1,0]
	v_pk_mul_f32 v[140:141], v[16:17], v[136:137] op_sel_hi:[1,0]
	v_cvt_pk_bf16_f32 v132, v132, v133
	v_cvt_pk_bf16_f32 v133, v134, v135
	v_cvt_pk_bf16_f32 v134, v140, v141
	v_cvt_pk_bf16_f32 v135, v138, v139
	flat_store_dwordx4 v[128:129], v[132:135] sc1
	v_pk_mul_f32 v[138:139], v[82:83], v[136:137] op_sel_hi:[1,0]
	s_nop 0
	v_pk_mul_f32 v[134:135], v[86:87], v[136:137] op_sel_hi:[1,0]
	v_pk_mul_f32 v[132:133], v[84:85], v[136:137] op_sel_hi:[1,0]
	v_pk_mul_f32 v[136:137], v[80:81], v[136:137] op_sel_hi:[1,0]
	v_cvt_pk_bf16_f32 v132, v132, v133
	v_cvt_pk_bf16_f32 v133, v134, v135
	v_cvt_pk_bf16_f32 v134, v136, v137
	v_cvt_pk_bf16_f32 v135, v138, v139
	flat_store_dwordx4 v[128:129], v[132:135] offset:256 sc1
	v_add_u32_e32 v128, 0xa0, v166
	v_ashrrev_i32_e32 v129, 31, v128
	v_lshlrev_b64 v[132:133], 6, v[128:129]
	v_lshl_add_u64 v[132:133], v[160:161], 0, v[132:133]
	flat_load_dwordx4 v[132:135], v[132:133]
	v_lshlrev_b64 v[128:129], 10, v[128:129]
	v_lshl_add_u64 v[128:129], s[8:9], 0, v[128:129]
	v_lshl_add_u64 v[128:129], v[128:129], 0, v[192:193]
	s_waitcnt vmcnt(0) lgkmcnt(0)
	v_mov_b32_e32 v136, v133
	v_mov_b32_e32 v137, v134
	v_mov_b32_e32 v133, v135
	v_pk_add_f32 v[132:133], v[136:137], v[132:133]
	s_nop 0
	v_add_f32_e32 v132, v132, v133
	ds_bpermute_b32 v133, v130, v132
	s_waitcnt lgkmcnt(0)
	v_add_f32_e32 v132, v132, v133
	ds_bpermute_b32 v133, v131, v132
	s_waitcnt lgkmcnt(0)
	v_add_f32_e32 v132, v132, v133
	v_fmamk_f32 v132, v132, 0x3a800000, v212
	v_rsq_f32_e32 v136, v132
	s_nop 0
	v_pk_mul_f32 v[134:135], v[14:15], v[136:137] op_sel_hi:[1,0]
	v_pk_mul_f32 v[132:133], v[12:13], v[136:137] op_sel_hi:[1,0]
	v_pk_mul_f32 v[138:139], v[10:11], v[136:137] op_sel_hi:[1,0]
	v_pk_mul_f32 v[140:141], v[8:9], v[136:137] op_sel_hi:[1,0]
	v_cvt_pk_bf16_f32 v132, v132, v133
	v_cvt_pk_bf16_f32 v133, v134, v135
	v_cvt_pk_bf16_f32 v134, v140, v141
	v_cvt_pk_bf16_f32 v135, v138, v139
	flat_store_dwordx4 v[128:129], v[132:135] sc1
	v_pk_mul_f32 v[138:139], v[74:75], v[136:137] op_sel_hi:[1,0]
	s_nop 0
	v_pk_mul_f32 v[134:135], v[78:79], v[136:137] op_sel_hi:[1,0]
	v_pk_mul_f32 v[132:133], v[76:77], v[136:137] op_sel_hi:[1,0]
	v_pk_mul_f32 v[136:137], v[72:73], v[136:137] op_sel_hi:[1,0]
	v_cvt_pk_bf16_f32 v132, v132, v133
	v_cvt_pk_bf16_f32 v133, v134, v135
	v_cvt_pk_bf16_f32 v134, v136, v137
	v_cvt_pk_bf16_f32 v135, v138, v139
	flat_store_dwordx4 v[128:129], v[132:135] offset:256 sc1
	v_add_u32_e32 v128, 0xb0, v166
	v_ashrrev_i32_e32 v129, 31, v128
	v_lshlrev_b64 v[132:133], 6, v[128:129]
	v_lshl_add_u64 v[132:133], v[160:161], 0, v[132:133]
	flat_load_dwordx4 v[132:135], v[132:133]
	v_lshlrev_b64 v[128:129], 10, v[128:129]
	s_waitcnt vmcnt(0) lgkmcnt(0)
	v_mov_b32_e32 v136, v133
	v_mov_b32_e32 v137, v134
	v_mov_b32_e32 v133, v135
	v_pk_add_f32 v[132:133], v[136:137], v[132:133]
	v_lshl_add_u64 v[134:135], s[8:9], 0, v[128:129]
	v_add_f32_e32 v132, v132, v133
	ds_bpermute_b32 v130, v130, v132
	v_lshl_add_u64 v[134:135], v[134:135], 0, v[192:193]
	s_mov_b64 s[8:9], 0
	s_waitcnt lgkmcnt(0)
	v_add_f32_e32 v130, v132, v130
	ds_bpermute_b32 v131, v131, v130
	s_waitcnt lgkmcnt(0)
	v_add_f32_e32 v130, v130, v131
	v_fmamk_f32 v130, v130, 0x3a800000, v212
	v_rsq_f32_e32 v132, v130
	s_nop 0
	v_pk_mul_f32 v[130:131], v[6:7], v[132:133] op_sel_hi:[1,0]
	v_pk_mul_f32 v[128:129], v[4:5], v[132:133] op_sel_hi:[1,0]
	v_pk_mul_f32 v[136:137], v[2:3], v[132:133] op_sel_hi:[1,0]
	v_pk_mul_f32 v[138:139], v[0:1], v[132:133] op_sel_hi:[1,0]
	v_cvt_pk_bf16_f32 v128, v128, v129
	v_cvt_pk_bf16_f32 v129, v130, v131
	v_cvt_pk_bf16_f32 v130, v138, v139
	v_cvt_pk_bf16_f32 v131, v136, v137
	flat_store_dwordx4 v[134:135], v[128:131] sc1
	v_pk_mul_f32 v[136:137], v[66:67], v[132:133] op_sel_hi:[1,0]
	s_nop 0
	v_pk_mul_f32 v[130:131], v[70:71], v[132:133] op_sel_hi:[1,0]
	v_pk_mul_f32 v[128:129], v[68:69], v[132:133] op_sel_hi:[1,0]
	v_pk_mul_f32 v[132:133], v[64:65], v[132:133] op_sel_hi:[1,0]
	v_cvt_pk_bf16_f32 v128, v128, v129
	v_cvt_pk_bf16_f32 v129, v130, v131
	v_cvt_pk_bf16_f32 v130, v132, v133
	v_cvt_pk_bf16_f32 v131, v136, v137
	flat_store_dwordx4 v[134:135], v[128:131] offset:256 sc1

; __device__ __forceinline__ float silu_f(float x) { return x * __builtin_amdgcn_rcpf(1.f + __expf(-x)); }
; __device__ __forceinline__ v4u pack8(const f32x4 a, const f32x4 b) { v4u w; w.x = cvt_pk_bf16(a[0], a[1]); w.y = cvt_pk_bf16(a[2], a[3]); w.z = cvt_pk_bf16(b[0], b[1]); w.w = cvt_pk_bf16(b[2], b[3]); return w; }
; __device__ __forceinline__ float row_rstd(const float* ssq, int row, int fq) {
;     const f32x4 v = *(const f32x4*)(ssq + (size_t)row * 16 + fq * 4);
;     float s = (v[0] + v[1]) + (v[2] + v[3]);
;     s += __shfl_xor(s, 16); s += __shfl_xor(s, 32);
;     return __builtin_amdgcn_rsqf(s * (1.f / DM) + EPS);
; }
;     __device__ __forceinline__ void operator()(const f32x4 (&acc)[2][2][4][2], const pg8::Unit& u, int wr, int wc, int fr, int fq) const {
;     ...
;         if (grp == 0) { WIN_LOOP( _Pragma("unroll") for (int i = 0; i < 4; ++i) { a[i] = silu_f(a[i]); b[i] = silu_f(b[i]); } *(v4u*)(QO + (size_t)row * DM + c) = pack8(a, b); ) }
;         else if (grp == 3) { WIN_LOOP( _Pragma("unroll") for (int i = 0; i < 4; ++i) { a[i] = silu_f(a[i]); b[i] = silu_f(b[i]); } *(v4u*)(GH + (size_t)row * 512 + c) = pack8(a, b); ) }
;         else if (grp == 1) {
;             f32x4 l0[2], l1[2];
; #pragma unroll
;             for (int bj = 0; bj < 2; ++bj) { l0[bj] = *(const f32x4*)(lb + cb + bj * 128); l1[bj] = *(const f32x4*)(lb + cb + bj * 128 + 4); }
;             WIN_LOOP( _Pragma("unroll") for (int i = 0; i < 4; ++i) { const float s0 = fminf(a[i], 0.f) - __logf(1.f + __expf(-fabsf(a[i]))), s1 = fminf(b[i], 0.f) - __logf(1.f + __expf(-fabsf(b[i]))); const float la = l0[bj][i], lbv = l1[bj][i];
;                     a[i] = la > 0.f ? __logf(la + (1.f - la) * __expf(s0)) : s0; b[i] = lbv > 0.f ? __logf(lbv + (1.f - lbv) * __expf(s1)) : s1; }
;                 *(f32x4*)(LF + (size_t)row * 512 + c) = a; *(f32x4*)(LF + (size_t)row * 512 + c + 4) = b; __builtin_amdgcn_sched_barrier(0); ) }
;         else if (grp == 2) { WIN_LOOP( *(v4u*)(VH + (size_t)row * 512 + c) = pack8(a, b); ) }
;         else if (grp == 4) { WIN_LOOP( *(v4u*)(QO + (size_t)row * DM + 512 + c) = pack8(a * C2Q, b * C2Q); ) }
;         else if (grp == 5) { WIN_LOOP( *(v4u*)(FK + (size_t)row * 512 + c) = pack8(a, b); ) }
;         else { WIN_LOOP( *(v4u*)(FV + (size_t)row * 512 + c) = pack8(a, b); ) }
.LBB0_412:
	s_and_b64 vcc, exec, s[10:11]
	s_cbranch_vccz .LBB0_414
	v_and_b32_e32 v129, 64, v215
	v_xor_b32_e32 v128, 16, v215
	v_add_u32_e32 v129, 64, v129
	v_cmp_lt_i32_e32 vcc, v128, v129
	v_ashrrev_i32_e32 v167, 31, v166
	v_readlane_b32 s8, v255, 43
	v_cndmask_b32_e32 v128, v215, v128, vcc
	v_lshlrev_b32_e32 v130, 2, v128
	v_xor_b32_e32 v128, 32, v215
	v_cmp_lt_i32_e32 vcc, v128, v129
	v_readlane_b32 s9, v255, 44
	v_lshlrev_b32_e32 v192, 1, v176
	v_cndmask_b32_e32 v128, v215, v128, vcc
	v_lshlrev_b32_e32 v131, 2, v128
	v_lshlrev_b64 v[128:129], 6, v[166:167]
	v_lshl_add_u64 v[128:129], v[160:161], 0, v[128:129]
	flat_load_dwordx4 v[132:135], v[128:129]
	s_waitcnt vmcnt(0) lgkmcnt(0)
	v_mov_b32_e32 v128, v133
	v_mov_b32_e32 v129, v134
	v_mov_b32_e32 v133, v135
	v_pk_add_f32 v[128:129], v[128:129], v[132:133]
	v_lshlrev_b64 v[132:133], 10, v[166:167]
	v_add_f32_e32 v128, v128, v129
	ds_bpermute_b32 v129, v130, v128
	v_lshl_add_u64 v[136:137], s[8:9], 0, v[132:133]
	v_lshl_add_u64 v[136:137], v[136:137], 0, v[192:193]
	s_waitcnt lgkmcnt(0)
	v_add_f32_e32 v128, v128, v129
	ds_bpermute_b32 v129, v131, v128
	s_waitcnt lgkmcnt(0)
	v_add_f32_e32 v128, v128, v129
	v_fmamk_f32 v128, v128, 0x3a800000, v212
	v_rsq_f32_e32 v128, v128
	s_nop 0
	v_pk_mul_f32 v[134:135], v[62:63], v[128:129] op_sel_hi:[1,0]
	v_pk_mul_f32 v[132:133], v[60:61], v[128:129] op_sel_hi:[1,0]
	v_pk_mul_f32 v[138:139], v[58:59], v[128:129] op_sel_hi:[1,0]
	v_pk_mul_f32 v[140:141], v[56:57], v[128:129] op_sel_hi:[1,0]
	v_cvt_pk_bf16_f32 v132, v132, v133
	v_cvt_pk_bf16_f32 v133, v134, v135
	v_cvt_pk_bf16_f32 v134, v140, v141
	v_cvt_pk_bf16_f32 v135, v138, v139
	flat_store_dwordx4 v[136:137], v[132:135] sc1
	v_pk_mul_f32 v[138:139], v[122:123], v[128:129] op_sel_hi:[1,0]
	s_nop 0
	v_pk_mul_f32 v[134:135], v[126:127], v[128:129] op_sel_hi:[1,0]
	v_pk_mul_f32 v[132:133], v[124:125], v[128:129] op_sel_hi:[1,0]
	v_pk_mul_f32 v[128:129], v[120:121], v[128:129] op_sel_hi:[1,0]
	v_cvt_pk_bf16_f32 v132, v132, v133
	v_cvt_pk_bf16_f32 v133, v134, v135
	v_cvt_pk_bf16_f32 v134, v128, v129
	v_or_b32_e32 v128, 16, v166
	v_cvt_pk_bf16_f32 v135, v138, v139
	v_ashrrev_i32_e32 v129, 31, v128
	flat_store_dwordx4 v[136:137], v[132:135] offset:256 sc1
	s_nop 1
	v_lshlrev_b64 v[132:133], 6, v[128:129]
	v_lshl_add_u64 v[132:133], v[160:161], 0, v[132:133]
	flat_load_dwordx4 v[132:135], v[132:133]
	v_lshlrev_b64 v[128:129], 10, v[128:129]
	v_lshl_add_u64 v[128:129], s[8:9], 0, v[128:129]
	v_lshl_add_u64 v[128:129], v[128:129], 0, v[192:193]
	s_waitcnt vmcnt(0) lgkmcnt(0)
	v_mov_b32_e32 v136, v133
	v_mov_b32_e32 v137, v134
	v_mov_b32_e32 v133, v135
	v_pk_add_f32 v[132:133], v[136:137], v[132:133]
	s_nop 0
	v_add_f32_e32 v132, v132, v133
	ds_bpermute_b32 v133, v130, v132
	s_waitcnt lgkmcnt(0)
	v_add_f32_e32 v132, v132, v133
	ds_bpermute_b32 v133, v131, v132
	s_waitcnt lgkmcnt(0)
	v_add_f32_e32 v132, v132, v133
	v_fmamk_f32 v132, v132, 0x3a800000, v212
	v_rsq_f32_e32 v136, v132
	s_nop 0
	v_pk_mul_f32 v[134:135], v[54:55], v[136:137] op_sel_hi:[1,0]
	v_pk_mul_f32 v[132:133], v[52:53], v[136:137] op_sel_hi:[1,0]
	v_pk_mul_f32 v[138:139], v[50:51], v[136:137] op_sel_hi:[1,0]
	v_pk_mul_f32 v[140:141], v[48:49], v[136:137] op_sel_hi:[1,0]
	v_cvt_pk_bf16_f32 v132, v132, v133
	v_cvt_pk_bf16_f32 v133, v134, v135
	v_cvt_pk_bf16_f32 v134, v140, v141
	v_cvt_pk_bf16_f32 v135, v138, v139
	flat_store_dwordx4 v[128:129], v[132:135] sc1
	v_pk_mul_f32 v[138:139], v[114:115], v[136:137] op_sel_hi:[1,0]
	s_nop 0
	v_pk_mul_f32 v[134:135], v[118:119], v[136:137] op_sel_hi:[1,0]
	v_pk_mul_f32 v[132:133], v[116:117], v[136:137] op_sel_hi:[1,0]
	v_pk_mul_f32 v[136:137], v[112:113], v[136:137] op_sel_hi:[1,0]
	v_cvt_pk_bf16_f32 v132, v132, v133
	v_cvt_pk_bf16_f32 v133, v134, v135
	v_cvt_pk_bf16_f32 v134, v136, v137
	v_cvt_pk_bf16_f32 v135, v138, v139
	flat_store_dwordx4 v[128:129], v[132:135] offset:256 sc1
	v_or_b32_e32 v128, 32, v166
	v_ashrrev_i32_e32 v129, 31, v128
	v_lshlrev_b64 v[132:133], 6, v[128:129]
	v_lshl_add_u64 v[132:133], v[160:161], 0, v[132:133]
	flat_load_dwordx4 v[132:135], v[132:133]
	v_lshlrev_b64 v[128:129], 10, v[128:129]
	v_lshl_add_u64 v[128:129], s[8:9], 0, v[128:129]
	v_lshl_add_u64 v[128:129], v[128:129], 0, v[192:193]
	s_waitcnt vmcnt(0) lgkmcnt(0)
	v_mov_b32_e32 v136, v133
	v_mov_b32_e32 v137, v134
	v_mov_b32_e32 v133, v135
	v_pk_add_f32 v[132:133], v[136:137], v[132:133]
	s_nop 0
	v_add_f32_e32 v132, v132, v133
	ds_bpermute_b32 v133, v130, v132
	s_waitcnt lgkmcnt(0)
	v_add_f32_e32 v132, v132, v133
	ds_bpermute_b32 v133, v131, v132
	s_waitcnt lgkmcnt(0)
	v_add_f32_e32 v132, v132, v133
	v_fmamk_f32 v132, v132, 0x3a800000, v212
	v_rsq_f32_e32 v136, v132
	s_nop 0
	v_pk_mul_f32 v[134:135], v[46:47], v[136:137] op_sel_hi:[1,0]
	v_pk_mul_f32 v[132:133], v[44:45], v[136:137] op_sel_hi:[1,0]
	v_pk_mul_f32 v[138:139], v[42:43], v[136:137] op_sel_hi:[1,0]
	v_pk_mul_f32 v[140:141], v[40:41], v[136:137] op_sel_hi:[1,0]
	v_cvt_pk_bf16_f32 v132, v132, v133
	v_cvt_pk_bf16_f32 v133, v134, v135
	v_cvt_pk_bf16_f32 v134, v140, v141
	v_cvt_pk_bf16_f32 v135, v138, v139
	flat_store_dwordx4 v[128:129], v[132:135] sc1
	v_pk_mul_f32 v[138:139], v[106:107], v[136:137] op_sel_hi:[1,0]
	s_nop 0
	v_pk_mul_f32 v[134:135], v[110:111], v[136:137] op_sel_hi:[1,0]
	v_pk_mul_f32 v[132:133], v[108:109], v[136:137] op_sel_hi:[1,0]
	v_pk_mul_f32 v[136:137], v[104:105], v[136:137] op_sel_hi:[1,0]
	v_cvt_pk_bf16_f32 v132, v132, v133
	v_cvt_pk_bf16_f32 v133, v134, v135
	v_cvt_pk_bf16_f32 v134, v136, v137
	v_cvt_pk_bf16_f32 v135, v138, v139
	flat_store_dwordx4 v[128:129], v[132:135] offset:256 sc1
	v_or_b32_e32 v128, 48, v166
	v_ashrrev_i32_e32 v129, 31, v128
	v_lshlrev_b64 v[132:133], 6, v[128:129]
	v_lshl_add_u64 v[132:133], v[160:161], 0, v[132:133]
	flat_load_dwordx4 v[132:135], v[132:133]
	v_lshlrev_b64 v[128:129], 10, v[128:129]
	v_lshl_add_u64 v[128:129], s[8:9], 0, v[128:129]
	v_lshl_add_u64 v[128:129], v[128:129], 0, v[192:193]
	s_waitcnt vmcnt(0) lgkmcnt(0)
; __device__ __forceinline__ float silu_f(float x) { return x * __builtin_amdgcn_rcpf(1.f + __expf(-x)); }
; __device__ __forceinline__ v4u pack8(const f32x4 a, const f32x4 b) { v4u w; w.x = cvt_pk_bf16(a[0], a[1]); w.y = cvt_pk_bf16(a[2], a[3]); w.z = cvt_pk_bf16(b[0], b[1]); w.w = cvt_pk_bf16(b[2], b[3]); return w; }
; __device__ __forceinline__ float row_rstd(const float* ssq, int row, int fq) {
;     const f32x4 v = *(const f32x4*)(ssq + (size_t)row * 16 + fq * 4);
;     float s = (v[0] + v[1]) + (v[2] + v[3]);
;     s += __shfl_xor(s, 16); s += __shfl_xor(s, 32);
;     return __builtin_amdgcn_rsqf(s * (1.f / DM) + EPS);
; }
;     __device__ __forceinline__ void operator()(const f32x4 (&acc)[2][2][4][2], const pg8::Unit& u, int wr, int wc, int fr, int fq) const {
;     ...
;         if (grp == 0) { WIN_LOOP( _Pragma("unroll") for (int i = 0; i < 4; ++i) { a[i] = silu_f(a[i]); b[i] = silu_f(b[i]); } *(v4u*)(QO + (size_t)row * DM + c) = pack8(a, b); ) }
;         else if (grp == 3) { WIN_LOOP( _Pragma("unroll") for (int i = 0; i < 4; ++i) { a[i] = silu_f(a[i]); b[i] = silu_f(b[i]); } *(v4u*)(GH + (size_t)row * 512 + c) = pack8(a, b); ) }
;         else if (grp == 1) {
;             f32x4 l0[2], l1[2];
; #pragma unroll
;             for (int bj = 0; bj < 2; ++bj) { l0[bj] = *(const f32x4*)(lb + cb + bj * 128); l1[bj] = *(const f32x4*)(lb + cb + bj * 128 + 4); }
;             WIN_LOOP( _Pragma("unroll") for (int i = 0; i < 4; ++i) { const float s0 = fminf(a[i], 0.f) - __logf(1.f + __expf(-fabsf(a[i]))), s1 = fminf(b[i], 0.f) - __logf(1.f + __expf(-fabsf(b[i]))); const float la = l0[bj][i], lbv = l1[bj][i];
;                     a[i] = la > 0.f ? __logf(la + (1.f - la) * __expf(s0)) : s0; b[i] = lbv > 0.f ? __logf(lbv + (1.f - lbv) * __expf(s1)) : s1; }
;                 *(f32x4*)(LF + (size_t)row * 512 + c) = a; *(f32x4*)(LF + (size_t)row * 512 + c + 4) = b; __builtin_amdgcn_sched_barrier(0); ) }
;         else if (grp == 2) { WIN_LOOP( *(v4u*)(VH + (size_t)row * 512 + c) = pack8(a, b); ) }
;         else if (grp == 4) { WIN_LOOP( *(v4u*)(QO + (size_t)row * DM + 512 + c) = pack8(a * C2Q, b * C2Q); ) }
;         else if (grp == 5) { WIN_LOOP( *(v4u*)(FK + (size_t)row * 512 + c) = pack8(a, b); ) }
;         else { WIN_LOOP( *(v4u*)(FV + (size_t)row * 512 + c) = pack8(a, b); ) }
	v_mov_b32_e32 v136, v133
	v_mov_b32_e32 v137, v134
	v_mov_b32_e32 v133, v135
	v_pk_add_f32 v[132:133], v[136:137], v[132:133]
	s_nop 0
	v_add_f32_e32 v132, v132, v133
	ds_bpermute_b32 v133, v130, v132
	s_waitcnt lgkmcnt(0)
	v_add_f32_e32 v132, v132, v133
	ds_bpermute_b32 v133, v131, v132
	s_waitcnt lgkmcnt(0)
	v_add_f32_e32 v132, v132, v133
	v_fmamk_f32 v132, v132, 0x3a800000, v212
	v_rsq_f32_e32 v136, v132
	s_nop 0
	v_pk_mul_f32 v[134:135], v[38:39], v[136:137] op_sel_hi:[1,0]
	v_pk_mul_f32 v[132:133], v[36:37], v[136:137] op_sel_hi:[1,0]
	v_pk_mul_f32 v[138:139], v[34:35], v[136:137] op_sel_hi:[1,0]
	v_pk_mul_f32 v[140:141], v[32:33], v[136:137] op_sel_hi:[1,0]
	v_cvt_pk_bf16_f32 v132, v132, v133
	v_cvt_pk_bf16_f32 v133, v134, v135
	v_cvt_pk_bf16_f32 v134, v140, v141
	v_cvt_pk_bf16_f32 v135, v138, v139
	flat_store_dwordx4 v[128:129], v[132:135] sc1
	v_pk_mul_f32 v[138:139], v[98:99], v[136:137] op_sel_hi:[1,0]
	s_nop 0
	v_pk_mul_f32 v[134:135], v[102:103], v[136:137] op_sel_hi:[1,0]
	v_pk_mul_f32 v[132:133], v[100:101], v[136:137] op_sel_hi:[1,0]
	v_pk_mul_f32 v[136:137], v[96:97], v[136:137] op_sel_hi:[1,0]
	v_cvt_pk_bf16_f32 v132, v132, v133
	v_cvt_pk_bf16_f32 v133, v134, v135
	v_cvt_pk_bf16_f32 v134, v136, v137
	v_cvt_pk_bf16_f32 v135, v138, v139
	flat_store_dwordx4 v[128:129], v[132:135] offset:256 sc1
	v_add_u32_e32 v128, 0x80, v166
	v_ashrrev_i32_e32 v129, 31, v128
	v_lshlrev_b64 v[132:133], 6, v[128:129]
	v_lshl_add_u64 v[132:133], v[160:161], 0, v[132:133]
	flat_load_dwordx4 v[132:135], v[132:133]
	v_lshlrev_b64 v[128:129], 10, v[128:129]
	v_lshl_add_u64 v[128:129], s[8:9], 0, v[128:129]
	v_lshl_add_u64 v[128:129], v[128:129], 0, v[192:193]
	s_waitcnt vmcnt(0) lgkmcnt(0)
	v_mov_b32_e32 v136, v133
	v_mov_b32_e32 v137, v134
	v_mov_b32_e32 v133, v135
	v_pk_add_f32 v[132:133], v[136:137], v[132:133]
	s_nop 0
	v_add_f32_e32 v132, v132, v133
	ds_bpermute_b32 v133, v130, v132
	s_waitcnt lgkmcnt(0)
	v_add_f32_e32 v132, v132, v133
	ds_bpermute_b32 v133, v131, v132
	s_waitcnt lgkmcnt(0)
	v_add_f32_e32 v132, v132, v133
	v_fmamk_f32 v132, v132, 0x3a800000, v212
	v_rsq_f32_e32 v136, v132
	s_nop 0
	v_pk_mul_f32 v[134:135], v[30:31], v[136:137] op_sel_hi:[1,0]
	v_pk_mul_f32 v[132:133], v[28:29], v[136:137] op_sel_hi:[1,0]
	v_pk_mul_f32 v[138:139], v[26:27], v[136:137] op_sel_hi:[1,0]
	v_pk_mul_f32 v[140:141], v[24:25], v[136:137] op_sel_hi:[1,0]
	v_cvt_pk_bf16_f32 v132, v132, v133
	v_cvt_pk_bf16_f32 v133, v134, v135
	v_cvt_pk_bf16_f32 v134, v140, v141
	v_cvt_pk_bf16_f32 v135, v138, v139
	flat_store_dwordx4 v[128:129], v[132:135] sc1
	v_pk_mul_f32 v[138:139], v[90:91], v[136:137] op_sel_hi:[1,0]
	s_nop 0
	v_pk_mul_f32 v[134:135], v[94:95], v[136:137] op_sel_hi:[1,0]
	v_pk_mul_f32 v[132:133], v[92:93], v[136:137] op_sel_hi:[1,0]
	v_pk_mul_f32 v[136:137], v[88:89], v[136:137] op_sel_hi:[1,0]
	v_cvt_pk_bf16_f32 v132, v132, v133
	v_cvt_pk_bf16_f32 v133, v134, v135
	v_cvt_pk_bf16_f32 v134, v136, v137
	v_cvt_pk_bf16_f32 v135, v138, v139
	flat_store_dwordx4 v[128:129], v[132:135] offset:256 sc1
	v_add_u32_e32 v128, 0x90, v166
	v_ashrrev_i32_e32 v129, 31, v128
	v_lshlrev_b64 v[132:133], 6, v[128:129]
	v_lshl_add_u64 v[132:133], v[160:161], 0, v[132:133]
	flat_load_dwordx4 v[132:135], v[132:133]
	v_lshlrev_b64 v[128:129], 10, v[128:129]
	v_lshl_add_u64 v[128:129], s[8:9], 0, v[128:129]
	v_lshl_add_u64 v[128:129], v[128:129], 0, v[192:193]
	s_waitcnt vmcnt(0) lgkmcnt(0)
	v_mov_b32_e32 v136, v133
	v_mov_b32_e32 v137, v134
	v_mov_b32_e32 v133, v135
	v_pk_add_f32 v[132:133], v[136:137], v[132:133]
	s_nop 0
	v_add_f32_e32 v132, v132, v133
	ds_bpermute_b32 v133, v130, v132
	s_waitcnt lgkmcnt(0)
	v_add_f32_e32 v132, v132, v133
	ds_bpermute_b32 v133, v131, v132
	s_waitcnt lgkmcnt(0)
	v_add_f32_e32 v132, v132, v133
	v_fmamk_f32 v132, v132, 0x3a800000, v212
	v_rsq_f32_e32 v136, v132
	s_nop 0
	v_pk_mul_f32 v[134:135], v[22:23], v[136:137] op_sel_hi:[1,0]
	v_pk_mul_f32 v[132:133], v[20:21], v[136:137] op_sel_hi:[1,0]
	v_pk_mul_f32 v[138:139], v[18:19], v[136:137] op_sel_hi:[1,0]
	v_pk_mul_f32 v[140:141], v[16:17], v[136:137] op_sel_hi:[1,0]
	v_cvt_pk_bf16_f32 v132, v132, v133
	v_cvt_pk_bf16_f32 v133, v134, v135
	v_cvt_pk_bf16_f32 v134, v140, v141
	v_cvt_pk_bf16_f32 v135, v138, v139
	flat_store_dwordx4 v[128:129], v[132:135] sc1
	v_pk_mul_f32 v[138:139], v[82:83], v[136:137] op_sel_hi:[1,0]
	s_nop 0
	v_pk_mul_f32 v[134:135], v[86:87], v[136:137] op_sel_hi:[1,0]
	v_pk_mul_f32 v[132:133], v[84:85], v[136:137] op_sel_hi:[1,0]
	v_pk_mul_f32 v[136:137], v[80:81], v[136:137] op_sel_hi:[1,0]
	v_cvt_pk_bf16_f32 v132, v132, v133
	v_cvt_pk_bf16_f32 v133, v134, v135
	v_cvt_pk_bf16_f32 v134, v136, v137
	v_cvt_pk_bf16_f32 v135, v138, v139
	flat_store_dwordx4 v[128:129], v[132:135] offset:256 sc1
	v_add_u32_e32 v128, 0xa0, v166
	v_ashrrev_i32_e32 v129, 31, v128
	v_lshlrev_b64 v[132:133], 6, v[128:129]
	v_lshl_add_u64 v[132:133], v[160:161], 0, v[132:133]
	flat_load_dwordx4 v[132:135], v[132:133]
	v_lshlrev_b64 v[128:129], 10, v[128:129]
	v_lshl_add_u64 v[128:129], s[8:9], 0, v[128:129]
	v_lshl_add_u64 v[128:129], v[128:129], 0, v[192:193]
	s_waitcnt vmcnt(0) lgkmcnt(0)
	v_mov_b32_e32 v136, v133
	v_mov_b32_e32 v137, v134
	v_mov_b32_e32 v133, v135
	v_pk_add_f32 v[132:133], v[136:137], v[132:133]
	s_nop 0
	v_add_f32_e32 v132, v132, v133
	ds_bpermute_b32 v133, v130, v132
	s_waitcnt lgkmcnt(0)
	v_add_f32_e32 v132, v132, v133
	ds_bpermute_b32 v133, v131, v132
	s_waitcnt lgkmcnt(0)
; __device__ __forceinline__ float silu_f(float x) { return x * __builtin_amdgcn_rcpf(1.f + __expf(-x)); }
; __device__ __forceinline__ v4u pack8(const f32x4 a, const f32x4 b) { v4u w; w.x = cvt_pk_bf16(a[0], a[1]); w.y = cvt_pk_bf16(a[2], a[3]); w.z = cvt_pk_bf16(b[0], b[1]); w.w = cvt_pk_bf16(b[2], b[3]); return w; }
; __device__ __forceinline__ float row_rstd(const float* ssq, int row, int fq) {
;     const f32x4 v = *(const f32x4*)(ssq + (size_t)row * 16 + fq * 4);
;     float s = (v[0] + v[1]) + (v[2] + v[3]);
;     s += __shfl_xor(s, 16); s += __shfl_xor(s, 32);
;     return __builtin_amdgcn_rsqf(s * (1.f / DM) + EPS);
; }
;     __device__ __forceinline__ void operator()(const f32x4 (&acc)[2][2][4][2], const pg8::Unit& u, int wr, int wc, int fr, int fq) const {
;     ...
;         if (grp == 0) { WIN_LOOP( _Pragma("unroll") for (int i = 0; i < 4; ++i) { a[i] = silu_f(a[i]); b[i] = silu_f(b[i]); } *(v4u*)(QO + (size_t)row * DM + c) = pack8(a, b); ) }
;         else if (grp == 3) { WIN_LOOP( _Pragma("unroll") for (int i = 0; i < 4; ++i) { a[i] = silu_f(a[i]); b[i] = silu_f(b[i]); } *(v4u*)(GH + (size_t)row * 512 + c) = pack8(a, b); ) }
;         else if (grp == 1) {
;             f32x4 l0[2], l1[2];
; #pragma unroll
;             for (int bj = 0; bj < 2; ++bj) { l0[bj] = *(const f32x4*)(lb + cb + bj * 128); l1[bj] = *(const f32x4*)(lb + cb + bj * 128 + 4); }
;             WIN_LOOP( _Pragma("unroll") for (int i = 0; i < 4; ++i) { const float s0 = fminf(a[i], 0.f) - __logf(1.f + __expf(-fabsf(a[i]))), s1 = fminf(b[i], 0.f) - __logf(1.f + __expf(-fabsf(b[i]))); const float la = l0[bj][i], lbv = l1[bj][i];
;                     a[i] = la > 0.f ? __logf(la + (1.f - la) * __expf(s0)) : s0; b[i] = lbv > 0.f ? __logf(lbv + (1.f - lbv) * __expf(s1)) : s1; }
;                 *(f32x4*)(LF + (size_t)row * 512 + c) = a; *(f32x4*)(LF + (size_t)row * 512 + c + 4) = b; __builtin_amdgcn_sched_barrier(0); ) }
;         else if (grp == 2) { WIN_LOOP( *(v4u*)(VH + (size_t)row * 512 + c) = pack8(a, b); ) }
;         else if (grp == 4) { WIN_LOOP( *(v4u*)(QO + (size_t)row * DM + 512 + c) = pack8(a * C2Q, b * C2Q); ) }
;         else if (grp == 5) { WIN_LOOP( *(v4u*)(FK + (size_t)row * 512 + c) = pack8(a, b); ) }
;         else { WIN_LOOP( *(v4u*)(FV + (size_t)row * 512 + c) = pack8(a, b); ) }
	v_add_f32_e32 v132, v132, v133
	v_fmamk_f32 v132, v132, 0x3a800000, v212
	v_rsq_f32_e32 v136, v132
	s_nop 0
	v_pk_mul_f32 v[134:135], v[14:15], v[136:137] op_sel_hi:[1,0]
	v_pk_mul_f32 v[132:133], v[12:13], v[136:137] op_sel_hi:[1,0]
	v_pk_mul_f32 v[138:139], v[10:11], v[136:137] op_sel_hi:[1,0]
	v_pk_mul_f32 v[140:141], v[8:9], v[136:137] op_sel_hi:[1,0]
	v_cvt_pk_bf16_f32 v132, v132, v133
	v_cvt_pk_bf16_f32 v133, v134, v135
	v_cvt_pk_bf16_f32 v134, v140, v141
	v_cvt_pk_bf16_f32 v135, v138, v139
	flat_store_dwordx4 v[128:129], v[132:135] sc1
	v_pk_mul_f32 v[138:139], v[74:75], v[136:137] op_sel_hi:[1,0]
	s_nop 0
	v_pk_mul_f32 v[134:135], v[78:79], v[136:137] op_sel_hi:[1,0]
	v_pk_mul_f32 v[132:133], v[76:77], v[136:137] op_sel_hi:[1,0]
	v_pk_mul_f32 v[136:137], v[72:73], v[136:137] op_sel_hi:[1,0]
	v_cvt_pk_bf16_f32 v132, v132, v133
	v_cvt_pk_bf16_f32 v133, v134, v135
	v_cvt_pk_bf16_f32 v134, v136, v137
	v_cvt_pk_bf16_f32 v135, v138, v139
	flat_store_dwordx4 v[128:129], v[132:135] offset:256 sc1
	v_add_u32_e32 v128, 0xb0, v166
	v_ashrrev_i32_e32 v129, 31, v128
	v_lshlrev_b64 v[132:133], 6, v[128:129]
	v_lshl_add_u64 v[132:133], v[160:161], 0, v[132:133]
	flat_load_dwordx4 v[132:135], v[132:133]
	v_lshlrev_b64 v[128:129], 10, v[128:129]
	s_waitcnt vmcnt(0) lgkmcnt(0)
	v_mov_b32_e32 v136, v133
	v_mov_b32_e32 v137, v134
	v_mov_b32_e32 v133, v135
	v_pk_add_f32 v[132:133], v[136:137], v[132:133]
	v_lshl_add_u64 v[134:135], s[8:9], 0, v[128:129]
	v_add_f32_e32 v132, v132, v133
	ds_bpermute_b32 v130, v130, v132
	v_lshl_add_u64 v[134:135], v[134:135], 0, v[192:193]
	s_mov_b64 s[8:9], 0
	s_waitcnt lgkmcnt(0)
	v_add_f32_e32 v130, v132, v130
	ds_bpermute_b32 v131, v131, v130
	s_waitcnt lgkmcnt(0)
	v_add_f32_e32 v130, v130, v131
	v_fmamk_f32 v130, v130, 0x3a800000, v212
	v_rsq_f32_e32 v132, v130
	s_nop 0
	v_pk_mul_f32 v[130:131], v[6:7], v[132:133] op_sel_hi:[1,0]
	v_pk_mul_f32 v[128:129], v[4:5], v[132:133] op_sel_hi:[1,0]
	v_pk_mul_f32 v[136:137], v[2:3], v[132:133] op_sel_hi:[1,0]
	v_pk_mul_f32 v[138:139], v[0:1], v[132:133] op_sel_hi:[1,0]
	v_cvt_pk_bf16_f32 v128, v128, v129
	v_cvt_pk_bf16_f32 v129, v130, v131
	v_cvt_pk_bf16_f32 v130, v138, v139
	v_cvt_pk_bf16_f32 v131, v136, v137
	flat_store_dwordx4 v[134:135], v[128:131] sc1
	v_pk_mul_f32 v[136:137], v[66:67], v[132:133] op_sel_hi:[1,0]
	s_nop 0
	v_pk_mul_f32 v[130:131], v[70:71], v[132:133] op_sel_hi:[1,0]
	v_pk_mul_f32 v[128:129], v[68:69], v[132:133] op_sel_hi:[1,0]
	v_pk_mul_f32 v[132:133], v[64:65], v[132:133] op_sel_hi:[1,0]
	v_cvt_pk_bf16_f32 v128, v128, v129
	v_cvt_pk_bf16_f32 v129, v130, v131
	v_cvt_pk_bf16_f32 v130, v132, v133
	v_cvt_pk_bf16_f32 v131, v136, v137
	flat_store_dwordx4 v[134:135], v[128:131] offset:256 sc1
.LBB0_414:
	s_andn2_b64 vcc, exec, s[8:9]
	s_cbranch_vccnz .LBB0_416
	v_ashrrev_i32_e32 v167, 31, v166
	v_lshlrev_b64 v[128:129], 6, v[166:167]
	v_lshl_add_u64 v[128:129], v[160:161], 0, v[128:129]
	flat_load_dwordx4 v[128:131], v[128:129]
	v_readlane_b32 s8, v255, 35
	v_lshlrev_b32_e32 v192, 2, v176
	v_readlane_b32 s9, v255, 36
	v_and_b32_e32 v133, 64, v215
	v_xor_b32_e32 v132, 16, v215
	v_lshl_add_u64 v[144:145], s[8:9], 0, v[192:193]
	flat_load_dwordx4 v[140:143], v[144:145]
	flat_load_dwordx4 v[136:139], v[144:145] offset:16
	v_add_u32_e32 v134, 64, v133
	v_cmp_lt_i32_e32 vcc, v132, v134
	v_lshlrev_b64 v[146:147], 11, v[166:167]
	v_readlane_b32 s50, v255, 45
	v_cndmask_b32_e32 v132, v215, v132, vcc
	v_lshlrev_b32_e32 v169, 2, v132
	v_readlane_b32 s51, v255, 46
	s_mov_b32 s95, s28
	s_mov_b32 s91, s29
	v_lshl_add_u64 v[170:171], s[50:51], 0, v[146:147]
	v_lshl_add_u64 v[170:171], v[170:171], 0, v[192:193]
	s_waitcnt vmcnt(0) lgkmcnt(0)
	v_mov_b32_e32 v132, v129
	v_mov_b32_e32 v133, v130
	v_mov_b32_e32 v129, v131
	v_pk_add_f32 v[128:129], v[132:133], v[128:129]
	v_xor_b32_e32 v130, 32, v215
	v_add_f32_e32 v128, v128, v129
	ds_bpermute_b32 v129, v169, v128
	v_cmp_lt_i32_e32 vcc, v130, v134
	v_sub_f32_e32 v190, 1.0, v140
	v_sub_f32_e32 v191, 1.0, v136
	v_cndmask_b32_e32 v130, v215, v130, vcc
	v_lshlrev_b32_e32 v202, 2, v130
	s_waitcnt lgkmcnt(0)
	v_add_f32_e32 v148, v128, v129
	ds_bpermute_b32 v149, v202, v148
	flat_load_dwordx4 v[132:135], v[144:145] offset:512
	flat_load_dwordx4 v[128:131], v[144:145] offset:528
	v_sub_f32_e32 v188, 1.0, v141
	v_cmp_lt_f32_e64 s[38:39], 0, v140
	v_cmp_lt_f32_e64 s[36:37], 0, v136
	s_waitcnt lgkmcnt(0)
;     __device__ __forceinline__ void operator()(const f32x4 (&acc)[2][2][4][2], const pg8::Unit& u, int wr, int wc, int fr, int fq) const {
;     ...
;         else if (grp == 1) {
;             f32x4 l0[2], l1[2];
; #pragma unroll
;             for (int bj = 0; bj < 2; ++bj) { l0[bj] = *(const f32x4*)(lb + cb + bj * 128); l1[bj] = *(const f32x4*)(lb + cb + bj * 128 + 4); }
;             WIN_LOOP( _Pragma("unroll") for (int i = 0; i < 4; ++i) { const float s0 = fminf(a[i], 0.f) - __logf(1.f + __expf(-fabsf(a[i]))), s1 = fminf(b[i], 0.f) - __logf(1.f + __expf(-fabsf(b[i]))); const float la = l0[bj][i], lbv = l1[bj][i];
;                     a[i] = la > 0.f ? __logf(la + (1.f - la) * __expf(s0)) : s0; b[i] = lbv > 0.f ? __logf(lbv + (1.f - lbv) * __expf(s1)) : s1; }
;                 *(f32x4*)(LF + (size_t)row * 512 + c) = a; *(f32x4*)(LF + (size_t)row * 512 + c + 4) = b; __builtin_amdgcn_sched_barrier(0); ) }
	v_add_f32_e32 v144, v148, v149
	v_fmamk_f32 v144, v144, 0x3a800000, v212
	v_rsq_f32_e32 v168, v144
	v_sub_f32_e32 v189, 1.0, v137
	v_cmp_lt_f32_e64 s[34:35], 0, v141
	v_cmp_lt_f32_e64 s[30:31], 0, v137
	v_pk_mul_f32 v[144:145], v[60:61], v[168:169] op_sel_hi:[1,0]
	v_pk_mul_f32 v[148:149], v[56:57], v[168:169] op_sel_hi:[1,0]
	v_min_f32_e32 v167, 0, v144
	v_mul_f32_e64 v144, |v144|, s57
	v_min_f32_e32 v177, 0, v148
	v_mul_f32_e64 v148, |v148|, s57
	v_exp_f32_e32 v144, v144
	v_exp_f32_e32 v148, v148
	v_min_f32_e32 v179, 0, v149
	v_mul_f32_e64 v149, |v149|, s57
	v_add_f32_e32 v144, 1.0, v144
	v_exp_f32_e32 v149, v149
	v_add_f32_e32 v148, 1.0, v148
	v_cmp_gt_f32_e64 s[8:9], s97, v144
	v_cmp_gt_f32_e64 s[10:11], s97, v148
	v_min_f32_e32 v178, 0, v145
	v_cndmask_b32_e64 v180, 0, 32, s[8:9]
	v_mul_f32_e64 v145, |v145|, s57
	v_cndmask_b32_e64 v181, 0, 32, s[10:11]
	v_ldexp_f32 v144, v144, v180
	v_exp_f32_e32 v145, v145
	v_ldexp_f32 v148, v148, v181
	v_log_f32_e32 v144, v144
	v_add_f32_e32 v149, 1.0, v149
	v_log_f32_e32 v148, v148
	v_cmp_gt_f32_e32 vcc, s97, v149
	v_add_f32_e32 v145, 1.0, v145
	v_cmp_gt_f32_e64 s[12:13], s97, v145
	v_cndmask_b32_e64 v183, 0, 32, vcc
	v_ldexp_f32 v149, v149, v183
	v_mul_f32_e32 v183, 0x3f317217, v144
	v_mul_f32_e32 v184, 0x3f317217, v148
	v_fma_f32 v183, v144, s52, -v183
	v_cndmask_b32_e64 v182, 0, 32, s[12:13]
	v_fma_f32 v184, v148, s52, -v184
	v_fmac_f32_e32 v183, 0x3377d1cf, v144
	v_cndmask_b32_e64 v180, 0, v216, s[8:9]
	v_ldexp_f32 v145, v145, v182
	v_fmac_f32_e32 v184, 0x3377d1cf, v148
	v_fmac_f32_e32 v183, 0x3f317217, v144
	v_cmp_lt_f32_e64 s[8:9], |v144|, s53
	v_log_f32_e32 v145, v145
	v_fmac_f32_e32 v184, 0x3f317217, v148
	v_cndmask_b32_e64 v144, v144, v183, s[8:9]
	v_cmp_lt_f32_e64 s[8:9], |v148|, s53
	v_cndmask_b32_e64 v181, 0, v216, s[10:11]
	v_log_f32_e32 v149, v149
	v_cndmask_b32_e64 v148, v148, v184, s[8:9]
	v_sub_f32_e32 v144, v144, v180
	v_sub_f32_e32 v148, v148, v181
	v_sub_f32_e32 v144, v167, v144
	v_sub_f32_e32 v167, v177, v148
	v_mul_f32_e32 v148, 0x3fb8aa3b, v144
	v_mul_f32_e32 v185, 0x3f317217, v145
	v_mul_f32_e32 v177, 0x3fb8aa3b, v167
	v_exp_f32_e32 v148, v148
	v_mul_f32_e32 v186, 0x3f317217, v149
	v_fma_f32 v185, v145, s52, -v185
	v_exp_f32_e32 v177, v177
	v_fma_f32 v186, v149, s52, -v186
	v_fmac_f32_e32 v185, 0x3377d1cf, v145
	v_fmac_f32_e32 v186, 0x3377d1cf, v149
	v_fmac_f32_e32 v185, 0x3f317217, v145
	v_cmp_lt_f32_e64 s[8:9], |v145|, s53
	v_fmac_f32_e32 v186, 0x3f317217, v149
	v_fma_f32 v148, v190, v148, v140
	v_cndmask_b32_e64 v145, v145, v185, s[8:9]
	v_cmp_lt_f32_e64 s[8:9], |v149|, s53
	v_fma_f32 v177, v191, v177, v136
	v_cmp_gt_f32_e64 s[10:11], s97, v177
	v_cndmask_b32_e64 v149, v149, v186, s[8:9]
	v_cmp_gt_f32_e64 s[8:9], s97, v148
	v_cndmask_b32_e64 v181, 0, 32, s[10:11]
	v_ldexp_f32 v177, v177, v181
	v_cndmask_b32_e64 v180, 0, 32, s[8:9]
	v_ldexp_f32 v148, v148, v180
	v_log_f32_e32 v148, v148
	v_cndmask_b32_e64 v182, 0, v216, s[12:13]
	v_log_f32_e32 v177, v177
	v_sub_f32_e32 v145, v145, v182
	v_sub_f32_e32 v145, v178, v145
	v_mul_f32_e32 v178, 0x3fb8aa3b, v145
	v_mul_f32_e32 v182, 0x3f317217, v148
	v_exp_f32_e32 v178, v178
	v_mul_f32_e32 v183, 0x3f317217, v177
	v_fma_f32 v182, v148, s52, -v182
	v_fma_f32 v183, v177, s52, -v183
	v_fmac_f32_e32 v182, 0x3377d1cf, v148
	v_cndmask_b32_e64 v180, 0, v216, s[8:9]
	v_fmac_f32_e32 v183, 0x3377d1cf, v177
	v_fmac_f32_e32 v182, 0x3f317217, v148
	v_cmp_lt_f32_e64 s[8:9], |v148|, s53
	v_fmac_f32_e32 v183, 0x3f317217, v177
	v_fma_f32 v178, v188, v178, v141
	v_cndmask_b32_e64 v148, v148, v182, s[8:9]
	v_cmp_lt_f32_e64 s[8:9], |v177|, s53
	v_cndmask_b32_e64 v181, 0, v216, s[10:11]
	v_sub_f32_e32 v148, v148, v180
	v_cndmask_b32_e64 v177, v177, v183, s[8:9]
	v_sub_f32_e32 v177, v177, v181
	v_cmp_gt_f32_e64 s[8:9], s97, v178
	v_cndmask_b32_e64 v148, v144, v148, s[38:39]
	v_cndmask_b32_e64 v144, v167, v177, s[36:37]
	v_cndmask_b32_e64 v167, 0, 32, s[8:9]
	v_ldexp_f32 v167, v178, v167
	v_cndmask_b32_e32 v177, 0, v216, vcc
	v_log_f32_e32 v167, v167
	v_sub_f32_e32 v149, v149, v177
	v_sub_f32_e32 v177, v179, v149
	v_mul_f32_e32 v178, 0x3fb8aa3b, v177
	v_exp_f32_e32 v178, v178
	v_mul_f32_e32 v149, 0x3f317217, v167
	v_fma_f32 v149, v167, s52, -v149
	v_fmac_f32_e32 v149, 0x3377d1cf, v167
	v_fmac_f32_e32 v149, 0x3f317217, v167
	v_cmp_lt_f32_e64 vcc, |v167|, s53
	v_fma_f32 v178, v189, v178, v137
	v_pk_mul_f32 v[150:151], v[62:63], v[168:169] op_sel_hi:[1,0]
	v_cndmask_b32_e32 v149, v167, v149, vcc
	v_cmp_gt_f32_e32 vcc, s97, v178
	v_cndmask_b32_e64 v167, 0, v216, s[8:9]
	v_sub_f32_e32 v149, v149, v167
	v_cndmask_b32_e64 v179, 0, 32, vcc
	v_ldexp_f32 v178, v178, v179
	v_log_f32_e32 v178, v178
	v_mul_f32_e64 v167, |v150|, s57
	v_exp_f32_e32 v167, v167
	v_cndmask_b32_e64 v149, v145, v149, s[34:35]
	v_mul_f32_e32 v145, 0x3f317217, v178
	v_fma_f32 v145, v178, s52, -v145
	v_fmac_f32_e32 v145, 0x3377d1cf, v178
	v_fmac_f32_e32 v145, 0x3f317217, v178
	v_cmp_lt_f32_e64 s[8:9], |v178|, s53
	v_add_f32_e32 v167, 1.0, v167
	v_pk_mul_f32 v[146:147], v[58:59], v[168:169] op_sel_hi:[1,0]
	v_cndmask_b32_e64 v145, v178, v145, s[8:9]
	v_cndmask_b32_e32 v178, 0, v216, vcc
	v_cmp_gt_f32_e32 vcc, s97, v167
	v_sub_f32_e32 v145, v145, v178
	v_cndmask_b32_e64 v145, v177, v145, s[30:31]
	v_cndmask_b32_e64 v178, 0, 32, vcc
	v_ldexp_f32 v167, v167, v178
	v_log_f32_e32 v167, v167
	v_mul_f32_e64 v178, |v146|, s57
	v_exp_f32_e32 v178, v178
	v_min_f32_e32 v150, 0, v150
	v_mul_f32_e32 v177, 0x3f317217, v167
	v_fma_f32 v177, v167, s52, -v177
	v_fmac_f32_e32 v177, 0x3377d1cf, v167
	v_fmac_f32_e32 v177, 0x3f317217, v167
	v_cmp_lt_f32_e64 s[8:9], |v167|, s53
	v_add_f32_e32 v178, 1.0, v178
;     __device__ __forceinline__ void operator()(const f32x4 (&acc)[2][2][4][2], const pg8::Unit& u, int wr, int wc, int fr, int fq) const {
;     ...
;         else if (grp == 1) {
;             f32x4 l0[2], l1[2];
; #pragma unroll
;             for (int bj = 0; bj < 2; ++bj) { l0[bj] = *(const f32x4*)(lb + cb + bj * 128); l1[bj] = *(const f32x4*)(lb + cb + bj * 128 + 4); }
;             WIN_LOOP( _Pragma("unroll") for (int i = 0; i < 4; ++i) { const float s0 = fminf(a[i], 0.f) - __logf(1.f + __expf(-fabsf(a[i]))), s1 = fminf(b[i], 0.f) - __logf(1.f + __expf(-fabsf(b[i]))); const float la = l0[bj][i], lbv = l1[bj][i];
;                     a[i] = la > 0.f ? __logf(la + (1.f - la) * __expf(s0)) : s0; b[i] = lbv > 0.f ? __logf(lbv + (1.f - lbv) * __expf(s1)) : s1; }
;                 *(f32x4*)(LF + (size_t)row * 512 + c) = a; *(f32x4*)(LF + (size_t)row * 512 + c + 4) = b; __builtin_amdgcn_sched_barrier(0); ) }
	v_sub_f32_e32 v187, 1.0, v142
	v_cndmask_b32_e64 v167, v167, v177, s[8:9]
	v_cndmask_b32_e32 v177, 0, v216, vcc
	v_cmp_gt_f32_e32 vcc, s97, v178
	v_sub_f32_e32 v167, v167, v177
	v_sub_f32_e32 v150, v150, v167
	v_cndmask_b32_e64 v179, 0, 32, vcc
	v_ldexp_f32 v178, v178, v179
	v_log_f32_e32 v178, v178
	v_mul_f32_e32 v177, 0x3fb8aa3b, v150
	v_exp_f32_e32 v177, v177
	v_min_f32_e32 v146, 0, v146
	v_mul_f32_e32 v167, 0x3f317217, v178
	v_fma_f32 v167, v178, s52, -v167
	v_fmac_f32_e32 v167, 0x3377d1cf, v178
	v_fmac_f32_e32 v167, 0x3f317217, v178
	v_cmp_lt_f32_e64 s[8:9], |v178|, s53
	v_fma_f32 v177, v187, v177, v142
	v_sub_f32_e32 v186, 1.0, v138
	v_cndmask_b32_e64 v167, v178, v167, s[8:9]
	v_cmp_gt_f32_e64 s[8:9], s97, v177
	v_cmp_lt_f32_e64 s[28:29], 0, v142
	v_cmp_lt_f32_e64 s[26:27], 0, v138
	v_cndmask_b32_e64 v178, 0, 32, s[8:9]
	v_ldexp_f32 v177, v177, v178
	v_cndmask_b32_e32 v178, 0, v216, vcc
	v_log_f32_e32 v177, v177
	v_sub_f32_e32 v167, v167, v178
	v_sub_f32_e32 v146, v146, v167
	v_mul_f32_e32 v178, 0x3fb8aa3b, v146
	v_exp_f32_e32 v178, v178
	v_mul_f32_e32 v167, 0x3f317217, v177
	v_fma_f32 v167, v177, s52, -v167
	v_fmac_f32_e32 v167, 0x3377d1cf, v177
	v_fmac_f32_e32 v167, 0x3f317217, v177
	v_cmp_lt_f32_e64 vcc, |v177|, s53
	v_fma_f32 v178, v186, v178, v138
	v_sub_f32_e32 v185, 1.0, v143
	v_cndmask_b32_e32 v167, v177, v167, vcc
	v_cmp_gt_f32_e32 vcc, s97, v178
	v_cndmask_b32_e64 v177, 0, v216, s[8:9]
	v_sub_f32_e32 v167, v167, v177
	v_cndmask_b32_e64 v179, 0, 32, vcc
	v_ldexp_f32 v178, v178, v179
	v_log_f32_e32 v178, v178
	v_mul_f32_e64 v177, |v151|, s57
	v_exp_f32_e32 v177, v177
	v_cndmask_b32_e64 v150, v150, v167, s[28:29]
	v_mul_f32_e32 v167, 0x3f317217, v178
	v_fma_f32 v167, v178, s52, -v167
	v_fmac_f32_e32 v167, 0x3377d1cf, v178
	v_fmac_f32_e32 v167, 0x3f317217, v178
	v_cmp_lt_f32_e64 s[8:9], |v178|, s53
	v_add_f32_e32 v177, 1.0, v177
	v_min_f32_e32 v151, 0, v151
	v_cndmask_b32_e64 v167, v178, v167, s[8:9]
	v_cndmask_b32_e32 v178, 0, v216, vcc
	v_cmp_gt_f32_e32 vcc, s97, v177
	v_sub_f32_e32 v167, v167, v178
	v_cndmask_b32_e64 v146, v146, v167, s[26:27]
	v_cndmask_b32_e64 v178, 0, 32, vcc
	v_ldexp_f32 v177, v177, v178
	v_log_f32_e32 v177, v177
	v_mul_f32_e64 v178, |v147|, s57
	v_exp_f32_e32 v178, v178
	v_min_f32_e32 v147, 0, v147
	v_mul_f32_e32 v167, 0x3f317217, v177
	v_fma_f32 v167, v177, s52, -v167
	v_fmac_f32_e32 v167, 0x3377d1cf, v177
	v_fmac_f32_e32 v167, 0x3f317217, v177
	v_cmp_lt_f32_e64 s[8:9], |v177|, s53
	v_add_f32_e32 v178, 1.0, v178
	v_sub_f32_e32 v184, 1.0, v139
	v_cndmask_b32_e64 v167, v177, v167, s[8:9]
	v_cndmask_b32_e32 v177, 0, v216, vcc
	v_cmp_gt_f32_e32 vcc, s97, v178
	v_sub_f32_e32 v167, v167, v177
	v_sub_f32_e32 v151, v151, v167
	v_cndmask_b32_e64 v179, 0, 32, vcc
	v_ldexp_f32 v178, v178, v179
	v_log_f32_e32 v178, v178
	v_mul_f32_e32 v177, 0x3fb8aa3b, v151
	v_exp_f32_e32 v177, v177
	v_cmp_lt_f32_e64 s[24:25], 0, v143
	v_mul_f32_e32 v167, 0x3f317217, v178
	v_fma_f32 v167, v178, s52, -v167
	v_fmac_f32_e32 v167, 0x3377d1cf, v178
	v_fmac_f32_e32 v167, 0x3f317217, v178
	v_cmp_lt_f32_e64 s[8:9], |v178|, s53
	v_fma_f32 v177, v185, v177, v143
	v_cmp_lt_f32_e64 s[22:23], 0, v139
	v_cndmask_b32_e64 v167, v178, v167, s[8:9]
	v_cmp_gt_f32_e64 s[8:9], s97, v177
	s_nop 1
	v_cndmask_b32_e64 v178, 0, 32, s[8:9]
	v_ldexp_f32 v177, v177, v178
	v_cndmask_b32_e32 v178, 0, v216, vcc
	v_log_f32_e32 v177, v177
	v_sub_f32_e32 v167, v167, v178
	v_sub_f32_e32 v147, v147, v167
	v_mul_f32_e32 v178, 0x3fb8aa3b, v147
	v_exp_f32_e32 v178, v178
	v_mul_f32_e32 v167, 0x3f317217, v177
	v_fma_f32 v167, v177, s52, -v167
	v_fmac_f32_e32 v167, 0x3377d1cf, v177
	v_fmac_f32_e32 v167, 0x3f317217, v177
	v_cmp_lt_f32_e64 vcc, |v177|, s53
	v_fma_f32 v178, v184, v178, v139
	s_nop 0
	v_cndmask_b32_e32 v167, v177, v167, vcc
	v_cmp_gt_f32_e32 vcc, s97, v178
	v_cndmask_b32_e64 v177, 0, v216, s[8:9]
	v_sub_f32_e32 v167, v167, v177
	v_cndmask_b32_e64 v179, 0, 32, vcc
	v_ldexp_f32 v178, v178, v179
	v_log_f32_e32 v178, v178
	v_cndmask_b32_e64 v151, v151, v167, s[24:25]
	v_cndmask_b32_e32 v177, 0, v216, vcc
	v_mul_f32_e32 v167, 0x3f317217, v178
	v_fma_f32 v167, v178, s52, -v167
	v_fmac_f32_e32 v167, 0x3377d1cf, v178
	v_fmac_f32_e32 v167, 0x3f317217, v178
	v_cmp_lt_f32_e64 s[8:9], |v178|, s53
	s_nop 1
	v_cndmask_b32_e64 v167, v178, v167, s[8:9]
	v_sub_f32_e32 v167, v167, v177
	v_cndmask_b32_e64 v147, v147, v167, s[22:23]
	flat_store_dwordx4 v[170:171], v[148:151] sc1
	flat_store_dwordx4 v[170:171], v[144:147] offset:16 sc1
	s_nop 1
	v_pk_mul_f32 v[144:145], v[124:125], v[168:169] op_sel_hi:[1,0]
	v_pk_mul_f32 v[150:151], v[126:127], v[168:169] op_sel_hi:[1,0]
	v_mul_f32_e64 v146, |v144|, s57
	v_exp_f32_e32 v148, v146
	v_pk_mul_f32 v[146:147], v[122:123], v[168:169] op_sel_hi:[1,0]
	v_min_f32_e32 v144, 0, v144
	s_waitcnt vmcnt(0)
;     __device__ __forceinline__ void operator()(const f32x4 (&acc)[2][2][4][2], const pg8::Unit& u, int wr, int wc, int fr, int fq) const {
;     ...
;             WIN_LOOP( _Pragma("unroll") for (int i = 0; i < 4; ++i) { const float s0 = fminf(a[i], 0.f) - __logf(1.f + __expf(-fabsf(a[i]))), s1 = fminf(b[i], 0.f) - __logf(1.f + __expf(-fabsf(b[i]))); const float la = l0[bj][i], lbv = l1[bj][i];
;                     a[i] = la > 0.f ? __logf(la + (1.f - la) * __expf(s0)) : s0; b[i] = lbv > 0.f ? __logf(lbv + (1.f - lbv) * __expf(s1)) : s1; }
	v_sub_f32_e32 v183, 1.0, v132
	v_add_f32_e32 v148, 1.0, v148
	v_cmp_gt_f32_e32 vcc, s97, v148
	v_sub_f32_e32 v182, 1.0, v128
	v_cmp_lt_f32_e64 s[20:21], 0, v132
	v_cndmask_b32_e64 v149, 0, 32, vcc
	v_ldexp_f32 v148, v148, v149
	v_log_f32_e32 v167, v148
	v_pk_mul_f32 v[148:149], v[120:121], v[168:169] op_sel_hi:[1,0]
	v_cmp_lt_f32_e64 s[18:19], 0, v128
	v_mul_f32_e64 v168, |v148|, s57
	v_exp_f32_e32 v168, v168
	v_mul_f32_e32 v177, 0x3f317217, v167
	v_fma_f32 v177, v167, s52, -v177
	v_fmac_f32_e32 v177, 0x3377d1cf, v167
	v_fmac_f32_e32 v177, 0x3f317217, v167
	v_cmp_lt_f32_e64 s[8:9], |v167|, s53
	v_add_f32_e32 v168, 1.0, v168
	v_min_f32_e32 v148, 0, v148
	v_cndmask_b32_e64 v167, v167, v177, s[8:9]
	v_cndmask_b32_e32 v177, 0, v216, vcc
	v_cmp_gt_f32_e32 vcc, s97, v168
	v_sub_f32_e32 v167, v167, v177
	v_sub_f32_e32 v144, v144, v167
	v_cndmask_b32_e64 v178, 0, 32, vcc
	v_ldexp_f32 v168, v168, v178
	v_log_f32_e32 v168, v168
	v_mul_f32_e32 v177, 0x3fb8aa3b, v144
	v_exp_f32_e32 v177, v177
	v_sub_f32_e32 v181, 1.0, v133
	v_mul_f32_e32 v167, 0x3f317217, v168
	v_fma_f32 v167, v168, s52, -v167
	v_fmac_f32_e32 v167, 0x3377d1cf, v168
	v_fmac_f32_e32 v167, 0x3f317217, v168
	v_cmp_lt_f32_e64 s[8:9], |v168|, s53
	v_sub_f32_e32 v180, 1.0, v129
	v_cmp_lt_f32_e64 s[16:17], 0, v133
	v_cndmask_b32_e64 v167, v168, v167, s[8:9]
	v_fma_f32 v168, v183, v177, v132
	v_cmp_gt_f32_e64 s[8:9], s97, v168
	v_cmp_lt_f32_e64 s[14:15], 0, v129
	v_sub_f32_e32 v179, 1.0, v134
	v_cndmask_b32_e64 v177, 0, 32, s[8:9]
	v_ldexp_f32 v168, v168, v177
	v_cndmask_b32_e32 v177, 0, v216, vcc
	v_log_f32_e32 v168, v168
	v_sub_f32_e32 v167, v167, v177
	v_sub_f32_e32 v148, v148, v167
	v_mul_f32_e32 v177, 0x3fb8aa3b, v148
	v_exp_f32_e32 v177, v177
	v_mul_f32_e32 v167, 0x3f317217, v168
	v_fma_f32 v167, v168, s52, -v167
	v_fmac_f32_e32 v167, 0x3377d1cf, v168
	v_fmac_f32_e32 v167, 0x3f317217, v168
	v_cmp_lt_f32_e64 vcc, |v168|, s53
	v_fma_f32 v177, v182, v177, v128
	v_cmp_lt_f32_e64 s[12:13], 0, v134
	v_cndmask_b32_e32 v167, v168, v167, vcc
	v_cmp_gt_f32_e32 vcc, s97, v177
	v_cndmask_b32_e64 v168, 0, v216, s[8:9]
	v_sub_f32_e32 v167, v167, v168
	v_cndmask_b32_e64 v178, 0, 32, vcc
	v_ldexp_f32 v177, v177, v178
	v_log_f32_e32 v177, v177
	v_mul_f32_e64 v168, |v145|, s57
	v_exp_f32_e32 v168, v168
	v_cndmask_b32_e64 v144, v144, v167, s[20:21]
	v_mul_f32_e32 v167, 0x3f317217, v177
	v_fma_f32 v167, v177, s52, -v167
	v_fmac_f32_e32 v167, 0x3377d1cf, v177
	v_fmac_f32_e32 v167, 0x3f317217, v177
	v_cmp_lt_f32_e64 s[8:9], |v177|, s53
	v_add_f32_e32 v168, 1.0, v168
	v_min_f32_e32 v145, 0, v145
	v_cndmask_b32_e64 v167, v177, v167, s[8:9]
	v_cndmask_b32_e32 v177, 0, v216, vcc
	v_cmp_gt_f32_e32 vcc, s97, v168
	v_sub_f32_e32 v167, v167, v177
	v_cndmask_b32_e64 v148, v148, v167, s[18:19]
	v_cndmask_b32_e64 v177, 0, 32, vcc
	v_ldexp_f32 v168, v168, v177
	v_log_f32_e32 v168, v168
	v_mul_f32_e64 v177, |v149|, s57
	v_exp_f32_e32 v177, v177
	v_min_f32_e32 v149, 0, v149
	v_mul_f32_e32 v167, 0x3f317217, v168
	v_fma_f32 v167, v168, s52, -v167
	v_fmac_f32_e32 v167, 0x3377d1cf, v168
	v_fmac_f32_e32 v167, 0x3f317217, v168
	v_cmp_lt_f32_e64 s[8:9], |v168|, s53
	v_add_f32_e32 v177, 1.0, v177
	v_cmp_lt_f32_e64 s[10:11], 0, v130
	v_cndmask_b32_e64 v167, v168, v167, s[8:9]
	v_cndmask_b32_e32 v168, 0, v216, vcc
	v_cmp_gt_f32_e32 vcc, s97, v177
	v_sub_f32_e32 v167, v167, v168
	v_sub_f32_e32 v145, v145, v167
	v_cndmask_b32_e64 v178, 0, 32, vcc
	v_ldexp_f32 v177, v177, v178
	v_log_f32_e32 v177, v177
	v_mul_f32_e32 v168, 0x3fb8aa3b, v145
	v_exp_f32_e32 v168, v168
	s_mov_b32 s2, s40
	v_mul_f32_e32 v167, 0x3f317217, v177
	v_fma_f32 v167, v177, s52, -v167
	v_fmac_f32_e32 v167, 0x3377d1cf, v177
	v_fmac_f32_e32 v167, 0x3f317217, v177
	v_cmp_lt_f32_e64 s[8:9], |v177|, s53
	v_fma_f32 v168, v181, v168, v133
	s_nop 0
	v_cndmask_b32_e64 v167, v177, v167, s[8:9]
	v_cmp_gt_f32_e64 s[8:9], s97, v168
	s_nop 1
	v_cndmask_b32_e64 v177, 0, 32, s[8:9]
	v_ldexp_f32 v168, v168, v177
	v_cndmask_b32_e32 v177, 0, v216, vcc
	v_log_f32_e32 v168, v168
	v_sub_f32_e32 v167, v167, v177
	v_sub_f32_e32 v149, v149, v167
	v_mul_f32_e32 v177, 0x3fb8aa3b, v149
	v_exp_f32_e32 v177, v177
	v_mul_f32_e32 v167, 0x3f317217, v168
	v_fma_f32 v167, v168, s52, -v167
	v_fmac_f32_e32 v167, 0x3377d1cf, v168
	v_fmac_f32_e32 v167, 0x3f317217, v168
	v_cmp_lt_f32_e64 vcc, |v168|, s53
	v_fma_f32 v177, v180, v177, v129
	s_nop 0
	v_cndmask_b32_e32 v167, v168, v167, vcc
	v_cmp_gt_f32_e32 vcc, s97, v177
	v_cndmask_b32_e64 v168, 0, v216, s[8:9]
	v_sub_f32_e32 v167, v167, v168
	v_cndmask_b32_e64 v178, 0, 32, vcc
	v_ldexp_f32 v177, v177, v178
	v_log_f32_e32 v177, v177
	v_mul_f32_e64 v168, |v150|, s57
	v_exp_f32_e32 v168, v168
	v_cndmask_b32_e64 v145, v145, v167, s[16:17]
	v_mul_f32_e32 v167, 0x3f317217, v177
	v_fma_f32 v167, v177, s52, -v167
	v_fmac_f32_e32 v167, 0x3377d1cf, v177
	v_fmac_f32_e32 v167, 0x3f317217, v177
	v_cmp_lt_f32_e64 s[8:9], |v177|, s53
	v_add_f32_e32 v168, 1.0, v168
	v_min_f32_e32 v150, 0, v150
	v_cndmask_b32_e64 v167, v177, v167, s[8:9]
	v_cndmask_b32_e32 v177, 0, v216, vcc
	v_cmp_gt_f32_e32 vcc, s97, v168
	v_sub_f32_e32 v167, v167, v177
	v_cndmask_b32_e64 v149, v149, v167, s[14:15]
	v_cndmask_b32_e64 v177, 0, 32, vcc
	v_ldexp_f32 v168, v168, v177
	v_log_f32_e32 v168, v168
	v_mul_f32_e64 v177, |v146|, s57
	v_exp_f32_e32 v177, v177
	v_min_f32_e32 v146, 0, v146
	v_mul_f32_e32 v167, 0x3f317217, v168
	v_fma_f32 v167, v168, s52, -v167
	v_fmac_f32_e32 v167, 0x3377d1cf, v168
	v_fmac_f32_e32 v167, 0x3f317217, v168
	v_cmp_lt_f32_e64 s[8:9], |v168|, s53
	v_add_f32_e32 v177, 1.0, v177
	s_nop 0
	v_cndmask_b32_e64 v167, v168, v167, s[8:9]
	v_cndmask_b32_e32 v168, 0, v216, vcc
; __device__ __forceinline__ float row_rstd(const float* ssq, int row, int fq) {
;     const f32x4 v = *(const f32x4*)(ssq + (size_t)row * 16 + fq * 4);
;     float s = (v[0] + v[1]) + (v[2] + v[3]);
;     s += __shfl_xor(s, 16); s += __shfl_xor(s, 32);
;     return __builtin_amdgcn_rsqf(s * (1.f / DM) + EPS);
; }
;     __device__ __forceinline__ void operator()(const f32x4 (&acc)[2][2][4][2], const pg8::Unit& u, int wr, int wc, int fr, int fq) const {
;     ...
;             WIN_LOOP( _Pragma("unroll") for (int i = 0; i < 4; ++i) { const float s0 = fminf(a[i], 0.f) - __logf(1.f + __expf(-fabsf(a[i]))), s1 = fminf(b[i], 0.f) - __logf(1.f + __expf(-fabsf(b[i]))); const float la = l0[bj][i], lbv = l1[bj][i];
;                     a[i] = la > 0.f ? __logf(la + (1.f - la) * __expf(s0)) : s0; b[i] = lbv > 0.f ? __logf(lbv + (1.f - lbv) * __expf(s1)) : s1; }
;                 *(f32x4*)(LF + (size_t)row * 512 + c) = a; *(f32x4*)(LF + (size_t)row * 512 + c + 4) = b; __builtin_amdgcn_sched_barrier(0); ) }
	v_cmp_gt_f32_e32 vcc, s97, v177
	v_sub_f32_e32 v167, v167, v168
	v_sub_f32_e32 v150, v150, v167
	v_cndmask_b32_e64 v178, 0, 32, vcc
	v_ldexp_f32 v177, v177, v178
	v_log_f32_e32 v177, v177
	v_mul_f32_e32 v168, 0x3fb8aa3b, v150
	v_exp_f32_e32 v168, v168
	v_sub_f32_e32 v178, 1.0, v130
	v_mul_f32_e32 v167, 0x3f317217, v177
	v_fma_f32 v167, v177, s52, -v167
	v_fmac_f32_e32 v167, 0x3377d1cf, v177
	v_fmac_f32_e32 v167, 0x3f317217, v177
	v_cmp_lt_f32_e64 s[8:9], |v177|, s53
	v_fma_f32 v168, v179, v168, v134
	s_nop 0
	v_cndmask_b32_e64 v167, v177, v167, s[8:9]
	v_cmp_gt_f32_e64 s[8:9], s97, v168
	s_nop 1
	v_cndmask_b32_e64 v177, 0, 32, s[8:9]
	v_ldexp_f32 v168, v168, v177
	v_cndmask_b32_e32 v177, 0, v216, vcc
	v_log_f32_e32 v168, v168
	v_sub_f32_e32 v167, v167, v177
	v_sub_f32_e32 v167, v146, v167
	v_mul_f32_e32 v177, 0x3fb8aa3b, v167
	v_exp_f32_e32 v177, v177
	v_mul_f32_e32 v146, 0x3f317217, v168
	v_fma_f32 v146, v168, s52, -v146
	v_fmac_f32_e32 v146, 0x3377d1cf, v168
	v_fmac_f32_e32 v146, 0x3f317217, v168
	v_cmp_lt_f32_e64 vcc, |v168|, s53
	v_fma_f32 v177, v178, v177, v130
	s_nop 0
	v_cndmask_b32_e32 v146, v168, v146, vcc
	v_cmp_gt_f32_e32 vcc, s97, v177
	v_cndmask_b32_e64 v168, 0, v216, s[8:9]
	v_sub_f32_e32 v146, v146, v168
	v_cndmask_b32_e64 v194, 0, 32, vcc
	v_ldexp_f32 v177, v177, v194
	v_log_f32_e32 v177, v177
	v_mul_f32_e64 v168, |v151|, s57
	v_exp_f32_e32 v168, v168
	v_cndmask_b32_e64 v146, v150, v146, s[12:13]
	v_mul_f32_e32 v150, 0x3f317217, v177
	v_fma_f32 v150, v177, s52, -v150
	v_fmac_f32_e32 v150, 0x3377d1cf, v177
	v_fmac_f32_e32 v150, 0x3f317217, v177
	v_cmp_lt_f32_e64 s[8:9], |v177|, s53
	v_add_f32_e32 v168, 1.0, v168
	v_min_f32_e32 v151, 0, v151
	v_cndmask_b32_e64 v150, v177, v150, s[8:9]
	v_cndmask_b32_e32 v177, 0, v216, vcc
	v_cmp_gt_f32_e32 vcc, s97, v168
	v_sub_f32_e32 v150, v150, v177
	v_cndmask_b32_e64 v150, v167, v150, s[10:11]
	v_cndmask_b32_e64 v177, 0, 32, vcc
	v_ldexp_f32 v168, v168, v177
	v_log_f32_e32 v168, v168
	v_mul_f32_e64 v177, |v147|, s57
	v_exp_f32_e32 v177, v177
	v_min_f32_e32 v147, 0, v147
	v_mul_f32_e32 v167, 0x3f317217, v168
	v_fma_f32 v167, v168, s52, -v167
	v_fmac_f32_e32 v167, 0x3377d1cf, v168
	v_fmac_f32_e32 v167, 0x3f317217, v168
	v_cmp_lt_f32_e64 s[8:9], |v168|, s53
	v_add_f32_e32 v177, 1.0, v177
	s_nop 0
	v_cndmask_b32_e64 v167, v168, v167, s[8:9]
	v_cndmask_b32_e32 v168, 0, v216, vcc
	v_cmp_gt_f32_e32 vcc, s97, v177
	v_sub_f32_e32 v167, v167, v168
	v_sub_f32_e32 v151, v151, v167
	v_cndmask_b32_e64 v194, 0, 32, vcc
	v_ldexp_f32 v177, v177, v194
	v_log_f32_e32 v177, v177
	v_mul_f32_e32 v168, 0x3fb8aa3b, v151
	v_exp_f32_e32 v168, v168
	v_mul_f32_e32 v167, 0x3f317217, v177
	v_fma_f32 v167, v177, s52, -v167
	v_fmac_f32_e32 v167, 0x3377d1cf, v177
	v_fmac_f32_e32 v167, 0x3f317217, v177
	v_cmp_lt_f32_e64 s[8:9], |v177|, s53
	s_nop 1
	v_cndmask_b32_e64 v167, v177, v167, s[8:9]
	v_sub_f32_e32 v177, 1.0, v135
	v_fma_f32 v168, v177, v168, v135
	v_cmp_gt_f32_e64 s[8:9], s97, v168
	s_nop 1
	v_cndmask_b32_e64 v194, 0, 32, s[8:9]
	v_ldexp_f32 v168, v168, v194
	v_cndmask_b32_e32 v194, 0, v216, vcc
	v_log_f32_e32 v168, v168
	v_sub_f32_e32 v167, v167, v194
	v_sub_f32_e32 v194, v147, v167
	v_mul_f32_e32 v167, 0x3fb8aa3b, v194
	v_exp_f32_e32 v195, v167
	v_mul_f32_e32 v147, 0x3f317217, v168
	v_fma_f32 v147, v168, s52, -v147
	v_fmac_f32_e32 v147, 0x3377d1cf, v168
	v_sub_f32_e32 v167, 1.0, v131
	v_fmac_f32_e32 v147, 0x3f317217, v168
	v_cmp_lt_f32_e64 vcc, |v168|, s53
	v_fma_f32 v195, v167, v195, v131
	s_nop 0
	v_cndmask_b32_e32 v147, v168, v147, vcc
	v_cmp_gt_f32_e32 vcc, s97, v195
	v_cndmask_b32_e64 v168, 0, v216, s[8:9]
	v_sub_f32_e32 v147, v147, v168
	v_cndmask_b32_e64 v204, 0, 32, vcc
	v_ldexp_f32 v195, v195, v204
	v_log_f32_e32 v195, v195
	v_cmp_lt_f32_e64 s[8:9], 0, v135
	v_cndmask_b32_e32 v168, 0, v216, vcc
	v_cmp_lt_f32_e32 vcc, 0, v131
	v_cndmask_b32_e64 v147, v151, v147, s[8:9]
	v_mul_f32_e32 v151, 0x3f317217, v195
	v_fma_f32 v151, v195, s52, -v151
	v_fmac_f32_e32 v151, 0x3377d1cf, v195
	v_fmac_f32_e32 v151, 0x3f317217, v195
	v_cmp_lt_f32_e64 s[40:41], |v195|, s53
	s_nop 1
	v_cndmask_b32_e64 v151, v195, v151, s[40:41]
	v_sub_f32_e32 v151, v151, v168
	v_cndmask_b32_e32 v151, v194, v151, vcc
	flat_store_dwordx4 v[170:171], v[144:147] offset:512 sc1
	flat_store_dwordx4 v[170:171], v[148:151] offset:528 sc1
	s_nop 1
	v_or_b32_e32 v148, 16, v166
	v_ashrrev_i32_e32 v149, 31, v148
	v_lshlrev_b64 v[144:145], 6, v[148:149]
	v_lshl_add_u64 v[144:145], v[160:161], 0, v[144:145]
	flat_load_dwordx4 v[144:147], v[144:145]
	s_waitcnt vmcnt(0) lgkmcnt(0)
	v_mov_b32_e32 v150, v145
	v_mov_b32_e32 v151, v146
	v_mov_b32_e32 v145, v147
	v_pk_add_f32 v[144:145], v[150:151], v[144:145]
	s_nop 0
	v_add_f32_e32 v144, v144, v145
	ds_bpermute_b32 v145, v169, v144
	s_waitcnt lgkmcnt(0)
	v_add_f32_e32 v144, v144, v145
	ds_bpermute_b32 v145, v202, v144
	s_waitcnt lgkmcnt(0)
; __device__ __forceinline__ float row_rstd(const float* ssq, int row, int fq) {
;     const f32x4 v = *(const f32x4*)(ssq + (size_t)row * 16 + fq * 4);
;     float s = (v[0] + v[1]) + (v[2] + v[3]);
;     s += __shfl_xor(s, 16); s += __shfl_xor(s, 32);
;     return __builtin_amdgcn_rsqf(s * (1.f / DM) + EPS);
; }
;     __device__ __forceinline__ void operator()(const f32x4 (&acc)[2][2][4][2], const pg8::Unit& u, int wr, int wc, int fr, int fq) const {
;     ...
;             WIN_LOOP( _Pragma("unroll") for (int i = 0; i < 4; ++i) { const float s0 = fminf(a[i], 0.f) - __logf(1.f + __expf(-fabsf(a[i]))), s1 = fminf(b[i], 0.f) - __logf(1.f + __expf(-fabsf(b[i]))); const float la = l0[bj][i], lbv = l1[bj][i];
;                     a[i] = la > 0.f ? __logf(la + (1.f - la) * __expf(s0)) : s0; b[i] = lbv > 0.f ? __logf(lbv + (1.f - lbv) * __expf(s1)) : s1; }
	v_add_f32_e32 v144, v144, v145
	v_fmamk_f32 v144, v144, 0x3a800000, v212
	v_rsq_f32_e32 v168, v144
	v_lshlrev_b64 v[144:145], 11, v[148:149]
	v_lshl_add_u64 v[170:171], s[50:51], 0, v[144:145]
	v_lshl_add_u64 v[170:171], v[170:171], 0, v[192:193]
	v_pk_mul_f32 v[148:149], v[52:53], v[168:169] op_sel_hi:[1,0]
	v_pk_mul_f32 v[144:145], v[48:49], v[168:169] op_sel_hi:[1,0]
	v_min_f32_e32 v194, 0, v148
	v_mul_f32_e64 v148, |v148|, s57
	v_exp_f32_e32 v148, v148
	v_pk_mul_f32 v[150:151], v[54:55], v[168:169] op_sel_hi:[1,0]
	v_pk_mul_f32 v[146:147], v[50:51], v[168:169] op_sel_hi:[1,0]
	v_add_f32_e32 v148, 1.0, v148
	v_cmp_gt_f32_e64 s[40:41], s97, v148
	s_nop 1
	v_cndmask_b32_e64 v195, 0, 32, s[40:41]
	v_ldexp_f32 v148, v148, v195
	v_log_f32_e32 v148, v148
	s_nop 0
	v_mul_f32_e32 v195, 0x3f317217, v148
	v_fma_f32 v195, v148, s52, -v195
	v_fmac_f32_e32 v195, 0x3377d1cf, v148
	v_fmac_f32_e32 v195, 0x3f317217, v148
	v_cmp_lt_f32_e64 s[42:43], |v148|, s53
	s_nop 1
	v_cndmask_b32_e64 v148, v148, v195, s[42:43]
	v_cndmask_b32_e64 v195, 0, v216, s[40:41]
	v_sub_f32_e32 v148, v148, v195
	v_sub_f32_e32 v148, v194, v148
	v_min_f32_e32 v194, 0, v144
	v_mul_f32_e64 v144, |v144|, s57
	v_exp_f32_e32 v144, v144
	s_nop 0
	v_add_f32_e32 v144, 1.0, v144
	v_cmp_gt_f32_e64 s[40:41], s97, v144
	s_nop 1
	v_cndmask_b32_e64 v195, 0, 32, s[40:41]
	v_ldexp_f32 v144, v144, v195
	v_log_f32_e32 v144, v144
	s_nop 0
	v_mul_f32_e32 v195, 0x3f317217, v144
	v_fma_f32 v195, v144, s52, -v195
	v_fmac_f32_e32 v195, 0x3377d1cf, v144
	v_fmac_f32_e32 v195, 0x3f317217, v144
	v_cmp_lt_f32_e64 s[42:43], |v144|, s53
	s_nop 1
	v_cndmask_b32_e64 v144, v144, v195, s[42:43]
	v_cndmask_b32_e64 v195, 0, v216, s[40:41]
	v_sub_f32_e32 v144, v144, v195
	v_sub_f32_e32 v194, v194, v144
	v_mul_f32_e32 v144, 0x3fb8aa3b, v148
	v_exp_f32_e32 v144, v144
	s_nop 0
	v_fma_f32 v144, v190, v144, v140
	v_cmp_gt_f32_e64 s[40:41], s97, v144
	s_nop 1
	v_cndmask_b32_e64 v195, 0, 32, s[40:41]
	v_ldexp_f32 v144, v144, v195
	v_log_f32_e32 v144, v144
	s_nop 0
	v_mul_f32_e32 v195, 0x3f317217, v144
	v_fma_f32 v195, v144, s52, -v195
	v_fmac_f32_e32 v195, 0x3377d1cf, v144
	v_fmac_f32_e32 v195, 0x3f317217, v144
	v_cmp_lt_f32_e64 s[42:43], |v144|, s53
	s_nop 1
	v_cndmask_b32_e64 v144, v144, v195, s[42:43]
	v_cndmask_b32_e64 v195, 0, v216, s[40:41]
	v_sub_f32_e32 v144, v144, v195
	v_cndmask_b32_e64 v144, v148, v144, s[38:39]
	v_mul_f32_e32 v148, 0x3fb8aa3b, v194
	v_exp_f32_e32 v148, v148
	s_nop 0
	v_fma_f32 v148, v191, v148, v136
	v_cmp_gt_f32_e64 s[40:41], s97, v148
	s_nop 1
	v_cndmask_b32_e64 v195, 0, 32, s[40:41]
	v_ldexp_f32 v148, v148, v195
	v_log_f32_e32 v148, v148
	s_nop 0
	v_mul_f32_e32 v195, 0x3f317217, v148
	v_fma_f32 v195, v148, s52, -v195
	v_fmac_f32_e32 v195, 0x3377d1cf, v148
	v_fmac_f32_e32 v195, 0x3f317217, v148
	v_cmp_lt_f32_e64 s[42:43], |v148|, s53
	s_nop 1
	v_cndmask_b32_e64 v148, v148, v195, s[42:43]
	v_cndmask_b32_e64 v195, 0, v216, s[40:41]
	v_sub_f32_e32 v148, v148, v195
	v_cndmask_b32_e64 v148, v194, v148, s[36:37]
	v_min_f32_e32 v194, 0, v149
	v_mul_f32_e64 v149, |v149|, s57
	v_exp_f32_e32 v149, v149
	s_nop 0
	v_add_f32_e32 v149, 1.0, v149
	v_cmp_gt_f32_e64 s[40:41], s97, v149
	s_nop 1
	v_cndmask_b32_e64 v195, 0, 32, s[40:41]
	v_ldexp_f32 v149, v149, v195
	v_log_f32_e32 v149, v149
	s_nop 0
	v_mul_f32_e32 v195, 0x3f317217, v149
	v_fma_f32 v195, v149, s52, -v195
	v_fmac_f32_e32 v195, 0x3377d1cf, v149
	v_fmac_f32_e32 v195, 0x3f317217, v149
	v_cmp_lt_f32_e64 s[42:43], |v149|, s53
	s_nop 1
	v_cndmask_b32_e64 v149, v149, v195, s[42:43]
	v_cndmask_b32_e64 v195, 0, v216, s[40:41]
	v_sub_f32_e32 v149, v149, v195
	v_sub_f32_e32 v149, v194, v149
	v_min_f32_e32 v194, 0, v145
	v_mul_f32_e64 v145, |v145|, s57
	v_exp_f32_e32 v145, v145
	s_nop 0
	v_add_f32_e32 v145, 1.0, v145
	v_cmp_gt_f32_e64 s[40:41], s97, v145
	s_nop 1
	v_cndmask_b32_e64 v195, 0, 32, s[40:41]
	v_ldexp_f32 v145, v145, v195
	v_log_f32_e32 v145, v145
	s_nop 0
	v_mul_f32_e32 v195, 0x3f317217, v145
	v_fma_f32 v195, v145, s52, -v195
	v_fmac_f32_e32 v195, 0x3377d1cf, v145
	v_fmac_f32_e32 v195, 0x3f317217, v145
	v_cmp_lt_f32_e64 s[42:43], |v145|, s53
	s_nop 1
	v_cndmask_b32_e64 v145, v145, v195, s[42:43]
	v_cndmask_b32_e64 v195, 0, v216, s[40:41]
	v_sub_f32_e32 v145, v145, v195
	v_sub_f32_e32 v194, v194, v145
	v_mul_f32_e32 v145, 0x3fb8aa3b, v149
	v_exp_f32_e32 v145, v145
	s_nop 0
	v_fma_f32 v145, v188, v145, v141
	v_cmp_gt_f32_e64 s[40:41], s97, v145
	s_nop 1
	v_cndmask_b32_e64 v195, 0, 32, s[40:41]
	v_ldexp_f32 v145, v145, v195
	v_log_f32_e32 v145, v145
	s_nop 0
	v_mul_f32_e32 v195, 0x3f317217, v145
	v_fma_f32 v195, v145, s52, -v195
	v_fmac_f32_e32 v195, 0x3377d1cf, v145
	v_fmac_f32_e32 v195, 0x3f317217, v145
	v_cmp_lt_f32_e64 s[42:43], |v145|, s53
	s_nop 1
	v_cndmask_b32_e64 v145, v145, v195, s[42:43]
	v_cndmask_b32_e64 v195, 0, v216, s[40:41]
	v_sub_f32_e32 v145, v145, v195
	v_cndmask_b32_e64 v145, v149, v145, s[34:35]
	v_mul_f32_e32 v149, 0x3fb8aa3b, v194
	v_exp_f32_e32 v149, v149
	s_nop 0
	v_fma_f32 v149, v189, v149, v137
	v_cmp_gt_f32_e64 s[40:41], s97, v149
	s_nop 1
	v_cndmask_b32_e64 v195, 0, 32, s[40:41]
	v_ldexp_f32 v149, v149, v195
	v_log_f32_e32 v149, v149
	s_nop 0
	v_mul_f32_e32 v195, 0x3f317217, v149
	v_fma_f32 v195, v149, s52, -v195
	v_fmac_f32_e32 v195, 0x3377d1cf, v149
	v_fmac_f32_e32 v195, 0x3f317217, v149
	v_cmp_lt_f32_e64 s[42:43], |v149|, s53
	s_nop 1
	v_cndmask_b32_e64 v149, v149, v195, s[42:43]
	v_cndmask_b32_e64 v195, 0, v216, s[40:41]
	v_sub_f32_e32 v149, v149, v195
	v_cndmask_b32_e64 v149, v194, v149, s[30:31]
	v_min_f32_e32 v194, 0, v150
	v_mul_f32_e64 v150, |v150|, s57
	v_exp_f32_e32 v150, v150
	s_nop 0
	v_add_f32_e32 v150, 1.0, v150
;     __device__ __forceinline__ void operator()(const f32x4 (&acc)[2][2][4][2], const pg8::Unit& u, int wr, int wc, int fr, int fq) const {
;     ...
;             WIN_LOOP( _Pragma("unroll") for (int i = 0; i < 4; ++i) { const float s0 = fminf(a[i], 0.f) - __logf(1.f + __expf(-fabsf(a[i]))), s1 = fminf(b[i], 0.f) - __logf(1.f + __expf(-fabsf(b[i]))); const float la = l0[bj][i], lbv = l1[bj][i];
;                     a[i] = la > 0.f ? __logf(la + (1.f - la) * __expf(s0)) : s0; b[i] = lbv > 0.f ? __logf(lbv + (1.f - lbv) * __expf(s1)) : s1; }
;                 *(f32x4*)(LF + (size_t)row * 512 + c) = a; *(f32x4*)(LF + (size_t)row * 512 + c + 4) = b; __builtin_amdgcn_sched_barrier(0); ) }
	v_cmp_gt_f32_e64 s[40:41], s97, v150
	s_nop 1
	v_cndmask_b32_e64 v195, 0, 32, s[40:41]
	v_ldexp_f32 v150, v150, v195
	v_log_f32_e32 v150, v150
	s_nop 0
	v_mul_f32_e32 v195, 0x3f317217, v150
	v_fma_f32 v195, v150, s52, -v195
	v_fmac_f32_e32 v195, 0x3377d1cf, v150
	v_fmac_f32_e32 v195, 0x3f317217, v150
	v_cmp_lt_f32_e64 s[42:43], |v150|, s53
	s_nop 1
	v_cndmask_b32_e64 v150, v150, v195, s[42:43]
	v_cndmask_b32_e64 v195, 0, v216, s[40:41]
	v_sub_f32_e32 v150, v150, v195
	v_sub_f32_e32 v150, v194, v150
	v_min_f32_e32 v194, 0, v146
	v_mul_f32_e64 v146, |v146|, s57
	v_exp_f32_e32 v146, v146
	s_nop 0
	v_add_f32_e32 v146, 1.0, v146
	v_cmp_gt_f32_e64 s[40:41], s97, v146
	s_nop 1
	v_cndmask_b32_e64 v195, 0, 32, s[40:41]
	v_ldexp_f32 v146, v146, v195
	v_log_f32_e32 v146, v146
	s_nop 0
	v_mul_f32_e32 v195, 0x3f317217, v146
	v_fma_f32 v195, v146, s52, -v195
	v_fmac_f32_e32 v195, 0x3377d1cf, v146
	v_fmac_f32_e32 v195, 0x3f317217, v146
	v_cmp_lt_f32_e64 s[42:43], |v146|, s53
	s_nop 1
	v_cndmask_b32_e64 v146, v146, v195, s[42:43]
	v_cndmask_b32_e64 v195, 0, v216, s[40:41]
	v_sub_f32_e32 v146, v146, v195
	v_sub_f32_e32 v194, v194, v146
	v_mul_f32_e32 v146, 0x3fb8aa3b, v150
	v_exp_f32_e32 v146, v146
	s_nop 0
	v_fma_f32 v146, v187, v146, v142
	v_cmp_gt_f32_e64 s[40:41], s97, v146
	s_nop 1
	v_cndmask_b32_e64 v195, 0, 32, s[40:41]
	v_ldexp_f32 v146, v146, v195
	v_log_f32_e32 v146, v146
	s_nop 0
	v_mul_f32_e32 v195, 0x3f317217, v146
	v_fma_f32 v195, v146, s52, -v195
	v_fmac_f32_e32 v195, 0x3377d1cf, v146
	v_fmac_f32_e32 v195, 0x3f317217, v146
	v_cmp_lt_f32_e64 s[42:43], |v146|, s53
	s_nop 1
	v_cndmask_b32_e64 v146, v146, v195, s[42:43]
	v_cndmask_b32_e64 v195, 0, v216, s[40:41]
	v_sub_f32_e32 v146, v146, v195
	v_cndmask_b32_e64 v146, v150, v146, s[28:29]
	v_mul_f32_e32 v150, 0x3fb8aa3b, v194
	v_exp_f32_e32 v150, v150
	s_nop 0
	v_fma_f32 v150, v186, v150, v138
	v_cmp_gt_f32_e64 s[40:41], s97, v150
	s_nop 1
	v_cndmask_b32_e64 v195, 0, 32, s[40:41]
	v_ldexp_f32 v150, v150, v195
	v_log_f32_e32 v150, v150
	s_nop 0
	v_mul_f32_e32 v195, 0x3f317217, v150
	v_fma_f32 v195, v150, s52, -v195
	v_fmac_f32_e32 v195, 0x3377d1cf, v150
	v_fmac_f32_e32 v195, 0x3f317217, v150
	v_cmp_lt_f32_e64 s[42:43], |v150|, s53
	s_nop 1
	v_cndmask_b32_e64 v150, v150, v195, s[42:43]
	v_cndmask_b32_e64 v195, 0, v216, s[40:41]
	v_sub_f32_e32 v150, v150, v195
	v_cndmask_b32_e64 v150, v194, v150, s[26:27]
	v_min_f32_e32 v194, 0, v151
	v_mul_f32_e64 v151, |v151|, s57
	v_exp_f32_e32 v151, v151
	s_nop 0
	v_add_f32_e32 v151, 1.0, v151
	v_cmp_gt_f32_e64 s[40:41], s97, v151
	s_nop 1
	v_cndmask_b32_e64 v195, 0, 32, s[40:41]
	v_ldexp_f32 v151, v151, v195
	v_log_f32_e32 v151, v151
	s_nop 0
	v_mul_f32_e32 v195, 0x3f317217, v151
	v_fma_f32 v195, v151, s52, -v195
	v_fmac_f32_e32 v195, 0x3377d1cf, v151
	v_fmac_f32_e32 v195, 0x3f317217, v151
	v_cmp_lt_f32_e64 s[42:43], |v151|, s53
	s_nop 1
	v_cndmask_b32_e64 v151, v151, v195, s[42:43]
	v_cndmask_b32_e64 v195, 0, v216, s[40:41]
	v_sub_f32_e32 v151, v151, v195
	v_sub_f32_e32 v151, v194, v151
	v_min_f32_e32 v194, 0, v147
	v_mul_f32_e64 v147, |v147|, s57
	v_exp_f32_e32 v147, v147
	s_nop 0
	v_add_f32_e32 v147, 1.0, v147
	v_cmp_gt_f32_e64 s[40:41], s97, v147
	s_nop 1
	v_cndmask_b32_e64 v195, 0, 32, s[40:41]
	v_ldexp_f32 v147, v147, v195
	v_log_f32_e32 v147, v147
	s_nop 0
	v_mul_f32_e32 v195, 0x3f317217, v147
	v_fma_f32 v195, v147, s52, -v195
	v_fmac_f32_e32 v195, 0x3377d1cf, v147
	v_fmac_f32_e32 v195, 0x3f317217, v147
	v_cmp_lt_f32_e64 s[42:43], |v147|, s53
	s_nop 1
	v_cndmask_b32_e64 v147, v147, v195, s[42:43]
	v_cndmask_b32_e64 v195, 0, v216, s[40:41]
	v_sub_f32_e32 v147, v147, v195
	v_sub_f32_e32 v194, v194, v147
	v_mul_f32_e32 v147, 0x3fb8aa3b, v151
	v_exp_f32_e32 v147, v147
	s_nop 0
	v_fma_f32 v147, v185, v147, v143
	v_cmp_gt_f32_e64 s[40:41], s97, v147
	s_nop 1
	v_cndmask_b32_e64 v195, 0, 32, s[40:41]
	v_ldexp_f32 v147, v147, v195
	v_log_f32_e32 v147, v147
	s_nop 0
	v_mul_f32_e32 v195, 0x3f317217, v147
	v_fma_f32 v195, v147, s52, -v195
	v_fmac_f32_e32 v195, 0x3377d1cf, v147
	v_fmac_f32_e32 v195, 0x3f317217, v147
	v_cmp_lt_f32_e64 s[42:43], |v147|, s53
	s_nop 1
	v_cndmask_b32_e64 v147, v147, v195, s[42:43]
	v_cndmask_b32_e64 v195, 0, v216, s[40:41]
	v_sub_f32_e32 v147, v147, v195
	v_cndmask_b32_e64 v147, v151, v147, s[24:25]
	v_mul_f32_e32 v151, 0x3fb8aa3b, v194
	v_exp_f32_e32 v151, v151
	s_nop 0
	v_fma_f32 v151, v184, v151, v139
	v_cmp_gt_f32_e64 s[40:41], s97, v151
	s_nop 1
	v_cndmask_b32_e64 v195, 0, 32, s[40:41]
	v_ldexp_f32 v151, v151, v195
	v_log_f32_e32 v151, v151
	s_nop 0
	v_mul_f32_e32 v195, 0x3f317217, v151
	v_fma_f32 v195, v151, s52, -v195
	v_fmac_f32_e32 v195, 0x3377d1cf, v151
	v_fmac_f32_e32 v195, 0x3f317217, v151
	v_cmp_lt_f32_e64 s[42:43], |v151|, s53
	s_nop 1
	v_cndmask_b32_e64 v151, v151, v195, s[42:43]
	v_cndmask_b32_e64 v195, 0, v216, s[40:41]
	v_sub_f32_e32 v151, v151, v195
	v_cndmask_b32_e64 v151, v194, v151, s[22:23]
	flat_store_dwordx4 v[170:171], v[144:147] sc1
	flat_store_dwordx4 v[170:171], v[148:151] offset:16 sc1
	s_nop 1
	v_pk_mul_f32 v[148:149], v[116:117], v[168:169] op_sel_hi:[1,0]
	v_pk_mul_f32 v[150:151], v[118:119], v[168:169] op_sel_hi:[1,0]
	v_pk_mul_f32 v[146:147], v[114:115], v[168:169] op_sel_hi:[1,0]
	v_pk_mul_f32 v[144:145], v[112:113], v[168:169] op_sel_hi:[1,0]
	v_min_f32_e32 v168, 0, v148
	v_mul_f32_e64 v148, |v148|, s57
	v_exp_f32_e32 v148, v148
	s_nop 0
	v_add_f32_e32 v148, 1.0, v148
	v_cmp_gt_f32_e64 s[40:41], s97, v148
	s_nop 1
	v_cndmask_b32_e64 v194, 0, 32, s[40:41]
	v_ldexp_f32 v148, v148, v194
	v_log_f32_e32 v148, v148
	s_nop 0
	v_mul_f32_e32 v194, 0x3f317217, v148
	v_fma_f32 v194, v148, s52, -v194
;     __device__ __forceinline__ void operator()(const f32x4 (&acc)[2][2][4][2], const pg8::Unit& u, int wr, int wc, int fr, int fq) const {
;     ...
;             WIN_LOOP( _Pragma("unroll") for (int i = 0; i < 4; ++i) { const float s0 = fminf(a[i], 0.f) - __logf(1.f + __expf(-fabsf(a[i]))), s1 = fminf(b[i], 0.f) - __logf(1.f + __expf(-fabsf(b[i]))); const float la = l0[bj][i], lbv = l1[bj][i];
;                     a[i] = la > 0.f ? __logf(la + (1.f - la) * __expf(s0)) : s0; b[i] = lbv > 0.f ? __logf(lbv + (1.f - lbv) * __expf(s1)) : s1; }
	v_fmac_f32_e32 v194, 0x3377d1cf, v148
	v_fmac_f32_e32 v194, 0x3f317217, v148
	v_cmp_lt_f32_e64 s[42:43], |v148|, s53
	s_nop 1
	v_cndmask_b32_e64 v148, v148, v194, s[42:43]
	v_cndmask_b32_e64 v194, 0, v216, s[40:41]
	v_sub_f32_e32 v148, v148, v194
	v_sub_f32_e32 v148, v168, v148
	v_min_f32_e32 v168, 0, v144
	v_mul_f32_e64 v144, |v144|, s57
	v_exp_f32_e32 v144, v144
	s_nop 0
	v_add_f32_e32 v144, 1.0, v144
	v_cmp_gt_f32_e64 s[40:41], s97, v144
	s_nop 1
	v_cndmask_b32_e64 v194, 0, 32, s[40:41]
	v_ldexp_f32 v144, v144, v194
	v_log_f32_e32 v144, v144
	s_nop 0
	v_mul_f32_e32 v194, 0x3f317217, v144
	v_fma_f32 v194, v144, s52, -v194
	v_fmac_f32_e32 v194, 0x3377d1cf, v144
	v_fmac_f32_e32 v194, 0x3f317217, v144
	v_cmp_lt_f32_e64 s[42:43], |v144|, s53
	s_nop 1
	v_cndmask_b32_e64 v144, v144, v194, s[42:43]
	v_cndmask_b32_e64 v194, 0, v216, s[40:41]
	v_sub_f32_e32 v144, v144, v194
	v_sub_f32_e32 v168, v168, v144
	v_mul_f32_e32 v144, 0x3fb8aa3b, v148
	v_exp_f32_e32 v144, v144
	s_nop 0
	v_fma_f32 v144, v183, v144, v132
	v_cmp_gt_f32_e64 s[40:41], s97, v144
	s_nop 1
	v_cndmask_b32_e64 v194, 0, 32, s[40:41]
	v_ldexp_f32 v144, v144, v194
	v_log_f32_e32 v144, v144
	s_nop 0
	v_mul_f32_e32 v194, 0x3f317217, v144
	v_fma_f32 v194, v144, s52, -v194
	v_fmac_f32_e32 v194, 0x3377d1cf, v144
	v_fmac_f32_e32 v194, 0x3f317217, v144
	v_cmp_lt_f32_e64 s[42:43], |v144|, s53
	s_nop 1
	v_cndmask_b32_e64 v144, v144, v194, s[42:43]
	v_cndmask_b32_e64 v194, 0, v216, s[40:41]
	v_sub_f32_e32 v144, v144, v194
	v_cndmask_b32_e64 v144, v148, v144, s[20:21]
	v_mul_f32_e32 v148, 0x3fb8aa3b, v168
	v_exp_f32_e32 v148, v148
	s_nop 0
	v_fma_f32 v148, v182, v148, v128
	v_cmp_gt_f32_e64 s[40:41], s97, v148
	s_nop 1
	v_cndmask_b32_e64 v194, 0, 32, s[40:41]
	v_ldexp_f32 v148, v148, v194
	v_log_f32_e32 v148, v148
	s_nop 0
	v_mul_f32_e32 v194, 0x3f317217, v148
	v_fma_f32 v194, v148, s52, -v194
	v_fmac_f32_e32 v194, 0x3377d1cf, v148
	v_fmac_f32_e32 v194, 0x3f317217, v148
	v_cmp_lt_f32_e64 s[42:43], |v148|, s53
	s_nop 1
	v_cndmask_b32_e64 v148, v148, v194, s[42:43]
	v_cndmask_b32_e64 v194, 0, v216, s[40:41]
	v_sub_f32_e32 v148, v148, v194
	v_cndmask_b32_e64 v148, v168, v148, s[18:19]
	v_min_f32_e32 v168, 0, v149
	v_mul_f32_e64 v149, |v149|, s57
	v_exp_f32_e32 v149, v149
	s_nop 0
	v_add_f32_e32 v149, 1.0, v149
	v_cmp_gt_f32_e64 s[40:41], s97, v149
	s_nop 1
	v_cndmask_b32_e64 v194, 0, 32, s[40:41]
	v_ldexp_f32 v149, v149, v194
	v_log_f32_e32 v149, v149
	s_nop 0
	v_mul_f32_e32 v194, 0x3f317217, v149
	v_fma_f32 v194, v149, s52, -v194
	v_fmac_f32_e32 v194, 0x3377d1cf, v149
	v_fmac_f32_e32 v194, 0x3f317217, v149
	v_cmp_lt_f32_e64 s[42:43], |v149|, s53
	s_nop 1
	v_cndmask_b32_e64 v149, v149, v194, s[42:43]
	v_cndmask_b32_e64 v194, 0, v216, s[40:41]
	v_sub_f32_e32 v149, v149, v194
	v_sub_f32_e32 v149, v168, v149
	v_min_f32_e32 v168, 0, v145
	v_mul_f32_e64 v145, |v145|, s57
	v_exp_f32_e32 v145, v145
	s_nop 0
	v_add_f32_e32 v145, 1.0, v145
	v_cmp_gt_f32_e64 s[40:41], s97, v145
	s_nop 1
	v_cndmask_b32_e64 v194, 0, 32, s[40:41]
	v_ldexp_f32 v145, v145, v194
	v_log_f32_e32 v145, v145
	s_nop 0
	v_mul_f32_e32 v194, 0x3f317217, v145
	v_fma_f32 v194, v145, s52, -v194
	v_fmac_f32_e32 v194, 0x3377d1cf, v145
	v_fmac_f32_e32 v194, 0x3f317217, v145
	v_cmp_lt_f32_e64 s[42:43], |v145|, s53
	s_nop 1
	v_cndmask_b32_e64 v145, v145, v194, s[42:43]
	v_cndmask_b32_e64 v194, 0, v216, s[40:41]
	v_sub_f32_e32 v145, v145, v194
	v_sub_f32_e32 v168, v168, v145
	v_mul_f32_e32 v145, 0x3fb8aa3b, v149
	v_exp_f32_e32 v145, v145
	s_nop 0
	v_fma_f32 v145, v181, v145, v133
	v_cmp_gt_f32_e64 s[40:41], s97, v145
	s_nop 1
	v_cndmask_b32_e64 v194, 0, 32, s[40:41]
	v_ldexp_f32 v145, v145, v194
	v_log_f32_e32 v145, v145
	s_nop 0
	v_mul_f32_e32 v194, 0x3f317217, v145
	v_fma_f32 v194, v145, s52, -v194
	v_fmac_f32_e32 v194, 0x3377d1cf, v145
	v_fmac_f32_e32 v194, 0x3f317217, v145
	v_cmp_lt_f32_e64 s[42:43], |v145|, s53
	s_nop 1
	v_cndmask_b32_e64 v145, v145, v194, s[42:43]
	v_cndmask_b32_e64 v194, 0, v216, s[40:41]
	v_sub_f32_e32 v145, v145, v194
	v_cndmask_b32_e64 v145, v149, v145, s[16:17]
	v_mul_f32_e32 v149, 0x3fb8aa3b, v168
	v_exp_f32_e32 v149, v149
	s_nop 0
	v_fma_f32 v149, v180, v149, v129
	v_cmp_gt_f32_e64 s[40:41], s97, v149
	s_nop 1
	v_cndmask_b32_e64 v194, 0, 32, s[40:41]
	v_ldexp_f32 v149, v149, v194
	v_log_f32_e32 v149, v149
	s_nop 0
	v_mul_f32_e32 v194, 0x3f317217, v149
	v_fma_f32 v194, v149, s52, -v194
	v_fmac_f32_e32 v194, 0x3377d1cf, v149
	v_fmac_f32_e32 v194, 0x3f317217, v149
	v_cmp_lt_f32_e64 s[42:43], |v149|, s53
	s_nop 1
	v_cndmask_b32_e64 v149, v149, v194, s[42:43]
	v_cndmask_b32_e64 v194, 0, v216, s[40:41]
	v_sub_f32_e32 v149, v149, v194
	v_cndmask_b32_e64 v149, v168, v149, s[14:15]
	v_min_f32_e32 v168, 0, v150
	v_mul_f32_e64 v150, |v150|, s57
	v_exp_f32_e32 v150, v150
	s_nop 0
	v_add_f32_e32 v150, 1.0, v150
	v_cmp_gt_f32_e64 s[40:41], s97, v150
	s_nop 1
	v_cndmask_b32_e64 v194, 0, 32, s[40:41]
	v_ldexp_f32 v150, v150, v194
	v_log_f32_e32 v150, v150
	s_nop 0
	v_mul_f32_e32 v194, 0x3f317217, v150
	v_fma_f32 v194, v150, s52, -v194
	v_fmac_f32_e32 v194, 0x3377d1cf, v150
	v_fmac_f32_e32 v194, 0x3f317217, v150
	v_cmp_lt_f32_e64 s[42:43], |v150|, s53
	s_nop 1
	v_cndmask_b32_e64 v150, v150, v194, s[42:43]
	v_cndmask_b32_e64 v194, 0, v216, s[40:41]
	v_sub_f32_e32 v150, v150, v194
	v_sub_f32_e32 v150, v168, v150
	v_min_f32_e32 v168, 0, v146
	v_mul_f32_e64 v146, |v146|, s57
	v_exp_f32_e32 v146, v146
	s_nop 0
	v_add_f32_e32 v146, 1.0, v146
	v_cmp_gt_f32_e64 s[40:41], s97, v146
	s_nop 1
	v_cndmask_b32_e64 v194, 0, 32, s[40:41]
	v_ldexp_f32 v146, v146, v194
	v_log_f32_e32 v146, v146
	s_nop 0
	v_mul_f32_e32 v194, 0x3f317217, v146
; __device__ __forceinline__ float row_rstd(const float* ssq, int row, int fq) {
;     const f32x4 v = *(const f32x4*)(ssq + (size_t)row * 16 + fq * 4);
;     float s = (v[0] + v[1]) + (v[2] + v[3]);
;     s += __shfl_xor(s, 16); s += __shfl_xor(s, 32);
;     return __builtin_amdgcn_rsqf(s * (1.f / DM) + EPS);
; }
;     __device__ __forceinline__ void operator()(const f32x4 (&acc)[2][2][4][2], const pg8::Unit& u, int wr, int wc, int fr, int fq) const {
;     ...
;             WIN_LOOP( _Pragma("unroll") for (int i = 0; i < 4; ++i) { const float s0 = fminf(a[i], 0.f) - __logf(1.f + __expf(-fabsf(a[i]))), s1 = fminf(b[i], 0.f) - __logf(1.f + __expf(-fabsf(b[i]))); const float la = l0[bj][i], lbv = l1[bj][i];
;                     a[i] = la > 0.f ? __logf(la + (1.f - la) * __expf(s0)) : s0; b[i] = lbv > 0.f ? __logf(lbv + (1.f - lbv) * __expf(s1)) : s1; }
;                 *(f32x4*)(LF + (size_t)row * 512 + c) = a; *(f32x4*)(LF + (size_t)row * 512 + c + 4) = b; __builtin_amdgcn_sched_barrier(0); ) }
	v_fma_f32 v194, v146, s52, -v194
	v_fmac_f32_e32 v194, 0x3377d1cf, v146
	v_fmac_f32_e32 v194, 0x3f317217, v146
	v_cmp_lt_f32_e64 s[42:43], |v146|, s53
	s_nop 1
	v_cndmask_b32_e64 v146, v146, v194, s[42:43]
	v_cndmask_b32_e64 v194, 0, v216, s[40:41]
	v_sub_f32_e32 v146, v146, v194
	v_sub_f32_e32 v168, v168, v146
	v_mul_f32_e32 v146, 0x3fb8aa3b, v150
	v_exp_f32_e32 v146, v146
	s_nop 0
	v_fma_f32 v146, v179, v146, v134
	v_cmp_gt_f32_e64 s[40:41], s97, v146
	s_nop 1
	v_cndmask_b32_e64 v194, 0, 32, s[40:41]
	v_ldexp_f32 v146, v146, v194
	v_log_f32_e32 v146, v146
	s_nop 0
	v_mul_f32_e32 v194, 0x3f317217, v146
	v_fma_f32 v194, v146, s52, -v194
	v_fmac_f32_e32 v194, 0x3377d1cf, v146
	v_fmac_f32_e32 v194, 0x3f317217, v146
	v_cmp_lt_f32_e64 s[42:43], |v146|, s53
	s_nop 1
	v_cndmask_b32_e64 v146, v146, v194, s[42:43]
	v_cndmask_b32_e64 v194, 0, v216, s[40:41]
	v_sub_f32_e32 v146, v146, v194
	v_cndmask_b32_e64 v146, v150, v146, s[12:13]
	v_mul_f32_e32 v150, 0x3fb8aa3b, v168
	v_exp_f32_e32 v150, v150
	s_nop 0
	v_fma_f32 v150, v178, v150, v130
	v_cmp_gt_f32_e64 s[40:41], s97, v150
	s_nop 1
	v_cndmask_b32_e64 v194, 0, 32, s[40:41]
	v_ldexp_f32 v150, v150, v194
	v_log_f32_e32 v150, v150
	s_nop 0
	v_mul_f32_e32 v194, 0x3f317217, v150
	v_fma_f32 v194, v150, s52, -v194
	v_fmac_f32_e32 v194, 0x3377d1cf, v150
	v_fmac_f32_e32 v194, 0x3f317217, v150
	v_cmp_lt_f32_e64 s[42:43], |v150|, s53
	s_nop 1
	v_cndmask_b32_e64 v150, v150, v194, s[42:43]
	v_cndmask_b32_e64 v194, 0, v216, s[40:41]
	v_sub_f32_e32 v150, v150, v194
	v_cndmask_b32_e64 v150, v168, v150, s[10:11]
	v_min_f32_e32 v168, 0, v151
	v_mul_f32_e64 v151, |v151|, s57
	v_exp_f32_e32 v151, v151
	s_nop 0
	v_add_f32_e32 v151, 1.0, v151
	v_cmp_gt_f32_e64 s[40:41], s97, v151
	s_nop 1
	v_cndmask_b32_e64 v194, 0, 32, s[40:41]
	v_ldexp_f32 v151, v151, v194
	v_log_f32_e32 v151, v151
	s_nop 0
	v_mul_f32_e32 v194, 0x3f317217, v151
	v_fma_f32 v194, v151, s52, -v194
	v_fmac_f32_e32 v194, 0x3377d1cf, v151
	v_fmac_f32_e32 v194, 0x3f317217, v151
	v_cmp_lt_f32_e64 s[42:43], |v151|, s53
	s_nop 1
	v_cndmask_b32_e64 v151, v151, v194, s[42:43]
	v_cndmask_b32_e64 v194, 0, v216, s[40:41]
	v_sub_f32_e32 v151, v151, v194
	v_sub_f32_e32 v151, v168, v151
	v_min_f32_e32 v168, 0, v147
	v_mul_f32_e64 v147, |v147|, s57
	v_exp_f32_e32 v147, v147
	s_nop 0
	v_add_f32_e32 v147, 1.0, v147
	v_cmp_gt_f32_e64 s[40:41], s97, v147
	s_nop 1
	v_cndmask_b32_e64 v194, 0, 32, s[40:41]
	v_ldexp_f32 v147, v147, v194
	v_log_f32_e32 v147, v147
	s_nop 0
	v_mul_f32_e32 v194, 0x3f317217, v147
	v_fma_f32 v194, v147, s52, -v194
	v_fmac_f32_e32 v194, 0x3377d1cf, v147
	v_fmac_f32_e32 v194, 0x3f317217, v147
	v_cmp_lt_f32_e64 s[42:43], |v147|, s53
	s_nop 1
	v_cndmask_b32_e64 v147, v147, v194, s[42:43]
	v_cndmask_b32_e64 v194, 0, v216, s[40:41]
	v_sub_f32_e32 v147, v147, v194
	v_sub_f32_e32 v168, v168, v147
	v_mul_f32_e32 v147, 0x3fb8aa3b, v151
	v_exp_f32_e32 v147, v147
	s_nop 0
	v_fma_f32 v147, v177, v147, v135
	v_cmp_gt_f32_e64 s[40:41], s97, v147
	s_nop 1
	v_cndmask_b32_e64 v194, 0, 32, s[40:41]
	v_ldexp_f32 v147, v147, v194
	v_log_f32_e32 v147, v147
	s_nop 0
	v_mul_f32_e32 v194, 0x3f317217, v147
	v_fma_f32 v194, v147, s52, -v194
	v_fmac_f32_e32 v194, 0x3377d1cf, v147
	v_fmac_f32_e32 v194, 0x3f317217, v147
	v_cmp_lt_f32_e64 s[42:43], |v147|, s53
	s_nop 1
	v_cndmask_b32_e64 v147, v147, v194, s[42:43]
	v_cndmask_b32_e64 v194, 0, v216, s[40:41]
	v_sub_f32_e32 v147, v147, v194
	v_cndmask_b32_e64 v147, v151, v147, s[8:9]
	v_mul_f32_e32 v151, 0x3fb8aa3b, v168
	v_exp_f32_e32 v151, v151
	s_nop 0
	v_fma_f32 v151, v167, v151, v131
	v_cmp_gt_f32_e64 s[40:41], s97, v151
	s_nop 1
	v_cndmask_b32_e64 v194, 0, 32, s[40:41]
	v_ldexp_f32 v151, v151, v194
	v_log_f32_e32 v151, v151
	s_nop 0
	v_mul_f32_e32 v194, 0x3f317217, v151
	v_fma_f32 v194, v151, s52, -v194
	v_fmac_f32_e32 v194, 0x3377d1cf, v151
	v_fmac_f32_e32 v194, 0x3f317217, v151
	v_cmp_lt_f32_e64 s[42:43], |v151|, s53
	s_nop 1
	v_cndmask_b32_e64 v151, v151, v194, s[42:43]
	v_cndmask_b32_e64 v194, 0, v216, s[40:41]
	v_sub_f32_e32 v151, v151, v194
	v_cndmask_b32_e32 v151, v168, v151, vcc
	flat_store_dwordx4 v[170:171], v[144:147] offset:512 sc1
	flat_store_dwordx4 v[170:171], v[148:151] offset:528 sc1
	s_nop 1
	v_or_b32_e32 v148, 32, v166
	v_ashrrev_i32_e32 v149, 31, v148
	v_lshlrev_b64 v[144:145], 6, v[148:149]
	v_lshl_add_u64 v[144:145], v[160:161], 0, v[144:145]
	flat_load_dwordx4 v[144:147], v[144:145]
	s_waitcnt vmcnt(0) lgkmcnt(0)
	v_mov_b32_e32 v150, v145
	v_mov_b32_e32 v151, v146
	v_mov_b32_e32 v145, v147
	v_pk_add_f32 v[144:145], v[150:151], v[144:145]
	s_nop 0
	v_add_f32_e32 v144, v144, v145
	ds_bpermute_b32 v145, v169, v144
	s_waitcnt lgkmcnt(0)
	v_add_f32_e32 v144, v144, v145
	ds_bpermute_b32 v145, v202, v144
	s_waitcnt lgkmcnt(0)
; __device__ __forceinline__ float row_rstd(const float* ssq, int row, int fq) {
;     const f32x4 v = *(const f32x4*)(ssq + (size_t)row * 16 + fq * 4);
;     float s = (v[0] + v[1]) + (v[2] + v[3]);
;     s += __shfl_xor(s, 16); s += __shfl_xor(s, 32);
;     return __builtin_amdgcn_rsqf(s * (1.f / DM) + EPS);
; }
;     __device__ __forceinline__ void operator()(const f32x4 (&acc)[2][2][4][2], const pg8::Unit& u, int wr, int wc, int fr, int fq) const {
;     ...
;             WIN_LOOP( _Pragma("unroll") for (int i = 0; i < 4; ++i) { const float s0 = fminf(a[i], 0.f) - __logf(1.f + __expf(-fabsf(a[i]))), s1 = fminf(b[i], 0.f) - __logf(1.f + __expf(-fabsf(b[i]))); const float la = l0[bj][i], lbv = l1[bj][i];
;                     a[i] = la > 0.f ? __logf(la + (1.f - la) * __expf(s0)) : s0; b[i] = lbv > 0.f ? __logf(lbv + (1.f - lbv) * __expf(s1)) : s1; }
	v_add_f32_e32 v144, v144, v145
	v_fmamk_f32 v144, v144, 0x3a800000, v212
	v_rsq_f32_e32 v168, v144
	v_lshlrev_b64 v[144:145], 11, v[148:149]
	v_lshl_add_u64 v[170:171], s[50:51], 0, v[144:145]
	v_lshl_add_u64 v[170:171], v[170:171], 0, v[192:193]
	v_pk_mul_f32 v[148:149], v[44:45], v[168:169] op_sel_hi:[1,0]
	v_pk_mul_f32 v[144:145], v[40:41], v[168:169] op_sel_hi:[1,0]
	v_min_f32_e32 v194, 0, v148
	v_mul_f32_e64 v148, |v148|, s57
	v_exp_f32_e32 v148, v148
	v_pk_mul_f32 v[150:151], v[46:47], v[168:169] op_sel_hi:[1,0]
	v_pk_mul_f32 v[146:147], v[42:43], v[168:169] op_sel_hi:[1,0]
	v_add_f32_e32 v148, 1.0, v148
	v_cmp_gt_f32_e64 s[40:41], s97, v148
	s_nop 1
	v_cndmask_b32_e64 v195, 0, 32, s[40:41]
	v_ldexp_f32 v148, v148, v195
	v_log_f32_e32 v148, v148
	s_nop 0
	v_mul_f32_e32 v195, 0x3f317217, v148
	v_fma_f32 v195, v148, s52, -v195
	v_fmac_f32_e32 v195, 0x3377d1cf, v148
	v_fmac_f32_e32 v195, 0x3f317217, v148
	v_cmp_lt_f32_e64 s[42:43], |v148|, s53
	s_nop 1
	v_cndmask_b32_e64 v148, v148, v195, s[42:43]
	v_cndmask_b32_e64 v195, 0, v216, s[40:41]
	v_sub_f32_e32 v148, v148, v195
	v_sub_f32_e32 v148, v194, v148
	v_min_f32_e32 v194, 0, v144
	v_mul_f32_e64 v144, |v144|, s57
	v_exp_f32_e32 v144, v144
	s_nop 0
	v_add_f32_e32 v144, 1.0, v144
	v_cmp_gt_f32_e64 s[40:41], s97, v144
	s_nop 1
	v_cndmask_b32_e64 v195, 0, 32, s[40:41]
	v_ldexp_f32 v144, v144, v195
	v_log_f32_e32 v144, v144
	s_nop 0
	v_mul_f32_e32 v195, 0x3f317217, v144
	v_fma_f32 v195, v144, s52, -v195
	v_fmac_f32_e32 v195, 0x3377d1cf, v144
	v_fmac_f32_e32 v195, 0x3f317217, v144
	v_cmp_lt_f32_e64 s[42:43], |v144|, s53
	s_nop 1
	v_cndmask_b32_e64 v144, v144, v195, s[42:43]
	v_cndmask_b32_e64 v195, 0, v216, s[40:41]
	v_sub_f32_e32 v144, v144, v195
	v_sub_f32_e32 v194, v194, v144
	v_mul_f32_e32 v144, 0x3fb8aa3b, v148
	v_exp_f32_e32 v144, v144
	s_nop 0
	v_fma_f32 v144, v190, v144, v140
	v_cmp_gt_f32_e64 s[40:41], s97, v144
	s_nop 1
	v_cndmask_b32_e64 v195, 0, 32, s[40:41]
	v_ldexp_f32 v144, v144, v195
	v_log_f32_e32 v144, v144
	s_nop 0
	v_mul_f32_e32 v195, 0x3f317217, v144
	v_fma_f32 v195, v144, s52, -v195
	v_fmac_f32_e32 v195, 0x3377d1cf, v144
	v_fmac_f32_e32 v195, 0x3f317217, v144
	v_cmp_lt_f32_e64 s[42:43], |v144|, s53
	s_nop 1
	v_cndmask_b32_e64 v144, v144, v195, s[42:43]
	v_cndmask_b32_e64 v195, 0, v216, s[40:41]
	v_sub_f32_e32 v144, v144, v195
	v_cndmask_b32_e64 v144, v148, v144, s[38:39]
	v_mul_f32_e32 v148, 0x3fb8aa3b, v194
	v_exp_f32_e32 v148, v148
	s_nop 0
	v_fma_f32 v148, v191, v148, v136
	v_cmp_gt_f32_e64 s[40:41], s97, v148
	s_nop 1
	v_cndmask_b32_e64 v195, 0, 32, s[40:41]
	v_ldexp_f32 v148, v148, v195
	v_log_f32_e32 v148, v148
	s_nop 0
	v_mul_f32_e32 v195, 0x3f317217, v148
	v_fma_f32 v195, v148, s52, -v195
	v_fmac_f32_e32 v195, 0x3377d1cf, v148
	v_fmac_f32_e32 v195, 0x3f317217, v148
	v_cmp_lt_f32_e64 s[42:43], |v148|, s53
	s_nop 1
	v_cndmask_b32_e64 v148, v148, v195, s[42:43]
	v_cndmask_b32_e64 v195, 0, v216, s[40:41]
	v_sub_f32_e32 v148, v148, v195
	v_cndmask_b32_e64 v148, v194, v148, s[36:37]
	v_min_f32_e32 v194, 0, v149
	v_mul_f32_e64 v149, |v149|, s57
	v_exp_f32_e32 v149, v149
	s_nop 0
	v_add_f32_e32 v149, 1.0, v149
	v_cmp_gt_f32_e64 s[40:41], s97, v149
	s_nop 1
	v_cndmask_b32_e64 v195, 0, 32, s[40:41]
	v_ldexp_f32 v149, v149, v195
	v_log_f32_e32 v149, v149
	s_nop 0
	v_mul_f32_e32 v195, 0x3f317217, v149
	v_fma_f32 v195, v149, s52, -v195
	v_fmac_f32_e32 v195, 0x3377d1cf, v149
	v_fmac_f32_e32 v195, 0x3f317217, v149
	v_cmp_lt_f32_e64 s[42:43], |v149|, s53
	s_nop 1
	v_cndmask_b32_e64 v149, v149, v195, s[42:43]
	v_cndmask_b32_e64 v195, 0, v216, s[40:41]
	v_sub_f32_e32 v149, v149, v195
	v_sub_f32_e32 v149, v194, v149
	v_min_f32_e32 v194, 0, v145
	v_mul_f32_e64 v145, |v145|, s57
	v_exp_f32_e32 v145, v145
	s_nop 0
	v_add_f32_e32 v145, 1.0, v145
	v_cmp_gt_f32_e64 s[40:41], s97, v145
	s_nop 1
	v_cndmask_b32_e64 v195, 0, 32, s[40:41]
	v_ldexp_f32 v145, v145, v195
	v_log_f32_e32 v145, v145
	s_nop 0
	v_mul_f32_e32 v195, 0x3f317217, v145
	v_fma_f32 v195, v145, s52, -v195
	v_fmac_f32_e32 v195, 0x3377d1cf, v145
	v_fmac_f32_e32 v195, 0x3f317217, v145
	v_cmp_lt_f32_e64 s[42:43], |v145|, s53
	s_nop 1
	v_cndmask_b32_e64 v145, v145, v195, s[42:43]
	v_cndmask_b32_e64 v195, 0, v216, s[40:41]
	v_sub_f32_e32 v145, v145, v195
	v_sub_f32_e32 v194, v194, v145
	v_mul_f32_e32 v145, 0x3fb8aa3b, v149
	v_exp_f32_e32 v145, v145
	s_nop 0
	v_fma_f32 v145, v188, v145, v141
	v_cmp_gt_f32_e64 s[40:41], s97, v145
	s_nop 1
	v_cndmask_b32_e64 v195, 0, 32, s[40:41]
	v_ldexp_f32 v145, v145, v195
	v_log_f32_e32 v145, v145
	s_nop 0
	v_mul_f32_e32 v195, 0x3f317217, v145
	v_fma_f32 v195, v145, s52, -v195
	v_fmac_f32_e32 v195, 0x3377d1cf, v145
	v_fmac_f32_e32 v195, 0x3f317217, v145
	v_cmp_lt_f32_e64 s[42:43], |v145|, s53
	s_nop 1
	v_cndmask_b32_e64 v145, v145, v195, s[42:43]
	v_cndmask_b32_e64 v195, 0, v216, s[40:41]
	v_sub_f32_e32 v145, v145, v195
	v_cndmask_b32_e64 v145, v149, v145, s[34:35]
	v_mul_f32_e32 v149, 0x3fb8aa3b, v194
	v_exp_f32_e32 v149, v149
	s_nop 0
	v_fma_f32 v149, v189, v149, v137
	v_cmp_gt_f32_e64 s[40:41], s97, v149
	s_nop 1
	v_cndmask_b32_e64 v195, 0, 32, s[40:41]
	v_ldexp_f32 v149, v149, v195
	v_log_f32_e32 v149, v149
	s_nop 0
	v_mul_f32_e32 v195, 0x3f317217, v149
	v_fma_f32 v195, v149, s52, -v195
	v_fmac_f32_e32 v195, 0x3377d1cf, v149
	v_fmac_f32_e32 v195, 0x3f317217, v149
	v_cmp_lt_f32_e64 s[42:43], |v149|, s53
	s_nop 1
	v_cndmask_b32_e64 v149, v149, v195, s[42:43]
	v_cndmask_b32_e64 v195, 0, v216, s[40:41]
	v_sub_f32_e32 v149, v149, v195
	v_cndmask_b32_e64 v149, v194, v149, s[30:31]
	v_min_f32_e32 v194, 0, v150
	v_mul_f32_e64 v150, |v150|, s57
	v_exp_f32_e32 v150, v150
	s_nop 0
	v_add_f32_e32 v150, 1.0, v150
;     __device__ __forceinline__ void operator()(const f32x4 (&acc)[2][2][4][2], const pg8::Unit& u, int wr, int wc, int fr, int fq) const {
;     ...
;             WIN_LOOP( _Pragma("unroll") for (int i = 0; i < 4; ++i) { const float s0 = fminf(a[i], 0.f) - __logf(1.f + __expf(-fabsf(a[i]))), s1 = fminf(b[i], 0.f) - __logf(1.f + __expf(-fabsf(b[i]))); const float la = l0[bj][i], lbv = l1[bj][i];
;                     a[i] = la > 0.f ? __logf(la + (1.f - la) * __expf(s0)) : s0; b[i] = lbv > 0.f ? __logf(lbv + (1.f - lbv) * __expf(s1)) : s1; }
;                 *(f32x4*)(LF + (size_t)row * 512 + c) = a; *(f32x4*)(LF + (size_t)row * 512 + c + 4) = b; __builtin_amdgcn_sched_barrier(0); ) }
	v_cmp_gt_f32_e64 s[40:41], s97, v150
	s_nop 1
	v_cndmask_b32_e64 v195, 0, 32, s[40:41]
	v_ldexp_f32 v150, v150, v195
	v_log_f32_e32 v150, v150
	s_nop 0
	v_mul_f32_e32 v195, 0x3f317217, v150
	v_fma_f32 v195, v150, s52, -v195
	v_fmac_f32_e32 v195, 0x3377d1cf, v150
	v_fmac_f32_e32 v195, 0x3f317217, v150
	v_cmp_lt_f32_e64 s[42:43], |v150|, s53
	s_nop 1
	v_cndmask_b32_e64 v150, v150, v195, s[42:43]
	v_cndmask_b32_e64 v195, 0, v216, s[40:41]
	v_sub_f32_e32 v150, v150, v195
	v_sub_f32_e32 v150, v194, v150
	v_min_f32_e32 v194, 0, v146
	v_mul_f32_e64 v146, |v146|, s57
	v_exp_f32_e32 v146, v146
	s_nop 0
	v_add_f32_e32 v146, 1.0, v146
	v_cmp_gt_f32_e64 s[40:41], s97, v146
	s_nop 1
	v_cndmask_b32_e64 v195, 0, 32, s[40:41]
	v_ldexp_f32 v146, v146, v195
	v_log_f32_e32 v146, v146
	s_nop 0
	v_mul_f32_e32 v195, 0x3f317217, v146
	v_fma_f32 v195, v146, s52, -v195
	v_fmac_f32_e32 v195, 0x3377d1cf, v146
	v_fmac_f32_e32 v195, 0x3f317217, v146
	v_cmp_lt_f32_e64 s[42:43], |v146|, s53
	s_nop 1
	v_cndmask_b32_e64 v146, v146, v195, s[42:43]
	v_cndmask_b32_e64 v195, 0, v216, s[40:41]
	v_sub_f32_e32 v146, v146, v195
	v_sub_f32_e32 v194, v194, v146
	v_mul_f32_e32 v146, 0x3fb8aa3b, v150
	v_exp_f32_e32 v146, v146
	s_nop 0
	v_fma_f32 v146, v187, v146, v142
	v_cmp_gt_f32_e64 s[40:41], s97, v146
	s_nop 1
	v_cndmask_b32_e64 v195, 0, 32, s[40:41]
	v_ldexp_f32 v146, v146, v195
	v_log_f32_e32 v146, v146
	s_nop 0
	v_mul_f32_e32 v195, 0x3f317217, v146
	v_fma_f32 v195, v146, s52, -v195
	v_fmac_f32_e32 v195, 0x3377d1cf, v146
	v_fmac_f32_e32 v195, 0x3f317217, v146
	v_cmp_lt_f32_e64 s[42:43], |v146|, s53
	s_nop 1
	v_cndmask_b32_e64 v146, v146, v195, s[42:43]
	v_cndmask_b32_e64 v195, 0, v216, s[40:41]
	v_sub_f32_e32 v146, v146, v195
	v_cndmask_b32_e64 v146, v150, v146, s[28:29]
	v_mul_f32_e32 v150, 0x3fb8aa3b, v194
	v_exp_f32_e32 v150, v150
	s_nop 0
	v_fma_f32 v150, v186, v150, v138
	v_cmp_gt_f32_e64 s[40:41], s97, v150
	s_nop 1
	v_cndmask_b32_e64 v195, 0, 32, s[40:41]
	v_ldexp_f32 v150, v150, v195
	v_log_f32_e32 v150, v150
	s_nop 0
	v_mul_f32_e32 v195, 0x3f317217, v150
	v_fma_f32 v195, v150, s52, -v195
	v_fmac_f32_e32 v195, 0x3377d1cf, v150
	v_fmac_f32_e32 v195, 0x3f317217, v150
	v_cmp_lt_f32_e64 s[42:43], |v150|, s53
	s_nop 1
	v_cndmask_b32_e64 v150, v150, v195, s[42:43]
	v_cndmask_b32_e64 v195, 0, v216, s[40:41]
	v_sub_f32_e32 v150, v150, v195
	v_cndmask_b32_e64 v150, v194, v150, s[26:27]
	v_min_f32_e32 v194, 0, v151
	v_mul_f32_e64 v151, |v151|, s57
	v_exp_f32_e32 v151, v151
	s_nop 0
	v_add_f32_e32 v151, 1.0, v151
	v_cmp_gt_f32_e64 s[40:41], s97, v151
	s_nop 1
	v_cndmask_b32_e64 v195, 0, 32, s[40:41]
	v_ldexp_f32 v151, v151, v195
	v_log_f32_e32 v151, v151
	s_nop 0
	v_mul_f32_e32 v195, 0x3f317217, v151
	v_fma_f32 v195, v151, s52, -v195
	v_fmac_f32_e32 v195, 0x3377d1cf, v151
	v_fmac_f32_e32 v195, 0x3f317217, v151
	v_cmp_lt_f32_e64 s[42:43], |v151|, s53
	s_nop 1
	v_cndmask_b32_e64 v151, v151, v195, s[42:43]
	v_cndmask_b32_e64 v195, 0, v216, s[40:41]
	v_sub_f32_e32 v151, v151, v195
	v_sub_f32_e32 v151, v194, v151
	v_min_f32_e32 v194, 0, v147
	v_mul_f32_e64 v147, |v147|, s57
	v_exp_f32_e32 v147, v147
	s_nop 0
	v_add_f32_e32 v147, 1.0, v147
	v_cmp_gt_f32_e64 s[40:41], s97, v147
	s_nop 1
	v_cndmask_b32_e64 v195, 0, 32, s[40:41]
	v_ldexp_f32 v147, v147, v195
	v_log_f32_e32 v147, v147
	s_nop 0
	v_mul_f32_e32 v195, 0x3f317217, v147
	v_fma_f32 v195, v147, s52, -v195
	v_fmac_f32_e32 v195, 0x3377d1cf, v147
	v_fmac_f32_e32 v195, 0x3f317217, v147
	v_cmp_lt_f32_e64 s[42:43], |v147|, s53
	s_nop 1
	v_cndmask_b32_e64 v147, v147, v195, s[42:43]
	v_cndmask_b32_e64 v195, 0, v216, s[40:41]
	v_sub_f32_e32 v147, v147, v195
	v_sub_f32_e32 v194, v194, v147
	v_mul_f32_e32 v147, 0x3fb8aa3b, v151
	v_exp_f32_e32 v147, v147
	s_nop 0
	v_fma_f32 v147, v185, v147, v143
	v_cmp_gt_f32_e64 s[40:41], s97, v147
	s_nop 1
	v_cndmask_b32_e64 v195, 0, 32, s[40:41]
	v_ldexp_f32 v147, v147, v195
	v_log_f32_e32 v147, v147
	s_nop 0
	v_mul_f32_e32 v195, 0x3f317217, v147
	v_fma_f32 v195, v147, s52, -v195
	v_fmac_f32_e32 v195, 0x3377d1cf, v147
	v_fmac_f32_e32 v195, 0x3f317217, v147
	v_cmp_lt_f32_e64 s[42:43], |v147|, s53
	s_nop 1
	v_cndmask_b32_e64 v147, v147, v195, s[42:43]
	v_cndmask_b32_e64 v195, 0, v216, s[40:41]
	v_sub_f32_e32 v147, v147, v195
	v_cndmask_b32_e64 v147, v151, v147, s[24:25]
	v_mul_f32_e32 v151, 0x3fb8aa3b, v194
	v_exp_f32_e32 v151, v151
	s_nop 0
	v_fma_f32 v151, v184, v151, v139
	v_cmp_gt_f32_e64 s[40:41], s97, v151
	s_nop 1
	v_cndmask_b32_e64 v195, 0, 32, s[40:41]
	v_ldexp_f32 v151, v151, v195
	v_log_f32_e32 v151, v151
	s_nop 0
	v_mul_f32_e32 v195, 0x3f317217, v151
	v_fma_f32 v195, v151, s52, -v195
	v_fmac_f32_e32 v195, 0x3377d1cf, v151
	v_fmac_f32_e32 v195, 0x3f317217, v151
	v_cmp_lt_f32_e64 s[42:43], |v151|, s53
	s_nop 1
	v_cndmask_b32_e64 v151, v151, v195, s[42:43]
	v_cndmask_b32_e64 v195, 0, v216, s[40:41]
	v_sub_f32_e32 v151, v151, v195
	v_cndmask_b32_e64 v151, v194, v151, s[22:23]
	flat_store_dwordx4 v[170:171], v[144:147] sc1
	flat_store_dwordx4 v[170:171], v[148:151] offset:16 sc1
	s_nop 1
	v_pk_mul_f32 v[148:149], v[108:109], v[168:169] op_sel_hi:[1,0]
	v_pk_mul_f32 v[150:151], v[110:111], v[168:169] op_sel_hi:[1,0]
	v_pk_mul_f32 v[146:147], v[106:107], v[168:169] op_sel_hi:[1,0]
	v_pk_mul_f32 v[144:145], v[104:105], v[168:169] op_sel_hi:[1,0]
	v_min_f32_e32 v168, 0, v148
	v_mul_f32_e64 v148, |v148|, s57
	v_exp_f32_e32 v148, v148
	s_nop 0
	v_add_f32_e32 v148, 1.0, v148
	v_cmp_gt_f32_e64 s[40:41], s97, v148
	s_nop 1
	v_cndmask_b32_e64 v194, 0, 32, s[40:41]
	v_ldexp_f32 v148, v148, v194
	v_log_f32_e32 v148, v148
	s_nop 0
	v_mul_f32_e32 v194, 0x3f317217, v148
	v_fma_f32 v194, v148, s52, -v194
;     __device__ __forceinline__ void operator()(const f32x4 (&acc)[2][2][4][2], const pg8::Unit& u, int wr, int wc, int fr, int fq) const {
;     ...
;             WIN_LOOP( _Pragma("unroll") for (int i = 0; i < 4; ++i) { const float s0 = fminf(a[i], 0.f) - __logf(1.f + __expf(-fabsf(a[i]))), s1 = fminf(b[i], 0.f) - __logf(1.f + __expf(-fabsf(b[i]))); const float la = l0[bj][i], lbv = l1[bj][i];
;                     a[i] = la > 0.f ? __logf(la + (1.f - la) * __expf(s0)) : s0; b[i] = lbv > 0.f ? __logf(lbv + (1.f - lbv) * __expf(s1)) : s1; }
	v_fmac_f32_e32 v194, 0x3377d1cf, v148
	v_fmac_f32_e32 v194, 0x3f317217, v148
	v_cmp_lt_f32_e64 s[42:43], |v148|, s53
	s_nop 1
	v_cndmask_b32_e64 v148, v148, v194, s[42:43]
	v_cndmask_b32_e64 v194, 0, v216, s[40:41]
	v_sub_f32_e32 v148, v148, v194
	v_sub_f32_e32 v148, v168, v148
	v_min_f32_e32 v168, 0, v144
	v_mul_f32_e64 v144, |v144|, s57
	v_exp_f32_e32 v144, v144
	s_nop 0
	v_add_f32_e32 v144, 1.0, v144
	v_cmp_gt_f32_e64 s[40:41], s97, v144
	s_nop 1
	v_cndmask_b32_e64 v194, 0, 32, s[40:41]
	v_ldexp_f32 v144, v144, v194
	v_log_f32_e32 v144, v144
	s_nop 0
	v_mul_f32_e32 v194, 0x3f317217, v144
	v_fma_f32 v194, v144, s52, -v194
	v_fmac_f32_e32 v194, 0x3377d1cf, v144
	v_fmac_f32_e32 v194, 0x3f317217, v144
	v_cmp_lt_f32_e64 s[42:43], |v144|, s53
	s_nop 1
	v_cndmask_b32_e64 v144, v144, v194, s[42:43]
	v_cndmask_b32_e64 v194, 0, v216, s[40:41]
	v_sub_f32_e32 v144, v144, v194
	v_sub_f32_e32 v168, v168, v144
	v_mul_f32_e32 v144, 0x3fb8aa3b, v148
	v_exp_f32_e32 v144, v144
	s_nop 0
	v_fma_f32 v144, v183, v144, v132
	v_cmp_gt_f32_e64 s[40:41], s97, v144
	s_nop 1
	v_cndmask_b32_e64 v194, 0, 32, s[40:41]
	v_ldexp_f32 v144, v144, v194
	v_log_f32_e32 v144, v144
	s_nop 0
	v_mul_f32_e32 v194, 0x3f317217, v144
	v_fma_f32 v194, v144, s52, -v194
	v_fmac_f32_e32 v194, 0x3377d1cf, v144
	v_fmac_f32_e32 v194, 0x3f317217, v144
	v_cmp_lt_f32_e64 s[42:43], |v144|, s53
	s_nop 1
	v_cndmask_b32_e64 v144, v144, v194, s[42:43]
	v_cndmask_b32_e64 v194, 0, v216, s[40:41]
	v_sub_f32_e32 v144, v144, v194
	v_cndmask_b32_e64 v144, v148, v144, s[20:21]
	v_mul_f32_e32 v148, 0x3fb8aa3b, v168
	v_exp_f32_e32 v148, v148
	s_nop 0
	v_fma_f32 v148, v182, v148, v128
	v_cmp_gt_f32_e64 s[40:41], s97, v148
	s_nop 1
	v_cndmask_b32_e64 v194, 0, 32, s[40:41]
	v_ldexp_f32 v148, v148, v194
	v_log_f32_e32 v148, v148
	s_nop 0
	v_mul_f32_e32 v194, 0x3f317217, v148
	v_fma_f32 v194, v148, s52, -v194
	v_fmac_f32_e32 v194, 0x3377d1cf, v148
	v_fmac_f32_e32 v194, 0x3f317217, v148
	v_cmp_lt_f32_e64 s[42:43], |v148|, s53
	s_nop 1
	v_cndmask_b32_e64 v148, v148, v194, s[42:43]
	v_cndmask_b32_e64 v194, 0, v216, s[40:41]
	v_sub_f32_e32 v148, v148, v194
	v_cndmask_b32_e64 v148, v168, v148, s[18:19]
	v_min_f32_e32 v168, 0, v149
	v_mul_f32_e64 v149, |v149|, s57
	v_exp_f32_e32 v149, v149
	s_nop 0
	v_add_f32_e32 v149, 1.0, v149
	v_cmp_gt_f32_e64 s[40:41], s97, v149
	s_nop 1
	v_cndmask_b32_e64 v194, 0, 32, s[40:41]
	v_ldexp_f32 v149, v149, v194
	v_log_f32_e32 v149, v149
	s_nop 0
	v_mul_f32_e32 v194, 0x3f317217, v149
	v_fma_f32 v194, v149, s52, -v194
	v_fmac_f32_e32 v194, 0x3377d1cf, v149
	v_fmac_f32_e32 v194, 0x3f317217, v149
	v_cmp_lt_f32_e64 s[42:43], |v149|, s53
	s_nop 1
	v_cndmask_b32_e64 v149, v149, v194, s[42:43]
	v_cndmask_b32_e64 v194, 0, v216, s[40:41]
	v_sub_f32_e32 v149, v149, v194
	v_sub_f32_e32 v149, v168, v149
	v_min_f32_e32 v168, 0, v145
	v_mul_f32_e64 v145, |v145|, s57
	v_exp_f32_e32 v145, v145
	s_nop 0
	v_add_f32_e32 v145, 1.0, v145
	v_cmp_gt_f32_e64 s[40:41], s97, v145
	s_nop 1
	v_cndmask_b32_e64 v194, 0, 32, s[40:41]
	v_ldexp_f32 v145, v145, v194
	v_log_f32_e32 v145, v145
	s_nop 0
	v_mul_f32_e32 v194, 0x3f317217, v145
	v_fma_f32 v194, v145, s52, -v194
	v_fmac_f32_e32 v194, 0x3377d1cf, v145
	v_fmac_f32_e32 v194, 0x3f317217, v145
	v_cmp_lt_f32_e64 s[42:43], |v145|, s53
	s_nop 1
	v_cndmask_b32_e64 v145, v145, v194, s[42:43]
	v_cndmask_b32_e64 v194, 0, v216, s[40:41]
	v_sub_f32_e32 v145, v145, v194
	v_sub_f32_e32 v168, v168, v145
	v_mul_f32_e32 v145, 0x3fb8aa3b, v149
	v_exp_f32_e32 v145, v145
	s_nop 0
	v_fma_f32 v145, v181, v145, v133
	v_cmp_gt_f32_e64 s[40:41], s97, v145
	s_nop 1
	v_cndmask_b32_e64 v194, 0, 32, s[40:41]
	v_ldexp_f32 v145, v145, v194
	v_log_f32_e32 v145, v145
	s_nop 0
	v_mul_f32_e32 v194, 0x3f317217, v145
	v_fma_f32 v194, v145, s52, -v194
	v_fmac_f32_e32 v194, 0x3377d1cf, v145
	v_fmac_f32_e32 v194, 0x3f317217, v145
	v_cmp_lt_f32_e64 s[42:43], |v145|, s53
	s_nop 1
	v_cndmask_b32_e64 v145, v145, v194, s[42:43]
	v_cndmask_b32_e64 v194, 0, v216, s[40:41]
	v_sub_f32_e32 v145, v145, v194
	v_cndmask_b32_e64 v145, v149, v145, s[16:17]
	v_mul_f32_e32 v149, 0x3fb8aa3b, v168
	v_exp_f32_e32 v149, v149
	s_nop 0
	v_fma_f32 v149, v180, v149, v129
	v_cmp_gt_f32_e64 s[40:41], s97, v149
	s_nop 1
	v_cndmask_b32_e64 v194, 0, 32, s[40:41]
	v_ldexp_f32 v149, v149, v194
	v_log_f32_e32 v149, v149
	s_nop 0
	v_mul_f32_e32 v194, 0x3f317217, v149
	v_fma_f32 v194, v149, s52, -v194
	v_fmac_f32_e32 v194, 0x3377d1cf, v149
	v_fmac_f32_e32 v194, 0x3f317217, v149
	v_cmp_lt_f32_e64 s[42:43], |v149|, s53
	s_nop 1
	v_cndmask_b32_e64 v149, v149, v194, s[42:43]
	v_cndmask_b32_e64 v194, 0, v216, s[40:41]
	v_sub_f32_e32 v149, v149, v194
	v_cndmask_b32_e64 v149, v168, v149, s[14:15]
	v_min_f32_e32 v168, 0, v150
	v_mul_f32_e64 v150, |v150|, s57
	v_exp_f32_e32 v150, v150
	s_nop 0
	v_add_f32_e32 v150, 1.0, v150
	v_cmp_gt_f32_e64 s[40:41], s97, v150
	s_nop 1
	v_cndmask_b32_e64 v194, 0, 32, s[40:41]
	v_ldexp_f32 v150, v150, v194
	v_log_f32_e32 v150, v150
	s_nop 0
	v_mul_f32_e32 v194, 0x3f317217, v150
	v_fma_f32 v194, v150, s52, -v194
	v_fmac_f32_e32 v194, 0x3377d1cf, v150
	v_fmac_f32_e32 v194, 0x3f317217, v150
	v_cmp_lt_f32_e64 s[42:43], |v150|, s53
	s_nop 1
	v_cndmask_b32_e64 v150, v150, v194, s[42:43]
	v_cndmask_b32_e64 v194, 0, v216, s[40:41]
	v_sub_f32_e32 v150, v150, v194
	v_sub_f32_e32 v150, v168, v150
	v_min_f32_e32 v168, 0, v146
	v_mul_f32_e64 v146, |v146|, s57
	v_exp_f32_e32 v146, v146
	s_nop 0
	v_add_f32_e32 v146, 1.0, v146
	v_cmp_gt_f32_e64 s[40:41], s97, v146
	s_nop 1
	v_cndmask_b32_e64 v194, 0, 32, s[40:41]
	v_ldexp_f32 v146, v146, v194
	v_log_f32_e32 v146, v146
	s_nop 0
	v_mul_f32_e32 v194, 0x3f317217, v146
; __device__ __forceinline__ float row_rstd(const float* ssq, int row, int fq) {
;     const f32x4 v = *(const f32x4*)(ssq + (size_t)row * 16 + fq * 4);
;     float s = (v[0] + v[1]) + (v[2] + v[3]);
;     s += __shfl_xor(s, 16); s += __shfl_xor(s, 32);
;     return __builtin_amdgcn_rsqf(s * (1.f / DM) + EPS);
; }
;     __device__ __forceinline__ void operator()(const f32x4 (&acc)[2][2][4][2], const pg8::Unit& u, int wr, int wc, int fr, int fq) const {
;     ...
;             WIN_LOOP( _Pragma("unroll") for (int i = 0; i < 4; ++i) { const float s0 = fminf(a[i], 0.f) - __logf(1.f + __expf(-fabsf(a[i]))), s1 = fminf(b[i], 0.f) - __logf(1.f + __expf(-fabsf(b[i]))); const float la = l0[bj][i], lbv = l1[bj][i];
;                     a[i] = la > 0.f ? __logf(la + (1.f - la) * __expf(s0)) : s0; b[i] = lbv > 0.f ? __logf(lbv + (1.f - lbv) * __expf(s1)) : s1; }
;                 *(f32x4*)(LF + (size_t)row * 512 + c) = a; *(f32x4*)(LF + (size_t)row * 512 + c + 4) = b; __builtin_amdgcn_sched_barrier(0); ) }
	v_fma_f32 v194, v146, s52, -v194
	v_fmac_f32_e32 v194, 0x3377d1cf, v146
	v_fmac_f32_e32 v194, 0x3f317217, v146
	v_cmp_lt_f32_e64 s[42:43], |v146|, s53
	s_nop 1
	v_cndmask_b32_e64 v146, v146, v194, s[42:43]
	v_cndmask_b32_e64 v194, 0, v216, s[40:41]
	v_sub_f32_e32 v146, v146, v194
	v_sub_f32_e32 v168, v168, v146
	v_mul_f32_e32 v146, 0x3fb8aa3b, v150
	v_exp_f32_e32 v146, v146
	s_nop 0
	v_fma_f32 v146, v179, v146, v134
	v_cmp_gt_f32_e64 s[40:41], s97, v146
	s_nop 1
	v_cndmask_b32_e64 v194, 0, 32, s[40:41]
	v_ldexp_f32 v146, v146, v194
	v_log_f32_e32 v146, v146
	s_nop 0
	v_mul_f32_e32 v194, 0x3f317217, v146
	v_fma_f32 v194, v146, s52, -v194
	v_fmac_f32_e32 v194, 0x3377d1cf, v146
	v_fmac_f32_e32 v194, 0x3f317217, v146
	v_cmp_lt_f32_e64 s[42:43], |v146|, s53
	s_nop 1
	v_cndmask_b32_e64 v146, v146, v194, s[42:43]
	v_cndmask_b32_e64 v194, 0, v216, s[40:41]
	v_sub_f32_e32 v146, v146, v194
	v_cndmask_b32_e64 v146, v150, v146, s[12:13]
	v_mul_f32_e32 v150, 0x3fb8aa3b, v168
	v_exp_f32_e32 v150, v150
	s_nop 0
	v_fma_f32 v150, v178, v150, v130
	v_cmp_gt_f32_e64 s[40:41], s97, v150
	s_nop 1
	v_cndmask_b32_e64 v194, 0, 32, s[40:41]
	v_ldexp_f32 v150, v150, v194
	v_log_f32_e32 v150, v150
	s_nop 0
	v_mul_f32_e32 v194, 0x3f317217, v150
	v_fma_f32 v194, v150, s52, -v194
	v_fmac_f32_e32 v194, 0x3377d1cf, v150
	v_fmac_f32_e32 v194, 0x3f317217, v150
	v_cmp_lt_f32_e64 s[42:43], |v150|, s53
	s_nop 1
	v_cndmask_b32_e64 v150, v150, v194, s[42:43]
	v_cndmask_b32_e64 v194, 0, v216, s[40:41]
	v_sub_f32_e32 v150, v150, v194
	v_cndmask_b32_e64 v150, v168, v150, s[10:11]
	v_min_f32_e32 v168, 0, v151
	v_mul_f32_e64 v151, |v151|, s57
	v_exp_f32_e32 v151, v151
	s_nop 0
	v_add_f32_e32 v151, 1.0, v151
	v_cmp_gt_f32_e64 s[40:41], s97, v151
	s_nop 1
	v_cndmask_b32_e64 v194, 0, 32, s[40:41]
	v_ldexp_f32 v151, v151, v194
	v_log_f32_e32 v151, v151
	s_nop 0
	v_mul_f32_e32 v194, 0x3f317217, v151
	v_fma_f32 v194, v151, s52, -v194
	v_fmac_f32_e32 v194, 0x3377d1cf, v151
	v_fmac_f32_e32 v194, 0x3f317217, v151
	v_cmp_lt_f32_e64 s[42:43], |v151|, s53
	s_nop 1
	v_cndmask_b32_e64 v151, v151, v194, s[42:43]
	v_cndmask_b32_e64 v194, 0, v216, s[40:41]
	v_sub_f32_e32 v151, v151, v194
	v_sub_f32_e32 v151, v168, v151
	v_min_f32_e32 v168, 0, v147
	v_mul_f32_e64 v147, |v147|, s57
	v_exp_f32_e32 v147, v147
	s_nop 0
	v_add_f32_e32 v147, 1.0, v147
	v_cmp_gt_f32_e64 s[40:41], s97, v147
	s_nop 1
	v_cndmask_b32_e64 v194, 0, 32, s[40:41]
	v_ldexp_f32 v147, v147, v194
	v_log_f32_e32 v147, v147
	s_nop 0
	v_mul_f32_e32 v194, 0x3f317217, v147
	v_fma_f32 v194, v147, s52, -v194
	v_fmac_f32_e32 v194, 0x3377d1cf, v147
	v_fmac_f32_e32 v194, 0x3f317217, v147
	v_cmp_lt_f32_e64 s[42:43], |v147|, s53
	s_nop 1
	v_cndmask_b32_e64 v147, v147, v194, s[42:43]
	v_cndmask_b32_e64 v194, 0, v216, s[40:41]
	v_sub_f32_e32 v147, v147, v194
	v_sub_f32_e32 v168, v168, v147
	v_mul_f32_e32 v147, 0x3fb8aa3b, v151
	v_exp_f32_e32 v147, v147
	s_nop 0
	v_fma_f32 v147, v177, v147, v135
	v_cmp_gt_f32_e64 s[40:41], s97, v147
	s_nop 1
	v_cndmask_b32_e64 v194, 0, 32, s[40:41]
	v_ldexp_f32 v147, v147, v194
	v_log_f32_e32 v147, v147
	s_nop 0
	v_mul_f32_e32 v194, 0x3f317217, v147
	v_fma_f32 v194, v147, s52, -v194
	v_fmac_f32_e32 v194, 0x3377d1cf, v147
	v_fmac_f32_e32 v194, 0x3f317217, v147
	v_cmp_lt_f32_e64 s[42:43], |v147|, s53
	s_nop 1
	v_cndmask_b32_e64 v147, v147, v194, s[42:43]
	v_cndmask_b32_e64 v194, 0, v216, s[40:41]
	v_sub_f32_e32 v147, v147, v194
	v_cndmask_b32_e64 v147, v151, v147, s[8:9]
	v_mul_f32_e32 v151, 0x3fb8aa3b, v168
	v_exp_f32_e32 v151, v151
	s_nop 0
	v_fma_f32 v151, v167, v151, v131
	v_cmp_gt_f32_e64 s[40:41], s97, v151
	s_nop 1
	v_cndmask_b32_e64 v194, 0, 32, s[40:41]
	v_ldexp_f32 v151, v151, v194
	v_log_f32_e32 v151, v151
	s_nop 0
	v_mul_f32_e32 v194, 0x3f317217, v151
	v_fma_f32 v194, v151, s52, -v194
	v_fmac_f32_e32 v194, 0x3377d1cf, v151
	v_fmac_f32_e32 v194, 0x3f317217, v151
	v_cmp_lt_f32_e64 s[42:43], |v151|, s53
	s_nop 1
	v_cndmask_b32_e64 v151, v151, v194, s[42:43]
	v_cndmask_b32_e64 v194, 0, v216, s[40:41]
	v_sub_f32_e32 v151, v151, v194
	v_cndmask_b32_e32 v151, v168, v151, vcc
	flat_store_dwordx4 v[170:171], v[144:147] offset:512 sc1
	flat_store_dwordx4 v[170:171], v[148:151] offset:528 sc1
	s_nop 1
	v_or_b32_e32 v148, 48, v166
	v_ashrrev_i32_e32 v149, 31, v148
	v_lshlrev_b64 v[144:145], 6, v[148:149]
	v_lshl_add_u64 v[144:145], v[160:161], 0, v[144:145]
	flat_load_dwordx4 v[144:147], v[144:145]
	s_waitcnt vmcnt(0) lgkmcnt(0)
	v_mov_b32_e32 v150, v145
	v_mov_b32_e32 v151, v146
	v_mov_b32_e32 v145, v147
	v_pk_add_f32 v[144:145], v[150:151], v[144:145]
	s_nop 0
	v_add_f32_e32 v144, v144, v145
	ds_bpermute_b32 v145, v169, v144
	s_waitcnt lgkmcnt(0)
	v_add_f32_e32 v144, v144, v145
	ds_bpermute_b32 v145, v202, v144
	s_waitcnt lgkmcnt(0)
; __device__ __forceinline__ float row_rstd(const float* ssq, int row, int fq) {
;     const f32x4 v = *(const f32x4*)(ssq + (size_t)row * 16 + fq * 4);
;     float s = (v[0] + v[1]) + (v[2] + v[3]);
;     s += __shfl_xor(s, 16); s += __shfl_xor(s, 32);
;     return __builtin_amdgcn_rsqf(s * (1.f / DM) + EPS);
; }
;     __device__ __forceinline__ void operator()(const f32x4 (&acc)[2][2][4][2], const pg8::Unit& u, int wr, int wc, int fr, int fq) const {
;     ...
;             WIN_LOOP( _Pragma("unroll") for (int i = 0; i < 4; ++i) { const float s0 = fminf(a[i], 0.f) - __logf(1.f + __expf(-fabsf(a[i]))), s1 = fminf(b[i], 0.f) - __logf(1.f + __expf(-fabsf(b[i]))); const float la = l0[bj][i], lbv = l1[bj][i];
;                     a[i] = la > 0.f ? __logf(la + (1.f - la) * __expf(s0)) : s0; b[i] = lbv > 0.f ? __logf(lbv + (1.f - lbv) * __expf(s1)) : s1; }
	v_add_f32_e32 v144, v144, v145
	v_fmamk_f32 v144, v144, 0x3a800000, v212
	v_rsq_f32_e32 v168, v144
	v_lshlrev_b64 v[144:145], 11, v[148:149]
	v_lshl_add_u64 v[170:171], s[50:51], 0, v[144:145]
	v_lshl_add_u64 v[170:171], v[170:171], 0, v[192:193]
	v_pk_mul_f32 v[148:149], v[36:37], v[168:169] op_sel_hi:[1,0]
	v_pk_mul_f32 v[144:145], v[32:33], v[168:169] op_sel_hi:[1,0]
	v_min_f32_e32 v194, 0, v148
	v_mul_f32_e64 v148, |v148|, s57
	v_exp_f32_e32 v148, v148
	v_pk_mul_f32 v[150:151], v[38:39], v[168:169] op_sel_hi:[1,0]
	v_pk_mul_f32 v[146:147], v[34:35], v[168:169] op_sel_hi:[1,0]
	v_add_f32_e32 v148, 1.0, v148
	v_cmp_gt_f32_e64 s[40:41], s97, v148
	s_nop 1
	v_cndmask_b32_e64 v195, 0, 32, s[40:41]
	v_ldexp_f32 v148, v148, v195
	v_log_f32_e32 v148, v148
	s_nop 0
	v_mul_f32_e32 v195, 0x3f317217, v148
	v_fma_f32 v195, v148, s52, -v195
	v_fmac_f32_e32 v195, 0x3377d1cf, v148
	v_fmac_f32_e32 v195, 0x3f317217, v148
	v_cmp_lt_f32_e64 s[42:43], |v148|, s53
	s_nop 1
	v_cndmask_b32_e64 v148, v148, v195, s[42:43]
	v_cndmask_b32_e64 v195, 0, v216, s[40:41]
	v_sub_f32_e32 v148, v148, v195
	v_sub_f32_e32 v148, v194, v148
	v_min_f32_e32 v194, 0, v144
	v_mul_f32_e64 v144, |v144|, s57
	v_exp_f32_e32 v144, v144
	s_nop 0
	v_add_f32_e32 v144, 1.0, v144
	v_cmp_gt_f32_e64 s[40:41], s97, v144
	s_nop 1
	v_cndmask_b32_e64 v195, 0, 32, s[40:41]
	v_ldexp_f32 v144, v144, v195
	v_log_f32_e32 v144, v144
	s_nop 0
	v_mul_f32_e32 v195, 0x3f317217, v144
	v_fma_f32 v195, v144, s52, -v195
	v_fmac_f32_e32 v195, 0x3377d1cf, v144
	v_fmac_f32_e32 v195, 0x3f317217, v144
	v_cmp_lt_f32_e64 s[42:43], |v144|, s53
	s_nop 1
	v_cndmask_b32_e64 v144, v144, v195, s[42:43]
	v_cndmask_b32_e64 v195, 0, v216, s[40:41]
	v_sub_f32_e32 v144, v144, v195
	v_sub_f32_e32 v194, v194, v144
	v_mul_f32_e32 v144, 0x3fb8aa3b, v148
	v_exp_f32_e32 v144, v144
	s_nop 0
	v_fma_f32 v144, v190, v144, v140
	v_cmp_gt_f32_e64 s[40:41], s97, v144
	s_nop 1
	v_cndmask_b32_e64 v195, 0, 32, s[40:41]
	v_ldexp_f32 v144, v144, v195
	v_log_f32_e32 v144, v144
	s_nop 0
	v_mul_f32_e32 v195, 0x3f317217, v144
	v_fma_f32 v195, v144, s52, -v195
	v_fmac_f32_e32 v195, 0x3377d1cf, v144
	v_fmac_f32_e32 v195, 0x3f317217, v144
	v_cmp_lt_f32_e64 s[42:43], |v144|, s53
	s_nop 1
	v_cndmask_b32_e64 v144, v144, v195, s[42:43]
	v_cndmask_b32_e64 v195, 0, v216, s[40:41]
	v_sub_f32_e32 v144, v144, v195
	v_cndmask_b32_e64 v144, v148, v144, s[38:39]
	v_mul_f32_e32 v148, 0x3fb8aa3b, v194
	v_exp_f32_e32 v148, v148
	s_nop 0
	v_fma_f32 v148, v191, v148, v136
	v_cmp_gt_f32_e64 s[40:41], s97, v148
	s_nop 1
	v_cndmask_b32_e64 v195, 0, 32, s[40:41]
	v_ldexp_f32 v148, v148, v195
	v_log_f32_e32 v148, v148
	s_nop 0
	v_mul_f32_e32 v195, 0x3f317217, v148
	v_fma_f32 v195, v148, s52, -v195
	v_fmac_f32_e32 v195, 0x3377d1cf, v148
	v_fmac_f32_e32 v195, 0x3f317217, v148
	v_cmp_lt_f32_e64 s[42:43], |v148|, s53
	s_nop 1
	v_cndmask_b32_e64 v148, v148, v195, s[42:43]
	v_cndmask_b32_e64 v195, 0, v216, s[40:41]
	v_sub_f32_e32 v148, v148, v195
	v_cndmask_b32_e64 v148, v194, v148, s[36:37]
	v_min_f32_e32 v194, 0, v149
	v_mul_f32_e64 v149, |v149|, s57
	v_exp_f32_e32 v149, v149
	s_nop 0
	v_add_f32_e32 v149, 1.0, v149
	v_cmp_gt_f32_e64 s[40:41], s97, v149
	s_nop 1
	v_cndmask_b32_e64 v195, 0, 32, s[40:41]
	v_ldexp_f32 v149, v149, v195
	v_log_f32_e32 v149, v149
	s_nop 0
	v_mul_f32_e32 v195, 0x3f317217, v149
	v_fma_f32 v195, v149, s52, -v195
	v_fmac_f32_e32 v195, 0x3377d1cf, v149
	v_fmac_f32_e32 v195, 0x3f317217, v149
	v_cmp_lt_f32_e64 s[42:43], |v149|, s53
	s_nop 1
	v_cndmask_b32_e64 v149, v149, v195, s[42:43]
	v_cndmask_b32_e64 v195, 0, v216, s[40:41]
	v_sub_f32_e32 v149, v149, v195
	v_sub_f32_e32 v149, v194, v149
	v_min_f32_e32 v194, 0, v145
	v_mul_f32_e64 v145, |v145|, s57
	v_exp_f32_e32 v145, v145
	s_nop 0
	v_add_f32_e32 v145, 1.0, v145
	v_cmp_gt_f32_e64 s[40:41], s97, v145
	s_nop 1
	v_cndmask_b32_e64 v195, 0, 32, s[40:41]
	v_ldexp_f32 v145, v145, v195
	v_log_f32_e32 v145, v145
	s_nop 0
	v_mul_f32_e32 v195, 0x3f317217, v145
	v_fma_f32 v195, v145, s52, -v195
	v_fmac_f32_e32 v195, 0x3377d1cf, v145
	v_fmac_f32_e32 v195, 0x3f317217, v145
	v_cmp_lt_f32_e64 s[42:43], |v145|, s53
	s_nop 1
	v_cndmask_b32_e64 v145, v145, v195, s[42:43]
	v_cndmask_b32_e64 v195, 0, v216, s[40:41]
	v_sub_f32_e32 v145, v145, v195
	v_sub_f32_e32 v194, v194, v145
	v_mul_f32_e32 v145, 0x3fb8aa3b, v149
	v_exp_f32_e32 v145, v145
	s_nop 0
	v_fma_f32 v145, v188, v145, v141
	v_cmp_gt_f32_e64 s[40:41], s97, v145
	s_nop 1
	v_cndmask_b32_e64 v195, 0, 32, s[40:41]
	v_ldexp_f32 v145, v145, v195
	v_log_f32_e32 v145, v145
	s_nop 0
	v_mul_f32_e32 v195, 0x3f317217, v145
	v_fma_f32 v195, v145, s52, -v195
	v_fmac_f32_e32 v195, 0x3377d1cf, v145
	v_fmac_f32_e32 v195, 0x3f317217, v145
	v_cmp_lt_f32_e64 s[42:43], |v145|, s53
	s_nop 1
	v_cndmask_b32_e64 v145, v145, v195, s[42:43]
	v_cndmask_b32_e64 v195, 0, v216, s[40:41]
	v_sub_f32_e32 v145, v145, v195
	v_cndmask_b32_e64 v145, v149, v145, s[34:35]
	v_mul_f32_e32 v149, 0x3fb8aa3b, v194
	v_exp_f32_e32 v149, v149
	s_nop 0
	v_fma_f32 v149, v189, v149, v137
	v_cmp_gt_f32_e64 s[40:41], s97, v149
	s_nop 1
	v_cndmask_b32_e64 v195, 0, 32, s[40:41]
	v_ldexp_f32 v149, v149, v195
	v_log_f32_e32 v149, v149
	s_nop 0
	v_mul_f32_e32 v195, 0x3f317217, v149
	v_fma_f32 v195, v149, s52, -v195
	v_fmac_f32_e32 v195, 0x3377d1cf, v149
	v_fmac_f32_e32 v195, 0x3f317217, v149
	v_cmp_lt_f32_e64 s[42:43], |v149|, s53
	s_nop 1
	v_cndmask_b32_e64 v149, v149, v195, s[42:43]
	v_cndmask_b32_e64 v195, 0, v216, s[40:41]
	v_sub_f32_e32 v149, v149, v195
	v_cndmask_b32_e64 v149, v194, v149, s[30:31]
	v_min_f32_e32 v194, 0, v150
	v_mul_f32_e64 v150, |v150|, s57
	v_exp_f32_e32 v150, v150
	s_nop 0
	v_add_f32_e32 v150, 1.0, v150
;     __device__ __forceinline__ void operator()(const f32x4 (&acc)[2][2][4][2], const pg8::Unit& u, int wr, int wc, int fr, int fq) const {
;     ...
;             WIN_LOOP( _Pragma("unroll") for (int i = 0; i < 4; ++i) { const float s0 = fminf(a[i], 0.f) - __logf(1.f + __expf(-fabsf(a[i]))), s1 = fminf(b[i], 0.f) - __logf(1.f + __expf(-fabsf(b[i]))); const float la = l0[bj][i], lbv = l1[bj][i];
;                     a[i] = la > 0.f ? __logf(la + (1.f - la) * __expf(s0)) : s0; b[i] = lbv > 0.f ? __logf(lbv + (1.f - lbv) * __expf(s1)) : s1; }
;                 *(f32x4*)(LF + (size_t)row * 512 + c) = a; *(f32x4*)(LF + (size_t)row * 512 + c + 4) = b; __builtin_amdgcn_sched_barrier(0); ) }
	v_cmp_gt_f32_e64 s[40:41], s97, v150
	s_nop 1
	v_cndmask_b32_e64 v195, 0, 32, s[40:41]
	v_ldexp_f32 v150, v150, v195
	v_log_f32_e32 v150, v150
	s_nop 0
	v_mul_f32_e32 v195, 0x3f317217, v150
	v_fma_f32 v195, v150, s52, -v195
	v_fmac_f32_e32 v195, 0x3377d1cf, v150
	v_fmac_f32_e32 v195, 0x3f317217, v150
	v_cmp_lt_f32_e64 s[42:43], |v150|, s53
	s_nop 1
	v_cndmask_b32_e64 v150, v150, v195, s[42:43]
	v_cndmask_b32_e64 v195, 0, v216, s[40:41]
	v_sub_f32_e32 v150, v150, v195
	v_sub_f32_e32 v150, v194, v150
	v_min_f32_e32 v194, 0, v146
	v_mul_f32_e64 v146, |v146|, s57
	v_exp_f32_e32 v146, v146
	s_nop 0
	v_add_f32_e32 v146, 1.0, v146
	v_cmp_gt_f32_e64 s[40:41], s97, v146
	s_nop 1
	v_cndmask_b32_e64 v195, 0, 32, s[40:41]
	v_ldexp_f32 v146, v146, v195
	v_log_f32_e32 v146, v146
	s_nop 0
	v_mul_f32_e32 v195, 0x3f317217, v146
	v_fma_f32 v195, v146, s52, -v195
	v_fmac_f32_e32 v195, 0x3377d1cf, v146
	v_fmac_f32_e32 v195, 0x3f317217, v146
	v_cmp_lt_f32_e64 s[42:43], |v146|, s53
	s_nop 1
	v_cndmask_b32_e64 v146, v146, v195, s[42:43]
	v_cndmask_b32_e64 v195, 0, v216, s[40:41]
	v_sub_f32_e32 v146, v146, v195
	v_sub_f32_e32 v194, v194, v146
	v_mul_f32_e32 v146, 0x3fb8aa3b, v150
	v_exp_f32_e32 v146, v146
	s_nop 0
	v_fma_f32 v146, v187, v146, v142
	v_cmp_gt_f32_e64 s[40:41], s97, v146
	s_nop 1
	v_cndmask_b32_e64 v195, 0, 32, s[40:41]
	v_ldexp_f32 v146, v146, v195
	v_log_f32_e32 v146, v146
	s_nop 0
	v_mul_f32_e32 v195, 0x3f317217, v146
	v_fma_f32 v195, v146, s52, -v195
	v_fmac_f32_e32 v195, 0x3377d1cf, v146
	v_fmac_f32_e32 v195, 0x3f317217, v146
	v_cmp_lt_f32_e64 s[42:43], |v146|, s53
	s_nop 1
	v_cndmask_b32_e64 v146, v146, v195, s[42:43]
	v_cndmask_b32_e64 v195, 0, v216, s[40:41]
	v_sub_f32_e32 v146, v146, v195
	v_cndmask_b32_e64 v146, v150, v146, s[28:29]
	v_mul_f32_e32 v150, 0x3fb8aa3b, v194
	v_exp_f32_e32 v150, v150
	s_nop 0
	v_fma_f32 v150, v186, v150, v138
	v_cmp_gt_f32_e64 s[40:41], s97, v150
	s_nop 1
	v_cndmask_b32_e64 v195, 0, 32, s[40:41]
	v_ldexp_f32 v150, v150, v195
	v_log_f32_e32 v150, v150
	s_nop 0
	v_mul_f32_e32 v195, 0x3f317217, v150
	v_fma_f32 v195, v150, s52, -v195
	v_fmac_f32_e32 v195, 0x3377d1cf, v150
	v_fmac_f32_e32 v195, 0x3f317217, v150
	v_cmp_lt_f32_e64 s[42:43], |v150|, s53
	s_nop 1
	v_cndmask_b32_e64 v150, v150, v195, s[42:43]
	v_cndmask_b32_e64 v195, 0, v216, s[40:41]
	v_sub_f32_e32 v150, v150, v195
	v_cndmask_b32_e64 v150, v194, v150, s[26:27]
	v_min_f32_e32 v194, 0, v151
	v_mul_f32_e64 v151, |v151|, s57
	v_exp_f32_e32 v151, v151
	s_nop 0
	v_add_f32_e32 v151, 1.0, v151
	v_cmp_gt_f32_e64 s[40:41], s97, v151
	s_nop 1
	v_cndmask_b32_e64 v195, 0, 32, s[40:41]
	v_ldexp_f32 v151, v151, v195
	v_log_f32_e32 v151, v151
	s_nop 0
	v_mul_f32_e32 v195, 0x3f317217, v151
	v_fma_f32 v195, v151, s52, -v195
	v_fmac_f32_e32 v195, 0x3377d1cf, v151
	v_fmac_f32_e32 v195, 0x3f317217, v151
	v_cmp_lt_f32_e64 s[42:43], |v151|, s53
	s_nop 1
	v_cndmask_b32_e64 v151, v151, v195, s[42:43]
	v_cndmask_b32_e64 v195, 0, v216, s[40:41]
	v_sub_f32_e32 v151, v151, v195
	v_sub_f32_e32 v151, v194, v151
	v_min_f32_e32 v194, 0, v147
	v_mul_f32_e64 v147, |v147|, s57
	v_exp_f32_e32 v147, v147
	s_nop 0
	v_add_f32_e32 v147, 1.0, v147
	v_cmp_gt_f32_e64 s[40:41], s97, v147
	s_nop 1
	v_cndmask_b32_e64 v195, 0, 32, s[40:41]
	v_ldexp_f32 v147, v147, v195
	v_log_f32_e32 v147, v147
	s_nop 0
	v_mul_f32_e32 v195, 0x3f317217, v147
	v_fma_f32 v195, v147, s52, -v195
	v_fmac_f32_e32 v195, 0x3377d1cf, v147
	v_fmac_f32_e32 v195, 0x3f317217, v147
	v_cmp_lt_f32_e64 s[42:43], |v147|, s53
	s_nop 1
	v_cndmask_b32_e64 v147, v147, v195, s[42:43]
	v_cndmask_b32_e64 v195, 0, v216, s[40:41]
	v_sub_f32_e32 v147, v147, v195
	v_sub_f32_e32 v194, v194, v147
	v_mul_f32_e32 v147, 0x3fb8aa3b, v151
	v_exp_f32_e32 v147, v147
	s_nop 0
	v_fma_f32 v147, v185, v147, v143
	v_cmp_gt_f32_e64 s[40:41], s97, v147
	s_nop 1
	v_cndmask_b32_e64 v195, 0, 32, s[40:41]
	v_ldexp_f32 v147, v147, v195
	v_log_f32_e32 v147, v147
	s_nop 0
	v_mul_f32_e32 v195, 0x3f317217, v147
	v_fma_f32 v195, v147, s52, -v195
	v_fmac_f32_e32 v195, 0x3377d1cf, v147
	v_fmac_f32_e32 v195, 0x3f317217, v147
	v_cmp_lt_f32_e64 s[42:43], |v147|, s53
	s_nop 1
	v_cndmask_b32_e64 v147, v147, v195, s[42:43]
	v_cndmask_b32_e64 v195, 0, v216, s[40:41]
	v_sub_f32_e32 v147, v147, v195
	v_cndmask_b32_e64 v147, v151, v147, s[24:25]
	v_mul_f32_e32 v151, 0x3fb8aa3b, v194
	v_exp_f32_e32 v151, v151
	s_nop 0
	v_fma_f32 v151, v184, v151, v139
	v_cmp_gt_f32_e64 s[40:41], s97, v151
	s_nop 1
	v_cndmask_b32_e64 v195, 0, 32, s[40:41]
	v_ldexp_f32 v151, v151, v195
	v_log_f32_e32 v151, v151
	s_nop 0
	v_mul_f32_e32 v195, 0x3f317217, v151
	v_fma_f32 v195, v151, s52, -v195
	v_fmac_f32_e32 v195, 0x3377d1cf, v151
	v_fmac_f32_e32 v195, 0x3f317217, v151
	v_cmp_lt_f32_e64 s[42:43], |v151|, s53
	s_nop 1
	v_cndmask_b32_e64 v151, v151, v195, s[42:43]
	v_cndmask_b32_e64 v195, 0, v216, s[40:41]
	v_sub_f32_e32 v151, v151, v195
	v_cndmask_b32_e64 v151, v194, v151, s[22:23]
	flat_store_dwordx4 v[170:171], v[144:147] sc1
	flat_store_dwordx4 v[170:171], v[148:151] offset:16 sc1
	s_nop 1
	v_pk_mul_f32 v[148:149], v[100:101], v[168:169] op_sel_hi:[1,0]
	v_pk_mul_f32 v[150:151], v[102:103], v[168:169] op_sel_hi:[1,0]
	v_pk_mul_f32 v[146:147], v[98:99], v[168:169] op_sel_hi:[1,0]
	v_pk_mul_f32 v[144:145], v[96:97], v[168:169] op_sel_hi:[1,0]
	v_min_f32_e32 v168, 0, v148
	v_mul_f32_e64 v148, |v148|, s57
	v_exp_f32_e32 v148, v148
	s_nop 0
	v_add_f32_e32 v148, 1.0, v148
	v_cmp_gt_f32_e64 s[40:41], s97, v148
	s_nop 1
	v_cndmask_b32_e64 v194, 0, 32, s[40:41]
	v_ldexp_f32 v148, v148, v194
	v_log_f32_e32 v148, v148
	s_nop 0
	v_mul_f32_e32 v194, 0x3f317217, v148
	v_fma_f32 v194, v148, s52, -v194
;     __device__ __forceinline__ void operator()(const f32x4 (&acc)[2][2][4][2], const pg8::Unit& u, int wr, int wc, int fr, int fq) const {
;     ...
;             WIN_LOOP( _Pragma("unroll") for (int i = 0; i < 4; ++i) { const float s0 = fminf(a[i], 0.f) - __logf(1.f + __expf(-fabsf(a[i]))), s1 = fminf(b[i], 0.f) - __logf(1.f + __expf(-fabsf(b[i]))); const float la = l0[bj][i], lbv = l1[bj][i];
;                     a[i] = la > 0.f ? __logf(la + (1.f - la) * __expf(s0)) : s0; b[i] = lbv > 0.f ? __logf(lbv + (1.f - lbv) * __expf(s1)) : s1; }
	v_fmac_f32_e32 v194, 0x3377d1cf, v148
	v_fmac_f32_e32 v194, 0x3f317217, v148
	v_cmp_lt_f32_e64 s[42:43], |v148|, s53
	s_nop 1
	v_cndmask_b32_e64 v148, v148, v194, s[42:43]
	v_cndmask_b32_e64 v194, 0, v216, s[40:41]
	v_sub_f32_e32 v148, v148, v194
	v_sub_f32_e32 v148, v168, v148
	v_min_f32_e32 v168, 0, v144
	v_mul_f32_e64 v144, |v144|, s57
	v_exp_f32_e32 v144, v144
	s_nop 0
	v_add_f32_e32 v144, 1.0, v144
	v_cmp_gt_f32_e64 s[40:41], s97, v144
	s_nop 1
	v_cndmask_b32_e64 v194, 0, 32, s[40:41]
	v_ldexp_f32 v144, v144, v194
	v_log_f32_e32 v144, v144
	s_nop 0
	v_mul_f32_e32 v194, 0x3f317217, v144
	v_fma_f32 v194, v144, s52, -v194
	v_fmac_f32_e32 v194, 0x3377d1cf, v144
	v_fmac_f32_e32 v194, 0x3f317217, v144
	v_cmp_lt_f32_e64 s[42:43], |v144|, s53
	s_nop 1
	v_cndmask_b32_e64 v144, v144, v194, s[42:43]
	v_cndmask_b32_e64 v194, 0, v216, s[40:41]
	v_sub_f32_e32 v144, v144, v194
	v_sub_f32_e32 v168, v168, v144
	v_mul_f32_e32 v144, 0x3fb8aa3b, v148
	v_exp_f32_e32 v144, v144
	s_nop 0
	v_fma_f32 v144, v183, v144, v132
	v_cmp_gt_f32_e64 s[40:41], s97, v144
	s_nop 1
	v_cndmask_b32_e64 v194, 0, 32, s[40:41]
	v_ldexp_f32 v144, v144, v194
	v_log_f32_e32 v144, v144
	s_nop 0
	v_mul_f32_e32 v194, 0x3f317217, v144
	v_fma_f32 v194, v144, s52, -v194
	v_fmac_f32_e32 v194, 0x3377d1cf, v144
	v_fmac_f32_e32 v194, 0x3f317217, v144
	v_cmp_lt_f32_e64 s[42:43], |v144|, s53
	s_nop 1
	v_cndmask_b32_e64 v144, v144, v194, s[42:43]
	v_cndmask_b32_e64 v194, 0, v216, s[40:41]
	v_sub_f32_e32 v144, v144, v194
	v_cndmask_b32_e64 v144, v148, v144, s[20:21]
	v_mul_f32_e32 v148, 0x3fb8aa3b, v168
	v_exp_f32_e32 v148, v148
	s_nop 0
	v_fma_f32 v148, v182, v148, v128
	v_cmp_gt_f32_e64 s[40:41], s97, v148
	s_nop 1
	v_cndmask_b32_e64 v194, 0, 32, s[40:41]
	v_ldexp_f32 v148, v148, v194
	v_log_f32_e32 v148, v148
	s_nop 0
	v_mul_f32_e32 v194, 0x3f317217, v148
	v_fma_f32 v194, v148, s52, -v194
	v_fmac_f32_e32 v194, 0x3377d1cf, v148
	v_fmac_f32_e32 v194, 0x3f317217, v148
	v_cmp_lt_f32_e64 s[42:43], |v148|, s53
	s_nop 1
	v_cndmask_b32_e64 v148, v148, v194, s[42:43]
	v_cndmask_b32_e64 v194, 0, v216, s[40:41]
	v_sub_f32_e32 v148, v148, v194
	v_cndmask_b32_e64 v148, v168, v148, s[18:19]
	v_min_f32_e32 v168, 0, v149
	v_mul_f32_e64 v149, |v149|, s57
	v_exp_f32_e32 v149, v149
	s_nop 0
	v_add_f32_e32 v149, 1.0, v149
	v_cmp_gt_f32_e64 s[40:41], s97, v149
	s_nop 1
	v_cndmask_b32_e64 v194, 0, 32, s[40:41]
	v_ldexp_f32 v149, v149, v194
	v_log_f32_e32 v149, v149
	s_nop 0
	v_mul_f32_e32 v194, 0x3f317217, v149
	v_fma_f32 v194, v149, s52, -v194
	v_fmac_f32_e32 v194, 0x3377d1cf, v149
	v_fmac_f32_e32 v194, 0x3f317217, v149
	v_cmp_lt_f32_e64 s[42:43], |v149|, s53
	s_nop 1
	v_cndmask_b32_e64 v149, v149, v194, s[42:43]
	v_cndmask_b32_e64 v194, 0, v216, s[40:41]
	v_sub_f32_e32 v149, v149, v194
	v_sub_f32_e32 v149, v168, v149
	v_min_f32_e32 v168, 0, v145
	v_mul_f32_e64 v145, |v145|, s57
	v_exp_f32_e32 v145, v145
	s_nop 0
	v_add_f32_e32 v145, 1.0, v145
	v_cmp_gt_f32_e64 s[40:41], s97, v145
	s_nop 1
	v_cndmask_b32_e64 v194, 0, 32, s[40:41]
	v_ldexp_f32 v145, v145, v194
	v_log_f32_e32 v145, v145
	s_nop 0
	v_mul_f32_e32 v194, 0x3f317217, v145
	v_fma_f32 v194, v145, s52, -v194
	v_fmac_f32_e32 v194, 0x3377d1cf, v145
	v_fmac_f32_e32 v194, 0x3f317217, v145
	v_cmp_lt_f32_e64 s[42:43], |v145|, s53
	s_nop 1
	v_cndmask_b32_e64 v145, v145, v194, s[42:43]
	v_cndmask_b32_e64 v194, 0, v216, s[40:41]
	v_sub_f32_e32 v145, v145, v194
	v_sub_f32_e32 v168, v168, v145
	v_mul_f32_e32 v145, 0x3fb8aa3b, v149
	v_exp_f32_e32 v145, v145
	s_nop 0
	v_fma_f32 v145, v181, v145, v133
	v_cmp_gt_f32_e64 s[40:41], s97, v145
	s_nop 1
	v_cndmask_b32_e64 v194, 0, 32, s[40:41]
	v_ldexp_f32 v145, v145, v194
	v_log_f32_e32 v145, v145
	s_nop 0
	v_mul_f32_e32 v194, 0x3f317217, v145
	v_fma_f32 v194, v145, s52, -v194
	v_fmac_f32_e32 v194, 0x3377d1cf, v145
	v_fmac_f32_e32 v194, 0x3f317217, v145
	v_cmp_lt_f32_e64 s[42:43], |v145|, s53
	s_nop 1
	v_cndmask_b32_e64 v145, v145, v194, s[42:43]
	v_cndmask_b32_e64 v194, 0, v216, s[40:41]
	v_sub_f32_e32 v145, v145, v194
	v_cndmask_b32_e64 v145, v149, v145, s[16:17]
	v_mul_f32_e32 v149, 0x3fb8aa3b, v168
	v_exp_f32_e32 v149, v149
	s_nop 0
	v_fma_f32 v149, v180, v149, v129
	v_cmp_gt_f32_e64 s[40:41], s97, v149
	s_nop 1
	v_cndmask_b32_e64 v194, 0, 32, s[40:41]
	v_ldexp_f32 v149, v149, v194
	v_log_f32_e32 v149, v149
	s_nop 0
	v_mul_f32_e32 v194, 0x3f317217, v149
	v_fma_f32 v194, v149, s52, -v194
	v_fmac_f32_e32 v194, 0x3377d1cf, v149
	v_fmac_f32_e32 v194, 0x3f317217, v149
	v_cmp_lt_f32_e64 s[42:43], |v149|, s53
	s_nop 1
	v_cndmask_b32_e64 v149, v149, v194, s[42:43]
	v_cndmask_b32_e64 v194, 0, v216, s[40:41]
	v_sub_f32_e32 v149, v149, v194
	v_cndmask_b32_e64 v149, v168, v149, s[14:15]
	v_min_f32_e32 v168, 0, v150
	v_mul_f32_e64 v150, |v150|, s57
	v_exp_f32_e32 v150, v150
	s_nop 0
	v_add_f32_e32 v150, 1.0, v150
	v_cmp_gt_f32_e64 s[40:41], s97, v150
	s_nop 1
	v_cndmask_b32_e64 v194, 0, 32, s[40:41]
	v_ldexp_f32 v150, v150, v194
	v_log_f32_e32 v150, v150
	s_nop 0
	v_mul_f32_e32 v194, 0x3f317217, v150
	v_fma_f32 v194, v150, s52, -v194
	v_fmac_f32_e32 v194, 0x3377d1cf, v150
	v_fmac_f32_e32 v194, 0x3f317217, v150
	v_cmp_lt_f32_e64 s[42:43], |v150|, s53
	s_nop 1
	v_cndmask_b32_e64 v150, v150, v194, s[42:43]
	v_cndmask_b32_e64 v194, 0, v216, s[40:41]
	v_sub_f32_e32 v150, v150, v194
	v_sub_f32_e32 v150, v168, v150
	v_min_f32_e32 v168, 0, v146
	v_mul_f32_e64 v146, |v146|, s57
	v_exp_f32_e32 v146, v146
	s_nop 0
	v_add_f32_e32 v146, 1.0, v146
	v_cmp_gt_f32_e64 s[40:41], s97, v146
	s_nop 1
	v_cndmask_b32_e64 v194, 0, 32, s[40:41]
	v_ldexp_f32 v146, v146, v194
	v_log_f32_e32 v146, v146
	s_nop 0
	v_mul_f32_e32 v194, 0x3f317217, v146
; __device__ __forceinline__ float row_rstd(const float* ssq, int row, int fq) {
;     const f32x4 v = *(const f32x4*)(ssq + (size_t)row * 16 + fq * 4);
;     float s = (v[0] + v[1]) + (v[2] + v[3]);
;     s += __shfl_xor(s, 16); s += __shfl_xor(s, 32);
;     return __builtin_amdgcn_rsqf(s * (1.f / DM) + EPS);
; }
;     __device__ __forceinline__ void operator()(const f32x4 (&acc)[2][2][4][2], const pg8::Unit& u, int wr, int wc, int fr, int fq) const {
;     ...
;             WIN_LOOP( _Pragma("unroll") for (int i = 0; i < 4; ++i) { const float s0 = fminf(a[i], 0.f) - __logf(1.f + __expf(-fabsf(a[i]))), s1 = fminf(b[i], 0.f) - __logf(1.f + __expf(-fabsf(b[i]))); const float la = l0[bj][i], lbv = l1[bj][i];
;                     a[i] = la > 0.f ? __logf(la + (1.f - la) * __expf(s0)) : s0; b[i] = lbv > 0.f ? __logf(lbv + (1.f - lbv) * __expf(s1)) : s1; }
;                 *(f32x4*)(LF + (size_t)row * 512 + c) = a; *(f32x4*)(LF + (size_t)row * 512 + c + 4) = b; __builtin_amdgcn_sched_barrier(0); ) }
	v_fma_f32 v194, v146, s52, -v194
	v_fmac_f32_e32 v194, 0x3377d1cf, v146
	v_fmac_f32_e32 v194, 0x3f317217, v146
	v_cmp_lt_f32_e64 s[42:43], |v146|, s53
	s_nop 1
	v_cndmask_b32_e64 v146, v146, v194, s[42:43]
	v_cndmask_b32_e64 v194, 0, v216, s[40:41]
	v_sub_f32_e32 v146, v146, v194
	v_sub_f32_e32 v168, v168, v146
	v_mul_f32_e32 v146, 0x3fb8aa3b, v150
	v_exp_f32_e32 v146, v146
	s_nop 0
	v_fma_f32 v146, v179, v146, v134
	v_cmp_gt_f32_e64 s[40:41], s97, v146
	s_nop 1
	v_cndmask_b32_e64 v194, 0, 32, s[40:41]
	v_ldexp_f32 v146, v146, v194
	v_log_f32_e32 v146, v146
	s_nop 0
	v_mul_f32_e32 v194, 0x3f317217, v146
	v_fma_f32 v194, v146, s52, -v194
	v_fmac_f32_e32 v194, 0x3377d1cf, v146
	v_fmac_f32_e32 v194, 0x3f317217, v146
	v_cmp_lt_f32_e64 s[42:43], |v146|, s53
	s_nop 1
	v_cndmask_b32_e64 v146, v146, v194, s[42:43]
	v_cndmask_b32_e64 v194, 0, v216, s[40:41]
	v_sub_f32_e32 v146, v146, v194
	v_cndmask_b32_e64 v146, v150, v146, s[12:13]
	v_mul_f32_e32 v150, 0x3fb8aa3b, v168
	v_exp_f32_e32 v150, v150
	s_nop 0
	v_fma_f32 v150, v178, v150, v130
	v_cmp_gt_f32_e64 s[40:41], s97, v150
	s_nop 1
	v_cndmask_b32_e64 v194, 0, 32, s[40:41]
	v_ldexp_f32 v150, v150, v194
	v_log_f32_e32 v150, v150
	s_nop 0
	v_mul_f32_e32 v194, 0x3f317217, v150
	v_fma_f32 v194, v150, s52, -v194
	v_fmac_f32_e32 v194, 0x3377d1cf, v150
	v_fmac_f32_e32 v194, 0x3f317217, v150
	v_cmp_lt_f32_e64 s[42:43], |v150|, s53
	s_nop 1
	v_cndmask_b32_e64 v150, v150, v194, s[42:43]
	v_cndmask_b32_e64 v194, 0, v216, s[40:41]
	v_sub_f32_e32 v150, v150, v194
	v_cndmask_b32_e64 v150, v168, v150, s[10:11]
	v_min_f32_e32 v168, 0, v151
	v_mul_f32_e64 v151, |v151|, s57
	v_exp_f32_e32 v151, v151
	s_nop 0
	v_add_f32_e32 v151, 1.0, v151
	v_cmp_gt_f32_e64 s[40:41], s97, v151
	s_nop 1
	v_cndmask_b32_e64 v194, 0, 32, s[40:41]
	v_ldexp_f32 v151, v151, v194
	v_log_f32_e32 v151, v151
	s_nop 0
	v_mul_f32_e32 v194, 0x3f317217, v151
	v_fma_f32 v194, v151, s52, -v194
	v_fmac_f32_e32 v194, 0x3377d1cf, v151
	v_fmac_f32_e32 v194, 0x3f317217, v151
	v_cmp_lt_f32_e64 s[42:43], |v151|, s53
	s_nop 1
	v_cndmask_b32_e64 v151, v151, v194, s[42:43]
	v_cndmask_b32_e64 v194, 0, v216, s[40:41]
	v_sub_f32_e32 v151, v151, v194
	v_sub_f32_e32 v151, v168, v151
	v_min_f32_e32 v168, 0, v147
	v_mul_f32_e64 v147, |v147|, s57
	v_exp_f32_e32 v147, v147
	s_nop 0
	v_add_f32_e32 v147, 1.0, v147
	v_cmp_gt_f32_e64 s[40:41], s97, v147
	s_nop 1
	v_cndmask_b32_e64 v194, 0, 32, s[40:41]
	v_ldexp_f32 v147, v147, v194
	v_log_f32_e32 v147, v147
	s_nop 0
	v_mul_f32_e32 v194, 0x3f317217, v147
	v_fma_f32 v194, v147, s52, -v194
	v_fmac_f32_e32 v194, 0x3377d1cf, v147
	v_fmac_f32_e32 v194, 0x3f317217, v147
	v_cmp_lt_f32_e64 s[42:43], |v147|, s53
	s_nop 1
	v_cndmask_b32_e64 v147, v147, v194, s[42:43]
	v_cndmask_b32_e64 v194, 0, v216, s[40:41]
	v_sub_f32_e32 v147, v147, v194
	v_sub_f32_e32 v168, v168, v147
	v_mul_f32_e32 v147, 0x3fb8aa3b, v151
	v_exp_f32_e32 v147, v147
	s_nop 0
	v_fma_f32 v147, v177, v147, v135
	v_cmp_gt_f32_e64 s[40:41], s97, v147
	s_nop 1
	v_cndmask_b32_e64 v194, 0, 32, s[40:41]
	v_ldexp_f32 v147, v147, v194
	v_log_f32_e32 v147, v147
	s_nop 0
	v_mul_f32_e32 v194, 0x3f317217, v147
	v_fma_f32 v194, v147, s52, -v194
	v_fmac_f32_e32 v194, 0x3377d1cf, v147
	v_fmac_f32_e32 v194, 0x3f317217, v147
	v_cmp_lt_f32_e64 s[42:43], |v147|, s53
	s_nop 1
	v_cndmask_b32_e64 v147, v147, v194, s[42:43]
	v_cndmask_b32_e64 v194, 0, v216, s[40:41]
	v_sub_f32_e32 v147, v147, v194
	v_cndmask_b32_e64 v147, v151, v147, s[8:9]
	v_mul_f32_e32 v151, 0x3fb8aa3b, v168
	v_exp_f32_e32 v151, v151
	s_nop 0
	v_fma_f32 v151, v167, v151, v131
	v_cmp_gt_f32_e64 s[40:41], s97, v151
	s_nop 1
	v_cndmask_b32_e64 v194, 0, 32, s[40:41]
	v_ldexp_f32 v151, v151, v194
	v_log_f32_e32 v151, v151
	s_nop 0
	v_mul_f32_e32 v194, 0x3f317217, v151
	v_fma_f32 v194, v151, s52, -v194
	v_fmac_f32_e32 v194, 0x3377d1cf, v151
	v_fmac_f32_e32 v194, 0x3f317217, v151
	v_cmp_lt_f32_e64 s[42:43], |v151|, s53
	s_nop 1
	v_cndmask_b32_e64 v151, v151, v194, s[42:43]
	v_cndmask_b32_e64 v194, 0, v216, s[40:41]
	v_sub_f32_e32 v151, v151, v194
	v_cndmask_b32_e32 v151, v168, v151, vcc
	flat_store_dwordx4 v[170:171], v[144:147] offset:512 sc1
	flat_store_dwordx4 v[170:171], v[148:151] offset:528 sc1
	s_nop 1
	v_add_u32_e32 v148, 0x80, v166
	v_ashrrev_i32_e32 v149, 31, v148
	v_lshlrev_b64 v[144:145], 6, v[148:149]
	v_lshl_add_u64 v[144:145], v[160:161], 0, v[144:145]
	flat_load_dwordx4 v[144:147], v[144:145]
	s_waitcnt vmcnt(0) lgkmcnt(0)
	v_mov_b32_e32 v150, v145
	v_mov_b32_e32 v151, v146
	v_mov_b32_e32 v145, v147
	v_pk_add_f32 v[144:145], v[150:151], v[144:145]
	s_nop 0
	v_add_f32_e32 v144, v144, v145
	ds_bpermute_b32 v145, v169, v144
	s_waitcnt lgkmcnt(0)
	v_add_f32_e32 v144, v144, v145
	ds_bpermute_b32 v145, v202, v144
	s_waitcnt lgkmcnt(0)
; __device__ __forceinline__ float row_rstd(const float* ssq, int row, int fq) {
;     const f32x4 v = *(const f32x4*)(ssq + (size_t)row * 16 + fq * 4);
;     float s = (v[0] + v[1]) + (v[2] + v[3]);
;     s += __shfl_xor(s, 16); s += __shfl_xor(s, 32);
;     return __builtin_amdgcn_rsqf(s * (1.f / DM) + EPS);
; }
;     __device__ __forceinline__ void operator()(const f32x4 (&acc)[2][2][4][2], const pg8::Unit& u, int wr, int wc, int fr, int fq) const {
;     ...
;             WIN_LOOP( _Pragma("unroll") for (int i = 0; i < 4; ++i) { const float s0 = fminf(a[i], 0.f) - __logf(1.f + __expf(-fabsf(a[i]))), s1 = fminf(b[i], 0.f) - __logf(1.f + __expf(-fabsf(b[i]))); const float la = l0[bj][i], lbv = l1[bj][i];
;                     a[i] = la > 0.f ? __logf(la + (1.f - la) * __expf(s0)) : s0; b[i] = lbv > 0.f ? __logf(lbv + (1.f - lbv) * __expf(s1)) : s1; }
	v_add_f32_e32 v144, v144, v145
	v_fmamk_f32 v144, v144, 0x3a800000, v212
	v_rsq_f32_e32 v168, v144
	v_lshlrev_b64 v[144:145], 11, v[148:149]
	v_lshl_add_u64 v[170:171], s[50:51], 0, v[144:145]
	v_lshl_add_u64 v[170:171], v[170:171], 0, v[192:193]
	v_pk_mul_f32 v[148:149], v[28:29], v[168:169] op_sel_hi:[1,0]
	v_pk_mul_f32 v[144:145], v[24:25], v[168:169] op_sel_hi:[1,0]
	v_min_f32_e32 v194, 0, v148
	v_mul_f32_e64 v148, |v148|, s57
	v_exp_f32_e32 v148, v148
	v_pk_mul_f32 v[150:151], v[30:31], v[168:169] op_sel_hi:[1,0]
	v_pk_mul_f32 v[146:147], v[26:27], v[168:169] op_sel_hi:[1,0]
	v_add_f32_e32 v148, 1.0, v148
	v_cmp_gt_f32_e64 s[40:41], s97, v148
	s_nop 1
	v_cndmask_b32_e64 v195, 0, 32, s[40:41]
	v_ldexp_f32 v148, v148, v195
	v_log_f32_e32 v148, v148
	s_nop 0
	v_mul_f32_e32 v195, 0x3f317217, v148
	v_fma_f32 v195, v148, s52, -v195
	v_fmac_f32_e32 v195, 0x3377d1cf, v148
	v_fmac_f32_e32 v195, 0x3f317217, v148
	v_cmp_lt_f32_e64 s[42:43], |v148|, s53
	s_nop 1
	v_cndmask_b32_e64 v148, v148, v195, s[42:43]
	v_cndmask_b32_e64 v195, 0, v216, s[40:41]
	v_sub_f32_e32 v148, v148, v195
	v_sub_f32_e32 v148, v194, v148
	v_min_f32_e32 v194, 0, v144
	v_mul_f32_e64 v144, |v144|, s57
	v_exp_f32_e32 v144, v144
	s_nop 0
	v_add_f32_e32 v144, 1.0, v144
	v_cmp_gt_f32_e64 s[40:41], s97, v144
	s_nop 1
	v_cndmask_b32_e64 v195, 0, 32, s[40:41]
	v_ldexp_f32 v144, v144, v195
	v_log_f32_e32 v144, v144
	s_nop 0
	v_mul_f32_e32 v195, 0x3f317217, v144
	v_fma_f32 v195, v144, s52, -v195
	v_fmac_f32_e32 v195, 0x3377d1cf, v144
	v_fmac_f32_e32 v195, 0x3f317217, v144
	v_cmp_lt_f32_e64 s[42:43], |v144|, s53
	s_nop 1
	v_cndmask_b32_e64 v144, v144, v195, s[42:43]
	v_cndmask_b32_e64 v195, 0, v216, s[40:41]
	v_sub_f32_e32 v144, v144, v195
	v_sub_f32_e32 v194, v194, v144
	v_mul_f32_e32 v144, 0x3fb8aa3b, v148
	v_exp_f32_e32 v144, v144
	s_nop 0
	v_fma_f32 v144, v190, v144, v140
	v_cmp_gt_f32_e64 s[40:41], s97, v144
	s_nop 1
	v_cndmask_b32_e64 v195, 0, 32, s[40:41]
	v_ldexp_f32 v144, v144, v195
	v_log_f32_e32 v144, v144
	s_nop 0
	v_mul_f32_e32 v195, 0x3f317217, v144
	v_fma_f32 v195, v144, s52, -v195
	v_fmac_f32_e32 v195, 0x3377d1cf, v144
	v_fmac_f32_e32 v195, 0x3f317217, v144
	v_cmp_lt_f32_e64 s[42:43], |v144|, s53
	s_nop 1
	v_cndmask_b32_e64 v144, v144, v195, s[42:43]
	v_cndmask_b32_e64 v195, 0, v216, s[40:41]
	v_sub_f32_e32 v144, v144, v195
	v_cndmask_b32_e64 v144, v148, v144, s[38:39]
	v_mul_f32_e32 v148, 0x3fb8aa3b, v194
	v_exp_f32_e32 v148, v148
	s_nop 0
	v_fma_f32 v148, v191, v148, v136
	v_cmp_gt_f32_e64 s[40:41], s97, v148
	s_nop 1
	v_cndmask_b32_e64 v195, 0, 32, s[40:41]
	v_ldexp_f32 v148, v148, v195
	v_log_f32_e32 v148, v148
	s_nop 0
	v_mul_f32_e32 v195, 0x3f317217, v148
	v_fma_f32 v195, v148, s52, -v195
	v_fmac_f32_e32 v195, 0x3377d1cf, v148
	v_fmac_f32_e32 v195, 0x3f317217, v148
	v_cmp_lt_f32_e64 s[42:43], |v148|, s53
	s_nop 1
	v_cndmask_b32_e64 v148, v148, v195, s[42:43]
	v_cndmask_b32_e64 v195, 0, v216, s[40:41]
	v_sub_f32_e32 v148, v148, v195
	v_cndmask_b32_e64 v148, v194, v148, s[36:37]
	v_min_f32_e32 v194, 0, v149
	v_mul_f32_e64 v149, |v149|, s57
	v_exp_f32_e32 v149, v149
	s_nop 0
	v_add_f32_e32 v149, 1.0, v149
	v_cmp_gt_f32_e64 s[40:41], s97, v149
	s_nop 1
	v_cndmask_b32_e64 v195, 0, 32, s[40:41]
	v_ldexp_f32 v149, v149, v195
	v_log_f32_e32 v149, v149
	s_nop 0
	v_mul_f32_e32 v195, 0x3f317217, v149
	v_fma_f32 v195, v149, s52, -v195
	v_fmac_f32_e32 v195, 0x3377d1cf, v149
	v_fmac_f32_e32 v195, 0x3f317217, v149
	v_cmp_lt_f32_e64 s[42:43], |v149|, s53
	s_nop 1
	v_cndmask_b32_e64 v149, v149, v195, s[42:43]
	v_cndmask_b32_e64 v195, 0, v216, s[40:41]
	v_sub_f32_e32 v149, v149, v195
	v_sub_f32_e32 v149, v194, v149
	v_min_f32_e32 v194, 0, v145
	v_mul_f32_e64 v145, |v145|, s57
	v_exp_f32_e32 v145, v145
	s_nop 0
	v_add_f32_e32 v145, 1.0, v145
	v_cmp_gt_f32_e64 s[40:41], s97, v145
	s_nop 1
	v_cndmask_b32_e64 v195, 0, 32, s[40:41]
	v_ldexp_f32 v145, v145, v195
	v_log_f32_e32 v145, v145
	s_nop 0
	v_mul_f32_e32 v195, 0x3f317217, v145
	v_fma_f32 v195, v145, s52, -v195
	v_fmac_f32_e32 v195, 0x3377d1cf, v145
	v_fmac_f32_e32 v195, 0x3f317217, v145
	v_cmp_lt_f32_e64 s[42:43], |v145|, s53
	s_nop 1
	v_cndmask_b32_e64 v145, v145, v195, s[42:43]
	v_cndmask_b32_e64 v195, 0, v216, s[40:41]
	v_sub_f32_e32 v145, v145, v195
	v_sub_f32_e32 v194, v194, v145
	v_mul_f32_e32 v145, 0x3fb8aa3b, v149
	v_exp_f32_e32 v145, v145
	s_nop 0
	v_fma_f32 v145, v188, v145, v141
	v_cmp_gt_f32_e64 s[40:41], s97, v145
	s_nop 1
	v_cndmask_b32_e64 v195, 0, 32, s[40:41]
	v_ldexp_f32 v145, v145, v195
	v_log_f32_e32 v145, v145
	s_nop 0
	v_mul_f32_e32 v195, 0x3f317217, v145
	v_fma_f32 v195, v145, s52, -v195
	v_fmac_f32_e32 v195, 0x3377d1cf, v145
	v_fmac_f32_e32 v195, 0x3f317217, v145
	v_cmp_lt_f32_e64 s[42:43], |v145|, s53
	s_nop 1
	v_cndmask_b32_e64 v145, v145, v195, s[42:43]
	v_cndmask_b32_e64 v195, 0, v216, s[40:41]
	v_sub_f32_e32 v145, v145, v195
	v_cndmask_b32_e64 v145, v149, v145, s[34:35]
	v_mul_f32_e32 v149, 0x3fb8aa3b, v194
	v_exp_f32_e32 v149, v149
	s_nop 0
	v_fma_f32 v149, v189, v149, v137
	v_cmp_gt_f32_e64 s[40:41], s97, v149
	s_nop 1
	v_cndmask_b32_e64 v195, 0, 32, s[40:41]
	v_ldexp_f32 v149, v149, v195
	v_log_f32_e32 v149, v149
	s_nop 0
	v_mul_f32_e32 v195, 0x3f317217, v149
	v_fma_f32 v195, v149, s52, -v195
	v_fmac_f32_e32 v195, 0x3377d1cf, v149
	v_fmac_f32_e32 v195, 0x3f317217, v149
	v_cmp_lt_f32_e64 s[42:43], |v149|, s53
	s_nop 1
	v_cndmask_b32_e64 v149, v149, v195, s[42:43]
	v_cndmask_b32_e64 v195, 0, v216, s[40:41]
	v_sub_f32_e32 v149, v149, v195
	v_cndmask_b32_e64 v149, v194, v149, s[30:31]
	v_min_f32_e32 v194, 0, v150
	v_mul_f32_e64 v150, |v150|, s57
	v_exp_f32_e32 v150, v150
	s_nop 0
	v_add_f32_e32 v150, 1.0, v150
;     __device__ __forceinline__ void operator()(const f32x4 (&acc)[2][2][4][2], const pg8::Unit& u, int wr, int wc, int fr, int fq) const {
;     ...
;             WIN_LOOP( _Pragma("unroll") for (int i = 0; i < 4; ++i) { const float s0 = fminf(a[i], 0.f) - __logf(1.f + __expf(-fabsf(a[i]))), s1 = fminf(b[i], 0.f) - __logf(1.f + __expf(-fabsf(b[i]))); const float la = l0[bj][i], lbv = l1[bj][i];
;                     a[i] = la > 0.f ? __logf(la + (1.f - la) * __expf(s0)) : s0; b[i] = lbv > 0.f ? __logf(lbv + (1.f - lbv) * __expf(s1)) : s1; }
;                 *(f32x4*)(LF + (size_t)row * 512 + c) = a; *(f32x4*)(LF + (size_t)row * 512 + c + 4) = b; __builtin_amdgcn_sched_barrier(0); ) }
	v_cmp_gt_f32_e64 s[40:41], s97, v150
	s_nop 1
	v_cndmask_b32_e64 v195, 0, 32, s[40:41]
	v_ldexp_f32 v150, v150, v195
	v_log_f32_e32 v150, v150
	s_nop 0
	v_mul_f32_e32 v195, 0x3f317217, v150
	v_fma_f32 v195, v150, s52, -v195
	v_fmac_f32_e32 v195, 0x3377d1cf, v150
	v_fmac_f32_e32 v195, 0x3f317217, v150
	v_cmp_lt_f32_e64 s[42:43], |v150|, s53
	s_nop 1
	v_cndmask_b32_e64 v150, v150, v195, s[42:43]
	v_cndmask_b32_e64 v195, 0, v216, s[40:41]
	v_sub_f32_e32 v150, v150, v195
	v_sub_f32_e32 v150, v194, v150
	v_min_f32_e32 v194, 0, v146
	v_mul_f32_e64 v146, |v146|, s57
	v_exp_f32_e32 v146, v146
	s_nop 0
	v_add_f32_e32 v146, 1.0, v146
	v_cmp_gt_f32_e64 s[40:41], s97, v146
	s_nop 1
	v_cndmask_b32_e64 v195, 0, 32, s[40:41]
	v_ldexp_f32 v146, v146, v195
	v_log_f32_e32 v146, v146
	s_nop 0
	v_mul_f32_e32 v195, 0x3f317217, v146
	v_fma_f32 v195, v146, s52, -v195
	v_fmac_f32_e32 v195, 0x3377d1cf, v146
	v_fmac_f32_e32 v195, 0x3f317217, v146
	v_cmp_lt_f32_e64 s[42:43], |v146|, s53
	s_nop 1
	v_cndmask_b32_e64 v146, v146, v195, s[42:43]
	v_cndmask_b32_e64 v195, 0, v216, s[40:41]
	v_sub_f32_e32 v146, v146, v195
	v_sub_f32_e32 v194, v194, v146
	v_mul_f32_e32 v146, 0x3fb8aa3b, v150
	v_exp_f32_e32 v146, v146
	s_nop 0
	v_fma_f32 v146, v187, v146, v142
	v_cmp_gt_f32_e64 s[40:41], s97, v146
	s_nop 1
	v_cndmask_b32_e64 v195, 0, 32, s[40:41]
	v_ldexp_f32 v146, v146, v195
	v_log_f32_e32 v146, v146
	s_nop 0
	v_mul_f32_e32 v195, 0x3f317217, v146
	v_fma_f32 v195, v146, s52, -v195
	v_fmac_f32_e32 v195, 0x3377d1cf, v146
	v_fmac_f32_e32 v195, 0x3f317217, v146
	v_cmp_lt_f32_e64 s[42:43], |v146|, s53
	s_nop 1
	v_cndmask_b32_e64 v146, v146, v195, s[42:43]
	v_cndmask_b32_e64 v195, 0, v216, s[40:41]
	v_sub_f32_e32 v146, v146, v195
	v_cndmask_b32_e64 v146, v150, v146, s[28:29]
	v_mul_f32_e32 v150, 0x3fb8aa3b, v194
	v_exp_f32_e32 v150, v150
	s_nop 0
	v_fma_f32 v150, v186, v150, v138
	v_cmp_gt_f32_e64 s[40:41], s97, v150
	s_nop 1
	v_cndmask_b32_e64 v195, 0, 32, s[40:41]
	v_ldexp_f32 v150, v150, v195
	v_log_f32_e32 v150, v150
	s_nop 0
	v_mul_f32_e32 v195, 0x3f317217, v150
	v_fma_f32 v195, v150, s52, -v195
	v_fmac_f32_e32 v195, 0x3377d1cf, v150
	v_fmac_f32_e32 v195, 0x3f317217, v150
	v_cmp_lt_f32_e64 s[42:43], |v150|, s53
	s_nop 1
	v_cndmask_b32_e64 v150, v150, v195, s[42:43]
	v_cndmask_b32_e64 v195, 0, v216, s[40:41]
	v_sub_f32_e32 v150, v150, v195
	v_cndmask_b32_e64 v150, v194, v150, s[26:27]
	v_min_f32_e32 v194, 0, v151
	v_mul_f32_e64 v151, |v151|, s57
	v_exp_f32_e32 v151, v151
	s_nop 0
	v_add_f32_e32 v151, 1.0, v151
	v_cmp_gt_f32_e64 s[40:41], s97, v151
	s_nop 1
	v_cndmask_b32_e64 v195, 0, 32, s[40:41]
	v_ldexp_f32 v151, v151, v195
	v_log_f32_e32 v151, v151
	s_nop 0
	v_mul_f32_e32 v195, 0x3f317217, v151
	v_fma_f32 v195, v151, s52, -v195
	v_fmac_f32_e32 v195, 0x3377d1cf, v151
	v_fmac_f32_e32 v195, 0x3f317217, v151
	v_cmp_lt_f32_e64 s[42:43], |v151|, s53
	s_nop 1
	v_cndmask_b32_e64 v151, v151, v195, s[42:43]
	v_cndmask_b32_e64 v195, 0, v216, s[40:41]
	v_sub_f32_e32 v151, v151, v195
	v_sub_f32_e32 v151, v194, v151
	v_min_f32_e32 v194, 0, v147
	v_mul_f32_e64 v147, |v147|, s57
	v_exp_f32_e32 v147, v147
	s_nop 0
	v_add_f32_e32 v147, 1.0, v147
	v_cmp_gt_f32_e64 s[40:41], s97, v147
	s_nop 1
	v_cndmask_b32_e64 v195, 0, 32, s[40:41]
	v_ldexp_f32 v147, v147, v195
	v_log_f32_e32 v147, v147
	s_nop 0
	v_mul_f32_e32 v195, 0x3f317217, v147
	v_fma_f32 v195, v147, s52, -v195
	v_fmac_f32_e32 v195, 0x3377d1cf, v147
	v_fmac_f32_e32 v195, 0x3f317217, v147
	v_cmp_lt_f32_e64 s[42:43], |v147|, s53
	s_nop 1
	v_cndmask_b32_e64 v147, v147, v195, s[42:43]
	v_cndmask_b32_e64 v195, 0, v216, s[40:41]
	v_sub_f32_e32 v147, v147, v195
	v_sub_f32_e32 v194, v194, v147
	v_mul_f32_e32 v147, 0x3fb8aa3b, v151
	v_exp_f32_e32 v147, v147
	s_nop 0
	v_fma_f32 v147, v185, v147, v143
	v_cmp_gt_f32_e64 s[40:41], s97, v147
	s_nop 1
	v_cndmask_b32_e64 v195, 0, 32, s[40:41]
	v_ldexp_f32 v147, v147, v195
	v_log_f32_e32 v147, v147
	s_nop 0
	v_mul_f32_e32 v195, 0x3f317217, v147
	v_fma_f32 v195, v147, s52, -v195
	v_fmac_f32_e32 v195, 0x3377d1cf, v147
	v_fmac_f32_e32 v195, 0x3f317217, v147
	v_cmp_lt_f32_e64 s[42:43], |v147|, s53
	s_nop 1
	v_cndmask_b32_e64 v147, v147, v195, s[42:43]
	v_cndmask_b32_e64 v195, 0, v216, s[40:41]
	v_sub_f32_e32 v147, v147, v195
	v_cndmask_b32_e64 v147, v151, v147, s[24:25]
	v_mul_f32_e32 v151, 0x3fb8aa3b, v194
	v_exp_f32_e32 v151, v151
	s_nop 0
	v_fma_f32 v151, v184, v151, v139
	v_cmp_gt_f32_e64 s[40:41], s97, v151
	s_nop 1
	v_cndmask_b32_e64 v195, 0, 32, s[40:41]
	v_ldexp_f32 v151, v151, v195
	v_log_f32_e32 v151, v151
	s_nop 0
	v_mul_f32_e32 v195, 0x3f317217, v151
	v_fma_f32 v195, v151, s52, -v195
	v_fmac_f32_e32 v195, 0x3377d1cf, v151
	v_fmac_f32_e32 v195, 0x3f317217, v151
	v_cmp_lt_f32_e64 s[42:43], |v151|, s53
	s_nop 1
	v_cndmask_b32_e64 v151, v151, v195, s[42:43]
	v_cndmask_b32_e64 v195, 0, v216, s[40:41]
	v_sub_f32_e32 v151, v151, v195
	v_cndmask_b32_e64 v151, v194, v151, s[22:23]
	flat_store_dwordx4 v[170:171], v[144:147] sc1
	flat_store_dwordx4 v[170:171], v[148:151] offset:16 sc1
	s_nop 1
	v_pk_mul_f32 v[148:149], v[92:93], v[168:169] op_sel_hi:[1,0]
	v_pk_mul_f32 v[150:151], v[94:95], v[168:169] op_sel_hi:[1,0]
	v_pk_mul_f32 v[146:147], v[90:91], v[168:169] op_sel_hi:[1,0]
	v_pk_mul_f32 v[144:145], v[88:89], v[168:169] op_sel_hi:[1,0]
	v_min_f32_e32 v168, 0, v148
	v_mul_f32_e64 v148, |v148|, s57
	v_exp_f32_e32 v148, v148
	s_nop 0
	v_add_f32_e32 v148, 1.0, v148
	v_cmp_gt_f32_e64 s[40:41], s97, v148
	s_nop 1
	v_cndmask_b32_e64 v194, 0, 32, s[40:41]
	v_ldexp_f32 v148, v148, v194
	v_log_f32_e32 v148, v148
	s_nop 0
	v_mul_f32_e32 v194, 0x3f317217, v148
	v_fma_f32 v194, v148, s52, -v194
;     __device__ __forceinline__ void operator()(const f32x4 (&acc)[2][2][4][2], const pg8::Unit& u, int wr, int wc, int fr, int fq) const {
;     ...
;             WIN_LOOP( _Pragma("unroll") for (int i = 0; i < 4; ++i) { const float s0 = fminf(a[i], 0.f) - __logf(1.f + __expf(-fabsf(a[i]))), s1 = fminf(b[i], 0.f) - __logf(1.f + __expf(-fabsf(b[i]))); const float la = l0[bj][i], lbv = l1[bj][i];
;                     a[i] = la > 0.f ? __logf(la + (1.f - la) * __expf(s0)) : s0; b[i] = lbv > 0.f ? __logf(lbv + (1.f - lbv) * __expf(s1)) : s1; }
	v_fmac_f32_e32 v194, 0x3377d1cf, v148
	v_fmac_f32_e32 v194, 0x3f317217, v148
	v_cmp_lt_f32_e64 s[42:43], |v148|, s53
	s_nop 1
	v_cndmask_b32_e64 v148, v148, v194, s[42:43]
	v_cndmask_b32_e64 v194, 0, v216, s[40:41]
	v_sub_f32_e32 v148, v148, v194
	v_sub_f32_e32 v148, v168, v148
	v_min_f32_e32 v168, 0, v144
	v_mul_f32_e64 v144, |v144|, s57
	v_exp_f32_e32 v144, v144
	s_nop 0
	v_add_f32_e32 v144, 1.0, v144
	v_cmp_gt_f32_e64 s[40:41], s97, v144
	s_nop 1
	v_cndmask_b32_e64 v194, 0, 32, s[40:41]
	v_ldexp_f32 v144, v144, v194
	v_log_f32_e32 v144, v144
	s_nop 0
	v_mul_f32_e32 v194, 0x3f317217, v144
	v_fma_f32 v194, v144, s52, -v194
	v_fmac_f32_e32 v194, 0x3377d1cf, v144
	v_fmac_f32_e32 v194, 0x3f317217, v144
	v_cmp_lt_f32_e64 s[42:43], |v144|, s53
	s_nop 1
	v_cndmask_b32_e64 v144, v144, v194, s[42:43]
	v_cndmask_b32_e64 v194, 0, v216, s[40:41]
	v_sub_f32_e32 v144, v144, v194
	v_sub_f32_e32 v168, v168, v144
	v_mul_f32_e32 v144, 0x3fb8aa3b, v148
	v_exp_f32_e32 v144, v144
	s_nop 0
	v_fma_f32 v144, v183, v144, v132
	v_cmp_gt_f32_e64 s[40:41], s97, v144
	s_nop 1
	v_cndmask_b32_e64 v194, 0, 32, s[40:41]
	v_ldexp_f32 v144, v144, v194
	v_log_f32_e32 v144, v144
	s_nop 0
	v_mul_f32_e32 v194, 0x3f317217, v144
	v_fma_f32 v194, v144, s52, -v194
	v_fmac_f32_e32 v194, 0x3377d1cf, v144
	v_fmac_f32_e32 v194, 0x3f317217, v144
	v_cmp_lt_f32_e64 s[42:43], |v144|, s53
	s_nop 1
	v_cndmask_b32_e64 v144, v144, v194, s[42:43]
	v_cndmask_b32_e64 v194, 0, v216, s[40:41]
	v_sub_f32_e32 v144, v144, v194
	v_cndmask_b32_e64 v144, v148, v144, s[20:21]
	v_mul_f32_e32 v148, 0x3fb8aa3b, v168
	v_exp_f32_e32 v148, v148
	s_nop 0
	v_fma_f32 v148, v182, v148, v128
	v_cmp_gt_f32_e64 s[40:41], s97, v148
	s_nop 1
	v_cndmask_b32_e64 v194, 0, 32, s[40:41]
	v_ldexp_f32 v148, v148, v194
	v_log_f32_e32 v148, v148
	s_nop 0
	v_mul_f32_e32 v194, 0x3f317217, v148
	v_fma_f32 v194, v148, s52, -v194
	v_fmac_f32_e32 v194, 0x3377d1cf, v148
	v_fmac_f32_e32 v194, 0x3f317217, v148
	v_cmp_lt_f32_e64 s[42:43], |v148|, s53
	s_nop 1
	v_cndmask_b32_e64 v148, v148, v194, s[42:43]
	v_cndmask_b32_e64 v194, 0, v216, s[40:41]
	v_sub_f32_e32 v148, v148, v194
	v_cndmask_b32_e64 v148, v168, v148, s[18:19]
	v_min_f32_e32 v168, 0, v149
	v_mul_f32_e64 v149, |v149|, s57
	v_exp_f32_e32 v149, v149
	s_nop 0
	v_add_f32_e32 v149, 1.0, v149
	v_cmp_gt_f32_e64 s[40:41], s97, v149
	s_nop 1
	v_cndmask_b32_e64 v194, 0, 32, s[40:41]
	v_ldexp_f32 v149, v149, v194
	v_log_f32_e32 v149, v149
	s_nop 0
	v_mul_f32_e32 v194, 0x3f317217, v149
	v_fma_f32 v194, v149, s52, -v194
	v_fmac_f32_e32 v194, 0x3377d1cf, v149
	v_fmac_f32_e32 v194, 0x3f317217, v149
	v_cmp_lt_f32_e64 s[42:43], |v149|, s53
	s_nop 1
	v_cndmask_b32_e64 v149, v149, v194, s[42:43]
	v_cndmask_b32_e64 v194, 0, v216, s[40:41]
	v_sub_f32_e32 v149, v149, v194
	v_sub_f32_e32 v149, v168, v149
	v_min_f32_e32 v168, 0, v145
	v_mul_f32_e64 v145, |v145|, s57
	v_exp_f32_e32 v145, v145
	s_nop 0
	v_add_f32_e32 v145, 1.0, v145
	v_cmp_gt_f32_e64 s[40:41], s97, v145
	s_nop 1
	v_cndmask_b32_e64 v194, 0, 32, s[40:41]
	v_ldexp_f32 v145, v145, v194
	v_log_f32_e32 v145, v145
	s_nop 0
	v_mul_f32_e32 v194, 0x3f317217, v145
	v_fma_f32 v194, v145, s52, -v194
	v_fmac_f32_e32 v194, 0x3377d1cf, v145
	v_fmac_f32_e32 v194, 0x3f317217, v145
	v_cmp_lt_f32_e64 s[42:43], |v145|, s53
	s_nop 1
	v_cndmask_b32_e64 v145, v145, v194, s[42:43]
	v_cndmask_b32_e64 v194, 0, v216, s[40:41]
	v_sub_f32_e32 v145, v145, v194
	v_sub_f32_e32 v168, v168, v145
	v_mul_f32_e32 v145, 0x3fb8aa3b, v149
	v_exp_f32_e32 v145, v145
	s_nop 0
	v_fma_f32 v145, v181, v145, v133
	v_cmp_gt_f32_e64 s[40:41], s97, v145
	s_nop 1
	v_cndmask_b32_e64 v194, 0, 32, s[40:41]
	v_ldexp_f32 v145, v145, v194
	v_log_f32_e32 v145, v145
	s_nop 0
	v_mul_f32_e32 v194, 0x3f317217, v145
	v_fma_f32 v194, v145, s52, -v194
	v_fmac_f32_e32 v194, 0x3377d1cf, v145
	v_fmac_f32_e32 v194, 0x3f317217, v145
	v_cmp_lt_f32_e64 s[42:43], |v145|, s53
	s_nop 1
	v_cndmask_b32_e64 v145, v145, v194, s[42:43]
	v_cndmask_b32_e64 v194, 0, v216, s[40:41]
	v_sub_f32_e32 v145, v145, v194
	v_cndmask_b32_e64 v145, v149, v145, s[16:17]
	v_mul_f32_e32 v149, 0x3fb8aa3b, v168
	v_exp_f32_e32 v149, v149
	s_nop 0
	v_fma_f32 v149, v180, v149, v129
	v_cmp_gt_f32_e64 s[40:41], s97, v149
	s_nop 1
	v_cndmask_b32_e64 v194, 0, 32, s[40:41]
	v_ldexp_f32 v149, v149, v194
	v_log_f32_e32 v149, v149
	s_nop 0
	v_mul_f32_e32 v194, 0x3f317217, v149
	v_fma_f32 v194, v149, s52, -v194
	v_fmac_f32_e32 v194, 0x3377d1cf, v149
	v_fmac_f32_e32 v194, 0x3f317217, v149
	v_cmp_lt_f32_e64 s[42:43], |v149|, s53
	s_nop 1
	v_cndmask_b32_e64 v149, v149, v194, s[42:43]
	v_cndmask_b32_e64 v194, 0, v216, s[40:41]
	v_sub_f32_e32 v149, v149, v194
	v_cndmask_b32_e64 v149, v168, v149, s[14:15]
	v_min_f32_e32 v168, 0, v150
	v_mul_f32_e64 v150, |v150|, s57
	v_exp_f32_e32 v150, v150
	s_nop 0
	v_add_f32_e32 v150, 1.0, v150
	v_cmp_gt_f32_e64 s[40:41], s97, v150
	s_nop 1
	v_cndmask_b32_e64 v194, 0, 32, s[40:41]
	v_ldexp_f32 v150, v150, v194
	v_log_f32_e32 v150, v150
	s_nop 0
	v_mul_f32_e32 v194, 0x3f317217, v150
	v_fma_f32 v194, v150, s52, -v194
	v_fmac_f32_e32 v194, 0x3377d1cf, v150
	v_fmac_f32_e32 v194, 0x3f317217, v150
	v_cmp_lt_f32_e64 s[42:43], |v150|, s53
	s_nop 1
	v_cndmask_b32_e64 v150, v150, v194, s[42:43]
	v_cndmask_b32_e64 v194, 0, v216, s[40:41]
	v_sub_f32_e32 v150, v150, v194
	v_sub_f32_e32 v150, v168, v150
	v_min_f32_e32 v168, 0, v146
	v_mul_f32_e64 v146, |v146|, s57
	v_exp_f32_e32 v146, v146
	s_nop 0
	v_add_f32_e32 v146, 1.0, v146
	v_cmp_gt_f32_e64 s[40:41], s97, v146
	s_nop 1
	v_cndmask_b32_e64 v194, 0, 32, s[40:41]
	v_ldexp_f32 v146, v146, v194
	v_log_f32_e32 v146, v146
	s_nop 0
	v_mul_f32_e32 v194, 0x3f317217, v146
; __device__ __forceinline__ float row_rstd(const float* ssq, int row, int fq) {
;     const f32x4 v = *(const f32x4*)(ssq + (size_t)row * 16 + fq * 4);
;     float s = (v[0] + v[1]) + (v[2] + v[3]);
;     s += __shfl_xor(s, 16); s += __shfl_xor(s, 32);
;     return __builtin_amdgcn_rsqf(s * (1.f / DM) + EPS);
; }
;     __device__ __forceinline__ void operator()(const f32x4 (&acc)[2][2][4][2], const pg8::Unit& u, int wr, int wc, int fr, int fq) const {
;     ...
;             WIN_LOOP( _Pragma("unroll") for (int i = 0; i < 4; ++i) { const float s0 = fminf(a[i], 0.f) - __logf(1.f + __expf(-fabsf(a[i]))), s1 = fminf(b[i], 0.f) - __logf(1.f + __expf(-fabsf(b[i]))); const float la = l0[bj][i], lbv = l1[bj][i];
;                     a[i] = la > 0.f ? __logf(la + (1.f - la) * __expf(s0)) : s0; b[i] = lbv > 0.f ? __logf(lbv + (1.f - lbv) * __expf(s1)) : s1; }
;                 *(f32x4*)(LF + (size_t)row * 512 + c) = a; *(f32x4*)(LF + (size_t)row * 512 + c + 4) = b; __builtin_amdgcn_sched_barrier(0); ) }
	v_fma_f32 v194, v146, s52, -v194
	v_fmac_f32_e32 v194, 0x3377d1cf, v146
	v_fmac_f32_e32 v194, 0x3f317217, v146
	v_cmp_lt_f32_e64 s[42:43], |v146|, s53
	s_nop 1
	v_cndmask_b32_e64 v146, v146, v194, s[42:43]
	v_cndmask_b32_e64 v194, 0, v216, s[40:41]
	v_sub_f32_e32 v146, v146, v194
	v_sub_f32_e32 v168, v168, v146
	v_mul_f32_e32 v146, 0x3fb8aa3b, v150
	v_exp_f32_e32 v146, v146
	s_nop 0
	v_fma_f32 v146, v179, v146, v134
	v_cmp_gt_f32_e64 s[40:41], s97, v146
	s_nop 1
	v_cndmask_b32_e64 v194, 0, 32, s[40:41]
	v_ldexp_f32 v146, v146, v194
	v_log_f32_e32 v146, v146
	s_nop 0
	v_mul_f32_e32 v194, 0x3f317217, v146
	v_fma_f32 v194, v146, s52, -v194
	v_fmac_f32_e32 v194, 0x3377d1cf, v146
	v_fmac_f32_e32 v194, 0x3f317217, v146
	v_cmp_lt_f32_e64 s[42:43], |v146|, s53
	s_nop 1
	v_cndmask_b32_e64 v146, v146, v194, s[42:43]
	v_cndmask_b32_e64 v194, 0, v216, s[40:41]
	v_sub_f32_e32 v146, v146, v194
	v_cndmask_b32_e64 v146, v150, v146, s[12:13]
	v_mul_f32_e32 v150, 0x3fb8aa3b, v168
	v_exp_f32_e32 v150, v150
	s_nop 0
	v_fma_f32 v150, v178, v150, v130
	v_cmp_gt_f32_e64 s[40:41], s97, v150
	s_nop 1
	v_cndmask_b32_e64 v194, 0, 32, s[40:41]
	v_ldexp_f32 v150, v150, v194
	v_log_f32_e32 v150, v150
	s_nop 0
	v_mul_f32_e32 v194, 0x3f317217, v150
	v_fma_f32 v194, v150, s52, -v194
	v_fmac_f32_e32 v194, 0x3377d1cf, v150
	v_fmac_f32_e32 v194, 0x3f317217, v150
	v_cmp_lt_f32_e64 s[42:43], |v150|, s53
	s_nop 1
	v_cndmask_b32_e64 v150, v150, v194, s[42:43]
	v_cndmask_b32_e64 v194, 0, v216, s[40:41]
	v_sub_f32_e32 v150, v150, v194
	v_cndmask_b32_e64 v150, v168, v150, s[10:11]
	v_min_f32_e32 v168, 0, v151
	v_mul_f32_e64 v151, |v151|, s57
	v_exp_f32_e32 v151, v151
	s_nop 0
	v_add_f32_e32 v151, 1.0, v151
	v_cmp_gt_f32_e64 s[40:41], s97, v151
	s_nop 1
	v_cndmask_b32_e64 v194, 0, 32, s[40:41]
	v_ldexp_f32 v151, v151, v194
	v_log_f32_e32 v151, v151
	s_nop 0
	v_mul_f32_e32 v194, 0x3f317217, v151
	v_fma_f32 v194, v151, s52, -v194
	v_fmac_f32_e32 v194, 0x3377d1cf, v151
	v_fmac_f32_e32 v194, 0x3f317217, v151
	v_cmp_lt_f32_e64 s[42:43], |v151|, s53
	s_nop 1
	v_cndmask_b32_e64 v151, v151, v194, s[42:43]
	v_cndmask_b32_e64 v194, 0, v216, s[40:41]
	v_sub_f32_e32 v151, v151, v194
	v_sub_f32_e32 v151, v168, v151
	v_min_f32_e32 v168, 0, v147
	v_mul_f32_e64 v147, |v147|, s57
	v_exp_f32_e32 v147, v147
	s_nop 0
	v_add_f32_e32 v147, 1.0, v147
	v_cmp_gt_f32_e64 s[40:41], s97, v147
	s_nop 1
	v_cndmask_b32_e64 v194, 0, 32, s[40:41]
	v_ldexp_f32 v147, v147, v194
	v_log_f32_e32 v147, v147
	s_nop 0
	v_mul_f32_e32 v194, 0x3f317217, v147
	v_fma_f32 v194, v147, s52, -v194
	v_fmac_f32_e32 v194, 0x3377d1cf, v147
	v_fmac_f32_e32 v194, 0x3f317217, v147
	v_cmp_lt_f32_e64 s[42:43], |v147|, s53
	s_nop 1
	v_cndmask_b32_e64 v147, v147, v194, s[42:43]
	v_cndmask_b32_e64 v194, 0, v216, s[40:41]
	v_sub_f32_e32 v147, v147, v194
	v_sub_f32_e32 v168, v168, v147
	v_mul_f32_e32 v147, 0x3fb8aa3b, v151
	v_exp_f32_e32 v147, v147
	s_nop 0
	v_fma_f32 v147, v177, v147, v135
	v_cmp_gt_f32_e64 s[40:41], s97, v147
	s_nop 1
	v_cndmask_b32_e64 v194, 0, 32, s[40:41]
	v_ldexp_f32 v147, v147, v194
	v_log_f32_e32 v147, v147
	s_nop 0
	v_mul_f32_e32 v194, 0x3f317217, v147
	v_fma_f32 v194, v147, s52, -v194
	v_fmac_f32_e32 v194, 0x3377d1cf, v147
	v_fmac_f32_e32 v194, 0x3f317217, v147
	v_cmp_lt_f32_e64 s[42:43], |v147|, s53
	s_nop 1
	v_cndmask_b32_e64 v147, v147, v194, s[42:43]
	v_cndmask_b32_e64 v194, 0, v216, s[40:41]
	v_sub_f32_e32 v147, v147, v194
	v_cndmask_b32_e64 v147, v151, v147, s[8:9]
	v_mul_f32_e32 v151, 0x3fb8aa3b, v168
	v_exp_f32_e32 v151, v151
	s_nop 0
	v_fma_f32 v151, v167, v151, v131
	v_cmp_gt_f32_e64 s[40:41], s97, v151
	s_nop 1
	v_cndmask_b32_e64 v194, 0, 32, s[40:41]
	v_ldexp_f32 v151, v151, v194
	v_log_f32_e32 v151, v151
	s_nop 0
	v_mul_f32_e32 v194, 0x3f317217, v151
	v_fma_f32 v194, v151, s52, -v194
	v_fmac_f32_e32 v194, 0x3377d1cf, v151
	v_fmac_f32_e32 v194, 0x3f317217, v151
	v_cmp_lt_f32_e64 s[42:43], |v151|, s53
	s_nop 1
	v_cndmask_b32_e64 v151, v151, v194, s[42:43]
	v_cndmask_b32_e64 v194, 0, v216, s[40:41]
	v_sub_f32_e32 v151, v151, v194
	v_cndmask_b32_e32 v151, v168, v151, vcc
	flat_store_dwordx4 v[170:171], v[144:147] offset:512 sc1
	flat_store_dwordx4 v[170:171], v[148:151] offset:528 sc1
	s_nop 1
	v_add_u32_e32 v148, 0x90, v166
	v_ashrrev_i32_e32 v149, 31, v148
	v_lshlrev_b64 v[144:145], 6, v[148:149]
	v_lshl_add_u64 v[144:145], v[160:161], 0, v[144:145]
	flat_load_dwordx4 v[144:147], v[144:145]
	s_waitcnt vmcnt(0) lgkmcnt(0)
	v_mov_b32_e32 v150, v145
	v_mov_b32_e32 v151, v146
	v_mov_b32_e32 v145, v147
	v_pk_add_f32 v[144:145], v[150:151], v[144:145]
	s_nop 0
	v_add_f32_e32 v144, v144, v145
	ds_bpermute_b32 v145, v169, v144
	s_waitcnt lgkmcnt(0)
	v_add_f32_e32 v144, v144, v145
	ds_bpermute_b32 v145, v202, v144
	s_waitcnt lgkmcnt(0)
; __device__ __forceinline__ float row_rstd(const float* ssq, int row, int fq) {
;     const f32x4 v = *(const f32x4*)(ssq + (size_t)row * 16 + fq * 4);
;     float s = (v[0] + v[1]) + (v[2] + v[3]);
;     s += __shfl_xor(s, 16); s += __shfl_xor(s, 32);
;     return __builtin_amdgcn_rsqf(s * (1.f / DM) + EPS);
; }
;     __device__ __forceinline__ void operator()(const f32x4 (&acc)[2][2][4][2], const pg8::Unit& u, int wr, int wc, int fr, int fq) const {
;     ...
;             WIN_LOOP( _Pragma("unroll") for (int i = 0; i < 4; ++i) { const float s0 = fminf(a[i], 0.f) - __logf(1.f + __expf(-fabsf(a[i]))), s1 = fminf(b[i], 0.f) - __logf(1.f + __expf(-fabsf(b[i]))); const float la = l0[bj][i], lbv = l1[bj][i];
;                     a[i] = la > 0.f ? __logf(la + (1.f - la) * __expf(s0)) : s0; b[i] = lbv > 0.f ? __logf(lbv + (1.f - lbv) * __expf(s1)) : s1; }
	v_add_f32_e32 v144, v144, v145
	v_fmamk_f32 v144, v144, 0x3a800000, v212
	v_rsq_f32_e32 v168, v144
	v_lshlrev_b64 v[144:145], 11, v[148:149]
	v_lshl_add_u64 v[170:171], s[50:51], 0, v[144:145]
	v_lshl_add_u64 v[170:171], v[170:171], 0, v[192:193]
	v_pk_mul_f32 v[148:149], v[20:21], v[168:169] op_sel_hi:[1,0]
	v_pk_mul_f32 v[144:145], v[16:17], v[168:169] op_sel_hi:[1,0]
	v_min_f32_e32 v194, 0, v148
	v_mul_f32_e64 v148, |v148|, s57
	v_exp_f32_e32 v148, v148
	v_pk_mul_f32 v[150:151], v[22:23], v[168:169] op_sel_hi:[1,0]
	v_pk_mul_f32 v[146:147], v[18:19], v[168:169] op_sel_hi:[1,0]
	v_add_f32_e32 v148, 1.0, v148
	v_cmp_gt_f32_e64 s[40:41], s97, v148
	s_nop 1
	v_cndmask_b32_e64 v195, 0, 32, s[40:41]
	v_ldexp_f32 v148, v148, v195
	v_log_f32_e32 v148, v148
	s_nop 0
	v_mul_f32_e32 v195, 0x3f317217, v148
	v_fma_f32 v195, v148, s52, -v195
	v_fmac_f32_e32 v195, 0x3377d1cf, v148
	v_fmac_f32_e32 v195, 0x3f317217, v148
	v_cmp_lt_f32_e64 s[42:43], |v148|, s53
	s_nop 1
	v_cndmask_b32_e64 v148, v148, v195, s[42:43]
	v_cndmask_b32_e64 v195, 0, v216, s[40:41]
	v_sub_f32_e32 v148, v148, v195
	v_sub_f32_e32 v148, v194, v148
	v_min_f32_e32 v194, 0, v144
	v_mul_f32_e64 v144, |v144|, s57
	v_exp_f32_e32 v144, v144
	s_nop 0
	v_add_f32_e32 v144, 1.0, v144
	v_cmp_gt_f32_e64 s[40:41], s97, v144
	s_nop 1
	v_cndmask_b32_e64 v195, 0, 32, s[40:41]
	v_ldexp_f32 v144, v144, v195
	v_log_f32_e32 v144, v144
	s_nop 0
	v_mul_f32_e32 v195, 0x3f317217, v144
	v_fma_f32 v195, v144, s52, -v195
	v_fmac_f32_e32 v195, 0x3377d1cf, v144
	v_fmac_f32_e32 v195, 0x3f317217, v144
	v_cmp_lt_f32_e64 s[42:43], |v144|, s53
	s_nop 1
	v_cndmask_b32_e64 v144, v144, v195, s[42:43]
	v_cndmask_b32_e64 v195, 0, v216, s[40:41]
	v_sub_f32_e32 v144, v144, v195
	v_sub_f32_e32 v194, v194, v144
	v_mul_f32_e32 v144, 0x3fb8aa3b, v148
	v_exp_f32_e32 v144, v144
	s_nop 0
	v_fma_f32 v144, v190, v144, v140
	v_cmp_gt_f32_e64 s[40:41], s97, v144
	s_nop 1
	v_cndmask_b32_e64 v195, 0, 32, s[40:41]
	v_ldexp_f32 v144, v144, v195
	v_log_f32_e32 v144, v144
	s_nop 0
	v_mul_f32_e32 v195, 0x3f317217, v144
	v_fma_f32 v195, v144, s52, -v195
	v_fmac_f32_e32 v195, 0x3377d1cf, v144
	v_fmac_f32_e32 v195, 0x3f317217, v144
	v_cmp_lt_f32_e64 s[42:43], |v144|, s53
	s_nop 1
	v_cndmask_b32_e64 v144, v144, v195, s[42:43]
	v_cndmask_b32_e64 v195, 0, v216, s[40:41]
	v_sub_f32_e32 v144, v144, v195
	v_cndmask_b32_e64 v144, v148, v144, s[38:39]
	v_mul_f32_e32 v148, 0x3fb8aa3b, v194
	v_exp_f32_e32 v148, v148
	s_nop 0
	v_fma_f32 v148, v191, v148, v136
	v_cmp_gt_f32_e64 s[40:41], s97, v148
	s_nop 1
	v_cndmask_b32_e64 v195, 0, 32, s[40:41]
	v_ldexp_f32 v148, v148, v195
	v_log_f32_e32 v148, v148
	s_nop 0
	v_mul_f32_e32 v195, 0x3f317217, v148
	v_fma_f32 v195, v148, s52, -v195
	v_fmac_f32_e32 v195, 0x3377d1cf, v148
	v_fmac_f32_e32 v195, 0x3f317217, v148
	v_cmp_lt_f32_e64 s[42:43], |v148|, s53
	s_nop 1
	v_cndmask_b32_e64 v148, v148, v195, s[42:43]
	v_cndmask_b32_e64 v195, 0, v216, s[40:41]
	v_sub_f32_e32 v148, v148, v195
	v_cndmask_b32_e64 v148, v194, v148, s[36:37]
	v_min_f32_e32 v194, 0, v149
	v_mul_f32_e64 v149, |v149|, s57
	v_exp_f32_e32 v149, v149
	s_nop 0
	v_add_f32_e32 v149, 1.0, v149
	v_cmp_gt_f32_e64 s[40:41], s97, v149
	s_nop 1
	v_cndmask_b32_e64 v195, 0, 32, s[40:41]
	v_ldexp_f32 v149, v149, v195
	v_log_f32_e32 v149, v149
	s_nop 0
	v_mul_f32_e32 v195, 0x3f317217, v149
	v_fma_f32 v195, v149, s52, -v195
	v_fmac_f32_e32 v195, 0x3377d1cf, v149
	v_fmac_f32_e32 v195, 0x3f317217, v149
	v_cmp_lt_f32_e64 s[42:43], |v149|, s53
	s_nop 1
	v_cndmask_b32_e64 v149, v149, v195, s[42:43]
	v_cndmask_b32_e64 v195, 0, v216, s[40:41]
	v_sub_f32_e32 v149, v149, v195
	v_sub_f32_e32 v149, v194, v149
	v_min_f32_e32 v194, 0, v145
	v_mul_f32_e64 v145, |v145|, s57
	v_exp_f32_e32 v145, v145
	s_nop 0
	v_add_f32_e32 v145, 1.0, v145
	v_cmp_gt_f32_e64 s[40:41], s97, v145
	s_nop 1
	v_cndmask_b32_e64 v195, 0, 32, s[40:41]
	v_ldexp_f32 v145, v145, v195
	v_log_f32_e32 v145, v145
	s_nop 0
	v_mul_f32_e32 v195, 0x3f317217, v145
	v_fma_f32 v195, v145, s52, -v195
	v_fmac_f32_e32 v195, 0x3377d1cf, v145
	v_fmac_f32_e32 v195, 0x3f317217, v145
	v_cmp_lt_f32_e64 s[42:43], |v145|, s53
	s_nop 1
	v_cndmask_b32_e64 v145, v145, v195, s[42:43]
	v_cndmask_b32_e64 v195, 0, v216, s[40:41]
	v_sub_f32_e32 v145, v145, v195
	v_sub_f32_e32 v194, v194, v145
	v_mul_f32_e32 v145, 0x3fb8aa3b, v149
	v_exp_f32_e32 v145, v145
	s_nop 0
	v_fma_f32 v145, v188, v145, v141
	v_cmp_gt_f32_e64 s[40:41], s97, v145
	s_nop 1
	v_cndmask_b32_e64 v195, 0, 32, s[40:41]
	v_ldexp_f32 v145, v145, v195
	v_log_f32_e32 v145, v145
	s_nop 0
	v_mul_f32_e32 v195, 0x3f317217, v145
	v_fma_f32 v195, v145, s52, -v195
	v_fmac_f32_e32 v195, 0x3377d1cf, v145
	v_fmac_f32_e32 v195, 0x3f317217, v145
	v_cmp_lt_f32_e64 s[42:43], |v145|, s53
	s_nop 1
	v_cndmask_b32_e64 v145, v145, v195, s[42:43]
	v_cndmask_b32_e64 v195, 0, v216, s[40:41]
	v_sub_f32_e32 v145, v145, v195
	v_cndmask_b32_e64 v145, v149, v145, s[34:35]
	v_mul_f32_e32 v149, 0x3fb8aa3b, v194
	v_exp_f32_e32 v149, v149
	s_nop 0
	v_fma_f32 v149, v189, v149, v137
	v_cmp_gt_f32_e64 s[40:41], s97, v149
	s_nop 1
	v_cndmask_b32_e64 v195, 0, 32, s[40:41]
	v_ldexp_f32 v149, v149, v195
	v_log_f32_e32 v149, v149
	s_nop 0
	v_mul_f32_e32 v195, 0x3f317217, v149
	v_fma_f32 v195, v149, s52, -v195
	v_fmac_f32_e32 v195, 0x3377d1cf, v149
	v_fmac_f32_e32 v195, 0x3f317217, v149
	v_cmp_lt_f32_e64 s[42:43], |v149|, s53
	s_nop 1
	v_cndmask_b32_e64 v149, v149, v195, s[42:43]
	v_cndmask_b32_e64 v195, 0, v216, s[40:41]
	v_sub_f32_e32 v149, v149, v195
	v_cndmask_b32_e64 v149, v194, v149, s[30:31]
	v_min_f32_e32 v194, 0, v150
	v_mul_f32_e64 v150, |v150|, s57
	v_exp_f32_e32 v150, v150
	s_nop 0
	v_add_f32_e32 v150, 1.0, v150
;     __device__ __forceinline__ void operator()(const f32x4 (&acc)[2][2][4][2], const pg8::Unit& u, int wr, int wc, int fr, int fq) const {
;     ...
;             WIN_LOOP( _Pragma("unroll") for (int i = 0; i < 4; ++i) { const float s0 = fminf(a[i], 0.f) - __logf(1.f + __expf(-fabsf(a[i]))), s1 = fminf(b[i], 0.f) - __logf(1.f + __expf(-fabsf(b[i]))); const float la = l0[bj][i], lbv = l1[bj][i];
;                     a[i] = la > 0.f ? __logf(la + (1.f - la) * __expf(s0)) : s0; b[i] = lbv > 0.f ? __logf(lbv + (1.f - lbv) * __expf(s1)) : s1; }
;                 *(f32x4*)(LF + (size_t)row * 512 + c) = a; *(f32x4*)(LF + (size_t)row * 512 + c + 4) = b; __builtin_amdgcn_sched_barrier(0); ) }
	v_cmp_gt_f32_e64 s[40:41], s97, v150
	s_nop 1
	v_cndmask_b32_e64 v195, 0, 32, s[40:41]
	v_ldexp_f32 v150, v150, v195
	v_log_f32_e32 v150, v150
	s_nop 0
	v_mul_f32_e32 v195, 0x3f317217, v150
	v_fma_f32 v195, v150, s52, -v195
	v_fmac_f32_e32 v195, 0x3377d1cf, v150
	v_fmac_f32_e32 v195, 0x3f317217, v150
	v_cmp_lt_f32_e64 s[42:43], |v150|, s53
	s_nop 1
	v_cndmask_b32_e64 v150, v150, v195, s[42:43]
	v_cndmask_b32_e64 v195, 0, v216, s[40:41]
	v_sub_f32_e32 v150, v150, v195
	v_sub_f32_e32 v150, v194, v150
	v_min_f32_e32 v194, 0, v146
	v_mul_f32_e64 v146, |v146|, s57
	v_exp_f32_e32 v146, v146
	s_nop 0
	v_add_f32_e32 v146, 1.0, v146
	v_cmp_gt_f32_e64 s[40:41], s97, v146
	s_nop 1
	v_cndmask_b32_e64 v195, 0, 32, s[40:41]
	v_ldexp_f32 v146, v146, v195
	v_log_f32_e32 v146, v146
	s_nop 0
	v_mul_f32_e32 v195, 0x3f317217, v146
	v_fma_f32 v195, v146, s52, -v195
	v_fmac_f32_e32 v195, 0x3377d1cf, v146
	v_fmac_f32_e32 v195, 0x3f317217, v146
	v_cmp_lt_f32_e64 s[42:43], |v146|, s53
	s_nop 1
	v_cndmask_b32_e64 v146, v146, v195, s[42:43]
	v_cndmask_b32_e64 v195, 0, v216, s[40:41]
	v_sub_f32_e32 v146, v146, v195
	v_sub_f32_e32 v194, v194, v146
	v_mul_f32_e32 v146, 0x3fb8aa3b, v150
	v_exp_f32_e32 v146, v146
	s_nop 0
	v_fma_f32 v146, v187, v146, v142
	v_cmp_gt_f32_e64 s[40:41], s97, v146
	s_nop 1
	v_cndmask_b32_e64 v195, 0, 32, s[40:41]
	v_ldexp_f32 v146, v146, v195
	v_log_f32_e32 v146, v146
	s_nop 0
	v_mul_f32_e32 v195, 0x3f317217, v146
	v_fma_f32 v195, v146, s52, -v195
	v_fmac_f32_e32 v195, 0x3377d1cf, v146
	v_fmac_f32_e32 v195, 0x3f317217, v146
	v_cmp_lt_f32_e64 s[42:43], |v146|, s53
	s_nop 1
	v_cndmask_b32_e64 v146, v146, v195, s[42:43]
	v_cndmask_b32_e64 v195, 0, v216, s[40:41]
	v_sub_f32_e32 v146, v146, v195
	v_cndmask_b32_e64 v146, v150, v146, s[28:29]
	v_mul_f32_e32 v150, 0x3fb8aa3b, v194
	v_exp_f32_e32 v150, v150
	s_nop 0
	v_fma_f32 v150, v186, v150, v138
	v_cmp_gt_f32_e64 s[40:41], s97, v150
	s_nop 1
	v_cndmask_b32_e64 v195, 0, 32, s[40:41]
	v_ldexp_f32 v150, v150, v195
	v_log_f32_e32 v150, v150
	s_nop 0
	v_mul_f32_e32 v195, 0x3f317217, v150
	v_fma_f32 v195, v150, s52, -v195
	v_fmac_f32_e32 v195, 0x3377d1cf, v150
	v_fmac_f32_e32 v195, 0x3f317217, v150
	v_cmp_lt_f32_e64 s[42:43], |v150|, s53
	s_nop 1
	v_cndmask_b32_e64 v150, v150, v195, s[42:43]
	v_cndmask_b32_e64 v195, 0, v216, s[40:41]
	v_sub_f32_e32 v150, v150, v195
	v_cndmask_b32_e64 v150, v194, v150, s[26:27]
	v_min_f32_e32 v194, 0, v151
	v_mul_f32_e64 v151, |v151|, s57
	v_exp_f32_e32 v151, v151
	s_nop 0
	v_add_f32_e32 v151, 1.0, v151
	v_cmp_gt_f32_e64 s[40:41], s97, v151
	s_nop 1
	v_cndmask_b32_e64 v195, 0, 32, s[40:41]
	v_ldexp_f32 v151, v151, v195
	v_log_f32_e32 v151, v151
	s_nop 0
	v_mul_f32_e32 v195, 0x3f317217, v151
	v_fma_f32 v195, v151, s52, -v195
	v_fmac_f32_e32 v195, 0x3377d1cf, v151
	v_fmac_f32_e32 v195, 0x3f317217, v151
	v_cmp_lt_f32_e64 s[42:43], |v151|, s53
	s_nop 1
	v_cndmask_b32_e64 v151, v151, v195, s[42:43]
	v_cndmask_b32_e64 v195, 0, v216, s[40:41]
	v_sub_f32_e32 v151, v151, v195
	v_sub_f32_e32 v151, v194, v151
	v_min_f32_e32 v194, 0, v147
	v_mul_f32_e64 v147, |v147|, s57
	v_exp_f32_e32 v147, v147
	s_nop 0
	v_add_f32_e32 v147, 1.0, v147
	v_cmp_gt_f32_e64 s[40:41], s97, v147
	s_nop 1
	v_cndmask_b32_e64 v195, 0, 32, s[40:41]
	v_ldexp_f32 v147, v147, v195
	v_log_f32_e32 v147, v147
	s_nop 0
	v_mul_f32_e32 v195, 0x3f317217, v147
	v_fma_f32 v195, v147, s52, -v195
	v_fmac_f32_e32 v195, 0x3377d1cf, v147
	v_fmac_f32_e32 v195, 0x3f317217, v147
	v_cmp_lt_f32_e64 s[42:43], |v147|, s53
	s_nop 1
	v_cndmask_b32_e64 v147, v147, v195, s[42:43]
	v_cndmask_b32_e64 v195, 0, v216, s[40:41]
	v_sub_f32_e32 v147, v147, v195
	v_sub_f32_e32 v194, v194, v147
	v_mul_f32_e32 v147, 0x3fb8aa3b, v151
	v_exp_f32_e32 v147, v147
	s_nop 0
	v_fma_f32 v147, v185, v147, v143
	v_cmp_gt_f32_e64 s[40:41], s97, v147
	s_nop 1
	v_cndmask_b32_e64 v195, 0, 32, s[40:41]
	v_ldexp_f32 v147, v147, v195
	v_log_f32_e32 v147, v147
	s_nop 0
	v_mul_f32_e32 v195, 0x3f317217, v147
	v_fma_f32 v195, v147, s52, -v195
	v_fmac_f32_e32 v195, 0x3377d1cf, v147
	v_fmac_f32_e32 v195, 0x3f317217, v147
	v_cmp_lt_f32_e64 s[42:43], |v147|, s53
	s_nop 1
	v_cndmask_b32_e64 v147, v147, v195, s[42:43]
	v_cndmask_b32_e64 v195, 0, v216, s[40:41]
	v_sub_f32_e32 v147, v147, v195
	v_cndmask_b32_e64 v147, v151, v147, s[24:25]
	v_mul_f32_e32 v151, 0x3fb8aa3b, v194
	v_exp_f32_e32 v151, v151
	s_nop 0
	v_fma_f32 v151, v184, v151, v139
	v_cmp_gt_f32_e64 s[40:41], s97, v151
	s_nop 1
	v_cndmask_b32_e64 v195, 0, 32, s[40:41]
	v_ldexp_f32 v151, v151, v195
	v_log_f32_e32 v151, v151
	s_nop 0
	v_mul_f32_e32 v195, 0x3f317217, v151
	v_fma_f32 v195, v151, s52, -v195
	v_fmac_f32_e32 v195, 0x3377d1cf, v151
	v_fmac_f32_e32 v195, 0x3f317217, v151
	v_cmp_lt_f32_e64 s[42:43], |v151|, s53
	s_nop 1
	v_cndmask_b32_e64 v151, v151, v195, s[42:43]
	v_cndmask_b32_e64 v195, 0, v216, s[40:41]
	v_sub_f32_e32 v151, v151, v195
	v_cndmask_b32_e64 v151, v194, v151, s[22:23]
	flat_store_dwordx4 v[170:171], v[144:147] sc1
	flat_store_dwordx4 v[170:171], v[148:151] offset:16 sc1
	s_nop 1
	v_pk_mul_f32 v[148:149], v[84:85], v[168:169] op_sel_hi:[1,0]
	v_pk_mul_f32 v[150:151], v[86:87], v[168:169] op_sel_hi:[1,0]
	v_pk_mul_f32 v[146:147], v[82:83], v[168:169] op_sel_hi:[1,0]
	v_pk_mul_f32 v[144:145], v[80:81], v[168:169] op_sel_hi:[1,0]
	v_min_f32_e32 v168, 0, v148
	v_mul_f32_e64 v148, |v148|, s57
	v_exp_f32_e32 v148, v148
	s_nop 0
	v_add_f32_e32 v148, 1.0, v148
	v_cmp_gt_f32_e64 s[40:41], s97, v148
	s_nop 1
	v_cndmask_b32_e64 v194, 0, 32, s[40:41]
	v_ldexp_f32 v148, v148, v194
	v_log_f32_e32 v148, v148
	s_nop 0
	v_mul_f32_e32 v194, 0x3f317217, v148
	v_fma_f32 v194, v148, s52, -v194
;     __device__ __forceinline__ void operator()(const f32x4 (&acc)[2][2][4][2], const pg8::Unit& u, int wr, int wc, int fr, int fq) const {
;     ...
;             WIN_LOOP( _Pragma("unroll") for (int i = 0; i < 4; ++i) { const float s0 = fminf(a[i], 0.f) - __logf(1.f + __expf(-fabsf(a[i]))), s1 = fminf(b[i], 0.f) - __logf(1.f + __expf(-fabsf(b[i]))); const float la = l0[bj][i], lbv = l1[bj][i];
;                     a[i] = la > 0.f ? __logf(la + (1.f - la) * __expf(s0)) : s0; b[i] = lbv > 0.f ? __logf(lbv + (1.f - lbv) * __expf(s1)) : s1; }
	v_fmac_f32_e32 v194, 0x3377d1cf, v148
	v_fmac_f32_e32 v194, 0x3f317217, v148
	v_cmp_lt_f32_e64 s[42:43], |v148|, s53
	s_nop 1
	v_cndmask_b32_e64 v148, v148, v194, s[42:43]
	v_cndmask_b32_e64 v194, 0, v216, s[40:41]
	v_sub_f32_e32 v148, v148, v194
	v_sub_f32_e32 v148, v168, v148
	v_min_f32_e32 v168, 0, v144
	v_mul_f32_e64 v144, |v144|, s57
	v_exp_f32_e32 v144, v144
	s_nop 0
	v_add_f32_e32 v144, 1.0, v144
	v_cmp_gt_f32_e64 s[40:41], s97, v144
	s_nop 1
	v_cndmask_b32_e64 v194, 0, 32, s[40:41]
	v_ldexp_f32 v144, v144, v194
	v_log_f32_e32 v144, v144
	s_nop 0
	v_mul_f32_e32 v194, 0x3f317217, v144
	v_fma_f32 v194, v144, s52, -v194
	v_fmac_f32_e32 v194, 0x3377d1cf, v144
	v_fmac_f32_e32 v194, 0x3f317217, v144
	v_cmp_lt_f32_e64 s[42:43], |v144|, s53
	s_nop 1
	v_cndmask_b32_e64 v144, v144, v194, s[42:43]
	v_cndmask_b32_e64 v194, 0, v216, s[40:41]
	v_sub_f32_e32 v144, v144, v194
	v_sub_f32_e32 v168, v168, v144
	v_mul_f32_e32 v144, 0x3fb8aa3b, v148
	v_exp_f32_e32 v144, v144
	s_nop 0
	v_fma_f32 v144, v183, v144, v132
	v_cmp_gt_f32_e64 s[40:41], s97, v144
	s_nop 1
	v_cndmask_b32_e64 v194, 0, 32, s[40:41]
	v_ldexp_f32 v144, v144, v194
	v_log_f32_e32 v144, v144
	s_nop 0
	v_mul_f32_e32 v194, 0x3f317217, v144
	v_fma_f32 v194, v144, s52, -v194
	v_fmac_f32_e32 v194, 0x3377d1cf, v144
	v_fmac_f32_e32 v194, 0x3f317217, v144
	v_cmp_lt_f32_e64 s[42:43], |v144|, s53
	s_nop 1
	v_cndmask_b32_e64 v144, v144, v194, s[42:43]
	v_cndmask_b32_e64 v194, 0, v216, s[40:41]
	v_sub_f32_e32 v144, v144, v194
	v_cndmask_b32_e64 v144, v148, v144, s[20:21]
	v_mul_f32_e32 v148, 0x3fb8aa3b, v168
	v_exp_f32_e32 v148, v148
	s_nop 0
	v_fma_f32 v148, v182, v148, v128
	v_cmp_gt_f32_e64 s[40:41], s97, v148
	s_nop 1
	v_cndmask_b32_e64 v194, 0, 32, s[40:41]
	v_ldexp_f32 v148, v148, v194
	v_log_f32_e32 v148, v148
	s_nop 0
	v_mul_f32_e32 v194, 0x3f317217, v148
	v_fma_f32 v194, v148, s52, -v194
	v_fmac_f32_e32 v194, 0x3377d1cf, v148
	v_fmac_f32_e32 v194, 0x3f317217, v148
	v_cmp_lt_f32_e64 s[42:43], |v148|, s53
	s_nop 1
	v_cndmask_b32_e64 v148, v148, v194, s[42:43]
	v_cndmask_b32_e64 v194, 0, v216, s[40:41]
	v_sub_f32_e32 v148, v148, v194
	v_cndmask_b32_e64 v148, v168, v148, s[18:19]
	v_min_f32_e32 v168, 0, v149
	v_mul_f32_e64 v149, |v149|, s57
	v_exp_f32_e32 v149, v149
	s_nop 0
	v_add_f32_e32 v149, 1.0, v149
	v_cmp_gt_f32_e64 s[40:41], s97, v149
	s_nop 1
	v_cndmask_b32_e64 v194, 0, 32, s[40:41]
	v_ldexp_f32 v149, v149, v194
	v_log_f32_e32 v149, v149
	s_nop 0
	v_mul_f32_e32 v194, 0x3f317217, v149
	v_fma_f32 v194, v149, s52, -v194
	v_fmac_f32_e32 v194, 0x3377d1cf, v149
	v_fmac_f32_e32 v194, 0x3f317217, v149
	v_cmp_lt_f32_e64 s[42:43], |v149|, s53
	s_nop 1
	v_cndmask_b32_e64 v149, v149, v194, s[42:43]
	v_cndmask_b32_e64 v194, 0, v216, s[40:41]
	v_sub_f32_e32 v149, v149, v194
	v_sub_f32_e32 v149, v168, v149
	v_min_f32_e32 v168, 0, v145
	v_mul_f32_e64 v145, |v145|, s57
	v_exp_f32_e32 v145, v145
	s_nop 0
	v_add_f32_e32 v145, 1.0, v145
	v_cmp_gt_f32_e64 s[40:41], s97, v145
	s_nop 1
	v_cndmask_b32_e64 v194, 0, 32, s[40:41]
	v_ldexp_f32 v145, v145, v194
	v_log_f32_e32 v145, v145
	s_nop 0
	v_mul_f32_e32 v194, 0x3f317217, v145
	v_fma_f32 v194, v145, s52, -v194
	v_fmac_f32_e32 v194, 0x3377d1cf, v145
	v_fmac_f32_e32 v194, 0x3f317217, v145
	v_cmp_lt_f32_e64 s[42:43], |v145|, s53
	s_nop 1
	v_cndmask_b32_e64 v145, v145, v194, s[42:43]
	v_cndmask_b32_e64 v194, 0, v216, s[40:41]
	v_sub_f32_e32 v145, v145, v194
	v_sub_f32_e32 v168, v168, v145
	v_mul_f32_e32 v145, 0x3fb8aa3b, v149
	v_exp_f32_e32 v145, v145
	s_nop 0
	v_fma_f32 v145, v181, v145, v133
	v_cmp_gt_f32_e64 s[40:41], s97, v145
	s_nop 1
	v_cndmask_b32_e64 v194, 0, 32, s[40:41]
	v_ldexp_f32 v145, v145, v194
	v_log_f32_e32 v145, v145
	s_nop 0
	v_mul_f32_e32 v194, 0x3f317217, v145
	v_fma_f32 v194, v145, s52, -v194
	v_fmac_f32_e32 v194, 0x3377d1cf, v145
	v_fmac_f32_e32 v194, 0x3f317217, v145
	v_cmp_lt_f32_e64 s[42:43], |v145|, s53
	s_nop 1
	v_cndmask_b32_e64 v145, v145, v194, s[42:43]
	v_cndmask_b32_e64 v194, 0, v216, s[40:41]
	v_sub_f32_e32 v145, v145, v194
	v_cndmask_b32_e64 v145, v149, v145, s[16:17]
	v_mul_f32_e32 v149, 0x3fb8aa3b, v168
	v_exp_f32_e32 v149, v149
	s_nop 0
	v_fma_f32 v149, v180, v149, v129
	v_cmp_gt_f32_e64 s[40:41], s97, v149
	s_nop 1
	v_cndmask_b32_e64 v194, 0, 32, s[40:41]
	v_ldexp_f32 v149, v149, v194
	v_log_f32_e32 v149, v149
	s_nop 0
	v_mul_f32_e32 v194, 0x3f317217, v149
	v_fma_f32 v194, v149, s52, -v194
	v_fmac_f32_e32 v194, 0x3377d1cf, v149
	v_fmac_f32_e32 v194, 0x3f317217, v149
	v_cmp_lt_f32_e64 s[42:43], |v149|, s53
	s_nop 1
	v_cndmask_b32_e64 v149, v149, v194, s[42:43]
	v_cndmask_b32_e64 v194, 0, v216, s[40:41]
	v_sub_f32_e32 v149, v149, v194
	v_cndmask_b32_e64 v149, v168, v149, s[14:15]
	v_min_f32_e32 v168, 0, v150
	v_mul_f32_e64 v150, |v150|, s57
	v_exp_f32_e32 v150, v150
	s_nop 0
	v_add_f32_e32 v150, 1.0, v150
	v_cmp_gt_f32_e64 s[40:41], s97, v150
	s_nop 1
	v_cndmask_b32_e64 v194, 0, 32, s[40:41]
	v_ldexp_f32 v150, v150, v194
	v_log_f32_e32 v150, v150
	s_nop 0
	v_mul_f32_e32 v194, 0x3f317217, v150
	v_fma_f32 v194, v150, s52, -v194
	v_fmac_f32_e32 v194, 0x3377d1cf, v150
	v_fmac_f32_e32 v194, 0x3f317217, v150
	v_cmp_lt_f32_e64 s[42:43], |v150|, s53
	s_nop 1
	v_cndmask_b32_e64 v150, v150, v194, s[42:43]
	v_cndmask_b32_e64 v194, 0, v216, s[40:41]
	v_sub_f32_e32 v150, v150, v194
	v_sub_f32_e32 v150, v168, v150
	v_min_f32_e32 v168, 0, v146
	v_mul_f32_e64 v146, |v146|, s57
	v_exp_f32_e32 v146, v146
	s_nop 0
	v_add_f32_e32 v146, 1.0, v146
	v_cmp_gt_f32_e64 s[40:41], s97, v146
	s_nop 1
	v_cndmask_b32_e64 v194, 0, 32, s[40:41]
	v_ldexp_f32 v146, v146, v194
	v_log_f32_e32 v146, v146
	s_nop 0
	v_mul_f32_e32 v194, 0x3f317217, v146
; __device__ __forceinline__ float row_rstd(const float* ssq, int row, int fq) {
;     const f32x4 v = *(const f32x4*)(ssq + (size_t)row * 16 + fq * 4);
;     float s = (v[0] + v[1]) + (v[2] + v[3]);
;     s += __shfl_xor(s, 16); s += __shfl_xor(s, 32);
;     return __builtin_amdgcn_rsqf(s * (1.f / DM) + EPS);
; }
;     __device__ __forceinline__ void operator()(const f32x4 (&acc)[2][2][4][2], const pg8::Unit& u, int wr, int wc, int fr, int fq) const {
;     ...
;             WIN_LOOP( _Pragma("unroll") for (int i = 0; i < 4; ++i) { const float s0 = fminf(a[i], 0.f) - __logf(1.f + __expf(-fabsf(a[i]))), s1 = fminf(b[i], 0.f) - __logf(1.f + __expf(-fabsf(b[i]))); const float la = l0[bj][i], lbv = l1[bj][i];
;                     a[i] = la > 0.f ? __logf(la + (1.f - la) * __expf(s0)) : s0; b[i] = lbv > 0.f ? __logf(lbv + (1.f - lbv) * __expf(s1)) : s1; }
;                 *(f32x4*)(LF + (size_t)row * 512 + c) = a; *(f32x4*)(LF + (size_t)row * 512 + c + 4) = b; __builtin_amdgcn_sched_barrier(0); ) }
	v_fma_f32 v194, v146, s52, -v194
	v_fmac_f32_e32 v194, 0x3377d1cf, v146
	v_fmac_f32_e32 v194, 0x3f317217, v146
	v_cmp_lt_f32_e64 s[42:43], |v146|, s53
	s_nop 1
	v_cndmask_b32_e64 v146, v146, v194, s[42:43]
	v_cndmask_b32_e64 v194, 0, v216, s[40:41]
	v_sub_f32_e32 v146, v146, v194
	v_sub_f32_e32 v168, v168, v146
	v_mul_f32_e32 v146, 0x3fb8aa3b, v150
	v_exp_f32_e32 v146, v146
	s_nop 0
	v_fma_f32 v146, v179, v146, v134
	v_cmp_gt_f32_e64 s[40:41], s97, v146
	s_nop 1
	v_cndmask_b32_e64 v194, 0, 32, s[40:41]
	v_ldexp_f32 v146, v146, v194
	v_log_f32_e32 v146, v146
	s_nop 0
	v_mul_f32_e32 v194, 0x3f317217, v146
	v_fma_f32 v194, v146, s52, -v194
	v_fmac_f32_e32 v194, 0x3377d1cf, v146
	v_fmac_f32_e32 v194, 0x3f317217, v146
	v_cmp_lt_f32_e64 s[42:43], |v146|, s53
	s_nop 1
	v_cndmask_b32_e64 v146, v146, v194, s[42:43]
	v_cndmask_b32_e64 v194, 0, v216, s[40:41]
	v_sub_f32_e32 v146, v146, v194
	v_cndmask_b32_e64 v146, v150, v146, s[12:13]
	v_mul_f32_e32 v150, 0x3fb8aa3b, v168
	v_exp_f32_e32 v150, v150
	s_nop 0
	v_fma_f32 v150, v178, v150, v130
	v_cmp_gt_f32_e64 s[40:41], s97, v150
	s_nop 1
	v_cndmask_b32_e64 v194, 0, 32, s[40:41]
	v_ldexp_f32 v150, v150, v194
	v_log_f32_e32 v150, v150
	s_nop 0
	v_mul_f32_e32 v194, 0x3f317217, v150
	v_fma_f32 v194, v150, s52, -v194
	v_fmac_f32_e32 v194, 0x3377d1cf, v150
	v_fmac_f32_e32 v194, 0x3f317217, v150
	v_cmp_lt_f32_e64 s[42:43], |v150|, s53
	s_nop 1
	v_cndmask_b32_e64 v150, v150, v194, s[42:43]
	v_cndmask_b32_e64 v194, 0, v216, s[40:41]
	v_sub_f32_e32 v150, v150, v194
	v_cndmask_b32_e64 v150, v168, v150, s[10:11]
	v_min_f32_e32 v168, 0, v151
	v_mul_f32_e64 v151, |v151|, s57
	v_exp_f32_e32 v151, v151
	s_nop 0
	v_add_f32_e32 v151, 1.0, v151
	v_cmp_gt_f32_e64 s[40:41], s97, v151
	s_nop 1
	v_cndmask_b32_e64 v194, 0, 32, s[40:41]
	v_ldexp_f32 v151, v151, v194
	v_log_f32_e32 v151, v151
	s_nop 0
	v_mul_f32_e32 v194, 0x3f317217, v151
	v_fma_f32 v194, v151, s52, -v194
	v_fmac_f32_e32 v194, 0x3377d1cf, v151
	v_fmac_f32_e32 v194, 0x3f317217, v151
	v_cmp_lt_f32_e64 s[42:43], |v151|, s53
	s_nop 1
	v_cndmask_b32_e64 v151, v151, v194, s[42:43]
	v_cndmask_b32_e64 v194, 0, v216, s[40:41]
	v_sub_f32_e32 v151, v151, v194
	v_sub_f32_e32 v151, v168, v151
	v_min_f32_e32 v168, 0, v147
	v_mul_f32_e64 v147, |v147|, s57
	v_exp_f32_e32 v147, v147
	s_nop 0
	v_add_f32_e32 v147, 1.0, v147
	v_cmp_gt_f32_e64 s[40:41], s97, v147
	s_nop 1
	v_cndmask_b32_e64 v194, 0, 32, s[40:41]
	v_ldexp_f32 v147, v147, v194
	v_log_f32_e32 v147, v147
	s_nop 0
	v_mul_f32_e32 v194, 0x3f317217, v147
	v_fma_f32 v194, v147, s52, -v194
	v_fmac_f32_e32 v194, 0x3377d1cf, v147
	v_fmac_f32_e32 v194, 0x3f317217, v147
	v_cmp_lt_f32_e64 s[42:43], |v147|, s53
	s_nop 1
	v_cndmask_b32_e64 v147, v147, v194, s[42:43]
	v_cndmask_b32_e64 v194, 0, v216, s[40:41]
	v_sub_f32_e32 v147, v147, v194
	v_sub_f32_e32 v168, v168, v147
	v_mul_f32_e32 v147, 0x3fb8aa3b, v151
	v_exp_f32_e32 v147, v147
	s_nop 0
	v_fma_f32 v147, v177, v147, v135
	v_cmp_gt_f32_e64 s[40:41], s97, v147
	s_nop 1
	v_cndmask_b32_e64 v194, 0, 32, s[40:41]
	v_ldexp_f32 v147, v147, v194
	v_log_f32_e32 v147, v147
	s_nop 0
	v_mul_f32_e32 v194, 0x3f317217, v147
	v_fma_f32 v194, v147, s52, -v194
	v_fmac_f32_e32 v194, 0x3377d1cf, v147
	v_fmac_f32_e32 v194, 0x3f317217, v147
	v_cmp_lt_f32_e64 s[42:43], |v147|, s53
	s_nop 1
	v_cndmask_b32_e64 v147, v147, v194, s[42:43]
	v_cndmask_b32_e64 v194, 0, v216, s[40:41]
	v_sub_f32_e32 v147, v147, v194
	v_cndmask_b32_e64 v147, v151, v147, s[8:9]
	v_mul_f32_e32 v151, 0x3fb8aa3b, v168
	v_exp_f32_e32 v151, v151
	s_nop 0
	v_fma_f32 v151, v167, v151, v131
	v_cmp_gt_f32_e64 s[40:41], s97, v151
	s_nop 1
	v_cndmask_b32_e64 v194, 0, 32, s[40:41]
	v_ldexp_f32 v151, v151, v194
	v_log_f32_e32 v151, v151
	s_nop 0
	v_mul_f32_e32 v194, 0x3f317217, v151
	v_fma_f32 v194, v151, s52, -v194
	v_fmac_f32_e32 v194, 0x3377d1cf, v151
	v_fmac_f32_e32 v194, 0x3f317217, v151
	v_cmp_lt_f32_e64 s[42:43], |v151|, s53
	s_nop 1
	v_cndmask_b32_e64 v151, v151, v194, s[42:43]
	v_cndmask_b32_e64 v194, 0, v216, s[40:41]
	v_sub_f32_e32 v151, v151, v194
	v_cndmask_b32_e32 v151, v168, v151, vcc
	flat_store_dwordx4 v[170:171], v[144:147] offset:512 sc1
	flat_store_dwordx4 v[170:171], v[148:151] offset:528 sc1
	s_nop 1
	v_add_u32_e32 v148, 0xa0, v166
	v_ashrrev_i32_e32 v149, 31, v148
	v_lshlrev_b64 v[144:145], 6, v[148:149]
	v_lshl_add_u64 v[144:145], v[160:161], 0, v[144:145]
	flat_load_dwordx4 v[144:147], v[144:145]
	s_waitcnt vmcnt(0) lgkmcnt(0)
	v_mov_b32_e32 v150, v145
	v_mov_b32_e32 v151, v146
	v_mov_b32_e32 v145, v147
	v_pk_add_f32 v[144:145], v[150:151], v[144:145]
	s_nop 0
	v_add_f32_e32 v144, v144, v145
	ds_bpermute_b32 v145, v169, v144
	s_waitcnt lgkmcnt(0)
	v_add_f32_e32 v144, v144, v145
	ds_bpermute_b32 v145, v202, v144
	s_waitcnt lgkmcnt(0)
; __device__ __forceinline__ float silu_f(float x) { return x * __builtin_amdgcn_rcpf(1.f + __expf(-x)); }
; __device__ __forceinline__ v4u pack8(const f32x4 a, const f32x4 b) { v4u w; w.x = cvt_pk_bf16(a[0], a[1]); w.y = cvt_pk_bf16(a[2], a[3]); w.z = cvt_pk_bf16(b[0], b[1]); w.w = cvt_pk_bf16(b[2], b[3]); return w; }
;     __device__ __forceinline__ void operator()(const f32x4 (&acc)[2][2][4][2], const pg8::Unit& u, int wr, int wc, int fr, int fq) const {
;     ...
;         if (grp == 0) { WIN_LOOP( _Pragma("unroll") for (int i = 0; i < 4; ++i) { a[i] = silu_f(a[i]); b[i] = silu_f(b[i]); } *(v4u*)(QO + (size_t)row * DM + c) = pack8(a, b); ) }
;         else if (grp == 3) { WIN_LOOP( _Pragma("unroll") for (int i = 0; i < 4; ++i) { a[i] = silu_f(a[i]); b[i] = silu_f(b[i]); } *(v4u*)(GH + (size_t)row * 512 + c) = pack8(a, b); ) }
;         else if (grp == 1) {
;             f32x4 l0[2], l1[2];
; #pragma unroll
;             for (int bj = 0; bj < 2; ++bj) { l0[bj] = *(const f32x4*)(lb + cb + bj * 128); l1[bj] = *(const f32x4*)(lb + cb + bj * 128 + 4); }
;             WIN_LOOP( _Pragma("unroll") for (int i = 0; i < 4; ++i) { const float s0 = fminf(a[i], 0.f) - __logf(1.f + __expf(-fabsf(a[i]))), s1 = fminf(b[i], 0.f) - __logf(1.f + __expf(-fabsf(b[i]))); const float la = l0[bj][i], lbv = l1[bj][i];
;                     a[i] = la > 0.f ? __logf(la + (1.f - la) * __expf(s0)) : s0; b[i] = lbv > 0.f ? __logf(lbv + (1.f - lbv) * __expf(s1)) : s1; }
;                 *(f32x4*)(LF + (size_t)row * 512 + c) = a; *(f32x4*)(LF + (size_t)row * 512 + c + 4) = b; __builtin_amdgcn_sched_barrier(0); ) }
	v_add_f32_e32 v144, v144, v145
	v_fmamk_f32 v144, v144, 0x3a800000, v212
	v_rsq_f32_e32 v168, v144
	v_lshlrev_b64 v[144:145], 11, v[148:149]
	v_lshl_add_u64 v[170:171], s[50:51], 0, v[144:145]
	v_lshl_add_u64 v[170:171], v[170:171], 0, v[192:193]
	v_pk_mul_f32 v[148:149], v[12:13], v[168:169] op_sel_hi:[1,0]
	v_pk_mul_f32 v[144:145], v[8:9], v[168:169] op_sel_hi:[1,0]
	v_min_f32_e32 v194, 0, v148
	v_mul_f32_e64 v148, |v148|, s57
	v_exp_f32_e32 v148, v148
	v_pk_mul_f32 v[150:151], v[14:15], v[168:169] op_sel_hi:[1,0]
	v_pk_mul_f32 v[146:147], v[10:11], v[168:169] op_sel_hi:[1,0]
	v_add_f32_e32 v148, 1.0, v148
	v_cmp_gt_f32_e64 s[40:41], s97, v148
	s_nop 1
	v_cndmask_b32_e64 v195, 0, 32, s[40:41]
	v_ldexp_f32 v148, v148, v195
	v_log_f32_e32 v148, v148
	s_nop 0
	v_mul_f32_e32 v195, 0x3f317217, v148
	v_fma_f32 v195, v148, s52, -v195
	v_fmac_f32_e32 v195, 0x3377d1cf, v148
	v_fmac_f32_e32 v195, 0x3f317217, v148
	v_cmp_lt_f32_e64 s[42:43], |v148|, s53
	s_nop 1
	v_cndmask_b32_e64 v148, v148, v195, s[42:43]
	v_cndmask_b32_e64 v195, 0, v216, s[40:41]
	v_sub_f32_e32 v148, v148, v195
	v_sub_f32_e32 v148, v194, v148
	v_min_f32_e32 v194, 0, v144
	v_mul_f32_e64 v144, |v144|, s57
	v_exp_f32_e32 v144, v144
	s_nop 0
	v_add_f32_e32 v144, 1.0, v144
	v_cmp_gt_f32_e64 s[40:41], s97, v144
	s_nop 1
	v_cndmask_b32_e64 v195, 0, 32, s[40:41]
	v_ldexp_f32 v144, v144, v195
	v_log_f32_e32 v144, v144
	s_nop 0
	v_mul_f32_e32 v195, 0x3f317217, v144
	v_fma_f32 v195, v144, s52, -v195
	v_fmac_f32_e32 v195, 0x3377d1cf, v144
	v_fmac_f32_e32 v195, 0x3f317217, v144
	v_cmp_lt_f32_e64 s[42:43], |v144|, s53
	s_nop 1
	v_cndmask_b32_e64 v144, v144, v195, s[42:43]
	v_cndmask_b32_e64 v195, 0, v216, s[40:41]
	v_sub_f32_e32 v144, v144, v195
	v_sub_f32_e32 v194, v194, v144
	v_mul_f32_e32 v144, 0x3fb8aa3b, v148
	v_exp_f32_e32 v144, v144
	s_nop 0
	v_fma_f32 v144, v190, v144, v140
	v_cmp_gt_f32_e64 s[40:41], s97, v144
	s_nop 1
	v_cndmask_b32_e64 v195, 0, 32, s[40:41]
	v_ldexp_f32 v144, v144, v195
	v_log_f32_e32 v144, v144
	s_nop 0
	v_mul_f32_e32 v195, 0x3f317217, v144
	v_fma_f32 v195, v144, s52, -v195
	v_fmac_f32_e32 v195, 0x3377d1cf, v144
	v_fmac_f32_e32 v195, 0x3f317217, v144
	v_cmp_lt_f32_e64 s[42:43], |v144|, s53
	s_nop 1
	v_cndmask_b32_e64 v144, v144, v195, s[42:43]
	v_cndmask_b32_e64 v195, 0, v216, s[40:41]
	v_sub_f32_e32 v144, v144, v195
	v_cndmask_b32_e64 v144, v148, v144, s[38:39]
	v_mul_f32_e32 v148, 0x3fb8aa3b, v194
	v_exp_f32_e32 v148, v148
	s_nop 0
	v_fma_f32 v148, v191, v148, v136
	v_cmp_gt_f32_e64 s[40:41], s97, v148
	s_nop 1
	v_cndmask_b32_e64 v195, 0, 32, s[40:41]
	v_ldexp_f32 v148, v148, v195
	v_log_f32_e32 v148, v148
	s_nop 0
	v_mul_f32_e32 v195, 0x3f317217, v148
	v_fma_f32 v195, v148, s52, -v195
	v_fmac_f32_e32 v195, 0x3377d1cf, v148
	v_fmac_f32_e32 v195, 0x3f317217, v148
	v_cmp_lt_f32_e64 s[42:43], |v148|, s53
	s_nop 1
	v_cndmask_b32_e64 v148, v148, v195, s[42:43]
	v_cndmask_b32_e64 v195, 0, v216, s[40:41]
	v_sub_f32_e32 v148, v148, v195
	v_cndmask_b32_e64 v148, v194, v148, s[36:37]
	v_min_f32_e32 v194, 0, v149
	v_mul_f32_e64 v149, |v149|, s57
	v_exp_f32_e32 v149, v149
	s_nop 0
	v_add_f32_e32 v149, 1.0, v149
	v_cmp_gt_f32_e64 s[40:41], s97, v149
	s_nop 1
	v_cndmask_b32_e64 v195, 0, 32, s[40:41]
	v_ldexp_f32 v149, v149, v195
	v_log_f32_e32 v149, v149
	s_nop 0
	v_mul_f32_e32 v195, 0x3f317217, v149
	v_fma_f32 v195, v149, s52, -v195
	v_fmac_f32_e32 v195, 0x3377d1cf, v149
	v_fmac_f32_e32 v195, 0x3f317217, v149
	v_cmp_lt_f32_e64 s[42:43], |v149|, s53
	s_nop 1
	v_cndmask_b32_e64 v149, v149, v195, s[42:43]
	v_cndmask_b32_e64 v195, 0, v216, s[40:41]
	v_sub_f32_e32 v149, v149, v195
	v_sub_f32_e32 v149, v194, v149
	v_min_f32_e32 v194, 0, v145
	v_mul_f32_e64 v145, |v145|, s57
	v_exp_f32_e32 v145, v145
	s_nop 0
	v_add_f32_e32 v145, 1.0, v145
	v_cmp_gt_f32_e64 s[40:41], s97, v145
	s_nop 1
	v_cndmask_b32_e64 v195, 0, 32, s[40:41]
	v_ldexp_f32 v145, v145, v195
	v_log_f32_e32 v145, v145
	s_nop 0
	v_mul_f32_e32 v195, 0x3f317217, v145
	v_fma_f32 v195, v145, s52, -v195
	v_fmac_f32_e32 v195, 0x3377d1cf, v145
	v_fmac_f32_e32 v195, 0x3f317217, v145
	v_cmp_lt_f32_e64 s[42:43], |v145|, s53
	s_nop 1
	v_cndmask_b32_e64 v145, v145, v195, s[42:43]
	v_cndmask_b32_e64 v195, 0, v216, s[40:41]
	v_sub_f32_e32 v145, v145, v195
	v_sub_f32_e32 v194, v194, v145
	v_mul_f32_e32 v145, 0x3fb8aa3b, v149
	v_exp_f32_e32 v145, v145
	s_nop 0
	v_fma_f32 v145, v188, v145, v141
	v_cmp_gt_f32_e64 s[40:41], s97, v145
	s_nop 1
	v_cndmask_b32_e64 v195, 0, 32, s[40:41]
	v_ldexp_f32 v145, v145, v195
	v_log_f32_e32 v145, v145
	s_nop 0
	v_mul_f32_e32 v195, 0x3f317217, v145
	v_fma_f32 v195, v145, s52, -v195
	v_fmac_f32_e32 v195, 0x3377d1cf, v145
	v_fmac_f32_e32 v195, 0x3f317217, v145
	v_cmp_lt_f32_e64 s[42:43], |v145|, s53
	s_nop 1
	v_cndmask_b32_e64 v145, v145, v195, s[42:43]
	v_cndmask_b32_e64 v195, 0, v216, s[40:41]
	v_sub_f32_e32 v145, v145, v195
	v_cndmask_b32_e64 v145, v149, v145, s[34:35]
	v_mul_f32_e32 v149, 0x3fb8aa3b, v194
	v_exp_f32_e32 v149, v149
	s_nop 0
	v_fma_f32 v149, v189, v149, v137
	v_cmp_gt_f32_e64 s[40:41], s97, v149
	s_nop 1
	v_cndmask_b32_e64 v195, 0, 32, s[40:41]
	v_ldexp_f32 v149, v149, v195
	v_log_f32_e32 v149, v149
	s_nop 0
	v_mul_f32_e32 v195, 0x3f317217, v149
	v_fma_f32 v195, v149, s52, -v195
	v_fmac_f32_e32 v195, 0x3377d1cf, v149
	v_fmac_f32_e32 v195, 0x3f317217, v149
	v_cmp_lt_f32_e64 s[42:43], |v149|, s53
	s_nop 1
	v_cndmask_b32_e64 v149, v149, v195, s[42:43]
	v_cndmask_b32_e64 v195, 0, v216, s[40:41]
	v_sub_f32_e32 v149, v149, v195
	v_cndmask_b32_e64 v149, v194, v149, s[30:31]
	v_min_f32_e32 v194, 0, v150
	v_mul_f32_e64 v150, |v150|, s57
	v_exp_f32_e32 v150, v150
	s_nop 0
	v_add_f32_e32 v150, 1.0, v150
; __device__ __forceinline__ float silu_f(float x) { return x * __builtin_amdgcn_rcpf(1.f + __expf(-x)); }
; __device__ __forceinline__ v4u pack8(const f32x4 a, const f32x4 b) { v4u w; w.x = cvt_pk_bf16(a[0], a[1]); w.y = cvt_pk_bf16(a[2], a[3]); w.z = cvt_pk_bf16(b[0], b[1]); w.w = cvt_pk_bf16(b[2], b[3]); return w; }
;     __device__ __forceinline__ void operator()(const f32x4 (&acc)[2][2][4][2], const pg8::Unit& u, int wr, int wc, int fr, int fq) const {
;     ...
;         if (grp == 0) { WIN_LOOP( _Pragma("unroll") for (int i = 0; i < 4; ++i) { a[i] = silu_f(a[i]); b[i] = silu_f(b[i]); } *(v4u*)(QO + (size_t)row * DM + c) = pack8(a, b); ) }
;         else if (grp == 3) { WIN_LOOP( _Pragma("unroll") for (int i = 0; i < 4; ++i) { a[i] = silu_f(a[i]); b[i] = silu_f(b[i]); } *(v4u*)(GH + (size_t)row * 512 + c) = pack8(a, b); ) }
;         else if (grp == 1) {
;             f32x4 l0[2], l1[2];
; #pragma unroll
;             for (int bj = 0; bj < 2; ++bj) { l0[bj] = *(const f32x4*)(lb + cb + bj * 128); l1[bj] = *(const f32x4*)(lb + cb + bj * 128 + 4); }
;             WIN_LOOP( _Pragma("unroll") for (int i = 0; i < 4; ++i) { const float s0 = fminf(a[i], 0.f) - __logf(1.f + __expf(-fabsf(a[i]))), s1 = fminf(b[i], 0.f) - __logf(1.f + __expf(-fabsf(b[i]))); const float la = l0[bj][i], lbv = l1[bj][i];
;                     a[i] = la > 0.f ? __logf(la + (1.f - la) * __expf(s0)) : s0; b[i] = lbv > 0.f ? __logf(lbv + (1.f - lbv) * __expf(s1)) : s1; }
;                 *(f32x4*)(LF + (size_t)row * 512 + c) = a; *(f32x4*)(LF + (size_t)row * 512 + c + 4) = b; __builtin_amdgcn_sched_barrier(0); ) }
	v_cmp_gt_f32_e64 s[40:41], s97, v150
	s_nop 1
	v_cndmask_b32_e64 v195, 0, 32, s[40:41]
	v_ldexp_f32 v150, v150, v195
	v_log_f32_e32 v150, v150
	s_nop 0
	v_mul_f32_e32 v195, 0x3f317217, v150
	v_fma_f32 v195, v150, s52, -v195
	v_fmac_f32_e32 v195, 0x3377d1cf, v150
	v_fmac_f32_e32 v195, 0x3f317217, v150
	v_cmp_lt_f32_e64 s[42:43], |v150|, s53
	s_nop 1
	v_cndmask_b32_e64 v150, v150, v195, s[42:43]
	v_cndmask_b32_e64 v195, 0, v216, s[40:41]
	v_sub_f32_e32 v150, v150, v195
	v_sub_f32_e32 v150, v194, v150
	v_min_f32_e32 v194, 0, v146
	v_mul_f32_e64 v146, |v146|, s57
	v_exp_f32_e32 v146, v146
	s_nop 0
	v_add_f32_e32 v146, 1.0, v146
	v_cmp_gt_f32_e64 s[40:41], s97, v146
	s_nop 1
	v_cndmask_b32_e64 v195, 0, 32, s[40:41]
	v_ldexp_f32 v146, v146, v195
	v_log_f32_e32 v146, v146
	s_nop 0
	v_mul_f32_e32 v195, 0x3f317217, v146
	v_fma_f32 v195, v146, s52, -v195
	v_fmac_f32_e32 v195, 0x3377d1cf, v146
	v_fmac_f32_e32 v195, 0x3f317217, v146
	v_cmp_lt_f32_e64 s[42:43], |v146|, s53
	s_nop 1
	v_cndmask_b32_e64 v146, v146, v195, s[42:43]
	v_cndmask_b32_e64 v195, 0, v216, s[40:41]
	v_sub_f32_e32 v146, v146, v195
	v_sub_f32_e32 v194, v194, v146
	v_mul_f32_e32 v146, 0x3fb8aa3b, v150
	v_exp_f32_e32 v146, v146
	s_nop 0
	v_fma_f32 v146, v187, v146, v142
	v_cmp_gt_f32_e64 s[40:41], s97, v146
	s_nop 1
	v_cndmask_b32_e64 v195, 0, 32, s[40:41]
	v_ldexp_f32 v146, v146, v195
	v_log_f32_e32 v146, v146
	s_nop 0
	v_mul_f32_e32 v195, 0x3f317217, v146
	v_fma_f32 v195, v146, s52, -v195
	v_fmac_f32_e32 v195, 0x3377d1cf, v146
	v_fmac_f32_e32 v195, 0x3f317217, v146
	v_cmp_lt_f32_e64 s[42:43], |v146|, s53
	s_nop 1
	v_cndmask_b32_e64 v146, v146, v195, s[42:43]
	v_cndmask_b32_e64 v195, 0, v216, s[40:41]
	v_sub_f32_e32 v146, v146, v195
	v_cndmask_b32_e64 v146, v150, v146, s[28:29]
	v_mul_f32_e32 v150, 0x3fb8aa3b, v194
	v_exp_f32_e32 v150, v150
	s_nop 0
	v_fma_f32 v150, v186, v150, v138
	v_cmp_gt_f32_e64 s[40:41], s97, v150
	s_nop 1
	v_cndmask_b32_e64 v195, 0, 32, s[40:41]
	v_ldexp_f32 v150, v150, v195
	v_log_f32_e32 v150, v150
	s_nop 0
	v_mul_f32_e32 v195, 0x3f317217, v150
	v_fma_f32 v195, v150, s52, -v195
	v_fmac_f32_e32 v195, 0x3377d1cf, v150
	v_fmac_f32_e32 v195, 0x3f317217, v150
	v_cmp_lt_f32_e64 s[42:43], |v150|, s53
	s_nop 1
	v_cndmask_b32_e64 v150, v150, v195, s[42:43]
	v_cndmask_b32_e64 v195, 0, v216, s[40:41]
	v_sub_f32_e32 v150, v150, v195
	v_cndmask_b32_e64 v150, v194, v150, s[26:27]
	v_min_f32_e32 v194, 0, v151
	v_mul_f32_e64 v151, |v151|, s57
	v_exp_f32_e32 v151, v151
	s_nop 0
	v_add_f32_e32 v151, 1.0, v151
	v_cmp_gt_f32_e64 s[40:41], s97, v151
	s_nop 1
	v_cndmask_b32_e64 v195, 0, 32, s[40:41]
	v_ldexp_f32 v151, v151, v195
	v_log_f32_e32 v151, v151
	s_nop 0
	v_mul_f32_e32 v195, 0x3f317217, v151
	v_fma_f32 v195, v151, s52, -v195
	v_fmac_f32_e32 v195, 0x3377d1cf, v151
	v_fmac_f32_e32 v195, 0x3f317217, v151
	v_cmp_lt_f32_e64 s[42:43], |v151|, s53
	s_nop 1
	v_cndmask_b32_e64 v151, v151, v195, s[42:43]
	v_cndmask_b32_e64 v195, 0, v216, s[40:41]
	v_sub_f32_e32 v151, v151, v195
	v_sub_f32_e32 v151, v194, v151
	v_min_f32_e32 v194, 0, v147
	v_mul_f32_e64 v147, |v147|, s57
	v_exp_f32_e32 v147, v147
	s_nop 0
	v_add_f32_e32 v147, 1.0, v147
	v_cmp_gt_f32_e64 s[40:41], s97, v147
	s_nop 1
	v_cndmask_b32_e64 v195, 0, 32, s[40:41]
	v_ldexp_f32 v147, v147, v195
	v_log_f32_e32 v147, v147
	s_nop 0
	v_mul_f32_e32 v195, 0x3f317217, v147
	v_fma_f32 v195, v147, s52, -v195
	v_fmac_f32_e32 v195, 0x3377d1cf, v147
	v_fmac_f32_e32 v195, 0x3f317217, v147
	v_cmp_lt_f32_e64 s[42:43], |v147|, s53
	s_nop 1
	v_cndmask_b32_e64 v147, v147, v195, s[42:43]
	v_cndmask_b32_e64 v195, 0, v216, s[40:41]
	v_sub_f32_e32 v147, v147, v195
	v_sub_f32_e32 v194, v194, v147
	v_mul_f32_e32 v147, 0x3fb8aa3b, v151
	v_exp_f32_e32 v147, v147
	s_nop 0
	v_fma_f32 v147, v185, v147, v143
	v_cmp_gt_f32_e64 s[40:41], s97, v147
	s_nop 1
	v_cndmask_b32_e64 v195, 0, 32, s[40:41]
	v_ldexp_f32 v147, v147, v195
	v_log_f32_e32 v147, v147
	s_nop 0
	v_mul_f32_e32 v195, 0x3f317217, v147
	v_fma_f32 v195, v147, s52, -v195
	v_fmac_f32_e32 v195, 0x3377d1cf, v147
	v_fmac_f32_e32 v195, 0x3f317217, v147
	v_cmp_lt_f32_e64 s[42:43], |v147|, s53
	s_nop 1
	v_cndmask_b32_e64 v147, v147, v195, s[42:43]
	v_cndmask_b32_e64 v195, 0, v216, s[40:41]
	v_sub_f32_e32 v147, v147, v195
	v_cndmask_b32_e64 v147, v151, v147, s[24:25]
	v_mul_f32_e32 v151, 0x3fb8aa3b, v194
	v_exp_f32_e32 v151, v151
	s_nop 0
	v_fma_f32 v151, v184, v151, v139
	v_cmp_gt_f32_e64 s[40:41], s97, v151
	s_nop 1
	v_cndmask_b32_e64 v195, 0, 32, s[40:41]
	v_ldexp_f32 v151, v151, v195
	v_log_f32_e32 v151, v151
	s_nop 0
	v_mul_f32_e32 v195, 0x3f317217, v151
	v_fma_f32 v195, v151, s52, -v195
	v_fmac_f32_e32 v195, 0x3377d1cf, v151
	v_fmac_f32_e32 v195, 0x3f317217, v151
	v_cmp_lt_f32_e64 s[42:43], |v151|, s53
	s_nop 1
	v_cndmask_b32_e64 v151, v151, v195, s[42:43]
	v_cndmask_b32_e64 v195, 0, v216, s[40:41]
	v_sub_f32_e32 v151, v151, v195
	v_cndmask_b32_e64 v151, v194, v151, s[22:23]
	flat_store_dwordx4 v[170:171], v[144:147] sc1
	flat_store_dwordx4 v[170:171], v[148:151] offset:16 sc1
	s_nop 1
	v_pk_mul_f32 v[148:149], v[76:77], v[168:169] op_sel_hi:[1,0]
	v_pk_mul_f32 v[150:151], v[78:79], v[168:169] op_sel_hi:[1,0]
	v_pk_mul_f32 v[146:147], v[74:75], v[168:169] op_sel_hi:[1,0]
	v_pk_mul_f32 v[144:145], v[72:73], v[168:169] op_sel_hi:[1,0]
	v_min_f32_e32 v168, 0, v148
	v_mul_f32_e64 v148, |v148|, s57
	v_exp_f32_e32 v148, v148
	s_nop 0
	v_add_f32_e32 v148, 1.0, v148
	v_cmp_gt_f32_e64 s[40:41], s97, v148
	s_nop 1
	v_cndmask_b32_e64 v194, 0, 32, s[40:41]
	v_ldexp_f32 v148, v148, v194
	v_log_f32_e32 v148, v148
	s_nop 0
	v_mul_f32_e32 v194, 0x3f317217, v148
	v_fma_f32 v194, v148, s52, -v194
; __device__ __forceinline__ float silu_f(float x) { return x * __builtin_amdgcn_rcpf(1.f + __expf(-x)); }
; __device__ __forceinline__ v4u pack8(const f32x4 a, const f32x4 b) { v4u w; w.x = cvt_pk_bf16(a[0], a[1]); w.y = cvt_pk_bf16(a[2], a[3]); w.z = cvt_pk_bf16(b[0], b[1]); w.w = cvt_pk_bf16(b[2], b[3]); return w; }
;     __device__ __forceinline__ void operator()(const f32x4 (&acc)[2][2][4][2], const pg8::Unit& u, int wr, int wc, int fr, int fq) const {
;     ...
;         if (grp == 0) { WIN_LOOP( _Pragma("unroll") for (int i = 0; i < 4; ++i) { a[i] = silu_f(a[i]); b[i] = silu_f(b[i]); } *(v4u*)(QO + (size_t)row * DM + c) = pack8(a, b); ) }
;         else if (grp == 3) { WIN_LOOP( _Pragma("unroll") for (int i = 0; i < 4; ++i) { a[i] = silu_f(a[i]); b[i] = silu_f(b[i]); } *(v4u*)(GH + (size_t)row * 512 + c) = pack8(a, b); ) }
;         else if (grp == 1) {
;             f32x4 l0[2], l1[2];
; #pragma unroll
;             for (int bj = 0; bj < 2; ++bj) { l0[bj] = *(const f32x4*)(lb + cb + bj * 128); l1[bj] = *(const f32x4*)(lb + cb + bj * 128 + 4); }
;             WIN_LOOP( _Pragma("unroll") for (int i = 0; i < 4; ++i) { const float s0 = fminf(a[i], 0.f) - __logf(1.f + __expf(-fabsf(a[i]))), s1 = fminf(b[i], 0.f) - __logf(1.f + __expf(-fabsf(b[i]))); const float la = l0[bj][i], lbv = l1[bj][i];
;                     a[i] = la > 0.f ? __logf(la + (1.f - la) * __expf(s0)) : s0; b[i] = lbv > 0.f ? __logf(lbv + (1.f - lbv) * __expf(s1)) : s1; }
;                 *(f32x4*)(LF + (size_t)row * 512 + c) = a; *(f32x4*)(LF + (size_t)row * 512 + c + 4) = b; __builtin_amdgcn_sched_barrier(0); ) }
	v_fmac_f32_e32 v194, 0x3377d1cf, v148
	v_fmac_f32_e32 v194, 0x3f317217, v148
	v_cmp_lt_f32_e64 s[42:43], |v148|, s53
	s_nop 1
	v_cndmask_b32_e64 v148, v148, v194, s[42:43]
	v_cndmask_b32_e64 v194, 0, v216, s[40:41]
	v_sub_f32_e32 v148, v148, v194
	v_sub_f32_e32 v148, v168, v148
	v_min_f32_e32 v168, 0, v144
	v_mul_f32_e64 v144, |v144|, s57
	v_exp_f32_e32 v144, v144
	s_nop 0
	v_add_f32_e32 v144, 1.0, v144
	v_cmp_gt_f32_e64 s[40:41], s97, v144
	s_nop 1
	v_cndmask_b32_e64 v194, 0, 32, s[40:41]
	v_ldexp_f32 v144, v144, v194
	v_log_f32_e32 v144, v144
	s_nop 0
	v_mul_f32_e32 v194, 0x3f317217, v144
	v_fma_f32 v194, v144, s52, -v194
	v_fmac_f32_e32 v194, 0x3377d1cf, v144
	v_fmac_f32_e32 v194, 0x3f317217, v144
	v_cmp_lt_f32_e64 s[42:43], |v144|, s53
	s_nop 1
	v_cndmask_b32_e64 v144, v144, v194, s[42:43]
	v_cndmask_b32_e64 v194, 0, v216, s[40:41]
	v_sub_f32_e32 v144, v144, v194
	v_sub_f32_e32 v168, v168, v144
	v_mul_f32_e32 v144, 0x3fb8aa3b, v148
	v_exp_f32_e32 v144, v144
	s_nop 0
	v_fma_f32 v144, v183, v144, v132
	v_cmp_gt_f32_e64 s[40:41], s97, v144
	s_nop 1
	v_cndmask_b32_e64 v194, 0, 32, s[40:41]
	v_ldexp_f32 v144, v144, v194
	v_log_f32_e32 v144, v144
	s_nop 0
	v_mul_f32_e32 v194, 0x3f317217, v144
	v_fma_f32 v194, v144, s52, -v194
	v_fmac_f32_e32 v194, 0x3377d1cf, v144
	v_fmac_f32_e32 v194, 0x3f317217, v144
	v_cmp_lt_f32_e64 s[42:43], |v144|, s53
	s_nop 1
	v_cndmask_b32_e64 v144, v144, v194, s[42:43]
	v_cndmask_b32_e64 v194, 0, v216, s[40:41]
	v_sub_f32_e32 v144, v144, v194
	v_cndmask_b32_e64 v144, v148, v144, s[20:21]
	v_mul_f32_e32 v148, 0x3fb8aa3b, v168
	v_exp_f32_e32 v148, v148
	s_nop 0
	v_fma_f32 v148, v182, v148, v128
	v_cmp_gt_f32_e64 s[40:41], s97, v148
	s_nop 1
	v_cndmask_b32_e64 v194, 0, 32, s[40:41]
	v_ldexp_f32 v148, v148, v194
	v_log_f32_e32 v148, v148
	s_nop 0
	v_mul_f32_e32 v194, 0x3f317217, v148
	v_fma_f32 v194, v148, s52, -v194
	v_fmac_f32_e32 v194, 0x3377d1cf, v148
	v_fmac_f32_e32 v194, 0x3f317217, v148
	v_cmp_lt_f32_e64 s[42:43], |v148|, s53
	s_nop 1
	v_cndmask_b32_e64 v148, v148, v194, s[42:43]
	v_cndmask_b32_e64 v194, 0, v216, s[40:41]
	v_sub_f32_e32 v148, v148, v194
	v_cndmask_b32_e64 v148, v168, v148, s[18:19]
	v_min_f32_e32 v168, 0, v149
	v_mul_f32_e64 v149, |v149|, s57
	v_exp_f32_e32 v149, v149
	s_nop 0
	v_add_f32_e32 v149, 1.0, v149
	v_cmp_gt_f32_e64 s[40:41], s97, v149
	s_nop 1
	v_cndmask_b32_e64 v194, 0, 32, s[40:41]
	v_ldexp_f32 v149, v149, v194
	v_log_f32_e32 v149, v149
	s_nop 0
	v_mul_f32_e32 v194, 0x3f317217, v149
	v_fma_f32 v194, v149, s52, -v194
	v_fmac_f32_e32 v194, 0x3377d1cf, v149
	v_fmac_f32_e32 v194, 0x3f317217, v149
	v_cmp_lt_f32_e64 s[42:43], |v149|, s53
	s_nop 1
	v_cndmask_b32_e64 v149, v149, v194, s[42:43]
	v_cndmask_b32_e64 v194, 0, v216, s[40:41]
	v_sub_f32_e32 v149, v149, v194
	v_sub_f32_e32 v149, v168, v149
	v_min_f32_e32 v168, 0, v145
	v_mul_f32_e64 v145, |v145|, s57
	v_exp_f32_e32 v145, v145
	s_nop 0
	v_add_f32_e32 v145, 1.0, v145
	v_cmp_gt_f32_e64 s[40:41], s97, v145
	s_nop 1
	v_cndmask_b32_e64 v194, 0, 32, s[40:41]
	v_ldexp_f32 v145, v145, v194
	v_log_f32_e32 v145, v145
	s_nop 0
	v_mul_f32_e32 v194, 0x3f317217, v145
	v_fma_f32 v194, v145, s52, -v194
	v_fmac_f32_e32 v194, 0x3377d1cf, v145
	v_fmac_f32_e32 v194, 0x3f317217, v145
	v_cmp_lt_f32_e64 s[42:43], |v145|, s53
	s_nop 1
	v_cndmask_b32_e64 v145, v145, v194, s[42:43]
	v_cndmask_b32_e64 v194, 0, v216, s[40:41]
	v_sub_f32_e32 v145, v145, v194
	v_sub_f32_e32 v168, v168, v145
	v_mul_f32_e32 v145, 0x3fb8aa3b, v149
	v_exp_f32_e32 v145, v145
	s_nop 0
	v_fma_f32 v145, v181, v145, v133
	v_cmp_gt_f32_e64 s[40:41], s97, v145
	s_nop 1
	v_cndmask_b32_e64 v194, 0, 32, s[40:41]
	v_ldexp_f32 v145, v145, v194
	v_log_f32_e32 v145, v145
	s_nop 0
	v_mul_f32_e32 v194, 0x3f317217, v145
	v_fma_f32 v194, v145, s52, -v194
	v_fmac_f32_e32 v194, 0x3377d1cf, v145
	v_fmac_f32_e32 v194, 0x3f317217, v145
	v_cmp_lt_f32_e64 s[42:43], |v145|, s53
	s_nop 1
	v_cndmask_b32_e64 v145, v145, v194, s[42:43]
	v_cndmask_b32_e64 v194, 0, v216, s[40:41]
	v_sub_f32_e32 v145, v145, v194
	v_cndmask_b32_e64 v145, v149, v145, s[16:17]
	v_mul_f32_e32 v149, 0x3fb8aa3b, v168
	v_exp_f32_e32 v149, v149
	s_nop 0
	v_fma_f32 v149, v180, v149, v129
	v_cmp_gt_f32_e64 s[40:41], s97, v149
	s_nop 1
	v_cndmask_b32_e64 v194, 0, 32, s[40:41]
	v_ldexp_f32 v149, v149, v194
	v_log_f32_e32 v149, v149
	s_nop 0
	v_mul_f32_e32 v194, 0x3f317217, v149
	v_fma_f32 v194, v149, s52, -v194
	v_fmac_f32_e32 v194, 0x3377d1cf, v149
	v_fmac_f32_e32 v194, 0x3f317217, v149
	v_cmp_lt_f32_e64 s[42:43], |v149|, s53
	s_nop 1
	v_cndmask_b32_e64 v149, v149, v194, s[42:43]
	v_cndmask_b32_e64 v194, 0, v216, s[40:41]
	v_sub_f32_e32 v149, v149, v194
	v_cndmask_b32_e64 v149, v168, v149, s[14:15]
	v_min_f32_e32 v168, 0, v150
	v_mul_f32_e64 v150, |v150|, s57
	v_exp_f32_e32 v150, v150
	s_nop 0
	v_add_f32_e32 v150, 1.0, v150
	v_cmp_gt_f32_e64 s[40:41], s97, v150
	s_nop 1
	v_cndmask_b32_e64 v194, 0, 32, s[40:41]
	v_ldexp_f32 v150, v150, v194
	v_log_f32_e32 v150, v150
	s_nop 0
	v_mul_f32_e32 v194, 0x3f317217, v150
	v_fma_f32 v194, v150, s52, -v194
	v_fmac_f32_e32 v194, 0x3377d1cf, v150
	v_fmac_f32_e32 v194, 0x3f317217, v150
	v_cmp_lt_f32_e64 s[42:43], |v150|, s53
	s_nop 1
	v_cndmask_b32_e64 v150, v150, v194, s[42:43]
	v_cndmask_b32_e64 v194, 0, v216, s[40:41]
	v_sub_f32_e32 v150, v150, v194
	v_sub_f32_e32 v150, v168, v150
	v_min_f32_e32 v168, 0, v146
	v_mul_f32_e64 v146, |v146|, s57
	v_exp_f32_e32 v146, v146
	s_nop 0
	v_add_f32_e32 v146, 1.0, v146
	v_cmp_gt_f32_e64 s[40:41], s97, v146
	s_nop 1
	v_cndmask_b32_e64 v194, 0, 32, s[40:41]
	v_ldexp_f32 v146, v146, v194
	v_log_f32_e32 v146, v146
	s_nop 0
	v_mul_f32_e32 v194, 0x3f317217, v146
; __device__ __forceinline__ float silu_f(float x) { return x * __builtin_amdgcn_rcpf(1.f + __expf(-x)); }
; __device__ __forceinline__ v4u pack8(const f32x4 a, const f32x4 b) { v4u w; w.x = cvt_pk_bf16(a[0], a[1]); w.y = cvt_pk_bf16(a[2], a[3]); w.z = cvt_pk_bf16(b[0], b[1]); w.w = cvt_pk_bf16(b[2], b[3]); return w; }
;     __device__ __forceinline__ void operator()(const f32x4 (&acc)[2][2][4][2], const pg8::Unit& u, int wr, int wc, int fr, int fq) const {
;     ...
;         if (grp == 0) { WIN_LOOP( _Pragma("unroll") for (int i = 0; i < 4; ++i) { a[i] = silu_f(a[i]); b[i] = silu_f(b[i]); } *(v4u*)(QO + (size_t)row * DM + c) = pack8(a, b); ) }
;         else if (grp == 3) { WIN_LOOP( _Pragma("unroll") for (int i = 0; i < 4; ++i) { a[i] = silu_f(a[i]); b[i] = silu_f(b[i]); } *(v4u*)(GH + (size_t)row * 512 + c) = pack8(a, b); ) }
;         else if (grp == 1) {
;             f32x4 l0[2], l1[2];
; #pragma unroll
;             for (int bj = 0; bj < 2; ++bj) { l0[bj] = *(const f32x4*)(lb + cb + bj * 128); l1[bj] = *(const f32x4*)(lb + cb + bj * 128 + 4); }
;             WIN_LOOP( _Pragma("unroll") for (int i = 0; i < 4; ++i) { const float s0 = fminf(a[i], 0.f) - __logf(1.f + __expf(-fabsf(a[i]))), s1 = fminf(b[i], 0.f) - __logf(1.f + __expf(-fabsf(b[i]))); const float la = l0[bj][i], lbv = l1[bj][i];
;                     a[i] = la > 0.f ? __logf(la + (1.f - la) * __expf(s0)) : s0; b[i] = lbv > 0.f ? __logf(lbv + (1.f - lbv) * __expf(s1)) : s1; }
;                 *(f32x4*)(LF + (size_t)row * 512 + c) = a; *(f32x4*)(LF + (size_t)row * 512 + c + 4) = b; __builtin_amdgcn_sched_barrier(0); ) }
	v_fma_f32 v194, v146, s52, -v194
	v_fmac_f32_e32 v194, 0x3377d1cf, v146
	v_fmac_f32_e32 v194, 0x3f317217, v146
	v_cmp_lt_f32_e64 s[42:43], |v146|, s53
	s_nop 1
	v_cndmask_b32_e64 v146, v146, v194, s[42:43]
	v_cndmask_b32_e64 v194, 0, v216, s[40:41]
	v_sub_f32_e32 v146, v146, v194
	v_sub_f32_e32 v168, v168, v146
	v_mul_f32_e32 v146, 0x3fb8aa3b, v150
	v_exp_f32_e32 v146, v146
	s_nop 0
	v_fma_f32 v146, v179, v146, v134
	v_cmp_gt_f32_e64 s[40:41], s97, v146
	s_nop 1
	v_cndmask_b32_e64 v194, 0, 32, s[40:41]
	v_ldexp_f32 v146, v146, v194
	v_log_f32_e32 v146, v146
	s_nop 0
	v_mul_f32_e32 v194, 0x3f317217, v146
	v_fma_f32 v194, v146, s52, -v194
	v_fmac_f32_e32 v194, 0x3377d1cf, v146
	v_fmac_f32_e32 v194, 0x3f317217, v146
	v_cmp_lt_f32_e64 s[42:43], |v146|, s53
	s_nop 1
	v_cndmask_b32_e64 v146, v146, v194, s[42:43]
	v_cndmask_b32_e64 v194, 0, v216, s[40:41]
	v_sub_f32_e32 v146, v146, v194
	v_cndmask_b32_e64 v146, v150, v146, s[12:13]
	v_mul_f32_e32 v150, 0x3fb8aa3b, v168
	v_exp_f32_e32 v150, v150
	s_nop 0
	v_fma_f32 v150, v178, v150, v130
	v_cmp_gt_f32_e64 s[40:41], s97, v150
	s_nop 1
	v_cndmask_b32_e64 v194, 0, 32, s[40:41]
	v_ldexp_f32 v150, v150, v194
	v_log_f32_e32 v150, v150
	s_nop 0
	v_mul_f32_e32 v194, 0x3f317217, v150
	v_fma_f32 v194, v150, s52, -v194
	v_fmac_f32_e32 v194, 0x3377d1cf, v150
	v_fmac_f32_e32 v194, 0x3f317217, v150
	v_cmp_lt_f32_e64 s[42:43], |v150|, s53
	s_nop 1
	v_cndmask_b32_e64 v150, v150, v194, s[42:43]
	v_cndmask_b32_e64 v194, 0, v216, s[40:41]
	v_sub_f32_e32 v150, v150, v194
	v_cndmask_b32_e64 v150, v168, v150, s[10:11]
	v_min_f32_e32 v168, 0, v151
	v_mul_f32_e64 v151, |v151|, s57
	v_exp_f32_e32 v151, v151
	s_nop 0
	v_add_f32_e32 v151, 1.0, v151
	v_cmp_gt_f32_e64 s[40:41], s97, v151
	s_nop 1
	v_cndmask_b32_e64 v194, 0, 32, s[40:41]
	v_ldexp_f32 v151, v151, v194
	v_log_f32_e32 v151, v151
	s_nop 0
	v_mul_f32_e32 v194, 0x3f317217, v151
	v_fma_f32 v194, v151, s52, -v194
	v_fmac_f32_e32 v194, 0x3377d1cf, v151
	v_fmac_f32_e32 v194, 0x3f317217, v151
	v_cmp_lt_f32_e64 s[42:43], |v151|, s53
	s_nop 1
	v_cndmask_b32_e64 v151, v151, v194, s[42:43]
	v_cndmask_b32_e64 v194, 0, v216, s[40:41]
	v_sub_f32_e32 v151, v151, v194
	v_sub_f32_e32 v151, v168, v151
	v_min_f32_e32 v168, 0, v147
	v_mul_f32_e64 v147, |v147|, s57
	v_exp_f32_e32 v147, v147
	s_nop 0
	v_add_f32_e32 v147, 1.0, v147
	v_cmp_gt_f32_e64 s[40:41], s97, v147
	s_nop 1
	v_cndmask_b32_e64 v194, 0, 32, s[40:41]
	v_ldexp_f32 v147, v147, v194
	v_log_f32_e32 v147, v147
	s_nop 0
	v_mul_f32_e32 v194, 0x3f317217, v147
	v_fma_f32 v194, v147, s52, -v194
	v_fmac_f32_e32 v194, 0x3377d1cf, v147
	v_fmac_f32_e32 v194, 0x3f317217, v147
	v_cmp_lt_f32_e64 s[42:43], |v147|, s53
	s_nop 1
	v_cndmask_b32_e64 v147, v147, v194, s[42:43]
	v_cndmask_b32_e64 v194, 0, v216, s[40:41]
	v_sub_f32_e32 v147, v147, v194
	v_sub_f32_e32 v168, v168, v147
	v_mul_f32_e32 v147, 0x3fb8aa3b, v151
	v_exp_f32_e32 v147, v147
	s_nop 0
	v_fma_f32 v147, v177, v147, v135
	v_cmp_gt_f32_e64 s[40:41], s97, v147
	s_nop 1
	v_cndmask_b32_e64 v194, 0, 32, s[40:41]
	v_ldexp_f32 v147, v147, v194
	v_log_f32_e32 v147, v147
	s_nop 0
	v_mul_f32_e32 v194, 0x3f317217, v147
	v_fma_f32 v194, v147, s52, -v194
	v_fmac_f32_e32 v194, 0x3377d1cf, v147
	v_fmac_f32_e32 v194, 0x3f317217, v147
	v_cmp_lt_f32_e64 s[42:43], |v147|, s53
	s_nop 1
	v_cndmask_b32_e64 v147, v147, v194, s[42:43]
	v_cndmask_b32_e64 v194, 0, v216, s[40:41]
	v_sub_f32_e32 v147, v147, v194
	v_cndmask_b32_e64 v147, v151, v147, s[8:9]
	v_mul_f32_e32 v151, 0x3fb8aa3b, v168
	v_exp_f32_e32 v151, v151
	s_nop 0
	v_fma_f32 v151, v167, v151, v131
	v_cmp_gt_f32_e64 s[40:41], s97, v151
	s_nop 1
	v_cndmask_b32_e64 v194, 0, 32, s[40:41]
	v_ldexp_f32 v151, v151, v194
	v_log_f32_e32 v151, v151
	s_nop 0
	v_mul_f32_e32 v194, 0x3f317217, v151
	v_fma_f32 v194, v151, s52, -v194
	v_fmac_f32_e32 v194, 0x3377d1cf, v151
	v_fmac_f32_e32 v194, 0x3f317217, v151
	v_cmp_lt_f32_e64 s[42:43], |v151|, s53
	s_nop 1
	v_cndmask_b32_e64 v151, v151, v194, s[42:43]
	v_cndmask_b32_e64 v194, 0, v216, s[40:41]
	v_sub_f32_e32 v151, v151, v194
	v_cndmask_b32_e32 v151, v168, v151, vcc
	flat_store_dwordx4 v[170:171], v[144:147] offset:512 sc1
	flat_store_dwordx4 v[170:171], v[148:151] offset:528 sc1
	s_nop 1
	v_add_u32_e32 v148, 0xb0, v166
	v_ashrrev_i32_e32 v149, 31, v148
	v_lshlrev_b64 v[144:145], 6, v[148:149]
	v_lshl_add_u64 v[144:145], v[160:161], 0, v[144:145]
	flat_load_dwordx4 v[144:147], v[144:145]
	s_waitcnt vmcnt(0) lgkmcnt(0)
	v_mov_b32_e32 v150, v145
	v_mov_b32_e32 v151, v146
	v_mov_b32_e32 v145, v147
	v_pk_add_f32 v[144:145], v[150:151], v[144:145]
	v_lshlrev_b64 v[146:147], 11, v[148:149]
	v_add_f32_e32 v144, v144, v145
	ds_bpermute_b32 v145, v169, v144
	v_lshl_add_u64 v[146:147], s[50:51], 0, v[146:147]
	v_lshl_add_u64 v[146:147], v[146:147], 0, v[192:193]
	s_waitcnt lgkmcnt(0)
	v_add_f32_e32 v144, v144, v145
	ds_bpermute_b32 v145, v202, v144
	s_waitcnt lgkmcnt(0)
; __device__ __forceinline__ float silu_f(float x) { return x * __builtin_amdgcn_rcpf(1.f + __expf(-x)); }
; __device__ __forceinline__ v4u pack8(const f32x4 a, const f32x4 b) { v4u w; w.x = cvt_pk_bf16(a[0], a[1]); w.y = cvt_pk_bf16(a[2], a[3]); w.z = cvt_pk_bf16(b[0], b[1]); w.w = cvt_pk_bf16(b[2], b[3]); return w; }
;     __device__ __forceinline__ void operator()(const f32x4 (&acc)[2][2][4][2], const pg8::Unit& u, int wr, int wc, int fr, int fq) const {
;     ...
;         if (grp == 0) { WIN_LOOP( _Pragma("unroll") for (int i = 0; i < 4; ++i) { a[i] = silu_f(a[i]); b[i] = silu_f(b[i]); } *(v4u*)(QO + (size_t)row * DM + c) = pack8(a, b); ) }
;         else if (grp == 3) { WIN_LOOP( _Pragma("unroll") for (int i = 0; i < 4; ++i) { a[i] = silu_f(a[i]); b[i] = silu_f(b[i]); } *(v4u*)(GH + (size_t)row * 512 + c) = pack8(a, b); ) }
;         else if (grp == 1) {
;             f32x4 l0[2], l1[2];
; #pragma unroll
;             for (int bj = 0; bj < 2; ++bj) { l0[bj] = *(const f32x4*)(lb + cb + bj * 128); l1[bj] = *(const f32x4*)(lb + cb + bj * 128 + 4); }
;             WIN_LOOP( _Pragma("unroll") for (int i = 0; i < 4; ++i) { const float s0 = fminf(a[i], 0.f) - __logf(1.f + __expf(-fabsf(a[i]))), s1 = fminf(b[i], 0.f) - __logf(1.f + __expf(-fabsf(b[i]))); const float la = l0[bj][i], lbv = l1[bj][i];
;                     a[i] = la > 0.f ? __logf(la + (1.f - la) * __expf(s0)) : s0; b[i] = lbv > 0.f ? __logf(lbv + (1.f - lbv) * __expf(s1)) : s1; }
;                 *(f32x4*)(LF + (size_t)row * 512 + c) = a; *(f32x4*)(LF + (size_t)row * 512 + c + 4) = b; __builtin_amdgcn_sched_barrier(0); ) }
	v_add_f32_e32 v144, v144, v145
	v_fmamk_f32 v144, v144, 0x3a800000, v212
	v_rsq_f32_e32 v144, v144
	s_nop 0
	v_pk_mul_f32 v[170:171], v[4:5], v[144:145] op_sel_hi:[1,0]
	v_pk_mul_f32 v[150:151], v[6:7], v[144:145] op_sel_hi:[1,0]
	v_pk_mul_f32 v[148:149], v[2:3], v[144:145] op_sel_hi:[1,0]
	v_pk_mul_f32 v[168:169], v[0:1], v[144:145] op_sel_hi:[1,0]
	v_min_f32_e32 v145, 0, v170
	v_mul_f32_e64 v170, |v170|, s57
	v_exp_f32_e32 v170, v170
	s_nop 0
	v_add_f32_e32 v170, 1.0, v170
	v_cmp_gt_f32_e64 s[40:41], s97, v170
	s_nop 1
	v_cndmask_b32_e64 v194, 0, 32, s[40:41]
	v_ldexp_f32 v170, v170, v194
	v_log_f32_e32 v170, v170
	s_nop 0
	v_mul_f32_e32 v194, 0x3f317217, v170
	v_fma_f32 v194, v170, s52, -v194
	v_fmac_f32_e32 v194, 0x3377d1cf, v170
	v_fmac_f32_e32 v194, 0x3f317217, v170
	v_cmp_lt_f32_e64 s[42:43], |v170|, s53
	s_nop 1
	v_cndmask_b32_e64 v170, v170, v194, s[42:43]
	v_cndmask_b32_e64 v194, 0, v216, s[40:41]
	v_sub_f32_e32 v170, v170, v194
	v_sub_f32_e32 v145, v145, v170
	v_min_f32_e32 v170, 0, v168
	v_mul_f32_e64 v168, |v168|, s57
	v_exp_f32_e32 v168, v168
	s_nop 0
	v_add_f32_e32 v168, 1.0, v168
	v_cmp_gt_f32_e64 s[40:41], s97, v168
	s_nop 1
	v_cndmask_b32_e64 v194, 0, 32, s[40:41]
	v_ldexp_f32 v168, v168, v194
	v_log_f32_e32 v168, v168
	s_nop 0
	v_mul_f32_e32 v194, 0x3f317217, v168
	v_fma_f32 v194, v168, s52, -v194
	v_fmac_f32_e32 v194, 0x3377d1cf, v168
	v_fmac_f32_e32 v194, 0x3f317217, v168
	v_cmp_lt_f32_e64 s[42:43], |v168|, s53
	s_nop 1
	v_cndmask_b32_e64 v168, v168, v194, s[42:43]
	v_cndmask_b32_e64 v194, 0, v216, s[40:41]
	v_sub_f32_e32 v168, v168, v194
	v_sub_f32_e32 v168, v170, v168
	v_mul_f32_e32 v170, 0x3fb8aa3b, v145
	v_exp_f32_e32 v170, v170
	s_nop 0
	v_fma_f32 v140, v190, v170, v140
	v_cmp_gt_f32_e64 s[40:41], s97, v140
	s_nop 1
	v_cndmask_b32_e64 v170, 0, 32, s[40:41]
	v_ldexp_f32 v140, v140, v170
	v_log_f32_e32 v140, v140
	s_nop 0
	v_mul_f32_e32 v170, 0x3f317217, v140
	v_fma_f32 v170, v140, s52, -v170
	v_fmac_f32_e32 v170, 0x3377d1cf, v140
	v_fmac_f32_e32 v170, 0x3f317217, v140
	v_cmp_lt_f32_e64 s[42:43], |v140|, s53
	s_nop 1
	v_cndmask_b32_e64 v140, v140, v170, s[42:43]
	v_cndmask_b32_e64 v170, 0, v216, s[40:41]
	v_sub_f32_e32 v140, v140, v170
	v_cndmask_b32_e64 v140, v145, v140, s[38:39]
	v_mul_f32_e32 v145, 0x3fb8aa3b, v168
	v_exp_f32_e32 v145, v145
	v_readlane_b32 s42, v255, 57
	v_readlane_b32 s43, v255, 58
	v_fma_f32 v136, v191, v145, v136
	v_cmp_gt_f32_e64 s[38:39], s97, v136
	s_nop 1
	v_cndmask_b32_e64 v145, 0, 32, s[38:39]
	v_ldexp_f32 v136, v136, v145
	v_log_f32_e32 v136, v136
	s_nop 0
	v_mul_f32_e32 v145, 0x3f317217, v136
	v_fma_f32 v145, v136, s52, -v145
	v_fmac_f32_e32 v145, 0x3377d1cf, v136
	v_fmac_f32_e32 v145, 0x3f317217, v136
	v_cmp_lt_f32_e64 s[40:41], |v136|, s53
	s_nop 1
	v_cndmask_b32_e64 v136, v136, v145, s[40:41]
	v_cndmask_b32_e64 v145, 0, v216, s[38:39]
	v_sub_f32_e32 v136, v136, v145
	v_cndmask_b32_e64 v136, v168, v136, s[36:37]
	v_mul_f32_e64 v168, |v171|, s57
	v_exp_f32_e32 v168, v168
	v_min_f32_e32 v145, 0, v171
	s_mov_b32 s40, s2
	v_add_f32_e32 v168, 1.0, v168
	v_cmp_gt_f32_e64 s[36:37], s97, v168
	s_nop 1
	v_cndmask_b32_e64 v170, 0, 32, s[36:37]
	v_ldexp_f32 v168, v168, v170
	v_log_f32_e32 v168, v168
	s_nop 0
	v_mul_f32_e32 v170, 0x3f317217, v168
	v_fma_f32 v170, v168, s52, -v170
	v_fmac_f32_e32 v170, 0x3377d1cf, v168
	v_fmac_f32_e32 v170, 0x3f317217, v168
	v_cmp_lt_f32_e64 s[38:39], |v168|, s53
	s_nop 1
	v_cndmask_b32_e64 v168, v168, v170, s[38:39]
	v_cndmask_b32_e64 v170, 0, v216, s[36:37]
	v_sub_f32_e32 v168, v168, v170
	v_sub_f32_e32 v145, v145, v168
	v_min_f32_e32 v168, 0, v169
	v_mul_f32_e64 v169, |v169|, s57
	v_exp_f32_e32 v169, v169
	s_nop 0
	v_add_f32_e32 v169, 1.0, v169
	v_cmp_gt_f32_e64 s[36:37], s97, v169
	s_nop 1
	v_cndmask_b32_e64 v170, 0, 32, s[36:37]
	v_ldexp_f32 v169, v169, v170
	v_log_f32_e32 v169, v169
	s_nop 0
	v_mul_f32_e32 v170, 0x3f317217, v169
	v_fma_f32 v170, v169, s52, -v170
	v_fmac_f32_e32 v170, 0x3377d1cf, v169
	v_fmac_f32_e32 v170, 0x3f317217, v169
	v_cmp_lt_f32_e64 s[38:39], |v169|, s53
	s_nop 1
	v_cndmask_b32_e64 v169, v169, v170, s[38:39]
	v_cndmask_b32_e64 v170, 0, v216, s[36:37]
	v_sub_f32_e32 v169, v169, v170
	v_sub_f32_e32 v168, v168, v169
	v_mul_f32_e32 v169, 0x3fb8aa3b, v145
	v_exp_f32_e32 v169, v169
	s_nop 0
	v_fma_f32 v141, v188, v169, v141
	v_cmp_gt_f32_e64 s[36:37], s97, v141
	s_nop 1
	v_cndmask_b32_e64 v169, 0, 32, s[36:37]
	v_ldexp_f32 v141, v141, v169
	v_log_f32_e32 v141, v141
	s_nop 0
	v_mul_f32_e32 v169, 0x3f317217, v141
	v_fma_f32 v169, v141, s52, -v169
	v_fmac_f32_e32 v169, 0x3377d1cf, v141
	v_fmac_f32_e32 v169, 0x3f317217, v141
	v_cmp_lt_f32_e64 s[38:39], |v141|, s53
	s_nop 1
	v_cndmask_b32_e64 v141, v141, v169, s[38:39]
	v_cndmask_b32_e64 v169, 0, v216, s[36:37]
	v_sub_f32_e32 v141, v141, v169
	v_cndmask_b32_e64 v141, v145, v141, s[34:35]
	v_mul_f32_e32 v145, 0x3fb8aa3b, v168
	v_exp_f32_e32 v145, v145
	v_readlane_b32 s38, v255, 53
	v_readlane_b32 s39, v255, 54
	v_fma_f32 v137, v189, v145, v137
	v_cmp_gt_f32_e64 s[34:35], s97, v137
	s_nop 1
	v_cndmask_b32_e64 v145, 0, 32, s[34:35]
	v_ldexp_f32 v137, v137, v145
	v_log_f32_e32 v137, v137
	s_nop 0
	v_mul_f32_e32 v145, 0x3f317217, v137
	v_fma_f32 v145, v137, s52, -v145
	v_fmac_f32_e32 v145, 0x3377d1cf, v137
	v_fmac_f32_e32 v145, 0x3f317217, v137
	v_cmp_lt_f32_e64 s[36:37], |v137|, s53
	s_nop 1
	v_cndmask_b32_e64 v137, v137, v145, s[36:37]
	v_cndmask_b32_e64 v145, 0, v216, s[34:35]
	v_sub_f32_e32 v137, v137, v145
	v_min_f32_e32 v145, 0, v150
	v_mul_f32_e64 v150, |v150|, s57
	v_exp_f32_e32 v150, v150
	v_cndmask_b32_e64 v137, v168, v137, s[30:31]
	v_readlane_b32 s36, v255, 51
	v_readlane_b32 s37, v255, 52
; __device__ __forceinline__ float silu_f(float x) { return x * __builtin_amdgcn_rcpf(1.f + __expf(-x)); }
; __device__ __forceinline__ v4u pack8(const f32x4 a, const f32x4 b) { v4u w; w.x = cvt_pk_bf16(a[0], a[1]); w.y = cvt_pk_bf16(a[2], a[3]); w.z = cvt_pk_bf16(b[0], b[1]); w.w = cvt_pk_bf16(b[2], b[3]); return w; }
;     __device__ __forceinline__ void operator()(const f32x4 (&acc)[2][2][4][2], const pg8::Unit& u, int wr, int wc, int fr, int fq) const {
;     ...
;         if (grp == 0) { WIN_LOOP( _Pragma("unroll") for (int i = 0; i < 4; ++i) { a[i] = silu_f(a[i]); b[i] = silu_f(b[i]); } *(v4u*)(QO + (size_t)row * DM + c) = pack8(a, b); ) }
;         else if (grp == 3) { WIN_LOOP( _Pragma("unroll") for (int i = 0; i < 4; ++i) { a[i] = silu_f(a[i]); b[i] = silu_f(b[i]); } *(v4u*)(GH + (size_t)row * 512 + c) = pack8(a, b); ) }
;         else if (grp == 1) {
;             f32x4 l0[2], l1[2];
; #pragma unroll
;             for (int bj = 0; bj < 2; ++bj) { l0[bj] = *(const f32x4*)(lb + cb + bj * 128); l1[bj] = *(const f32x4*)(lb + cb + bj * 128 + 4); }
;             WIN_LOOP( _Pragma("unroll") for (int i = 0; i < 4; ++i) { const float s0 = fminf(a[i], 0.f) - __logf(1.f + __expf(-fabsf(a[i]))), s1 = fminf(b[i], 0.f) - __logf(1.f + __expf(-fabsf(b[i]))); const float la = l0[bj][i], lbv = l1[bj][i];
;                     a[i] = la > 0.f ? __logf(la + (1.f - la) * __expf(s0)) : s0; b[i] = lbv > 0.f ? __logf(lbv + (1.f - lbv) * __expf(s1)) : s1; }
;                 *(f32x4*)(LF + (size_t)row * 512 + c) = a; *(f32x4*)(LF + (size_t)row * 512 + c + 4) = b; __builtin_amdgcn_sched_barrier(0); ) }
	v_add_f32_e32 v150, 1.0, v150
	v_cmp_gt_f32_e64 s[30:31], s97, v150
	s_nop 1
	v_cndmask_b32_e64 v168, 0, 32, s[30:31]
	v_ldexp_f32 v150, v150, v168
	v_log_f32_e32 v150, v150
	s_nop 0
	v_mul_f32_e32 v168, 0x3f317217, v150
	v_fma_f32 v168, v150, s52, -v168
	v_fmac_f32_e32 v168, 0x3377d1cf, v150
	v_fmac_f32_e32 v168, 0x3f317217, v150
	v_cmp_lt_f32_e64 s[34:35], |v150|, s53
	s_nop 1
	v_cndmask_b32_e64 v150, v150, v168, s[34:35]
	v_cndmask_b32_e64 v168, 0, v216, s[30:31]
	v_sub_f32_e32 v150, v150, v168
	v_sub_f32_e32 v145, v145, v150
	v_min_f32_e32 v150, 0, v148
	v_mul_f32_e64 v148, |v148|, s57
	v_exp_f32_e32 v148, v148
	s_nop 0
	v_add_f32_e32 v148, 1.0, v148
	v_cmp_gt_f32_e64 s[30:31], s97, v148
	s_nop 1
	v_cndmask_b32_e64 v168, 0, 32, s[30:31]
	v_ldexp_f32 v148, v148, v168
	v_log_f32_e32 v148, v148
	s_nop 0
	v_mul_f32_e32 v168, 0x3f317217, v148
	v_fma_f32 v168, v148, s52, -v168
	v_fmac_f32_e32 v168, 0x3377d1cf, v148
	v_fmac_f32_e32 v168, 0x3f317217, v148
	v_cmp_lt_f32_e64 s[34:35], |v148|, s53
	s_nop 1
	v_cndmask_b32_e64 v148, v148, v168, s[34:35]
	v_cndmask_b32_e64 v168, 0, v216, s[30:31]
	v_sub_f32_e32 v148, v148, v168
	v_sub_f32_e32 v148, v150, v148
	v_mul_f32_e32 v150, 0x3fb8aa3b, v145
	v_exp_f32_e32 v150, v150
	s_nop 0
	v_fma_f32 v142, v187, v150, v142
	v_cmp_gt_f32_e64 s[30:31], s97, v142
	s_nop 1
	v_cndmask_b32_e64 v150, 0, 32, s[30:31]
	v_ldexp_f32 v142, v142, v150
	v_log_f32_e32 v142, v142
	s_nop 0
	v_mul_f32_e32 v150, 0x3f317217, v142
	v_fma_f32 v150, v142, s52, -v150
	v_fmac_f32_e32 v150, 0x3377d1cf, v142
	v_fmac_f32_e32 v150, 0x3f317217, v142
	v_cmp_lt_f32_e64 s[34:35], |v142|, s53
	s_nop 1
	v_cndmask_b32_e64 v142, v142, v150, s[34:35]
	v_cndmask_b32_e64 v150, 0, v216, s[30:31]
	v_sub_f32_e32 v142, v142, v150
	v_cndmask_b32_e64 v142, v145, v142, s[28:29]
	v_mul_f32_e32 v145, 0x3fb8aa3b, v148
	v_exp_f32_e32 v145, v145
	v_readlane_b32 s34, v255, 49
	v_readlane_b32 s35, v255, 50
	v_fma_f32 v138, v186, v145, v138
	v_cmp_gt_f32_e64 s[28:29], s97, v138
	s_nop 1
	v_cndmask_b32_e64 v145, 0, 32, s[28:29]
	v_ldexp_f32 v138, v138, v145
	v_log_f32_e32 v138, v138
	s_nop 0
	v_mul_f32_e32 v145, 0x3f317217, v138
	v_fma_f32 v145, v138, s52, -v145
	v_fmac_f32_e32 v145, 0x3377d1cf, v138
	v_fmac_f32_e32 v145, 0x3f317217, v138
	v_cmp_lt_f32_e64 s[30:31], |v138|, s53
	s_nop 1
	v_cndmask_b32_e64 v138, v138, v145, s[30:31]
	v_cndmask_b32_e64 v145, 0, v216, s[28:29]
	v_sub_f32_e32 v138, v138, v145
	v_cndmask_b32_e64 v138, v148, v138, s[26:27]
	v_mul_f32_e64 v148, |v151|, s57
	v_exp_f32_e32 v148, v148
	v_min_f32_e32 v145, 0, v151
	v_readlane_b32 s30, v255, 47
	v_readlane_b32 s31, v255, 48
	v_add_f32_e32 v148, 1.0, v148
	v_cmp_gt_f32_e64 s[26:27], s97, v148
	s_nop 1
	v_cndmask_b32_e64 v150, 0, 32, s[26:27]
	v_ldexp_f32 v148, v148, v150
	v_log_f32_e32 v148, v148
	s_nop 0
	v_mul_f32_e32 v150, 0x3f317217, v148
	v_fma_f32 v150, v148, s52, -v150
	v_fmac_f32_e32 v150, 0x3377d1cf, v148
	v_fmac_f32_e32 v150, 0x3f317217, v148
	v_cmp_lt_f32_e64 s[28:29], |v148|, s53
	s_nop 1
	v_cndmask_b32_e64 v148, v148, v150, s[28:29]
	v_cndmask_b32_e64 v150, 0, v216, s[26:27]
	v_sub_f32_e32 v148, v148, v150
	v_sub_f32_e32 v145, v145, v148
	v_min_f32_e32 v148, 0, v149
	v_mul_f32_e64 v149, |v149|, s57
	v_exp_f32_e32 v149, v149
	s_nop 0
	v_add_f32_e32 v149, 1.0, v149
	v_cmp_gt_f32_e64 s[26:27], s97, v149
	s_nop 1
	v_cndmask_b32_e64 v150, 0, 32, s[26:27]
	v_ldexp_f32 v149, v149, v150
	v_log_f32_e32 v149, v149
	s_nop 0
	v_mul_f32_e32 v150, 0x3f317217, v149
	v_fma_f32 v150, v149, s52, -v150
	v_fmac_f32_e32 v150, 0x3377d1cf, v149
	v_fmac_f32_e32 v150, 0x3f317217, v149
	v_cmp_lt_f32_e64 s[28:29], |v149|, s53
	s_nop 1
	v_cndmask_b32_e64 v149, v149, v150, s[28:29]
	v_cndmask_b32_e64 v150, 0, v216, s[26:27]
	v_sub_f32_e32 v149, v149, v150
	v_sub_f32_e32 v148, v148, v149
	v_mul_f32_e32 v149, 0x3fb8aa3b, v145
	v_exp_f32_e32 v149, v149
	s_nop 0
	v_fmac_f32_e32 v143, v185, v149
	v_cmp_gt_f32_e64 s[26:27], s97, v143
	s_nop 1
	v_cndmask_b32_e64 v149, 0, 32, s[26:27]
	v_ldexp_f32 v143, v143, v149
	v_log_f32_e32 v143, v143
	s_nop 0
	v_mul_f32_e32 v149, 0x3f317217, v143
	v_fma_f32 v149, v143, s52, -v149
	v_fmac_f32_e32 v149, 0x3377d1cf, v143
	v_fmac_f32_e32 v149, 0x3f317217, v143
	v_cmp_lt_f32_e64 s[28:29], |v143|, s53
	s_nop 1
	v_cndmask_b32_e64 v143, v143, v149, s[28:29]
	v_cndmask_b32_e64 v149, 0, v216, s[26:27]
	v_sub_f32_e32 v143, v143, v149
	v_cndmask_b32_e64 v143, v145, v143, s[24:25]
	v_mul_f32_e32 v145, 0x3fb8aa3b, v148
	v_exp_f32_e32 v145, v145
	s_mov_b32 s29, s91
	s_mov_b32 s28, s95
	v_fmac_f32_e32 v139, v184, v145
	v_cmp_gt_f32_e64 s[24:25], s97, v139
	s_nop 1
	v_cndmask_b32_e64 v145, 0, 32, s[24:25]
	v_ldexp_f32 v139, v139, v145
	v_log_f32_e32 v139, v139
	s_nop 0
	v_mul_f32_e32 v145, 0x3f317217, v139
	v_fma_f32 v145, v139, s52, -v145
	v_fmac_f32_e32 v145, 0x3377d1cf, v139
	v_fmac_f32_e32 v145, 0x3f317217, v139
	v_cmp_lt_f32_e64 s[26:27], |v139|, s53
	s_nop 1
	v_cndmask_b32_e64 v139, v139, v145, s[26:27]
	v_cndmask_b32_e64 v145, 0, v216, s[24:25]
	v_readlane_b32 s27, v255, 56
	v_readlane_b32 s26, v255, 31
	v_sub_f32_e32 v139, v139, v145
	v_cndmask_b32_e64 v139, v148, v139, s[22:23]
	flat_store_dwordx4 v[146:147], v[140:143] sc1
	flat_store_dwordx4 v[146:147], v[136:139] offset:16 sc1
	s_nop 0
	v_pk_mul_f32 v[142:143], v[68:69], v[144:145] op_sel_hi:[1,0]
	v_pk_mul_f32 v[138:139], v[70:71], v[144:145] op_sel_hi:[1,0]
	v_pk_mul_f32 v[136:137], v[66:67], v[144:145] op_sel_hi:[1,0]
	v_pk_mul_f32 v[140:141], v[64:65], v[144:145] op_sel_hi:[1,0]
	v_min_f32_e32 v144, 0, v142
	v_mul_f32_e64 v142, |v142|, s57
	v_exp_f32_e32 v142, v142
	s_nop 0
	v_add_f32_e32 v142, 1.0, v142
; __device__ __forceinline__ float silu_f(float x) { return x * __builtin_amdgcn_rcpf(1.f + __expf(-x)); }
; __device__ __forceinline__ v4u pack8(const f32x4 a, const f32x4 b) { v4u w; w.x = cvt_pk_bf16(a[0], a[1]); w.y = cvt_pk_bf16(a[2], a[3]); w.z = cvt_pk_bf16(b[0], b[1]); w.w = cvt_pk_bf16(b[2], b[3]); return w; }
;     __device__ __forceinline__ void operator()(const f32x4 (&acc)[2][2][4][2], const pg8::Unit& u, int wr, int wc, int fr, int fq) const {
;     ...
;         if (grp == 0) { WIN_LOOP( _Pragma("unroll") for (int i = 0; i < 4; ++i) { a[i] = silu_f(a[i]); b[i] = silu_f(b[i]); } *(v4u*)(QO + (size_t)row * DM + c) = pack8(a, b); ) }
;         else if (grp == 3) { WIN_LOOP( _Pragma("unroll") for (int i = 0; i < 4; ++i) { a[i] = silu_f(a[i]); b[i] = silu_f(b[i]); } *(v4u*)(GH + (size_t)row * 512 + c) = pack8(a, b); ) }
;         else if (grp == 1) {
;             f32x4 l0[2], l1[2];
; #pragma unroll
;             for (int bj = 0; bj < 2; ++bj) { l0[bj] = *(const f32x4*)(lb + cb + bj * 128); l1[bj] = *(const f32x4*)(lb + cb + bj * 128 + 4); }
;             WIN_LOOP( _Pragma("unroll") for (int i = 0; i < 4; ++i) { const float s0 = fminf(a[i], 0.f) - __logf(1.f + __expf(-fabsf(a[i]))), s1 = fminf(b[i], 0.f) - __logf(1.f + __expf(-fabsf(b[i]))); const float la = l0[bj][i], lbv = l1[bj][i];
;                     a[i] = la > 0.f ? __logf(la + (1.f - la) * __expf(s0)) : s0; b[i] = lbv > 0.f ? __logf(lbv + (1.f - lbv) * __expf(s1)) : s1; }
;                 *(f32x4*)(LF + (size_t)row * 512 + c) = a; *(f32x4*)(LF + (size_t)row * 512 + c + 4) = b; __builtin_amdgcn_sched_barrier(0); ) }
	v_cmp_gt_f32_e64 s[22:23], s97, v142
	s_nop 1
	v_cndmask_b32_e64 v145, 0, 32, s[22:23]
	v_ldexp_f32 v142, v142, v145
	v_log_f32_e32 v142, v142
	s_nop 0
	v_mul_f32_e32 v145, 0x3f317217, v142
	v_fma_f32 v145, v142, s52, -v145
	v_fmac_f32_e32 v145, 0x3377d1cf, v142
	v_fmac_f32_e32 v145, 0x3f317217, v142
	v_cmp_lt_f32_e64 s[24:25], |v142|, s53
	s_nop 1
	v_cndmask_b32_e64 v142, v142, v145, s[24:25]
	v_cndmask_b32_e64 v145, 0, v216, s[22:23]
	v_sub_f32_e32 v142, v142, v145
	v_sub_f32_e32 v142, v144, v142
	v_min_f32_e32 v144, 0, v140
	v_mul_f32_e64 v140, |v140|, s57
	v_exp_f32_e32 v140, v140
	s_nop 0
	v_add_f32_e32 v140, 1.0, v140
	v_cmp_gt_f32_e64 s[22:23], s97, v140
	s_nop 1
	v_cndmask_b32_e64 v145, 0, 32, s[22:23]
	v_ldexp_f32 v140, v140, v145
	v_log_f32_e32 v140, v140
	s_nop 0
	v_mul_f32_e32 v145, 0x3f317217, v140
	v_fma_f32 v145, v140, s52, -v145
	v_fmac_f32_e32 v145, 0x3377d1cf, v140
	v_fmac_f32_e32 v145, 0x3f317217, v140
	v_cmp_lt_f32_e64 s[24:25], |v140|, s53
	s_nop 1
	v_cndmask_b32_e64 v140, v140, v145, s[24:25]
	v_cndmask_b32_e64 v145, 0, v216, s[22:23]
	v_sub_f32_e32 v140, v140, v145
	v_sub_f32_e32 v140, v144, v140
	v_mul_f32_e32 v144, 0x3fb8aa3b, v142
	v_exp_f32_e32 v144, v144
	s_nop 0
	v_fma_f32 v132, v183, v144, v132
	v_cmp_gt_f32_e64 s[22:23], s97, v132
	s_nop 1
	v_cndmask_b32_e64 v144, 0, 32, s[22:23]
	v_ldexp_f32 v132, v132, v144
	v_log_f32_e32 v132, v132
	s_nop 0
	v_mul_f32_e32 v144, 0x3f317217, v132
	v_fma_f32 v144, v132, s52, -v144
	v_fmac_f32_e32 v144, 0x3377d1cf, v132
	v_fmac_f32_e32 v144, 0x3f317217, v132
	v_cmp_lt_f32_e64 s[24:25], |v132|, s53
	s_nop 1
	v_cndmask_b32_e64 v132, v132, v144, s[24:25]
	v_cndmask_b32_e64 v144, 0, v216, s[22:23]
	v_sub_f32_e32 v132, v132, v144
	v_cndmask_b32_e64 v132, v142, v132, s[20:21]
	v_mul_f32_e32 v142, 0x3fb8aa3b, v140
	v_exp_f32_e32 v142, v142
	s_nop 0
	v_fma_f32 v128, v182, v142, v128
	v_cmp_gt_f32_e64 s[20:21], s97, v128
	s_nop 1
	v_cndmask_b32_e64 v142, 0, 32, s[20:21]
	v_ldexp_f32 v128, v128, v142
	v_log_f32_e32 v128, v128
	s_nop 0
	v_mul_f32_e32 v142, 0x3f317217, v128
	v_fma_f32 v142, v128, s52, -v142
	v_fmac_f32_e32 v142, 0x3377d1cf, v128
	v_fmac_f32_e32 v142, 0x3f317217, v128
	v_cmp_lt_f32_e64 s[22:23], |v128|, s53
	s_nop 1
	v_cndmask_b32_e64 v128, v128, v142, s[22:23]
	v_cndmask_b32_e64 v142, 0, v216, s[20:21]
	v_sub_f32_e32 v128, v128, v142
	v_mul_f32_e64 v142, |v143|, s57
	v_exp_f32_e32 v142, v142
	v_cndmask_b32_e64 v128, v140, v128, s[18:19]
	v_min_f32_e32 v140, 0, v143
	v_readlane_b32 s23, v255, 55
	v_add_f32_e32 v142, 1.0, v142
	v_cmp_gt_f32_e64 s[18:19], s97, v142
	s_nop 1
	v_cndmask_b32_e64 v143, 0, 32, s[18:19]
	v_ldexp_f32 v142, v142, v143
	v_log_f32_e32 v142, v142
	s_nop 0
	v_mul_f32_e32 v143, 0x3f317217, v142
	v_fma_f32 v143, v142, s52, -v143
	v_fmac_f32_e32 v143, 0x3377d1cf, v142
	v_fmac_f32_e32 v143, 0x3f317217, v142
	v_cmp_lt_f32_e64 s[20:21], |v142|, s53
	s_nop 1
	v_cndmask_b32_e64 v142, v142, v143, s[20:21]
	v_cndmask_b32_e64 v143, 0, v216, s[18:19]
	v_sub_f32_e32 v142, v142, v143
	v_sub_f32_e32 v140, v140, v142
	v_min_f32_e32 v142, 0, v141
	v_mul_f32_e64 v141, |v141|, s57
	v_exp_f32_e32 v141, v141
	s_nop 0
	v_add_f32_e32 v141, 1.0, v141
	v_cmp_gt_f32_e64 s[18:19], s97, v141
	s_nop 1
	v_cndmask_b32_e64 v143, 0, 32, s[18:19]
	v_ldexp_f32 v141, v141, v143
	v_log_f32_e32 v141, v141
	s_nop 0
	v_mul_f32_e32 v143, 0x3f317217, v141
	v_fma_f32 v143, v141, s52, -v143
	v_fmac_f32_e32 v143, 0x3377d1cf, v141
	v_fmac_f32_e32 v143, 0x3f317217, v141
	v_cmp_lt_f32_e64 s[20:21], |v141|, s53
	s_nop 1
	v_cndmask_b32_e64 v141, v141, v143, s[20:21]
	v_cndmask_b32_e64 v143, 0, v216, s[18:19]
	v_sub_f32_e32 v141, v141, v143
	v_sub_f32_e32 v141, v142, v141
	v_mul_f32_e32 v142, 0x3fb8aa3b, v140
	v_exp_f32_e32 v142, v142
	s_nop 0
	v_fma_f32 v133, v181, v142, v133
	v_cmp_gt_f32_e64 s[18:19], s97, v133
	s_nop 1
	v_cndmask_b32_e64 v142, 0, 32, s[18:19]
	v_ldexp_f32 v133, v133, v142
	v_log_f32_e32 v133, v133
	s_nop 0
	v_mul_f32_e32 v142, 0x3f317217, v133
	v_fma_f32 v142, v133, s52, -v142
	v_fmac_f32_e32 v142, 0x3377d1cf, v133
	v_fmac_f32_e32 v142, 0x3f317217, v133
	v_cmp_lt_f32_e64 s[20:21], |v133|, s53
	s_nop 1
	v_cndmask_b32_e64 v133, v133, v142, s[20:21]
	v_cndmask_b32_e64 v142, 0, v216, s[18:19]
	v_sub_f32_e32 v133, v133, v142
	v_cndmask_b32_e64 v133, v140, v133, s[16:17]
	v_mul_f32_e32 v140, 0x3fb8aa3b, v141
	v_exp_f32_e32 v140, v140
	s_nop 0
	v_fma_f32 v129, v180, v140, v129
	v_cmp_gt_f32_e64 s[16:17], s97, v129
	s_nop 1
	v_cndmask_b32_e64 v140, 0, 32, s[16:17]
	v_ldexp_f32 v129, v129, v140
	v_log_f32_e32 v129, v129
	s_nop 0
	v_mul_f32_e32 v140, 0x3f317217, v129
	v_fma_f32 v140, v129, s52, -v140
	v_fmac_f32_e32 v140, 0x3377d1cf, v129
	v_fmac_f32_e32 v140, 0x3f317217, v129
	v_cmp_lt_f32_e64 s[18:19], |v129|, s53
	s_nop 1
	v_cndmask_b32_e64 v129, v129, v140, s[18:19]
	v_cndmask_b32_e64 v140, 0, v216, s[16:17]
	v_sub_f32_e32 v129, v129, v140
	v_min_f32_e32 v140, 0, v138
	v_mul_f32_e64 v138, |v138|, s57
	v_exp_f32_e32 v138, v138
	v_cndmask_b32_e64 v129, v141, v129, s[14:15]
; __device__ __forceinline__ float silu_f(float x) { return x * __builtin_amdgcn_rcpf(1.f + __expf(-x)); }
; __device__ __forceinline__ v4u pack8(const f32x4 a, const f32x4 b) { v4u w; w.x = cvt_pk_bf16(a[0], a[1]); w.y = cvt_pk_bf16(a[2], a[3]); w.z = cvt_pk_bf16(b[0], b[1]); w.w = cvt_pk_bf16(b[2], b[3]); return w; }
;     __device__ __forceinline__ void operator()(const f32x4 (&acc)[2][2][4][2], const pg8::Unit& u, int wr, int wc, int fr, int fq) const {
;     ...
;         if (grp == 0) { WIN_LOOP( _Pragma("unroll") for (int i = 0; i < 4; ++i) { a[i] = silu_f(a[i]); b[i] = silu_f(b[i]); } *(v4u*)(QO + (size_t)row * DM + c) = pack8(a, b); ) }
;         else if (grp == 3) { WIN_LOOP( _Pragma("unroll") for (int i = 0; i < 4; ++i) { a[i] = silu_f(a[i]); b[i] = silu_f(b[i]); } *(v4u*)(GH + (size_t)row * 512 + c) = pack8(a, b); ) }
;         else if (grp == 1) {
;             f32x4 l0[2], l1[2];
; #pragma unroll
;             for (int bj = 0; bj < 2; ++bj) { l0[bj] = *(const f32x4*)(lb + cb + bj * 128); l1[bj] = *(const f32x4*)(lb + cb + bj * 128 + 4); }
;             WIN_LOOP( _Pragma("unroll") for (int i = 0; i < 4; ++i) { const float s0 = fminf(a[i], 0.f) - __logf(1.f + __expf(-fabsf(a[i]))), s1 = fminf(b[i], 0.f) - __logf(1.f + __expf(-fabsf(b[i]))); const float la = l0[bj][i], lbv = l1[bj][i];
;                     a[i] = la > 0.f ? __logf(la + (1.f - la) * __expf(s0)) : s0; b[i] = lbv > 0.f ? __logf(lbv + (1.f - lbv) * __expf(s1)) : s1; }
;                 *(f32x4*)(LF + (size_t)row * 512 + c) = a; *(f32x4*)(LF + (size_t)row * 512 + c + 4) = b; __builtin_amdgcn_sched_barrier(0); ) }
	v_add_f32_e32 v138, 1.0, v138
	v_cmp_gt_f32_e64 s[14:15], s97, v138
	s_nop 1
	v_cndmask_b32_e64 v141, 0, 32, s[14:15]
	v_ldexp_f32 v138, v138, v141
	v_log_f32_e32 v138, v138
	s_nop 0
	v_mul_f32_e32 v141, 0x3f317217, v138
	v_fma_f32 v141, v138, s52, -v141
	v_fmac_f32_e32 v141, 0x3377d1cf, v138
	v_fmac_f32_e32 v141, 0x3f317217, v138
	v_cmp_lt_f32_e64 s[16:17], |v138|, s53
	s_nop 1
	v_cndmask_b32_e64 v138, v138, v141, s[16:17]
	v_cndmask_b32_e64 v141, 0, v216, s[14:15]
	v_sub_f32_e32 v138, v138, v141
	v_sub_f32_e32 v138, v140, v138
	v_min_f32_e32 v140, 0, v136
	v_mul_f32_e64 v136, |v136|, s57
	v_exp_f32_e32 v136, v136
	s_nop 0
	v_add_f32_e32 v136, 1.0, v136
	v_cmp_gt_f32_e64 s[14:15], s97, v136
	s_nop 1
	v_cndmask_b32_e64 v141, 0, 32, s[14:15]
	v_ldexp_f32 v136, v136, v141
	v_log_f32_e32 v136, v136
	s_nop 0
	v_mul_f32_e32 v141, 0x3f317217, v136
	v_fma_f32 v141, v136, s52, -v141
	v_fmac_f32_e32 v141, 0x3377d1cf, v136
	v_fmac_f32_e32 v141, 0x3f317217, v136
	v_cmp_lt_f32_e64 s[16:17], |v136|, s53
	s_nop 1
	v_cndmask_b32_e64 v136, v136, v141, s[16:17]
	v_cndmask_b32_e64 v141, 0, v216, s[14:15]
	v_sub_f32_e32 v136, v136, v141
	v_sub_f32_e32 v136, v140, v136
	v_mul_f32_e32 v140, 0x3fb8aa3b, v138
	v_exp_f32_e32 v140, v140
	s_nop 0
	v_fma_f32 v134, v179, v140, v134
	v_cmp_gt_f32_e64 s[14:15], s97, v134
	s_nop 1
	v_cndmask_b32_e64 v140, 0, 32, s[14:15]
	v_ldexp_f32 v134, v134, v140
	v_log_f32_e32 v134, v134
	s_nop 0
	v_mul_f32_e32 v140, 0x3f317217, v134
	v_fma_f32 v140, v134, s52, -v140
	v_fmac_f32_e32 v140, 0x3377d1cf, v134
	v_fmac_f32_e32 v140, 0x3f317217, v134
	v_cmp_lt_f32_e64 s[16:17], |v134|, s53
	s_nop 1
	v_cndmask_b32_e64 v134, v134, v140, s[16:17]
	v_cndmask_b32_e64 v140, 0, v216, s[14:15]
	v_sub_f32_e32 v134, v134, v140
	v_cndmask_b32_e64 v134, v138, v134, s[12:13]
	v_mul_f32_e32 v138, 0x3fb8aa3b, v136
	v_exp_f32_e32 v138, v138
	s_nop 0
	v_fma_f32 v130, v178, v138, v130
	v_cmp_gt_f32_e64 s[12:13], s97, v130
	s_nop 1
	v_cndmask_b32_e64 v138, 0, 32, s[12:13]
	v_ldexp_f32 v130, v130, v138
	v_log_f32_e32 v130, v130
	s_nop 0
	v_mul_f32_e32 v138, 0x3f317217, v130
	v_fma_f32 v138, v130, s52, -v138
	v_fmac_f32_e32 v138, 0x3377d1cf, v130
	v_fmac_f32_e32 v138, 0x3f317217, v130
	v_cmp_lt_f32_e64 s[14:15], |v130|, s53
	s_nop 1
	v_cndmask_b32_e64 v130, v130, v138, s[14:15]
	v_cndmask_b32_e64 v138, 0, v216, s[12:13]
	v_sub_f32_e32 v130, v130, v138
	v_mul_f32_e64 v138, |v139|, s57
	v_exp_f32_e32 v138, v138
	v_cndmask_b32_e64 v130, v136, v130, s[10:11]
	v_min_f32_e32 v136, 0, v139
	v_add_f32_e32 v138, 1.0, v138
	v_cmp_gt_f32_e64 s[10:11], s97, v138
	s_nop 1
	v_cndmask_b32_e64 v139, 0, 32, s[10:11]
	v_ldexp_f32 v138, v138, v139
	v_log_f32_e32 v138, v138
	s_nop 0
	v_mul_f32_e32 v139, 0x3f317217, v138
	v_fma_f32 v139, v138, s52, -v139
	v_fmac_f32_e32 v139, 0x3377d1cf, v138
	v_fmac_f32_e32 v139, 0x3f317217, v138
	v_cmp_lt_f32_e64 s[12:13], |v138|, s53
	s_nop 1
	v_cndmask_b32_e64 v138, v138, v139, s[12:13]
	v_cndmask_b32_e64 v139, 0, v216, s[10:11]
	v_sub_f32_e32 v138, v138, v139
	v_sub_f32_e32 v136, v136, v138
	v_min_f32_e32 v138, 0, v137
	v_mul_f32_e64 v137, |v137|, s57
	v_exp_f32_e32 v137, v137
	s_nop 0
	v_add_f32_e32 v137, 1.0, v137
	v_cmp_gt_f32_e64 s[10:11], s97, v137
	s_nop 1
	v_cndmask_b32_e64 v139, 0, 32, s[10:11]
	v_ldexp_f32 v137, v137, v139
	v_log_f32_e32 v137, v137
	s_nop 0
	v_mul_f32_e32 v139, 0x3f317217, v137
	v_fma_f32 v139, v137, s52, -v139
	v_fmac_f32_e32 v139, 0x3377d1cf, v137
	v_fmac_f32_e32 v139, 0x3f317217, v137
	v_cmp_lt_f32_e64 s[12:13], |v137|, s53
	s_nop 1
	v_cndmask_b32_e64 v137, v137, v139, s[12:13]
	v_cndmask_b32_e64 v139, 0, v216, s[10:11]
	v_sub_f32_e32 v137, v137, v139
	v_sub_f32_e32 v137, v138, v137
	v_mul_f32_e32 v138, 0x3fb8aa3b, v136
	v_exp_f32_e32 v138, v138
	s_nop 0
	v_fmac_f32_e32 v135, v177, v138
	v_cmp_gt_f32_e64 s[10:11], s97, v135
	s_nop 1
	v_cndmask_b32_e64 v138, 0, 32, s[10:11]
	v_ldexp_f32 v135, v135, v138
	v_log_f32_e32 v135, v135
	s_nop 0
	v_mul_f32_e32 v138, 0x3f317217, v135
	v_fma_f32 v138, v135, s52, -v138
	v_fmac_f32_e32 v138, 0x3377d1cf, v135
	v_fmac_f32_e32 v138, 0x3f317217, v135
	v_cmp_lt_f32_e64 s[12:13], |v135|, s53
	s_nop 1
	v_cndmask_b32_e64 v135, v135, v138, s[12:13]
	v_cndmask_b32_e64 v138, 0, v216, s[10:11]
	v_sub_f32_e32 v135, v135, v138
	v_cndmask_b32_e64 v135, v136, v135, s[8:9]
	v_mul_f32_e32 v136, 0x3fb8aa3b, v137
	v_exp_f32_e32 v136, v136
	s_nop 0
	v_fmac_f32_e32 v131, v167, v136
	v_cmp_gt_f32_e64 s[8:9], s97, v131
	s_nop 1
	v_cndmask_b32_e64 v136, 0, 32, s[8:9]
	v_ldexp_f32 v131, v131, v136
	v_log_f32_e32 v131, v131
	s_nop 0
	v_mul_f32_e32 v136, 0x3f317217, v131
	v_fma_f32 v136, v131, s52, -v136
	v_fmac_f32_e32 v136, 0x3377d1cf, v131
	v_fmac_f32_e32 v136, 0x3f317217, v131
	v_cmp_lt_f32_e64 s[10:11], |v131|, s53
	s_nop 1
	v_cndmask_b32_e64 v131, v131, v136, s[10:11]
	v_cndmask_b32_e64 v136, 0, v216, s[8:9]
	v_sub_f32_e32 v131, v131, v136
	v_cndmask_b32_e32 v131, v137, v131, vcc
	flat_store_dwordx4 v[146:147], v[132:135] offset:512 sc1
	flat_store_dwordx4 v[146:147], v[128:131] offset:528 sc1

; __device__ __forceinline__ v4u pack8(const f32x4 a, const f32x4 b) { v4u w; w.x = cvt_pk_bf16(a[0], a[1]); w.y = cvt_pk_bf16(a[2], a[3]); w.z = cvt_pk_bf16(b[0], b[1]); w.w = cvt_pk_bf16(b[2], b[3]); return w; }
; __device__ __forceinline__ float silu_f(float x) { return x * __builtin_amdgcn_rcpf(1.f + __expf(-x)); }
;     __device__ __forceinline__ void operator()(const f32x4 (&acc)[2][2][4][2], const pg8::Unit& u, int wr, int wc, int fr, int fq) const {
;     ...
;         if (grp == 0) { WIN_LOOP( _Pragma("unroll") for (int i = 0; i < 4; ++i) { a[i] = silu_f(a[i]); b[i] = silu_f(b[i]); } *(v4u*)(QO + (size_t)row * DM + c) = pack8(a, b); ) }
.LBB0_417:
	s_and_b64 vcc, exec, s[8:9]
	s_cbranch_vccz .LBB0_419
	v_and_b32_e32 v129, 64, v215
	v_xor_b32_e32 v128, 16, v215
	v_add_u32_e32 v129, 64, v129
	v_cmp_lt_i32_e32 vcc, v128, v129
	v_xor_b32_e32 v130, 32, v215
	v_ashrrev_i32_e32 v167, 31, v166
	v_cndmask_b32_e32 v128, v215, v128, vcc
	v_cmp_lt_i32_e32 vcc, v130, v129
	v_lshlrev_b32_e32 v128, 2, v128
	v_lshlrev_b32_e32 v192, 1, v176
	v_cndmask_b32_e32 v129, v215, v130, vcc
	v_lshlrev_b64 v[130:131], 6, v[166:167]
	v_lshl_add_u64 v[130:131], v[160:161], 0, v[130:131]
	flat_load_dwordx4 v[130:133], v[130:131]
	v_lshlrev_b32_e32 v129, 2, v129
	s_waitcnt vmcnt(0) lgkmcnt(0)
	v_mov_b32_e32 v134, v131
	v_mov_b32_e32 v135, v132
	v_mov_b32_e32 v131, v133
	v_pk_add_f32 v[130:131], v[134:135], v[130:131]
	s_nop 0
	v_add_f32_e32 v130, v130, v131
	ds_bpermute_b32 v131, v128, v130
	s_waitcnt lgkmcnt(0)
	v_add_f32_e32 v130, v130, v131
	ds_bpermute_b32 v131, v129, v130
	s_waitcnt lgkmcnt(0)
	v_add_f32_e32 v130, v130, v131
	v_fmamk_f32 v130, v130, 0x3a800000, v212
	v_rsq_f32_e32 v134, v130
	v_lshlrev_b64 v[130:131], 11, v[166:167]
	v_lshl_add_u64 v[136:137], s[44:45], 0, v[130:131]
	v_lshl_add_u64 v[136:137], v[136:137], 0, v[192:193]
	v_pk_mul_f32 v[132:133], v[60:61], v[134:135] op_sel_hi:[1,0]
	v_pk_mul_f32 v[130:131], v[62:63], v[134:135] op_sel_hi:[1,0]
	v_pk_mul_f32 v[138:139], v[58:59], v[134:135] op_sel_hi:[1,0]
	v_pk_mul_f32 v[140:141], v[56:57], v[134:135] op_sel_hi:[1,0]
	v_mul_f32_e32 v135, 0xbfb8aa3b, v132
	v_exp_f32_e32 v135, v135
	s_nop 0
	v_add_f32_e32 v135, 1.0, v135
	v_rcp_f32_e32 v142, v135
	v_mul_f32_e32 v135, 0xbfb8aa3b, v140
	v_exp_f32_e32 v135, v135
	s_nop 0
	v_add_f32_e32 v135, 1.0, v135
	v_rcp_f32_e32 v144, v135
	v_mul_f32_e32 v135, 0xbfb8aa3b, v133
	v_exp_f32_e32 v135, v135
	s_nop 0
	v_add_f32_e32 v135, 1.0, v135
	v_rcp_f32_e32 v143, v135
	v_mul_f32_e32 v135, 0xbfb8aa3b, v141
	v_exp_f32_e32 v135, v135
	v_pk_mul_f32 v[132:133], v[132:133], v[142:143]
	v_add_f32_e32 v135, 1.0, v135
	v_rcp_f32_e32 v145, v135
	v_mul_f32_e32 v135, 0xbfb8aa3b, v130
	v_exp_f32_e32 v135, v135
	v_pk_mul_f32 v[140:141], v[140:141], v[144:145]
	v_add_f32_e32 v135, 1.0, v135
	v_rcp_f32_e32 v142, v135
	v_mul_f32_e32 v135, 0xbfb8aa3b, v138
	v_exp_f32_e32 v135, v135
	s_nop 0
	v_add_f32_e32 v135, 1.0, v135
	v_rcp_f32_e32 v144, v135
	v_mul_f32_e32 v135, 0xbfb8aa3b, v131
	v_exp_f32_e32 v135, v135
	s_nop 0
	v_add_f32_e32 v135, 1.0, v135
	v_rcp_f32_e32 v143, v135
	v_pk_mul_f32 v[120:121], v[120:121], v[134:135] op_sel_hi:[1,0]
	v_pk_mul_f32 v[124:125], v[124:125], v[134:135] op_sel_hi:[1,0]
	v_pk_mul_f32 v[122:123], v[122:123], v[134:135] op_sel_hi:[1,0]
	v_pk_mul_f32 v[142:143], v[130:131], v[142:143]
	v_mul_f32_e32 v130, 0xbfb8aa3b, v139
	v_exp_f32_e32 v130, v130
	v_cvt_pk_bf16_f32 v131, v142, v143
	v_pk_mul_f32 v[126:127], v[126:127], v[134:135] op_sel_hi:[1,0]
	v_add_f32_e32 v130, 1.0, v130
	v_rcp_f32_e32 v145, v130
	v_cvt_pk_bf16_f32 v130, v132, v133
	v_cvt_pk_bf16_f32 v132, v140, v141
	v_pk_mul_f32 v[138:139], v[138:139], v[144:145]
	s_nop 0
	v_cvt_pk_bf16_f32 v133, v138, v139
	flat_store_dwordx4 v[136:137], v[130:133] sc1
	s_nop 1
	v_mul_f32_e32 v131, 0xbfb8aa3b, v120
	v_exp_f32_e32 v131, v131
	v_mul_f32_e32 v130, 0xbfb8aa3b, v124
	v_exp_f32_e32 v130, v130
	v_add_f32_e32 v131, 1.0, v131
	v_rcp_f32_e32 v132, v131
	v_mul_f32_e32 v131, 0xbfb8aa3b, v125
	v_exp_f32_e32 v131, v131
	v_add_f32_e32 v130, 1.0, v130
	v_rcp_f32_e32 v130, v130
	v_add_f32_e32 v131, 1.0, v131
	v_rcp_f32_e32 v131, v131
	s_nop 0
	v_pk_mul_f32 v[124:125], v[124:125], v[130:131]
	v_mul_f32_e32 v130, 0xbfb8aa3b, v121
	v_exp_f32_e32 v130, v130
	s_nop 0
	v_add_f32_e32 v130, 1.0, v130
	v_rcp_f32_e32 v133, v130
	s_nop 0
	v_pk_mul_f32 v[130:131], v[120:121], v[132:133]
	v_mul_f32_e32 v121, 0xbfb8aa3b, v122
	v_exp_f32_e32 v121, v121
	v_mul_f32_e32 v120, 0xbfb8aa3b, v126
	v_exp_f32_e32 v120, v120
	v_add_f32_e32 v121, 1.0, v121
	v_rcp_f32_e32 v132, v121
	v_mul_f32_e32 v121, 0xbfb8aa3b, v127
	v_exp_f32_e32 v121, v121
	v_add_f32_e32 v120, 1.0, v120
	v_rcp_f32_e32 v120, v120
	v_add_f32_e32 v121, 1.0, v121
	v_rcp_f32_e32 v121, v121
	s_nop 0
	v_pk_mul_f32 v[126:127], v[126:127], v[120:121]
	v_mul_f32_e32 v120, 0xbfb8aa3b, v123
	v_exp_f32_e32 v120, v120
	v_cvt_pk_bf16_f32 v121, v126, v127
	v_add_f32_e32 v120, 1.0, v120
	v_rcp_f32_e32 v133, v120
	v_cvt_pk_bf16_f32 v120, v124, v125
	v_or_b32_e32 v124, 16, v166
	v_ashrrev_i32_e32 v125, 31, v124
	v_pk_mul_f32 v[132:133], v[122:123], v[132:133]
	v_cvt_pk_bf16_f32 v122, v130, v131
	v_cvt_pk_bf16_f32 v123, v132, v133
	flat_store_dwordx4 v[136:137], v[120:123] offset:256 sc1
	s_nop 1
	v_lshlrev_b64 v[120:121], 6, v[124:125]
	v_lshl_add_u64 v[120:121], v[160:161], 0, v[120:121]
	flat_load_dwordx4 v[120:123], v[120:121]
	s_waitcnt vmcnt(0) lgkmcnt(0)
	v_mov_b32_e32 v126, v121
	v_mov_b32_e32 v127, v122
	v_mov_b32_e32 v121, v123
	v_pk_add_f32 v[120:121], v[126:127], v[120:121]
	s_nop 0
	v_add_f32_e32 v120, v120, v121
	ds_bpermute_b32 v121, v128, v120
	s_waitcnt lgkmcnt(0)
	v_add_f32_e32 v120, v120, v121
	ds_bpermute_b32 v121, v129, v120
	s_waitcnt lgkmcnt(0)
; __device__ __forceinline__ v4u pack8(const f32x4 a, const f32x4 b) { v4u w; w.x = cvt_pk_bf16(a[0], a[1]); w.y = cvt_pk_bf16(a[2], a[3]); w.z = cvt_pk_bf16(b[0], b[1]); w.w = cvt_pk_bf16(b[2], b[3]); return w; }
; __device__ __forceinline__ float silu_f(float x) { return x * __builtin_amdgcn_rcpf(1.f + __expf(-x)); }
;     __device__ __forceinline__ void operator()(const f32x4 (&acc)[2][2][4][2], const pg8::Unit& u, int wr, int wc, int fr, int fq) const {
;     ...
;         if (grp == 0) { WIN_LOOP( _Pragma("unroll") for (int i = 0; i < 4; ++i) { a[i] = silu_f(a[i]); b[i] = silu_f(b[i]); } *(v4u*)(QO + (size_t)row * DM + c) = pack8(a, b); ) }
	v_add_f32_e32 v120, v120, v121
	v_fmamk_f32 v120, v120, 0x3a800000, v212
	v_rsq_f32_e32 v122, v120
	v_lshlrev_b64 v[120:121], 11, v[124:125]
	v_lshl_add_u64 v[120:121], s[44:45], 0, v[120:121]
	v_lshl_add_u64 v[120:121], v[120:121], 0, v[192:193]
	v_pk_mul_f32 v[126:127], v[52:53], v[122:123] op_sel_hi:[1,0]
	v_pk_mul_f32 v[124:125], v[54:55], v[122:123] op_sel_hi:[1,0]
	v_pk_mul_f32 v[130:131], v[50:51], v[122:123] op_sel_hi:[1,0]
	v_pk_mul_f32 v[132:133], v[48:49], v[122:123] op_sel_hi:[1,0]
	v_mul_f32_e32 v123, 0xbfb8aa3b, v126
	v_exp_f32_e32 v123, v123
	s_nop 0
	v_add_f32_e32 v123, 1.0, v123
	v_rcp_f32_e32 v134, v123
	v_mul_f32_e32 v123, 0xbfb8aa3b, v132
	v_exp_f32_e32 v123, v123
	s_nop 0
	v_add_f32_e32 v123, 1.0, v123
	v_rcp_f32_e32 v136, v123
	v_mul_f32_e32 v123, 0xbfb8aa3b, v127
	v_exp_f32_e32 v123, v123
	s_nop 0
	v_add_f32_e32 v123, 1.0, v123
	v_rcp_f32_e32 v135, v123
	v_mul_f32_e32 v123, 0xbfb8aa3b, v133
	v_exp_f32_e32 v123, v123
	v_pk_mul_f32 v[126:127], v[126:127], v[134:135]
	v_add_f32_e32 v123, 1.0, v123
	v_rcp_f32_e32 v137, v123
	v_mul_f32_e32 v123, 0xbfb8aa3b, v124
	v_exp_f32_e32 v123, v123
	v_pk_mul_f32 v[132:133], v[132:133], v[136:137]
	v_add_f32_e32 v123, 1.0, v123
	v_rcp_f32_e32 v134, v123
	v_mul_f32_e32 v123, 0xbfb8aa3b, v130
	v_exp_f32_e32 v123, v123
	s_nop 0
	v_add_f32_e32 v123, 1.0, v123
	v_rcp_f32_e32 v136, v123
	v_mul_f32_e32 v123, 0xbfb8aa3b, v125
	v_exp_f32_e32 v123, v123
	s_nop 0
	v_add_f32_e32 v123, 1.0, v123
	v_rcp_f32_e32 v135, v123
	v_mul_f32_e32 v123, 0xbfb8aa3b, v131
	v_exp_f32_e32 v123, v123
	v_pk_mul_f32 v[134:135], v[124:125], v[134:135]
	v_cvt_pk_bf16_f32 v124, v126, v127
	v_add_f32_e32 v123, 1.0, v123
	v_rcp_f32_e32 v137, v123
	v_cvt_pk_bf16_f32 v125, v134, v135
	v_cvt_pk_bf16_f32 v126, v132, v133
	v_pk_mul_f32 v[116:117], v[116:117], v[122:123] op_sel_hi:[1,0]
	v_pk_mul_f32 v[130:131], v[130:131], v[136:137]
	v_pk_mul_f32 v[114:115], v[114:115], v[122:123] op_sel_hi:[1,0]
	v_cvt_pk_bf16_f32 v127, v130, v131
	flat_store_dwordx4 v[120:121], v[124:127] sc1
	s_nop 1
	v_pk_mul_f32 v[124:125], v[118:119], v[122:123] op_sel_hi:[1,0]
	v_pk_mul_f32 v[118:119], v[112:113], v[122:123] op_sel_hi:[1,0]
	v_mul_f32_e32 v112, 0xbfb8aa3b, v116
	v_mul_f32_e32 v113, 0xbfb8aa3b, v118
	v_exp_f32_e32 v113, v113
	v_exp_f32_e32 v112, v112
	v_add_f32_e32 v113, 1.0, v113
	v_rcp_f32_e32 v122, v113
	v_mul_f32_e32 v113, 0xbfb8aa3b, v117
	v_exp_f32_e32 v113, v113
	v_add_f32_e32 v112, 1.0, v112
	v_rcp_f32_e32 v112, v112
	v_add_f32_e32 v113, 1.0, v113
	v_rcp_f32_e32 v113, v113
	s_nop 0
	v_pk_mul_f32 v[112:113], v[116:117], v[112:113]
	v_mul_f32_e32 v116, 0xbfb8aa3b, v119
	v_exp_f32_e32 v116, v116
	v_cvt_pk_bf16_f32 v112, v112, v113
	v_add_f32_e32 v116, 1.0, v116
	v_rcp_f32_e32 v123, v116
	s_nop 0
	v_pk_mul_f32 v[116:117], v[118:119], v[122:123]
	v_mul_f32_e32 v118, 0xbfb8aa3b, v124
	v_mul_f32_e32 v119, 0xbfb8aa3b, v125
	v_exp_f32_e32 v118, v118
	v_exp_f32_e32 v119, v119
	v_add_f32_e32 v118, 1.0, v118
	v_add_f32_e32 v119, 1.0, v119
	v_rcp_f32_e32 v122, v118
	v_mul_f32_e32 v118, 0xbfb8aa3b, v114
	v_rcp_f32_e32 v123, v119
	v_mul_f32_e32 v119, 0xbfb8aa3b, v115
	v_exp_f32_e32 v118, v118
	v_exp_f32_e32 v119, v119
	v_pk_mul_f32 v[122:123], v[124:125], v[122:123]
	v_add_f32_e32 v118, 1.0, v118
	v_add_f32_e32 v119, 1.0, v119
	v_rcp_f32_e32 v118, v118
	v_rcp_f32_e32 v119, v119
	v_cvt_pk_bf16_f32 v113, v122, v123
	v_pk_mul_f32 v[118:119], v[114:115], v[118:119]
	v_cvt_pk_bf16_f32 v114, v116, v117
	v_or_b32_e32 v116, 32, v166
	v_cvt_pk_bf16_f32 v115, v118, v119
	v_ashrrev_i32_e32 v117, 31, v116
	flat_store_dwordx4 v[120:121], v[112:115] offset:256 sc1
	s_nop 1
	v_lshlrev_b64 v[112:113], 6, v[116:117]
	v_lshl_add_u64 v[112:113], v[160:161], 0, v[112:113]
	flat_load_dwordx4 v[112:115], v[112:113]
	s_waitcnt vmcnt(0) lgkmcnt(0)
	v_mov_b32_e32 v118, v113
	v_mov_b32_e32 v119, v114
	v_mov_b32_e32 v113, v115
	v_pk_add_f32 v[112:113], v[118:119], v[112:113]
	s_nop 0
	v_add_f32_e32 v112, v112, v113
	ds_bpermute_b32 v113, v128, v112
	s_waitcnt lgkmcnt(0)
	v_add_f32_e32 v112, v112, v113
	ds_bpermute_b32 v113, v129, v112
	s_waitcnt lgkmcnt(0)
	v_add_f32_e32 v112, v112, v113
	v_fmamk_f32 v112, v112, 0x3a800000, v212
	v_rsq_f32_e32 v114, v112
	v_lshlrev_b64 v[112:113], 11, v[116:117]
	v_lshl_add_u64 v[112:113], s[44:45], 0, v[112:113]
	v_lshl_add_u64 v[112:113], v[112:113], 0, v[192:193]
	v_pk_mul_f32 v[118:119], v[44:45], v[114:115] op_sel_hi:[1,0]
	v_pk_mul_f32 v[116:117], v[46:47], v[114:115] op_sel_hi:[1,0]
	v_pk_mul_f32 v[120:121], v[42:43], v[114:115] op_sel_hi:[1,0]
	v_pk_mul_f32 v[122:123], v[40:41], v[114:115] op_sel_hi:[1,0]
	v_mul_f32_e32 v115, 0xbfb8aa3b, v118
	v_exp_f32_e32 v115, v115
	s_nop 0
	v_add_f32_e32 v115, 1.0, v115
	v_rcp_f32_e32 v124, v115
	v_mul_f32_e32 v115, 0xbfb8aa3b, v122
	v_exp_f32_e32 v115, v115
	s_nop 0
	v_add_f32_e32 v115, 1.0, v115
	v_rcp_f32_e32 v126, v115
	v_mul_f32_e32 v115, 0xbfb8aa3b, v119
	v_exp_f32_e32 v115, v115
	s_nop 0
	v_add_f32_e32 v115, 1.0, v115
	v_rcp_f32_e32 v125, v115
	v_mul_f32_e32 v115, 0xbfb8aa3b, v123
	v_exp_f32_e32 v115, v115
	v_pk_mul_f32 v[118:119], v[118:119], v[124:125]
	v_add_f32_e32 v115, 1.0, v115
	v_rcp_f32_e32 v127, v115
	v_mul_f32_e32 v115, 0xbfb8aa3b, v116
	v_exp_f32_e32 v115, v115
	v_pk_mul_f32 v[122:123], v[122:123], v[126:127]
	v_add_f32_e32 v115, 1.0, v115
	v_rcp_f32_e32 v124, v115
	v_mul_f32_e32 v115, 0xbfb8aa3b, v120
	v_exp_f32_e32 v115, v115
	s_nop 0
	v_add_f32_e32 v115, 1.0, v115
	v_rcp_f32_e32 v126, v115
	v_mul_f32_e32 v115, 0xbfb8aa3b, v117
	v_exp_f32_e32 v115, v115
	s_nop 0
	v_add_f32_e32 v115, 1.0, v115
	v_rcp_f32_e32 v125, v115
	v_mul_f32_e32 v115, 0xbfb8aa3b, v121
; __device__ __forceinline__ v4u pack8(const f32x4 a, const f32x4 b) { v4u w; w.x = cvt_pk_bf16(a[0], a[1]); w.y = cvt_pk_bf16(a[2], a[3]); w.z = cvt_pk_bf16(b[0], b[1]); w.w = cvt_pk_bf16(b[2], b[3]); return w; }
; __device__ __forceinline__ float silu_f(float x) { return x * __builtin_amdgcn_rcpf(1.f + __expf(-x)); }
;     __device__ __forceinline__ void operator()(const f32x4 (&acc)[2][2][4][2], const pg8::Unit& u, int wr, int wc, int fr, int fq) const {
;     ...
;         if (grp == 0) { WIN_LOOP( _Pragma("unroll") for (int i = 0; i < 4; ++i) { a[i] = silu_f(a[i]); b[i] = silu_f(b[i]); } *(v4u*)(QO + (size_t)row * DM + c) = pack8(a, b); ) }
	v_exp_f32_e32 v115, v115
	v_pk_mul_f32 v[124:125], v[116:117], v[124:125]
	v_cvt_pk_bf16_f32 v116, v118, v119
	v_add_f32_e32 v115, 1.0, v115
	v_rcp_f32_e32 v127, v115
	v_pk_mul_f32 v[110:111], v[110:111], v[114:115] op_sel_hi:[1,0]
	v_pk_mul_f32 v[108:109], v[108:109], v[114:115] op_sel_hi:[1,0]
	v_pk_mul_f32 v[106:107], v[106:107], v[114:115] op_sel_hi:[1,0]
	v_pk_mul_f32 v[114:115], v[104:105], v[114:115] op_sel_hi:[1,0]
	v_pk_mul_f32 v[120:121], v[120:121], v[126:127]
	v_mul_f32_e32 v105, 0xbfb8aa3b, v114
	v_exp_f32_e32 v105, v105
	v_cvt_pk_bf16_f32 v117, v124, v125
	v_cvt_pk_bf16_f32 v118, v122, v123
	v_cvt_pk_bf16_f32 v119, v120, v121
	v_add_f32_e32 v105, 1.0, v105
	flat_store_dwordx4 v[112:113], v[116:119] sc1
	v_mul_f32_e32 v104, 0xbfb8aa3b, v108
	v_exp_f32_e32 v104, v104
	v_rcp_f32_e32 v116, v105
	v_mul_f32_e32 v105, 0xbfb8aa3b, v109
	v_exp_f32_e32 v105, v105
	v_add_f32_e32 v104, 1.0, v104
	v_rcp_f32_e32 v104, v104
	v_add_f32_e32 v105, 1.0, v105
	v_rcp_f32_e32 v105, v105
	s_nop 0
	v_pk_mul_f32 v[104:105], v[108:109], v[104:105]
	v_mul_f32_e32 v108, 0xbfb8aa3b, v115
	v_exp_f32_e32 v108, v108
	v_cvt_pk_bf16_f32 v104, v104, v105
	v_add_f32_e32 v108, 1.0, v108
	v_rcp_f32_e32 v117, v108
	s_nop 0
	v_pk_mul_f32 v[108:109], v[114:115], v[116:117]
	v_mul_f32_e32 v114, 0xbfb8aa3b, v110
	v_mul_f32_e32 v115, 0xbfb8aa3b, v111
	v_exp_f32_e32 v114, v114
	v_exp_f32_e32 v115, v115
	v_add_f32_e32 v114, 1.0, v114
	v_add_f32_e32 v115, 1.0, v115
	v_rcp_f32_e32 v116, v114
	v_mul_f32_e32 v114, 0xbfb8aa3b, v106
	v_rcp_f32_e32 v117, v115
	v_mul_f32_e32 v115, 0xbfb8aa3b, v107
	v_exp_f32_e32 v114, v114
	v_exp_f32_e32 v115, v115
	v_pk_mul_f32 v[110:111], v[110:111], v[116:117]
	v_add_f32_e32 v114, 1.0, v114
	v_add_f32_e32 v115, 1.0, v115
	v_rcp_f32_e32 v114, v114
	v_rcp_f32_e32 v115, v115
	v_cvt_pk_bf16_f32 v105, v110, v111
	v_pk_mul_f32 v[114:115], v[106:107], v[114:115]
	v_cvt_pk_bf16_f32 v106, v108, v109
	v_or_b32_e32 v108, 48, v166
	v_cvt_pk_bf16_f32 v107, v114, v115
	v_ashrrev_i32_e32 v109, 31, v108
	flat_store_dwordx4 v[112:113], v[104:107] offset:256 sc1
	s_nop 1
	v_lshlrev_b64 v[104:105], 6, v[108:109]
	v_lshl_add_u64 v[104:105], v[160:161], 0, v[104:105]
	flat_load_dwordx4 v[104:107], v[104:105]
	s_waitcnt vmcnt(0) lgkmcnt(0)
	v_mov_b32_e32 v110, v105
	v_mov_b32_e32 v111, v106
	v_mov_b32_e32 v105, v107
	v_pk_add_f32 v[104:105], v[110:111], v[104:105]
	s_nop 0
	v_add_f32_e32 v104, v104, v105
	ds_bpermute_b32 v105, v128, v104
	s_waitcnt lgkmcnt(0)
	v_add_f32_e32 v104, v104, v105
	ds_bpermute_b32 v105, v129, v104
	s_waitcnt lgkmcnt(0)
	v_add_f32_e32 v104, v104, v105
	v_fmamk_f32 v104, v104, 0x3a800000, v212
	v_rsq_f32_e32 v110, v104
	v_lshlrev_b64 v[104:105], 11, v[108:109]
	v_lshl_add_u64 v[108:109], s[44:45], 0, v[104:105]
	v_lshl_add_u64 v[108:109], v[108:109], 0, v[192:193]
	v_pk_mul_f32 v[106:107], v[36:37], v[110:111] op_sel_hi:[1,0]
	v_pk_mul_f32 v[104:105], v[38:39], v[110:111] op_sel_hi:[1,0]
	v_pk_mul_f32 v[112:113], v[34:35], v[110:111] op_sel_hi:[1,0]
	v_pk_mul_f32 v[114:115], v[32:33], v[110:111] op_sel_hi:[1,0]
	v_mul_f32_e32 v111, 0xbfb8aa3b, v106
	v_exp_f32_e32 v111, v111
	s_nop 0
	v_add_f32_e32 v111, 1.0, v111
	v_rcp_f32_e32 v116, v111
	v_mul_f32_e32 v111, 0xbfb8aa3b, v114
	v_exp_f32_e32 v111, v111
	s_nop 0
	v_add_f32_e32 v111, 1.0, v111
	v_rcp_f32_e32 v118, v111
	v_mul_f32_e32 v111, 0xbfb8aa3b, v107
	v_exp_f32_e32 v111, v111
	s_nop 0
	v_add_f32_e32 v111, 1.0, v111
	v_rcp_f32_e32 v117, v111
	v_mul_f32_e32 v111, 0xbfb8aa3b, v115
	v_exp_f32_e32 v111, v111
	v_pk_mul_f32 v[106:107], v[106:107], v[116:117]
	v_add_f32_e32 v111, 1.0, v111
	v_rcp_f32_e32 v119, v111
	v_mul_f32_e32 v111, 0xbfb8aa3b, v104
	v_exp_f32_e32 v111, v111
	v_pk_mul_f32 v[114:115], v[114:115], v[118:119]
	v_add_f32_e32 v111, 1.0, v111
	v_rcp_f32_e32 v116, v111
	v_mul_f32_e32 v111, 0xbfb8aa3b, v112
	v_exp_f32_e32 v111, v111
	s_nop 0
	v_add_f32_e32 v111, 1.0, v111
	v_rcp_f32_e32 v118, v111
	v_mul_f32_e32 v111, 0xbfb8aa3b, v105
	v_exp_f32_e32 v111, v111
	s_nop 0
	v_add_f32_e32 v111, 1.0, v111
	v_rcp_f32_e32 v117, v111
	v_pk_mul_f32 v[96:97], v[96:97], v[110:111] op_sel_hi:[1,0]
	v_pk_mul_f32 v[100:101], v[100:101], v[110:111] op_sel_hi:[1,0]
	v_pk_mul_f32 v[98:99], v[98:99], v[110:111] op_sel_hi:[1,0]
	v_pk_mul_f32 v[116:117], v[104:105], v[116:117]
	v_mul_f32_e32 v104, 0xbfb8aa3b, v113
	v_exp_f32_e32 v104, v104
	v_cvt_pk_bf16_f32 v105, v116, v117
	v_pk_mul_f32 v[102:103], v[102:103], v[110:111] op_sel_hi:[1,0]
	v_add_f32_e32 v104, 1.0, v104
	v_rcp_f32_e32 v119, v104
	v_cvt_pk_bf16_f32 v104, v106, v107
	v_cvt_pk_bf16_f32 v106, v114, v115
	v_pk_mul_f32 v[112:113], v[112:113], v[118:119]
	s_nop 0
	v_cvt_pk_bf16_f32 v107, v112, v113
	flat_store_dwordx4 v[108:109], v[104:107] sc1
	s_nop 1
	v_mul_f32_e32 v105, 0xbfb8aa3b, v96
	v_exp_f32_e32 v105, v105
	v_mul_f32_e32 v104, 0xbfb8aa3b, v100
	v_exp_f32_e32 v104, v104
	v_add_f32_e32 v105, 1.0, v105
	v_rcp_f32_e32 v106, v105
	v_mul_f32_e32 v105, 0xbfb8aa3b, v101
	v_exp_f32_e32 v105, v105
	v_add_f32_e32 v104, 1.0, v104
	v_rcp_f32_e32 v104, v104
	v_add_f32_e32 v105, 1.0, v105
	v_rcp_f32_e32 v105, v105
	s_nop 0
	v_pk_mul_f32 v[100:101], v[100:101], v[104:105]
	v_mul_f32_e32 v104, 0xbfb8aa3b, v97
	v_exp_f32_e32 v104, v104
	s_nop 0
	v_add_f32_e32 v104, 1.0, v104
	v_rcp_f32_e32 v107, v104
	s_nop 0
	v_pk_mul_f32 v[104:105], v[96:97], v[106:107]
	v_mul_f32_e32 v97, 0xbfb8aa3b, v98
	v_exp_f32_e32 v97, v97
	v_mul_f32_e32 v96, 0xbfb8aa3b, v102
	v_exp_f32_e32 v96, v96
	v_add_f32_e32 v97, 1.0, v97
	v_rcp_f32_e32 v106, v97
	v_mul_f32_e32 v97, 0xbfb8aa3b, v103
	v_exp_f32_e32 v97, v97
	v_add_f32_e32 v96, 1.0, v96
	v_rcp_f32_e32 v96, v96
	v_add_f32_e32 v97, 1.0, v97
	v_rcp_f32_e32 v97, v97
	s_nop 0
	v_pk_mul_f32 v[102:103], v[102:103], v[96:97]
	v_mul_f32_e32 v96, 0xbfb8aa3b, v99
	v_exp_f32_e32 v96, v96
	v_cvt_pk_bf16_f32 v97, v102, v103
	v_add_f32_e32 v96, 1.0, v96
	v_rcp_f32_e32 v107, v96
	v_cvt_pk_bf16_f32 v96, v100, v101
	v_add_u32_e32 v100, 0x80, v166
	v_ashrrev_i32_e32 v101, 31, v100
	v_pk_mul_f32 v[106:107], v[98:99], v[106:107]
	v_cvt_pk_bf16_f32 v98, v104, v105
	v_cvt_pk_bf16_f32 v99, v106, v107
	flat_store_dwordx4 v[108:109], v[96:99] offset:256 sc1
	s_nop 1
	v_lshlrev_b64 v[96:97], 6, v[100:101]
	v_lshl_add_u64 v[96:97], v[160:161], 0, v[96:97]
	flat_load_dwordx4 v[96:99], v[96:97]
	s_waitcnt vmcnt(0) lgkmcnt(0)
; __device__ __forceinline__ v4u pack8(const f32x4 a, const f32x4 b) { v4u w; w.x = cvt_pk_bf16(a[0], a[1]); w.y = cvt_pk_bf16(a[2], a[3]); w.z = cvt_pk_bf16(b[0], b[1]); w.w = cvt_pk_bf16(b[2], b[3]); return w; }
; __device__ __forceinline__ float silu_f(float x) { return x * __builtin_amdgcn_rcpf(1.f + __expf(-x)); }
;     __device__ __forceinline__ void operator()(const f32x4 (&acc)[2][2][4][2], const pg8::Unit& u, int wr, int wc, int fr, int fq) const {
;     ...
;         if (grp == 0) { WIN_LOOP( _Pragma("unroll") for (int i = 0; i < 4; ++i) { a[i] = silu_f(a[i]); b[i] = silu_f(b[i]); } *(v4u*)(QO + (size_t)row * DM + c) = pack8(a, b); ) }
	v_mov_b32_e32 v102, v97
	v_mov_b32_e32 v103, v98
	v_mov_b32_e32 v97, v99
	v_pk_add_f32 v[96:97], v[102:103], v[96:97]
	s_nop 0
	v_add_f32_e32 v96, v96, v97
	ds_bpermute_b32 v97, v128, v96
	s_waitcnt lgkmcnt(0)
	v_add_f32_e32 v96, v96, v97
	ds_bpermute_b32 v97, v129, v96
	s_waitcnt lgkmcnt(0)
	v_add_f32_e32 v96, v96, v97
	v_fmamk_f32 v96, v96, 0x3a800000, v212
	v_rsq_f32_e32 v102, v96
	v_lshlrev_b64 v[96:97], 11, v[100:101]
	v_lshl_add_u64 v[100:101], s[44:45], 0, v[96:97]
	v_lshl_add_u64 v[100:101], v[100:101], 0, v[192:193]
	v_pk_mul_f32 v[98:99], v[28:29], v[102:103] op_sel_hi:[1,0]
	v_pk_mul_f32 v[96:97], v[30:31], v[102:103] op_sel_hi:[1,0]
	v_pk_mul_f32 v[104:105], v[26:27], v[102:103] op_sel_hi:[1,0]
	v_pk_mul_f32 v[106:107], v[24:25], v[102:103] op_sel_hi:[1,0]
	v_mul_f32_e32 v103, 0xbfb8aa3b, v98
	v_exp_f32_e32 v103, v103
	s_nop 0
	v_add_f32_e32 v103, 1.0, v103
	v_rcp_f32_e32 v108, v103
	v_mul_f32_e32 v103, 0xbfb8aa3b, v106
	v_exp_f32_e32 v103, v103
	s_nop 0
	v_add_f32_e32 v103, 1.0, v103
	v_rcp_f32_e32 v110, v103
	v_mul_f32_e32 v103, 0xbfb8aa3b, v99
	v_exp_f32_e32 v103, v103
	s_nop 0
	v_add_f32_e32 v103, 1.0, v103
	v_rcp_f32_e32 v109, v103
	v_mul_f32_e32 v103, 0xbfb8aa3b, v107
	v_exp_f32_e32 v103, v103
	v_pk_mul_f32 v[98:99], v[98:99], v[108:109]
	v_add_f32_e32 v103, 1.0, v103
	v_rcp_f32_e32 v111, v103
	v_mul_f32_e32 v103, 0xbfb8aa3b, v96
	v_exp_f32_e32 v103, v103
	v_pk_mul_f32 v[106:107], v[106:107], v[110:111]
	v_add_f32_e32 v103, 1.0, v103
	v_rcp_f32_e32 v108, v103
	v_mul_f32_e32 v103, 0xbfb8aa3b, v104
	v_exp_f32_e32 v103, v103
	s_nop 0
	v_add_f32_e32 v103, 1.0, v103
	v_rcp_f32_e32 v110, v103
	v_mul_f32_e32 v103, 0xbfb8aa3b, v97
	v_exp_f32_e32 v103, v103
	s_nop 0
	v_add_f32_e32 v103, 1.0, v103
	v_rcp_f32_e32 v109, v103
	v_pk_mul_f32 v[88:89], v[88:89], v[102:103] op_sel_hi:[1,0]
	v_pk_mul_f32 v[92:93], v[92:93], v[102:103] op_sel_hi:[1,0]
	v_pk_mul_f32 v[90:91], v[90:91], v[102:103] op_sel_hi:[1,0]
	v_pk_mul_f32 v[108:109], v[96:97], v[108:109]
	v_mul_f32_e32 v96, 0xbfb8aa3b, v105
	v_exp_f32_e32 v96, v96
	v_cvt_pk_bf16_f32 v97, v108, v109
	v_pk_mul_f32 v[94:95], v[94:95], v[102:103] op_sel_hi:[1,0]
	v_add_f32_e32 v96, 1.0, v96
	v_rcp_f32_e32 v111, v96
	v_cvt_pk_bf16_f32 v96, v98, v99
	v_cvt_pk_bf16_f32 v98, v106, v107
	v_pk_mul_f32 v[104:105], v[104:105], v[110:111]
	s_nop 0
	v_cvt_pk_bf16_f32 v99, v104, v105
	flat_store_dwordx4 v[100:101], v[96:99] sc1
	s_nop 1
	v_mul_f32_e32 v97, 0xbfb8aa3b, v88
	v_exp_f32_e32 v97, v97
	v_mul_f32_e32 v96, 0xbfb8aa3b, v92
	v_exp_f32_e32 v96, v96
	v_add_f32_e32 v97, 1.0, v97
	v_rcp_f32_e32 v98, v97
	v_mul_f32_e32 v97, 0xbfb8aa3b, v93
	v_exp_f32_e32 v97, v97
	v_add_f32_e32 v96, 1.0, v96
	v_rcp_f32_e32 v96, v96
	v_add_f32_e32 v97, 1.0, v97
	v_rcp_f32_e32 v97, v97
	s_nop 0
	v_pk_mul_f32 v[92:93], v[92:93], v[96:97]
	v_mul_f32_e32 v96, 0xbfb8aa3b, v89
	v_exp_f32_e32 v96, v96
	s_nop 0
	v_add_f32_e32 v96, 1.0, v96
	v_rcp_f32_e32 v99, v96
	s_nop 0
	v_pk_mul_f32 v[96:97], v[88:89], v[98:99]
	v_mul_f32_e32 v89, 0xbfb8aa3b, v90
	v_exp_f32_e32 v89, v89
	v_mul_f32_e32 v88, 0xbfb8aa3b, v94
	v_exp_f32_e32 v88, v88
	v_add_f32_e32 v89, 1.0, v89
	v_rcp_f32_e32 v98, v89
	v_mul_f32_e32 v89, 0xbfb8aa3b, v95
	v_exp_f32_e32 v89, v89
	v_add_f32_e32 v88, 1.0, v88
	v_rcp_f32_e32 v88, v88
	v_add_f32_e32 v89, 1.0, v89
	v_rcp_f32_e32 v89, v89
	s_nop 0
	v_pk_mul_f32 v[94:95], v[94:95], v[88:89]
	v_mul_f32_e32 v88, 0xbfb8aa3b, v91
	v_exp_f32_e32 v88, v88
	v_cvt_pk_bf16_f32 v89, v94, v95
	v_add_f32_e32 v88, 1.0, v88
	v_rcp_f32_e32 v99, v88
	v_cvt_pk_bf16_f32 v88, v92, v93
	v_add_u32_e32 v92, 0x90, v166
	v_ashrrev_i32_e32 v93, 31, v92
	v_pk_mul_f32 v[98:99], v[90:91], v[98:99]
	v_cvt_pk_bf16_f32 v90, v96, v97
	v_cvt_pk_bf16_f32 v91, v98, v99
	flat_store_dwordx4 v[100:101], v[88:91] offset:256 sc1
	s_nop 1
	v_lshlrev_b64 v[88:89], 6, v[92:93]
	v_lshl_add_u64 v[88:89], v[160:161], 0, v[88:89]
	flat_load_dwordx4 v[88:91], v[88:89]
	s_waitcnt vmcnt(0) lgkmcnt(0)
	v_mov_b32_e32 v94, v89
	v_mov_b32_e32 v95, v90
	v_mov_b32_e32 v89, v91
	v_pk_add_f32 v[88:89], v[94:95], v[88:89]
	s_nop 0
	v_add_f32_e32 v88, v88, v89
	ds_bpermute_b32 v89, v128, v88
	s_waitcnt lgkmcnt(0)
	v_add_f32_e32 v88, v88, v89
	ds_bpermute_b32 v89, v129, v88
	s_waitcnt lgkmcnt(0)
; __device__ __forceinline__ v4u pack8(const f32x4 a, const f32x4 b) { v4u w; w.x = cvt_pk_bf16(a[0], a[1]); w.y = cvt_pk_bf16(a[2], a[3]); w.z = cvt_pk_bf16(b[0], b[1]); w.w = cvt_pk_bf16(b[2], b[3]); return w; }
; __device__ __forceinline__ float silu_f(float x) { return x * __builtin_amdgcn_rcpf(1.f + __expf(-x)); }
;     __device__ __forceinline__ void operator()(const f32x4 (&acc)[2][2][4][2], const pg8::Unit& u, int wr, int wc, int fr, int fq) const {
;     ...
;         if (grp == 0) { WIN_LOOP( _Pragma("unroll") for (int i = 0; i < 4; ++i) { a[i] = silu_f(a[i]); b[i] = silu_f(b[i]); } *(v4u*)(QO + (size_t)row * DM + c) = pack8(a, b); ) }
	v_add_f32_e32 v88, v88, v89
	v_fmamk_f32 v88, v88, 0x3a800000, v212
	v_rsq_f32_e32 v94, v88
	v_lshlrev_b64 v[88:89], 11, v[92:93]
	v_lshl_add_u64 v[92:93], s[44:45], 0, v[88:89]
	v_lshl_add_u64 v[92:93], v[92:93], 0, v[192:193]
	v_pk_mul_f32 v[90:91], v[20:21], v[94:95] op_sel_hi:[1,0]
	v_pk_mul_f32 v[88:89], v[22:23], v[94:95] op_sel_hi:[1,0]
	v_pk_mul_f32 v[96:97], v[18:19], v[94:95] op_sel_hi:[1,0]
	v_pk_mul_f32 v[98:99], v[16:17], v[94:95] op_sel_hi:[1,0]
	v_mul_f32_e32 v95, 0xbfb8aa3b, v90
	v_exp_f32_e32 v95, v95
	s_nop 0
	v_add_f32_e32 v95, 1.0, v95
	v_rcp_f32_e32 v100, v95
	v_mul_f32_e32 v95, 0xbfb8aa3b, v98
	v_exp_f32_e32 v95, v95
	s_nop 0
	v_add_f32_e32 v95, 1.0, v95
	v_rcp_f32_e32 v102, v95
	v_mul_f32_e32 v95, 0xbfb8aa3b, v91
	v_exp_f32_e32 v95, v95
	s_nop 0
	v_add_f32_e32 v95, 1.0, v95
	v_rcp_f32_e32 v101, v95
	v_mul_f32_e32 v95, 0xbfb8aa3b, v99
	v_exp_f32_e32 v95, v95
	v_pk_mul_f32 v[90:91], v[90:91], v[100:101]
	v_add_f32_e32 v95, 1.0, v95
	v_rcp_f32_e32 v103, v95
	v_mul_f32_e32 v95, 0xbfb8aa3b, v88
	v_exp_f32_e32 v95, v95
	v_pk_mul_f32 v[98:99], v[98:99], v[102:103]
	v_add_f32_e32 v95, 1.0, v95
	v_rcp_f32_e32 v100, v95
	v_mul_f32_e32 v95, 0xbfb8aa3b, v96
	v_exp_f32_e32 v95, v95
	s_nop 0
	v_add_f32_e32 v95, 1.0, v95
	v_rcp_f32_e32 v102, v95
	v_mul_f32_e32 v95, 0xbfb8aa3b, v89
	v_exp_f32_e32 v95, v95
	s_nop 0
	v_add_f32_e32 v95, 1.0, v95
	v_rcp_f32_e32 v101, v95
	v_pk_mul_f32 v[80:81], v[80:81], v[94:95] op_sel_hi:[1,0]
	v_pk_mul_f32 v[84:85], v[84:85], v[94:95] op_sel_hi:[1,0]
	v_pk_mul_f32 v[82:83], v[82:83], v[94:95] op_sel_hi:[1,0]
	v_pk_mul_f32 v[100:101], v[88:89], v[100:101]
	v_mul_f32_e32 v88, 0xbfb8aa3b, v97
	v_exp_f32_e32 v88, v88
	v_cvt_pk_bf16_f32 v89, v100, v101
	v_pk_mul_f32 v[86:87], v[86:87], v[94:95] op_sel_hi:[1,0]
	v_add_f32_e32 v88, 1.0, v88
	v_rcp_f32_e32 v103, v88
	v_cvt_pk_bf16_f32 v88, v90, v91
	v_cvt_pk_bf16_f32 v90, v98, v99
	v_pk_mul_f32 v[96:97], v[96:97], v[102:103]
	s_nop 0
	v_cvt_pk_bf16_f32 v91, v96, v97
	flat_store_dwordx4 v[92:93], v[88:91] sc1
	s_nop 1
	v_mul_f32_e32 v89, 0xbfb8aa3b, v80
	v_exp_f32_e32 v89, v89
	v_mul_f32_e32 v88, 0xbfb8aa3b, v84
	v_exp_f32_e32 v88, v88
	v_add_f32_e32 v89, 1.0, v89
	v_rcp_f32_e32 v90, v89
	v_mul_f32_e32 v89, 0xbfb8aa3b, v85
	v_exp_f32_e32 v89, v89
	v_add_f32_e32 v88, 1.0, v88
	v_rcp_f32_e32 v88, v88
	v_add_f32_e32 v89, 1.0, v89
	v_rcp_f32_e32 v89, v89
	s_nop 0
	v_pk_mul_f32 v[84:85], v[84:85], v[88:89]
	v_mul_f32_e32 v88, 0xbfb8aa3b, v81
	v_exp_f32_e32 v88, v88
	s_nop 0
	v_add_f32_e32 v88, 1.0, v88
	v_rcp_f32_e32 v91, v88
	s_nop 0
	v_pk_mul_f32 v[88:89], v[80:81], v[90:91]
	v_mul_f32_e32 v81, 0xbfb8aa3b, v82
	v_exp_f32_e32 v81, v81
	v_mul_f32_e32 v80, 0xbfb8aa3b, v86
	v_exp_f32_e32 v80, v80
	v_add_f32_e32 v81, 1.0, v81
	v_rcp_f32_e32 v90, v81
	v_mul_f32_e32 v81, 0xbfb8aa3b, v87
	v_exp_f32_e32 v81, v81
	v_add_f32_e32 v80, 1.0, v80
	v_rcp_f32_e32 v80, v80
	v_add_f32_e32 v81, 1.0, v81
	v_rcp_f32_e32 v81, v81
	s_nop 0
	v_pk_mul_f32 v[86:87], v[86:87], v[80:81]
	v_mul_f32_e32 v80, 0xbfb8aa3b, v83
	v_exp_f32_e32 v80, v80
	v_cvt_pk_bf16_f32 v81, v86, v87
	v_add_f32_e32 v80, 1.0, v80
	v_rcp_f32_e32 v91, v80
	v_cvt_pk_bf16_f32 v80, v84, v85
	v_add_u32_e32 v84, 0xa0, v166
	v_ashrrev_i32_e32 v85, 31, v84
	v_pk_mul_f32 v[90:91], v[82:83], v[90:91]
	v_cvt_pk_bf16_f32 v82, v88, v89
	v_cvt_pk_bf16_f32 v83, v90, v91
	flat_store_dwordx4 v[92:93], v[80:83] offset:256 sc1
	s_nop 1
	v_lshlrev_b64 v[80:81], 6, v[84:85]
	v_lshl_add_u64 v[80:81], v[160:161], 0, v[80:81]
	flat_load_dwordx4 v[80:83], v[80:81]
	s_waitcnt vmcnt(0) lgkmcnt(0)
	v_mov_b32_e32 v86, v81
	v_mov_b32_e32 v87, v82
	v_mov_b32_e32 v81, v83
	v_pk_add_f32 v[80:81], v[86:87], v[80:81]
	s_nop 0
	v_add_f32_e32 v80, v80, v81
	ds_bpermute_b32 v81, v128, v80
	s_waitcnt lgkmcnt(0)
	v_add_f32_e32 v80, v80, v81
	ds_bpermute_b32 v81, v129, v80
	s_waitcnt lgkmcnt(0)
	v_add_f32_e32 v80, v80, v81
	v_fmamk_f32 v80, v80, 0x3a800000, v212
	v_rsq_f32_e32 v86, v80
	v_lshlrev_b64 v[80:81], 11, v[84:85]
	v_lshl_add_u64 v[84:85], s[44:45], 0, v[80:81]
	v_lshl_add_u64 v[84:85], v[84:85], 0, v[192:193]
	v_pk_mul_f32 v[82:83], v[12:13], v[86:87] op_sel_hi:[1,0]
	v_pk_mul_f32 v[80:81], v[14:15], v[86:87] op_sel_hi:[1,0]
	v_pk_mul_f32 v[88:89], v[10:11], v[86:87] op_sel_hi:[1,0]
	v_pk_mul_f32 v[90:91], v[8:9], v[86:87] op_sel_hi:[1,0]
	v_mul_f32_e32 v87, 0xbfb8aa3b, v82
	v_exp_f32_e32 v87, v87
	s_nop 0
	v_add_f32_e32 v87, 1.0, v87
	v_rcp_f32_e32 v92, v87
	v_mul_f32_e32 v87, 0xbfb8aa3b, v90
	v_exp_f32_e32 v87, v87
	s_nop 0
	v_add_f32_e32 v87, 1.0, v87
	v_rcp_f32_e32 v94, v87
	v_mul_f32_e32 v87, 0xbfb8aa3b, v83
	v_exp_f32_e32 v87, v87
	s_nop 0
	v_add_f32_e32 v87, 1.0, v87
	v_rcp_f32_e32 v93, v87
	v_mul_f32_e32 v87, 0xbfb8aa3b, v91
	v_exp_f32_e32 v87, v87
	v_pk_mul_f32 v[82:83], v[82:83], v[92:93]
	v_add_f32_e32 v87, 1.0, v87
	v_rcp_f32_e32 v95, v87
	v_mul_f32_e32 v87, 0xbfb8aa3b, v80
	v_exp_f32_e32 v87, v87
	v_pk_mul_f32 v[90:91], v[90:91], v[94:95]
	v_add_f32_e32 v87, 1.0, v87
	v_rcp_f32_e32 v92, v87
	v_mul_f32_e32 v87, 0xbfb8aa3b, v88
	v_exp_f32_e32 v87, v87
	s_nop 0
	v_add_f32_e32 v87, 1.0, v87
	v_rcp_f32_e32 v94, v87
	v_mul_f32_e32 v87, 0xbfb8aa3b, v81
	v_exp_f32_e32 v87, v87
	s_nop 0
	v_add_f32_e32 v87, 1.0, v87
	v_rcp_f32_e32 v93, v87
	v_pk_mul_f32 v[72:73], v[72:73], v[86:87] op_sel_hi:[1,0]
	v_pk_mul_f32 v[76:77], v[76:77], v[86:87] op_sel_hi:[1,0]
	v_pk_mul_f32 v[74:75], v[74:75], v[86:87] op_sel_hi:[1,0]
	v_pk_mul_f32 v[92:93], v[80:81], v[92:93]
	v_mul_f32_e32 v80, 0xbfb8aa3b, v89
; __device__ __forceinline__ v4u pack8(const f32x4 a, const f32x4 b) { v4u w; w.x = cvt_pk_bf16(a[0], a[1]); w.y = cvt_pk_bf16(a[2], a[3]); w.z = cvt_pk_bf16(b[0], b[1]); w.w = cvt_pk_bf16(b[2], b[3]); return w; }
; __device__ __forceinline__ float silu_f(float x) { return x * __builtin_amdgcn_rcpf(1.f + __expf(-x)); }
;     __device__ __forceinline__ void operator()(const f32x4 (&acc)[2][2][4][2], const pg8::Unit& u, int wr, int wc, int fr, int fq) const {
;     ...
;         if (grp == 0) { WIN_LOOP( _Pragma("unroll") for (int i = 0; i < 4; ++i) { a[i] = silu_f(a[i]); b[i] = silu_f(b[i]); } *(v4u*)(QO + (size_t)row * DM + c) = pack8(a, b); ) }
	v_exp_f32_e32 v80, v80
	v_cvt_pk_bf16_f32 v81, v92, v93
	v_pk_mul_f32 v[78:79], v[78:79], v[86:87] op_sel_hi:[1,0]
	v_add_f32_e32 v80, 1.0, v80
	v_rcp_f32_e32 v95, v80
	v_cvt_pk_bf16_f32 v80, v82, v83
	v_cvt_pk_bf16_f32 v82, v90, v91
	v_pk_mul_f32 v[88:89], v[88:89], v[94:95]
	s_nop 0
	v_cvt_pk_bf16_f32 v83, v88, v89
	flat_store_dwordx4 v[84:85], v[80:83] sc1
	s_nop 1
	v_mul_f32_e32 v81, 0xbfb8aa3b, v72
	v_exp_f32_e32 v81, v81
	v_mul_f32_e32 v80, 0xbfb8aa3b, v76
	v_exp_f32_e32 v80, v80
	v_add_f32_e32 v81, 1.0, v81
	v_rcp_f32_e32 v82, v81
	v_mul_f32_e32 v81, 0xbfb8aa3b, v77
	v_exp_f32_e32 v81, v81
	v_add_f32_e32 v80, 1.0, v80
	v_rcp_f32_e32 v80, v80
	v_add_f32_e32 v81, 1.0, v81
	v_rcp_f32_e32 v81, v81
	s_nop 0
	v_pk_mul_f32 v[76:77], v[76:77], v[80:81]
	v_mul_f32_e32 v80, 0xbfb8aa3b, v73
	v_exp_f32_e32 v80, v80
	s_nop 0
	v_add_f32_e32 v80, 1.0, v80
	v_rcp_f32_e32 v83, v80
	s_nop 0
	v_pk_mul_f32 v[80:81], v[72:73], v[82:83]
	v_mul_f32_e32 v73, 0xbfb8aa3b, v74
	v_exp_f32_e32 v73, v73
	v_mul_f32_e32 v72, 0xbfb8aa3b, v78
	v_exp_f32_e32 v72, v72
	v_add_f32_e32 v73, 1.0, v73
	v_rcp_f32_e32 v82, v73
	v_mul_f32_e32 v73, 0xbfb8aa3b, v79
	v_exp_f32_e32 v73, v73
	v_add_f32_e32 v72, 1.0, v72
	v_rcp_f32_e32 v72, v72
	v_add_f32_e32 v73, 1.0, v73
	v_rcp_f32_e32 v73, v73
	s_nop 0
	v_pk_mul_f32 v[78:79], v[78:79], v[72:73]
	v_mul_f32_e32 v72, 0xbfb8aa3b, v75
	v_exp_f32_e32 v72, v72
	v_cvt_pk_bf16_f32 v73, v78, v79
	v_add_f32_e32 v72, 1.0, v72
	v_rcp_f32_e32 v83, v72
	v_cvt_pk_bf16_f32 v72, v76, v77
	v_add_u32_e32 v76, 0xb0, v166
	v_ashrrev_i32_e32 v77, 31, v76
	v_pk_mul_f32 v[82:83], v[74:75], v[82:83]
	v_cvt_pk_bf16_f32 v74, v80, v81
	v_cvt_pk_bf16_f32 v75, v82, v83
	flat_store_dwordx4 v[84:85], v[72:75] offset:256 sc1
	s_nop 1
	v_lshlrev_b64 v[72:73], 6, v[76:77]
	v_lshl_add_u64 v[72:73], v[160:161], 0, v[72:73]
	flat_load_dwordx4 v[72:75], v[72:73]
	s_waitcnt vmcnt(0) lgkmcnt(0)
	v_mov_b32_e32 v78, v73
	v_mov_b32_e32 v79, v74
	v_mov_b32_e32 v73, v75
	v_pk_add_f32 v[72:73], v[78:79], v[72:73]
	s_nop 0
	v_add_f32_e32 v72, v72, v73
	ds_bpermute_b32 v73, v128, v72
	s_waitcnt lgkmcnt(0)
	v_add_f32_e32 v72, v72, v73
	ds_bpermute_b32 v73, v129, v72
	s_waitcnt lgkmcnt(0)
	v_add_f32_e32 v72, v72, v73
	v_fmamk_f32 v72, v72, 0x3a800000, v212
	v_rsq_f32_e32 v78, v72
	v_lshlrev_b64 v[72:73], 11, v[76:77]
	v_lshl_add_u64 v[76:77], s[44:45], 0, v[72:73]
	v_lshl_add_u64 v[76:77], v[76:77], 0, v[192:193]
	v_pk_mul_f32 v[74:75], v[4:5], v[78:79] op_sel_hi:[1,0]
	v_pk_mul_f32 v[72:73], v[6:7], v[78:79] op_sel_hi:[1,0]
	v_pk_mul_f32 v[80:81], v[2:3], v[78:79] op_sel_hi:[1,0]
	v_pk_mul_f32 v[82:83], v[0:1], v[78:79] op_sel_hi:[1,0]
	v_mul_f32_e32 v79, 0xbfb8aa3b, v74
	v_exp_f32_e32 v79, v79
	s_nop 0
	v_add_f32_e32 v79, 1.0, v79
	v_rcp_f32_e32 v84, v79
	v_mul_f32_e32 v79, 0xbfb8aa3b, v82
	v_exp_f32_e32 v79, v79
	s_nop 0
	v_add_f32_e32 v79, 1.0, v79
	v_rcp_f32_e32 v86, v79
	v_mul_f32_e32 v79, 0xbfb8aa3b, v75
	v_exp_f32_e32 v79, v79
	s_nop 0
	v_add_f32_e32 v79, 1.0, v79
	v_rcp_f32_e32 v85, v79
	v_mul_f32_e32 v79, 0xbfb8aa3b, v83
	v_exp_f32_e32 v79, v79
	v_pk_mul_f32 v[74:75], v[74:75], v[84:85]
	v_add_f32_e32 v79, 1.0, v79
	v_rcp_f32_e32 v87, v79
	v_mul_f32_e32 v79, 0xbfb8aa3b, v72
	v_exp_f32_e32 v79, v79
	v_pk_mul_f32 v[82:83], v[82:83], v[86:87]
	v_add_f32_e32 v79, 1.0, v79
	v_rcp_f32_e32 v84, v79
	v_mul_f32_e32 v79, 0xbfb8aa3b, v80
	v_exp_f32_e32 v79, v79
	s_nop 0
	v_add_f32_e32 v79, 1.0, v79
	v_rcp_f32_e32 v86, v79
	v_mul_f32_e32 v79, 0xbfb8aa3b, v73
	v_exp_f32_e32 v79, v79
	s_nop 0
	v_add_f32_e32 v79, 1.0, v79
	v_rcp_f32_e32 v85, v79
	v_pk_mul_f32 v[64:65], v[64:65], v[78:79] op_sel_hi:[1,0]
	v_pk_mul_f32 v[68:69], v[68:69], v[78:79] op_sel_hi:[1,0]
	v_pk_mul_f32 v[66:67], v[66:67], v[78:79] op_sel_hi:[1,0]
	v_pk_mul_f32 v[84:85], v[72:73], v[84:85]
	v_mul_f32_e32 v72, 0xbfb8aa3b, v81
	v_exp_f32_e32 v72, v72
	v_cvt_pk_bf16_f32 v73, v84, v85
	v_pk_mul_f32 v[70:71], v[70:71], v[78:79] op_sel_hi:[1,0]
	v_add_f32_e32 v72, 1.0, v72
	v_rcp_f32_e32 v87, v72
	v_cvt_pk_bf16_f32 v72, v74, v75
	v_cvt_pk_bf16_f32 v74, v82, v83
	v_pk_mul_f32 v[80:81], v[80:81], v[86:87]
	s_nop 0
	v_cvt_pk_bf16_f32 v75, v80, v81
	flat_store_dwordx4 v[76:77], v[72:75] sc1
	s_nop 1
	v_mul_f32_e32 v73, 0xbfb8aa3b, v64
	v_exp_f32_e32 v73, v73
	v_mul_f32_e32 v72, 0xbfb8aa3b, v68
	v_exp_f32_e32 v72, v72
	v_add_f32_e32 v73, 1.0, v73
	v_rcp_f32_e32 v74, v73
	v_mul_f32_e32 v73, 0xbfb8aa3b, v69
	v_exp_f32_e32 v73, v73
	v_add_f32_e32 v72, 1.0, v72
	v_rcp_f32_e32 v72, v72
	v_add_f32_e32 v73, 1.0, v73
	v_rcp_f32_e32 v73, v73
	s_nop 0
	v_pk_mul_f32 v[68:69], v[68:69], v[72:73]
	v_mul_f32_e32 v72, 0xbfb8aa3b, v65
	v_exp_f32_e32 v72, v72
	s_nop 0
	v_add_f32_e32 v72, 1.0, v72
	v_rcp_f32_e32 v75, v72
	s_nop 0
	v_pk_mul_f32 v[72:73], v[64:65], v[74:75]
	v_mul_f32_e32 v65, 0xbfb8aa3b, v66
	v_exp_f32_e32 v65, v65
	v_mul_f32_e32 v64, 0xbfb8aa3b, v70
	v_exp_f32_e32 v64, v64
	v_add_f32_e32 v65, 1.0, v65
	v_rcp_f32_e32 v74, v65
	v_mul_f32_e32 v65, 0xbfb8aa3b, v71
	v_exp_f32_e32 v65, v65
	v_add_f32_e32 v64, 1.0, v64
	v_rcp_f32_e32 v64, v64
	v_add_f32_e32 v65, 1.0, v65
	v_rcp_f32_e32 v65, v65
	s_nop 0
	v_pk_mul_f32 v[70:71], v[70:71], v[64:65]
	v_mul_f32_e32 v64, 0xbfb8aa3b, v67
	v_exp_f32_e32 v64, v64
	v_cvt_pk_bf16_f32 v65, v70, v71
	v_add_f32_e32 v64, 1.0, v64
	v_rcp_f32_e32 v75, v64
	v_cvt_pk_bf16_f32 v64, v68, v69
	v_pk_mul_f32 v[74:75], v[66:67], v[74:75]
	v_cvt_pk_bf16_f32 v66, v72, v73
	v_cvt_pk_bf16_f32 v67, v74, v75
	flat_store_dwordx4 v[76:77], v[64:67] offset:256 sc1

; __device__ __forceinline__ float logsig_f(float x) { return fminf(x, 0.f) - __logf(1.f + __expf(-fabsf(x))); }
;     __device__ __forceinline__ void operator()(const f32x4 (&acc)[2][2][4][2], const pg8::Unit& u, int wr, int wc, int fr, int fq) const {
;     ...
;         if (pn == 14) {
;             if (wc == 0 && fq == 0) {
;                 const f32x4 fb0 = *(const f32x4*)fbias, fb1 = *(const f32x4*)(fbias + 4);
; #pragma unroll
;                 for (int ai = 0; ai < 2; ++ai)
; #pragma unroll
;                     for (int m = 0; m < 4; ++m) {
;                         const int row = row0 + ai * 128 + m * 16;
;                         const f32x4 sv = *(const f32x4*)(ssq + (size_t)row * 16), sv1 = *(const f32x4*)(ssq + (size_t)row * 16 + 4), sv2 = *(const f32x4*)(ssq + (size_t)row * 16 + 8), sv3 = *(const f32x4*)(ssq + (size_t)row * 16 + 12);
;                         const float st = ((sv[0] + sv[1]) + (sv[2] + sv[3])) + ((sv1[0] + sv1[1]) + (sv1[2] + sv1[3])) + ((sv2[0] + sv2[1]) + (sv2[2] + sv2[3])) + ((sv3[0] + sv3[1]) + (sv3[2] + sv3[3]));
;                         const float rs = __builtin_amdgcn_rsqf(st * (1.f / DM) + EPS);
;                         f32x4 a = acc[ai][0][m][0] * rs, b = acc[ai][0][m][1] * rs;
; #pragma unroll
;                         for (int i = 0; i < 4; ++i) { a[i] = logsig_f(a[i] + fb0[i]) * LOG2E; b[i] = logsig_f(b[i] + fb1[i]) * LOG2E; }
;                         *(f32x4*)(FF + (size_t)row * 8) = a; *(f32x4*)(FF + (size_t)row * 8 + 4) = b;
;                         asm volatile("" ::: "memory");
;                     }
;             }
.LBB0_420:
	s_and_saveexec_b64 s[10:11], s[38:39]
	s_cbranch_execz .LBB0_422
	v_ashrrev_i32_e32 v167, 31, v166
	v_lshlrev_b64 v[72:73], 6, v[166:167]
	v_lshl_add_u64 v[84:85], s[82:83], 0, v[72:73]
	global_load_dwordx4 v[64:67], v193, s[34:35] offset:16
	global_load_dwordx4 v[68:71], v193, s[34:35]
	flat_load_dwordx4 v[72:75], v[84:85]
	flat_load_dwordx4 v[76:79], v[84:85] offset:16
	flat_load_dwordx4 v[80:83], v[84:85] offset:32
	s_nop 0
	flat_load_dwordx4 v[84:87], v[84:85] offset:48
	s_mov_b32 s2, 0x3fb8aa3b
	s_waitcnt vmcnt(0) lgkmcnt(0)
	v_mov_b32_e32 v88, v73
	v_mov_b32_e32 v89, v74
	v_mov_b32_e32 v73, v75
	v_mov_b32_e32 v74, v77
	v_mov_b32_e32 v75, v78
	v_mov_b32_e32 v77, v79
	v_pk_add_f32 v[72:73], v[88:89], v[72:73]
	v_pk_add_f32 v[74:75], v[74:75], v[76:77]
	v_pk_add_f32 v[72:73], v[72:73], v[72:73] op_sel:[0,1] op_sel_hi:[1,0]
	v_pk_add_f32 v[74:75], v[74:75], v[74:75] op_sel:[0,1] op_sel_hi:[1,0]
	v_add_f32_e32 v76, v80, v81
	v_add_f32_e32 v78, v82, v83
	v_mov_b32_e32 v73, v84
	v_mov_b32_e32 v75, v85
	v_mov_b32_e32 v77, v86
	v_mov_b32_e32 v79, v87
	v_pk_add_f32 v[72:73], v[72:73], v[74:75]
	v_pk_add_f32 v[74:75], v[76:77], v[78:79]
	s_nop 0
	v_pk_add_f32 v[72:73], v[72:73], v[74:75]
	s_nop 0
	v_add_f32_e32 v72, v72, v73
	v_fmamk_f32 v72, v72, 0x3a800000, v212
	v_rsq_f32_e32 v72, v72
	s_nop 0
	v_pk_mul_f32 v[60:61], v[60:61], v[72:73] op_sel_hi:[1,0]
	v_pk_mul_f32 v[74:75], v[62:63], v[72:73] op_sel_hi:[1,0]
	v_pk_mul_f32 v[58:59], v[58:59], v[72:73] op_sel_hi:[1,0]
	v_pk_mul_f32 v[72:73], v[56:57], v[72:73] op_sel_hi:[1,0]
	v_add_f32_e32 v57, v68, v60
	v_min_f32_e32 v56, 0, v57
	v_mul_f32_e64 v57, |v57|, s57
	v_exp_f32_e32 v57, v57
	v_add_f32_e32 v61, v69, v61
	v_add_f32_e32 v73, v65, v73
	v_add_f32_e32 v57, 1.0, v57
	v_cmp_gt_f32_e32 vcc, s97, v57
	s_nop 1
	v_cndmask_b32_e64 v60, 0, 32, vcc
	v_ldexp_f32 v57, v57, v60
	v_log_f32_e32 v57, v57
	s_nop 0
	v_mul_f32_e32 v60, 0x3f317217, v57
	v_fma_f32 v60, v57, s52, -v60
	v_fmac_f32_e32 v60, 0x3377d1cf, v57
	v_fmac_f32_e32 v60, 0x3f317217, v57
	v_cmp_lt_f32_e64 s[8:9], |v57|, s53
	s_nop 1
	v_cndmask_b32_e64 v57, v57, v60, s[8:9]
	v_cndmask_b32_e32 v60, 0, v216, vcc
	v_sub_f32_e32 v62, v57, v60
	v_add_f32_e32 v57, v64, v72
	v_min_f32_e32 v60, 0, v57
	v_mul_f32_e64 v57, |v57|, s57
	v_exp_f32_e32 v57, v57
	s_nop 0
	v_add_f32_e32 v57, 1.0, v57
	v_cmp_gt_f32_e32 vcc, s97, v57
	s_nop 1
	v_cndmask_b32_e64 v63, 0, 32, vcc
	v_ldexp_f32 v57, v57, v63
	v_log_f32_e32 v57, v57
	s_nop 0
	v_mul_f32_e32 v63, 0x3f317217, v57
	v_fma_f32 v63, v57, s52, -v63
	v_fmac_f32_e32 v63, 0x3377d1cf, v57
	v_fmac_f32_e32 v63, 0x3f317217, v57
	v_cmp_lt_f32_e64 s[8:9], |v57|, s53
	s_nop 1
	v_cndmask_b32_e64 v57, v57, v63, s[8:9]
	v_cndmask_b32_e32 v63, 0, v216, vcc
	v_sub_f32_e32 v72, v57, v63
	v_min_f32_e32 v57, 0, v61
	v_mul_f32_e64 v61, |v61|, s57
	v_exp_f32_e32 v61, v61
	s_nop 0
	v_add_f32_e32 v61, 1.0, v61
	v_cmp_gt_f32_e32 vcc, s97, v61
	s_nop 1
	v_cndmask_b32_e64 v63, 0, 32, vcc
	v_ldexp_f32 v61, v61, v63
	v_log_f32_e32 v61, v61
	s_nop 0
	v_mul_f32_e32 v63, 0x3f317217, v61
	v_fma_f32 v63, v61, s52, -v63
	v_fmac_f32_e32 v63, 0x3377d1cf, v61
	v_fmac_f32_e32 v63, 0x3f317217, v61
	v_cmp_lt_f32_e64 s[8:9], |v61|, s53
	s_nop 1
	v_cndmask_b32_e64 v61, v61, v63, s[8:9]
	v_cndmask_b32_e32 v63, 0, v216, vcc
	v_sub_f32_e32 v63, v61, v63
	v_min_f32_e32 v61, 0, v73
	v_mul_f32_e64 v73, |v73|, s57
	v_exp_f32_e32 v73, v73
	v_pk_add_f32 v[56:57], v[56:57], v[62:63] neg_lo:[0,1] neg_hi:[0,1]
	v_add_f32_e32 v73, 1.0, v73
	v_cmp_gt_f32_e32 vcc, s97, v73
	s_nop 1
	v_cndmask_b32_e64 v76, 0, 32, vcc
	v_ldexp_f32 v73, v73, v76
	v_log_f32_e32 v73, v73
	s_nop 0
	v_mul_f32_e32 v76, 0x3f317217, v73
	v_fma_f32 v76, v73, s52, -v76
	v_fmac_f32_e32 v76, 0x3377d1cf, v73
	v_fmac_f32_e32 v76, 0x3f317217, v73
	v_cmp_lt_f32_e64 s[8:9], |v73|, s53
	s_nop 1
	v_cndmask_b32_e64 v73, v73, v76, s[8:9]
	v_cndmask_b32_e32 v76, 0, v216, vcc
	v_sub_f32_e32 v73, v73, v76
	v_add_f32_e32 v76, v70, v74
	v_min_f32_e32 v74, 0, v76
	v_mul_f32_e64 v76, |v76|, s57
	v_exp_f32_e32 v76, v76
	s_nop 0
	v_add_f32_e32 v76, 1.0, v76
	v_cmp_gt_f32_e32 vcc, s97, v76
	s_nop 1
	v_cndmask_b32_e64 v77, 0, 32, vcc
	v_ldexp_f32 v76, v76, v77
	v_log_f32_e32 v76, v76
	s_nop 0
	v_mul_f32_e32 v77, 0x3f317217, v76
	v_fma_f32 v77, v76, s52, -v77
	v_fmac_f32_e32 v77, 0x3377d1cf, v76
	v_fmac_f32_e32 v77, 0x3f317217, v76
	v_cmp_lt_f32_e64 s[8:9], |v76|, s53
	s_nop 1
	v_cndmask_b32_e64 v76, v76, v77, s[8:9]
	v_cndmask_b32_e32 v77, 0, v216, vcc
	v_sub_f32_e32 v76, v76, v77
	v_add_f32_e32 v77, v66, v58
	v_min_f32_e32 v58, 0, v77
	v_mul_f32_e64 v77, |v77|, s57
	v_exp_f32_e32 v77, v77
	s_nop 0
	v_add_f32_e32 v77, 1.0, v77
	v_cmp_gt_f32_e32 vcc, s97, v77
	s_nop 1
	v_cndmask_b32_e64 v78, 0, 32, vcc
	v_ldexp_f32 v77, v77, v78
	v_log_f32_e32 v77, v77
	s_nop 0
	v_mul_f32_e32 v78, 0x3f317217, v77
	v_fma_f32 v78, v77, s52, -v78
	v_fmac_f32_e32 v78, 0x3377d1cf, v77
	v_fmac_f32_e32 v78, 0x3f317217, v77
	v_cmp_lt_f32_e64 s[8:9], |v77|, s53
	s_nop 1
	v_cndmask_b32_e64 v77, v77, v78, s[8:9]
	v_cndmask_b32_e32 v78, 0, v216, vcc
	v_sub_f32_e32 v78, v77, v78
	v_add_f32_e32 v77, v71, v75
	v_min_f32_e32 v75, 0, v77
	v_mul_f32_e64 v77, |v77|, s57
	v_exp_f32_e32 v77, v77
	s_nop 0
	v_add_f32_e32 v77, 1.0, v77
	v_cmp_gt_f32_e32 vcc, s97, v77
	s_nop 1
	v_cndmask_b32_e64 v79, 0, 32, vcc
	v_ldexp_f32 v77, v77, v79
	v_log_f32_e32 v77, v77
	s_nop 0
	v_mul_f32_e32 v79, 0x3f317217, v77
	v_fma_f32 v79, v77, s52, -v79
	v_fmac_f32_e32 v79, 0x3377d1cf, v77
	v_fmac_f32_e32 v79, 0x3f317217, v77
	v_cmp_lt_f32_e64 s[8:9], |v77|, s53
	s_nop 1
	v_cndmask_b32_e64 v77, v77, v79, s[8:9]
	v_cndmask_b32_e32 v79, 0, v216, vcc
; __device__ __forceinline__ float logsig_f(float x) { return fminf(x, 0.f) - __logf(1.f + __expf(-fabsf(x))); }
;     __device__ __forceinline__ void operator()(const f32x4 (&acc)[2][2][4][2], const pg8::Unit& u, int wr, int wc, int fr, int fq) const {
;     ...
;         if (pn == 14) {
;             if (wc == 0 && fq == 0) {
;                 const f32x4 fb0 = *(const f32x4*)fbias, fb1 = *(const f32x4*)(fbias + 4);
; #pragma unroll
;                 for (int ai = 0; ai < 2; ++ai)
; #pragma unroll
;                     for (int m = 0; m < 4; ++m) {
;                         const int row = row0 + ai * 128 + m * 16;
;                         const f32x4 sv = *(const f32x4*)(ssq + (size_t)row * 16), sv1 = *(const f32x4*)(ssq + (size_t)row * 16 + 4), sv2 = *(const f32x4*)(ssq + (size_t)row * 16 + 8), sv3 = *(const f32x4*)(ssq + (size_t)row * 16 + 12);
;                         const float st = ((sv[0] + sv[1]) + (sv[2] + sv[3])) + ((sv1[0] + sv1[1]) + (sv1[2] + sv1[3])) + ((sv2[0] + sv2[1]) + (sv2[2] + sv2[3])) + ((sv3[0] + sv3[1]) + (sv3[2] + sv3[3]));
;                         const float rs = __builtin_amdgcn_rsqf(st * (1.f / DM) + EPS);
;                         f32x4 a = acc[ai][0][m][0] * rs, b = acc[ai][0][m][1] * rs;
; #pragma unroll
;                         for (int i = 0; i < 4; ++i) { a[i] = logsig_f(a[i] + fb0[i]) * LOG2E; b[i] = logsig_f(b[i] + fb1[i]) * LOG2E; }
;                         *(f32x4*)(FF + (size_t)row * 8) = a; *(f32x4*)(FF + (size_t)row * 8 + 4) = b;
;                         asm volatile("" ::: "memory");
;                     }
;             }
	v_sub_f32_e32 v77, v77, v79
	v_pk_add_f32 v[62:63], v[74:75], v[76:77] neg_lo:[0,1] neg_hi:[0,1]
	v_pk_mul_f32 v[74:75], v[56:57], s[2:3] op_sel_hi:[1,0]
	v_add_f32_e32 v56, v67, v59
	v_min_f32_e32 v59, 0, v56
	v_mul_f32_e64 v56, |v56|, s57
	v_exp_f32_e32 v56, v56
	v_pk_mul_f32 v[76:77], v[62:63], s[2:3] op_sel_hi:[1,0]
	v_add_f32_e32 v56, 1.0, v56
	v_cmp_gt_f32_e32 vcc, s97, v56
	s_nop 1
	v_cndmask_b32_e64 v57, 0, 32, vcc
	v_ldexp_f32 v56, v56, v57
	v_log_f32_e32 v56, v56
	s_nop 0
	v_mul_f32_e32 v57, 0x3f317217, v56
	v_fma_f32 v57, v56, s52, -v57
	v_fmac_f32_e32 v57, 0x3377d1cf, v56
	v_fmac_f32_e32 v57, 0x3f317217, v56
	v_cmp_lt_f32_e64 s[8:9], |v56|, s53
	s_nop 1
	v_cndmask_b32_e64 v56, v56, v57, s[8:9]
	v_cndmask_b32_e32 v57, 0, v216, vcc
	v_sub_f32_e32 v79, v56, v57
	v_pk_add_f32 v[56:57], v[60:61], v[72:73] neg_lo:[0,1] neg_hi:[0,1]
	v_lshlrev_b64 v[60:61], 5, v[166:167]
	v_pk_add_f32 v[58:59], v[58:59], v[78:79] neg_lo:[0,1] neg_hi:[0,1]
	v_pk_mul_f32 v[56:57], v[56:57], s[2:3] op_sel_hi:[1,0]
	v_lshl_add_u64 v[60:61], s[42:43], 0, v[60:61]
	v_pk_mul_f32 v[58:59], v[58:59], s[2:3] op_sel_hi:[1,0]
	flat_store_dwordx4 v[60:61], v[74:77] sc1
	flat_store_dwordx4 v[60:61], v[56:59] offset:16 sc1
	s_nop 1
	v_or_b32_e32 v56, 16, v166
	v_ashrrev_i32_e32 v57, 31, v56
	v_lshlrev_b64 v[58:59], 6, v[56:57]
	v_lshl_add_u64 v[62:63], s[82:83], 0, v[58:59]
	flat_load_dwordx4 v[58:61], v[62:63]
	flat_load_dwordx4 v[72:75], v[62:63] offset:16
	flat_load_dwordx4 v[76:79], v[62:63] offset:32
	flat_load_dwordx4 v[80:83], v[62:63] offset:48
	s_waitcnt vmcnt(0) lgkmcnt(0)
	v_mov_b32_e32 v62, v59
	v_mov_b32_e32 v63, v60
	v_mov_b32_e32 v59, v61
	v_mov_b32_e32 v60, v73
	v_mov_b32_e32 v61, v74
	v_mov_b32_e32 v73, v75
	v_pk_add_f32 v[58:59], v[62:63], v[58:59]
	v_pk_add_f32 v[60:61], v[60:61], v[72:73]
	v_pk_add_f32 v[58:59], v[58:59], v[58:59] op_sel:[0,1] op_sel_hi:[1,0]
	v_pk_add_f32 v[60:61], v[60:61], v[60:61] op_sel:[0,1] op_sel_hi:[1,0]
	v_add_f32_e32 v62, v76, v77
	v_add_f32_e32 v72, v78, v79
	v_mov_b32_e32 v59, v80
	v_mov_b32_e32 v61, v81
	v_mov_b32_e32 v63, v82
	v_mov_b32_e32 v73, v83
	v_pk_add_f32 v[58:59], v[58:59], v[60:61]
	v_pk_add_f32 v[60:61], v[62:63], v[72:73]
	s_nop 0
	v_pk_add_f32 v[58:59], v[58:59], v[60:61]
	s_nop 0
	v_add_f32_e32 v58, v58, v59
	v_fmamk_f32 v58, v58, 0x3a800000, v212
	v_rsq_f32_e32 v60, v58
	s_nop 0
	v_pk_mul_f32 v[52:53], v[52:53], v[60:61] op_sel_hi:[1,0]
	v_pk_mul_f32 v[58:59], v[54:55], v[60:61] op_sel_hi:[1,0]
	v_add_f32_e32 v54, v68, v52
	v_min_f32_e32 v52, 0, v54
	v_mul_f32_e64 v54, |v54|, s57
	v_exp_f32_e32 v54, v54
	v_pk_mul_f32 v[48:49], v[48:49], v[60:61] op_sel_hi:[1,0]
	v_pk_mul_f32 v[50:51], v[50:51], v[60:61] op_sel_hi:[1,0]
	v_add_f32_e32 v54, 1.0, v54
	v_cmp_gt_f32_e32 vcc, s97, v54
	s_nop 1
	v_cndmask_b32_e64 v55, 0, 32, vcc
	v_ldexp_f32 v54, v54, v55
	v_log_f32_e32 v54, v54
	s_nop 0
	v_mul_f32_e32 v55, 0x3f317217, v54
	v_fma_f32 v55, v54, s52, -v55
	v_fmac_f32_e32 v55, 0x3377d1cf, v54
	v_fmac_f32_e32 v55, 0x3f317217, v54
	v_cmp_lt_f32_e64 s[8:9], |v54|, s53
	s_nop 1
	v_cndmask_b32_e64 v54, v54, v55, s[8:9]
	v_cndmask_b32_e32 v55, 0, v216, vcc
	v_sub_f32_e32 v60, v54, v55
	v_add_f32_e32 v54, v64, v48
	v_min_f32_e32 v48, 0, v54
	v_mul_f32_e64 v54, |v54|, s57
	v_exp_f32_e32 v54, v54
	s_nop 0
	v_add_f32_e32 v54, 1.0, v54
	v_cmp_gt_f32_e32 vcc, s97, v54
	s_nop 1
	v_cndmask_b32_e64 v55, 0, 32, vcc
	v_ldexp_f32 v54, v54, v55
	v_log_f32_e32 v54, v54
	s_nop 0
	v_mul_f32_e32 v55, 0x3f317217, v54
	v_fma_f32 v55, v54, s52, -v55
	v_fmac_f32_e32 v55, 0x3377d1cf, v54
	v_fmac_f32_e32 v55, 0x3f317217, v54
	v_cmp_lt_f32_e64 s[8:9], |v54|, s53
	s_nop 1
	v_cndmask_b32_e64 v54, v54, v55, s[8:9]
	v_cndmask_b32_e32 v55, 0, v216, vcc
	v_sub_f32_e32 v54, v54, v55
	v_add_f32_e32 v55, v69, v53
	v_min_f32_e32 v53, 0, v55
	v_mul_f32_e64 v55, |v55|, s57
	v_exp_f32_e32 v55, v55
	s_nop 0
	v_add_f32_e32 v55, 1.0, v55
	v_cmp_gt_f32_e32 vcc, s97, v55
	s_nop 1
	v_cndmask_b32_e64 v61, 0, 32, vcc
	v_ldexp_f32 v55, v55, v61
	v_log_f32_e32 v55, v55
	s_nop 0
	v_mul_f32_e32 v61, 0x3f317217, v55
	v_fma_f32 v61, v55, s52, -v61
	v_fmac_f32_e32 v61, 0x3377d1cf, v55
	v_fmac_f32_e32 v61, 0x3f317217, v55
	v_cmp_lt_f32_e64 s[8:9], |v55|, s53
	s_nop 1
	v_cndmask_b32_e64 v55, v55, v61, s[8:9]
	v_cndmask_b32_e32 v61, 0, v216, vcc
	v_sub_f32_e32 v61, v55, v61
	v_add_f32_e32 v55, v65, v49
	v_min_f32_e32 v49, 0, v55
	v_mul_f32_e64 v55, |v55|, s57
	v_exp_f32_e32 v55, v55
	v_pk_add_f32 v[52:53], v[52:53], v[60:61] neg_lo:[0,1] neg_hi:[0,1]
	v_add_f32_e32 v55, 1.0, v55
	v_cmp_gt_f32_e32 vcc, s97, v55
	s_nop 1
	v_cndmask_b32_e64 v62, 0, 32, vcc
	v_ldexp_f32 v55, v55, v62
	v_log_f32_e32 v55, v55
	s_nop 0
	v_mul_f32_e32 v62, 0x3f317217, v55
	v_fma_f32 v62, v55, s52, -v62
	v_fmac_f32_e32 v62, 0x3377d1cf, v55
	v_fmac_f32_e32 v62, 0x3f317217, v55
	v_cmp_lt_f32_e64 s[8:9], |v55|, s53
	s_nop 1
	v_cndmask_b32_e64 v55, v55, v62, s[8:9]
	v_cndmask_b32_e32 v62, 0, v216, vcc
	v_sub_f32_e32 v55, v55, v62
	v_add_f32_e32 v62, v70, v58
	v_min_f32_e32 v58, 0, v62
	v_mul_f32_e64 v62, |v62|, s57
	v_exp_f32_e32 v62, v62
	v_pk_add_f32 v[48:49], v[48:49], v[54:55] neg_lo:[0,1] neg_hi:[0,1]
	v_add_f32_e32 v62, 1.0, v62
	v_cmp_gt_f32_e32 vcc, s97, v62
	v_pk_mul_f32 v[48:49], v[48:49], s[2:3] op_sel_hi:[1,0]
	s_nop 0
	v_cndmask_b32_e64 v63, 0, 32, vcc
	v_ldexp_f32 v62, v62, v63
	v_log_f32_e32 v62, v62
	s_nop 0
	v_mul_f32_e32 v63, 0x3f317217, v62
	v_fma_f32 v63, v62, s52, -v63
	v_fmac_f32_e32 v63, 0x3377d1cf, v62
	v_fmac_f32_e32 v63, 0x3f317217, v62
	v_cmp_lt_f32_e64 s[8:9], |v62|, s53
	s_nop 1
	v_cndmask_b32_e64 v62, v62, v63, s[8:9]
	v_cndmask_b32_e32 v63, 0, v216, vcc
; __device__ __forceinline__ float logsig_f(float x) { return fminf(x, 0.f) - __logf(1.f + __expf(-fabsf(x))); }
;     __device__ __forceinline__ void operator()(const f32x4 (&acc)[2][2][4][2], const pg8::Unit& u, int wr, int wc, int fr, int fq) const {
;     ...
;         if (pn == 14) {
;             if (wc == 0 && fq == 0) {
;                 const f32x4 fb0 = *(const f32x4*)fbias, fb1 = *(const f32x4*)(fbias + 4);
; #pragma unroll
;                 for (int ai = 0; ai < 2; ++ai)
; #pragma unroll
;                     for (int m = 0; m < 4; ++m) {
;                         const int row = row0 + ai * 128 + m * 16;
;                         const f32x4 sv = *(const f32x4*)(ssq + (size_t)row * 16), sv1 = *(const f32x4*)(ssq + (size_t)row * 16 + 4), sv2 = *(const f32x4*)(ssq + (size_t)row * 16 + 8), sv3 = *(const f32x4*)(ssq + (size_t)row * 16 + 12);
;                         const float st = ((sv[0] + sv[1]) + (sv[2] + sv[3])) + ((sv1[0] + sv1[1]) + (sv1[2] + sv1[3])) + ((sv2[0] + sv2[1]) + (sv2[2] + sv2[3])) + ((sv3[0] + sv3[1]) + (sv3[2] + sv3[3]));
;                         const float rs = __builtin_amdgcn_rsqf(st * (1.f / DM) + EPS);
;                         f32x4 a = acc[ai][0][m][0] * rs, b = acc[ai][0][m][1] * rs;
; #pragma unroll
;                         for (int i = 0; i < 4; ++i) { a[i] = logsig_f(a[i] + fb0[i]) * LOG2E; b[i] = logsig_f(b[i] + fb1[i]) * LOG2E; }
;                         *(f32x4*)(FF + (size_t)row * 8) = a; *(f32x4*)(FF + (size_t)row * 8 + 4) = b;
;                         asm volatile("" ::: "memory");
;                     }
;             }
	v_sub_f32_e32 v62, v62, v63
	v_add_f32_e32 v63, v66, v50
	v_min_f32_e32 v50, 0, v63
	v_mul_f32_e64 v63, |v63|, s57
	v_exp_f32_e32 v63, v63
	s_nop 0
	v_add_f32_e32 v63, 1.0, v63
	v_cmp_gt_f32_e32 vcc, s97, v63
	s_nop 1
	v_cndmask_b32_e64 v72, 0, 32, vcc
	v_ldexp_f32 v63, v63, v72
	v_log_f32_e32 v63, v63
	s_nop 0
	v_mul_f32_e32 v72, 0x3f317217, v63
	v_fma_f32 v72, v63, s52, -v72
	v_fmac_f32_e32 v72, 0x3377d1cf, v63
	v_fmac_f32_e32 v72, 0x3f317217, v63
	v_cmp_lt_f32_e64 s[8:9], |v63|, s53
	s_nop 1
	v_cndmask_b32_e64 v63, v63, v72, s[8:9]
	v_cndmask_b32_e32 v72, 0, v216, vcc
	v_sub_f32_e32 v72, v63, v72
	v_add_f32_e32 v63, v71, v59
	v_min_f32_e32 v59, 0, v63
	v_mul_f32_e64 v63, |v63|, s57
	v_exp_f32_e32 v63, v63
	s_nop 0
	v_add_f32_e32 v63, 1.0, v63
	v_cmp_gt_f32_e32 vcc, s97, v63
	s_nop 1
	v_cndmask_b32_e64 v73, 0, 32, vcc
	v_ldexp_f32 v63, v63, v73
	v_log_f32_e32 v63, v63
	s_nop 0
	v_mul_f32_e32 v73, 0x3f317217, v63
	v_fma_f32 v73, v63, s52, -v73
	v_fmac_f32_e32 v73, 0x3377d1cf, v63
	v_fmac_f32_e32 v73, 0x3f317217, v63
	v_cmp_lt_f32_e64 s[8:9], |v63|, s53
	s_nop 1
	v_cndmask_b32_e64 v63, v63, v73, s[8:9]
	v_cndmask_b32_e32 v73, 0, v216, vcc
	v_sub_f32_e32 v63, v63, v73
	v_pk_add_f32 v[58:59], v[58:59], v[62:63] neg_lo:[0,1] neg_hi:[0,1]
	s_nop 0
	v_pk_mul_f32 v[60:61], v[58:59], s[2:3] op_sel_hi:[1,0]
	v_pk_mul_f32 v[58:59], v[52:53], s[2:3] op_sel_hi:[1,0]
	v_add_f32_e32 v52, v67, v51
	v_min_f32_e32 v51, 0, v52
	v_mul_f32_e64 v52, |v52|, s57
	v_exp_f32_e32 v52, v52
	s_nop 0
	v_add_f32_e32 v52, 1.0, v52
	v_cmp_gt_f32_e32 vcc, s97, v52
	s_nop 1
	v_cndmask_b32_e64 v53, 0, 32, vcc
	v_ldexp_f32 v52, v52, v53
	v_log_f32_e32 v52, v52
	s_nop 0
	v_mul_f32_e32 v53, 0x3f317217, v52
	v_fma_f32 v53, v52, s52, -v53
	v_fmac_f32_e32 v53, 0x3377d1cf, v52
	v_fmac_f32_e32 v53, 0x3f317217, v52
	v_cmp_lt_f32_e64 s[8:9], |v52|, s53
	s_nop 1
	v_cndmask_b32_e64 v52, v52, v53, s[8:9]
	v_cndmask_b32_e32 v53, 0, v216, vcc
	v_sub_f32_e32 v73, v52, v53
	v_lshlrev_b64 v[52:53], 5, v[56:57]
	v_pk_add_f32 v[50:51], v[50:51], v[72:73] neg_lo:[0,1] neg_hi:[0,1]
	v_lshl_add_u64 v[52:53], s[42:43], 0, v[52:53]
	v_pk_mul_f32 v[50:51], v[50:51], s[2:3] op_sel_hi:[1,0]
	flat_store_dwordx4 v[52:53], v[58:61] sc1
	flat_store_dwordx4 v[52:53], v[48:51] offset:16 sc1
	s_nop 1
	v_or_b32_e32 v48, 32, v166
	v_ashrrev_i32_e32 v49, 31, v48
	v_lshlrev_b64 v[50:51], 6, v[48:49]
	v_lshl_add_u64 v[62:63], s[82:83], 0, v[50:51]
	flat_load_dwordx4 v[50:53], v[62:63]
	flat_load_dwordx4 v[54:57], v[62:63] offset:16
	flat_load_dwordx4 v[58:61], v[62:63] offset:32
	flat_load_dwordx4 v[72:75], v[62:63] offset:48
	s_waitcnt vmcnt(0) lgkmcnt(0)
	v_mov_b32_e32 v62, v51
	v_mov_b32_e32 v63, v52
	v_mov_b32_e32 v51, v53
	v_mov_b32_e32 v52, v55
	v_mov_b32_e32 v53, v56
	v_mov_b32_e32 v55, v57
	v_pk_add_f32 v[50:51], v[62:63], v[50:51]
	v_pk_add_f32 v[52:53], v[52:53], v[54:55]
	v_pk_add_f32 v[50:51], v[50:51], v[50:51] op_sel:[0,1] op_sel_hi:[1,0]
	v_pk_add_f32 v[52:53], v[52:53], v[52:53] op_sel:[0,1] op_sel_hi:[1,0]
	v_add_f32_e32 v54, v58, v59
	v_add_f32_e32 v56, v60, v61
	v_mov_b32_e32 v51, v72
	v_mov_b32_e32 v53, v73
	v_mov_b32_e32 v55, v74
	v_mov_b32_e32 v57, v75
	v_pk_add_f32 v[50:51], v[50:51], v[52:53]
	v_pk_add_f32 v[52:53], v[54:55], v[56:57]
	s_nop 0
	v_pk_add_f32 v[50:51], v[50:51], v[52:53]
	s_nop 0
	v_add_f32_e32 v50, v50, v51
	v_fmamk_f32 v50, v50, 0x3a800000, v212
	v_rsq_f32_e32 v52, v50
	s_nop 0
	v_pk_mul_f32 v[44:45], v[44:45], v[52:53] op_sel_hi:[1,0]
	v_pk_mul_f32 v[50:51], v[46:47], v[52:53] op_sel_hi:[1,0]
	v_add_f32_e32 v46, v68, v44
	v_min_f32_e32 v44, 0, v46
	v_mul_f32_e64 v46, |v46|, s57
	v_exp_f32_e32 v46, v46
	v_pk_mul_f32 v[40:41], v[40:41], v[52:53] op_sel_hi:[1,0]
	v_pk_mul_f32 v[42:43], v[42:43], v[52:53] op_sel_hi:[1,0]
	v_add_f32_e32 v46, 1.0, v46
	v_cmp_gt_f32_e32 vcc, s97, v46
	s_nop 1
	v_cndmask_b32_e64 v47, 0, 32, vcc
	v_ldexp_f32 v46, v46, v47
	v_log_f32_e32 v46, v46
	s_nop 0
	v_mul_f32_e32 v47, 0x3f317217, v46
	v_fma_f32 v47, v46, s52, -v47
	v_fmac_f32_e32 v47, 0x3377d1cf, v46
	v_fmac_f32_e32 v47, 0x3f317217, v46
	v_cmp_lt_f32_e64 s[8:9], |v46|, s53
	s_nop 1
	v_cndmask_b32_e64 v46, v46, v47, s[8:9]
	v_cndmask_b32_e32 v47, 0, v216, vcc
	v_sub_f32_e32 v52, v46, v47
	v_add_f32_e32 v46, v64, v40
	v_min_f32_e32 v40, 0, v46
	v_mul_f32_e64 v46, |v46|, s57
	v_exp_f32_e32 v46, v46
	s_nop 0
	v_add_f32_e32 v46, 1.0, v46
	v_cmp_gt_f32_e32 vcc, s97, v46
	s_nop 1
	v_cndmask_b32_e64 v47, 0, 32, vcc
	v_ldexp_f32 v46, v46, v47
	v_log_f32_e32 v46, v46
	s_nop 0
	v_mul_f32_e32 v47, 0x3f317217, v46
	v_fma_f32 v47, v46, s52, -v47
	v_fmac_f32_e32 v47, 0x3377d1cf, v46
	v_fmac_f32_e32 v47, 0x3f317217, v46
	v_cmp_lt_f32_e64 s[8:9], |v46|, s53
	s_nop 1
	v_cndmask_b32_e64 v46, v46, v47, s[8:9]
	v_cndmask_b32_e32 v47, 0, v216, vcc
	v_sub_f32_e32 v46, v46, v47
	v_add_f32_e32 v47, v69, v45
	v_min_f32_e32 v45, 0, v47
	v_mul_f32_e64 v47, |v47|, s57
	v_exp_f32_e32 v47, v47
	s_nop 0
	v_add_f32_e32 v47, 1.0, v47
	v_cmp_gt_f32_e32 vcc, s97, v47
	s_nop 1
	v_cndmask_b32_e64 v53, 0, 32, vcc
	v_ldexp_f32 v47, v47, v53
	v_log_f32_e32 v47, v47
	s_nop 0
	v_mul_f32_e32 v53, 0x3f317217, v47
	v_fma_f32 v53, v47, s52, -v53
	v_fmac_f32_e32 v53, 0x3377d1cf, v47
	v_fmac_f32_e32 v53, 0x3f317217, v47
	v_cmp_lt_f32_e64 s[8:9], |v47|, s53
	s_nop 1
	v_cndmask_b32_e64 v47, v47, v53, s[8:9]
	v_cndmask_b32_e32 v53, 0, v216, vcc
	v_sub_f32_e32 v53, v47, v53
	v_add_f32_e32 v47, v65, v41
	v_min_f32_e32 v41, 0, v47
	v_mul_f32_e64 v47, |v47|, s57
	v_exp_f32_e32 v47, v47
	v_pk_add_f32 v[44:45], v[44:45], v[52:53] neg_lo:[0,1] neg_hi:[0,1]
	v_add_f32_e32 v47, 1.0, v47
	v_cmp_gt_f32_e32 vcc, s97, v47
	s_nop 1
; __device__ __forceinline__ float logsig_f(float x) { return fminf(x, 0.f) - __logf(1.f + __expf(-fabsf(x))); }
;     __device__ __forceinline__ void operator()(const f32x4 (&acc)[2][2][4][2], const pg8::Unit& u, int wr, int wc, int fr, int fq) const {
;     ...
;         if (pn == 14) {
;             if (wc == 0 && fq == 0) {
;                 const f32x4 fb0 = *(const f32x4*)fbias, fb1 = *(const f32x4*)(fbias + 4);
; #pragma unroll
;                 for (int ai = 0; ai < 2; ++ai)
; #pragma unroll
;                     for (int m = 0; m < 4; ++m) {
;                         const int row = row0 + ai * 128 + m * 16;
;                         const f32x4 sv = *(const f32x4*)(ssq + (size_t)row * 16), sv1 = *(const f32x4*)(ssq + (size_t)row * 16 + 4), sv2 = *(const f32x4*)(ssq + (size_t)row * 16 + 8), sv3 = *(const f32x4*)(ssq + (size_t)row * 16 + 12);
;                         const float st = ((sv[0] + sv[1]) + (sv[2] + sv[3])) + ((sv1[0] + sv1[1]) + (sv1[2] + sv1[3])) + ((sv2[0] + sv2[1]) + (sv2[2] + sv2[3])) + ((sv3[0] + sv3[1]) + (sv3[2] + sv3[3]));
;                         const float rs = __builtin_amdgcn_rsqf(st * (1.f / DM) + EPS);
;                         f32x4 a = acc[ai][0][m][0] * rs, b = acc[ai][0][m][1] * rs;
; #pragma unroll
;                         for (int i = 0; i < 4; ++i) { a[i] = logsig_f(a[i] + fb0[i]) * LOG2E; b[i] = logsig_f(b[i] + fb1[i]) * LOG2E; }
;                         *(f32x4*)(FF + (size_t)row * 8) = a; *(f32x4*)(FF + (size_t)row * 8 + 4) = b;
;                         asm volatile("" ::: "memory");
;                     }
;             }
	v_cndmask_b32_e64 v54, 0, 32, vcc
	v_ldexp_f32 v47, v47, v54
	v_log_f32_e32 v47, v47
	s_nop 0
	v_mul_f32_e32 v54, 0x3f317217, v47
	v_fma_f32 v54, v47, s52, -v54
	v_fmac_f32_e32 v54, 0x3377d1cf, v47
	v_fmac_f32_e32 v54, 0x3f317217, v47
	v_cmp_lt_f32_e64 s[8:9], |v47|, s53
	s_nop 1
	v_cndmask_b32_e64 v47, v47, v54, s[8:9]
	v_cndmask_b32_e32 v54, 0, v216, vcc
	v_sub_f32_e32 v47, v47, v54
	v_add_f32_e32 v54, v70, v50
	v_min_f32_e32 v50, 0, v54
	v_mul_f32_e64 v54, |v54|, s57
	v_exp_f32_e32 v54, v54
	v_pk_add_f32 v[40:41], v[40:41], v[46:47] neg_lo:[0,1] neg_hi:[0,1]
	v_add_f32_e32 v54, 1.0, v54
	v_cmp_gt_f32_e32 vcc, s97, v54
	v_pk_mul_f32 v[40:41], v[40:41], s[2:3] op_sel_hi:[1,0]
	s_nop 0
	v_cndmask_b32_e64 v55, 0, 32, vcc
	v_ldexp_f32 v54, v54, v55
	v_log_f32_e32 v54, v54
	s_nop 0
	v_mul_f32_e32 v55, 0x3f317217, v54
	v_fma_f32 v55, v54, s52, -v55
	v_fmac_f32_e32 v55, 0x3377d1cf, v54
	v_fmac_f32_e32 v55, 0x3f317217, v54
	v_cmp_lt_f32_e64 s[8:9], |v54|, s53
	s_nop 1
	v_cndmask_b32_e64 v54, v54, v55, s[8:9]
	v_cndmask_b32_e32 v55, 0, v216, vcc
	v_sub_f32_e32 v54, v54, v55
	v_add_f32_e32 v55, v66, v42
	v_min_f32_e32 v42, 0, v55
	v_mul_f32_e64 v55, |v55|, s57
	v_exp_f32_e32 v55, v55
	s_nop 0
	v_add_f32_e32 v55, 1.0, v55
	v_cmp_gt_f32_e32 vcc, s97, v55
	s_nop 1
	v_cndmask_b32_e64 v56, 0, 32, vcc
	v_ldexp_f32 v55, v55, v56
	v_log_f32_e32 v55, v55
	s_nop 0
	v_mul_f32_e32 v56, 0x3f317217, v55
	v_fma_f32 v56, v55, s52, -v56
	v_fmac_f32_e32 v56, 0x3377d1cf, v55
	v_fmac_f32_e32 v56, 0x3f317217, v55
	v_cmp_lt_f32_e64 s[8:9], |v55|, s53
	s_nop 1
	v_cndmask_b32_e64 v55, v55, v56, s[8:9]
	v_cndmask_b32_e32 v56, 0, v216, vcc
	v_sub_f32_e32 v56, v55, v56
	v_add_f32_e32 v55, v71, v51
	v_min_f32_e32 v51, 0, v55
	v_mul_f32_e64 v55, |v55|, s57
	v_exp_f32_e32 v55, v55
	s_nop 0
	v_add_f32_e32 v55, 1.0, v55
	v_cmp_gt_f32_e32 vcc, s97, v55
	s_nop 1
	v_cndmask_b32_e64 v57, 0, 32, vcc
	v_ldexp_f32 v55, v55, v57
	v_log_f32_e32 v55, v55
	s_nop 0
	v_mul_f32_e32 v57, 0x3f317217, v55
	v_fma_f32 v57, v55, s52, -v57
	v_fmac_f32_e32 v57, 0x3377d1cf, v55
	v_fmac_f32_e32 v57, 0x3f317217, v55
	v_cmp_lt_f32_e64 s[8:9], |v55|, s53
	s_nop 1
	v_cndmask_b32_e64 v55, v55, v57, s[8:9]
	v_cndmask_b32_e32 v57, 0, v216, vcc
	v_sub_f32_e32 v55, v55, v57
	v_pk_add_f32 v[50:51], v[50:51], v[54:55] neg_lo:[0,1] neg_hi:[0,1]
	s_nop 0
	v_pk_mul_f32 v[52:53], v[50:51], s[2:3] op_sel_hi:[1,0]
	v_pk_mul_f32 v[50:51], v[44:45], s[2:3] op_sel_hi:[1,0]
	v_add_f32_e32 v44, v67, v43
	v_min_f32_e32 v43, 0, v44
	v_mul_f32_e64 v44, |v44|, s57
	v_exp_f32_e32 v44, v44
	s_nop 0
	v_add_f32_e32 v44, 1.0, v44
	v_cmp_gt_f32_e32 vcc, s97, v44
	s_nop 1
	v_cndmask_b32_e64 v45, 0, 32, vcc
	v_ldexp_f32 v44, v44, v45
	v_log_f32_e32 v44, v44
	s_nop 0
	v_mul_f32_e32 v45, 0x3f317217, v44
	v_fma_f32 v45, v44, s52, -v45
	v_fmac_f32_e32 v45, 0x3377d1cf, v44
	v_fmac_f32_e32 v45, 0x3f317217, v44
	v_cmp_lt_f32_e64 s[8:9], |v44|, s53
	s_nop 1
	v_cndmask_b32_e64 v44, v44, v45, s[8:9]
	v_cndmask_b32_e32 v45, 0, v216, vcc
	v_sub_f32_e32 v57, v44, v45
	v_lshlrev_b64 v[44:45], 5, v[48:49]
	v_pk_add_f32 v[42:43], v[42:43], v[56:57] neg_lo:[0,1] neg_hi:[0,1]
	v_lshl_add_u64 v[44:45], s[42:43], 0, v[44:45]
	v_pk_mul_f32 v[42:43], v[42:43], s[2:3] op_sel_hi:[1,0]
	flat_store_dwordx4 v[44:45], v[50:53] sc1
	flat_store_dwordx4 v[44:45], v[40:43] offset:16 sc1
	s_nop 1
	v_or_b32_e32 v40, 48, v166
	v_ashrrev_i32_e32 v41, 31, v40
	v_lshlrev_b64 v[42:43], 6, v[40:41]
	v_lshl_add_u64 v[54:55], s[82:83], 0, v[42:43]
	flat_load_dwordx4 v[42:45], v[54:55]
	flat_load_dwordx4 v[46:49], v[54:55] offset:16
	flat_load_dwordx4 v[50:53], v[54:55] offset:32
	s_nop 0
	flat_load_dwordx4 v[54:57], v[54:55] offset:48
	s_waitcnt vmcnt(0) lgkmcnt(0)
	v_mov_b32_e32 v58, v43
	v_mov_b32_e32 v59, v44
	v_mov_b32_e32 v43, v45
	v_mov_b32_e32 v44, v47
	v_mov_b32_e32 v45, v48
	v_mov_b32_e32 v47, v49
	v_pk_add_f32 v[42:43], v[58:59], v[42:43]
	v_pk_add_f32 v[44:45], v[44:45], v[46:47]
	v_pk_add_f32 v[42:43], v[42:43], v[42:43] op_sel:[0,1] op_sel_hi:[1,0]
	v_pk_add_f32 v[44:45], v[44:45], v[44:45] op_sel:[0,1] op_sel_hi:[1,0]
	v_add_f32_e32 v46, v50, v51
	v_add_f32_e32 v48, v52, v53
	v_mov_b32_e32 v43, v54
	v_mov_b32_e32 v45, v55
	v_mov_b32_e32 v47, v56
	v_mov_b32_e32 v49, v57
	v_pk_add_f32 v[42:43], v[42:43], v[44:45]
	v_pk_add_f32 v[44:45], v[46:47], v[48:49]
	s_nop 0
	v_pk_add_f32 v[42:43], v[42:43], v[44:45]
	s_nop 0
	v_add_f32_e32 v42, v42, v43
	v_fmamk_f32 v42, v42, 0x3a800000, v212
	v_rsq_f32_e32 v44, v42
	s_nop 0
	v_pk_mul_f32 v[36:37], v[36:37], v[44:45] op_sel_hi:[1,0]
	v_pk_mul_f32 v[42:43], v[38:39], v[44:45] op_sel_hi:[1,0]
	v_add_f32_e32 v38, v68, v36
	v_min_f32_e32 v36, 0, v38
	v_mul_f32_e64 v38, |v38|, s57
	v_exp_f32_e32 v38, v38
	v_pk_mul_f32 v[32:33], v[32:33], v[44:45] op_sel_hi:[1,0]
	v_pk_mul_f32 v[34:35], v[34:35], v[44:45] op_sel_hi:[1,0]
	v_add_f32_e32 v38, 1.0, v38
	v_cmp_gt_f32_e32 vcc, s97, v38
	s_nop 1
	v_cndmask_b32_e64 v39, 0, 32, vcc
	v_ldexp_f32 v38, v38, v39
	v_log_f32_e32 v38, v38
	s_nop 0
	v_mul_f32_e32 v39, 0x3f317217, v38
	v_fma_f32 v39, v38, s52, -v39
	v_fmac_f32_e32 v39, 0x3377d1cf, v38
	v_fmac_f32_e32 v39, 0x3f317217, v38
	v_cmp_lt_f32_e64 s[8:9], |v38|, s53
	s_nop 1
	v_cndmask_b32_e64 v38, v38, v39, s[8:9]
	v_cndmask_b32_e32 v39, 0, v216, vcc
	v_sub_f32_e32 v44, v38, v39
	v_add_f32_e32 v38, v64, v32
	v_min_f32_e32 v32, 0, v38
	v_mul_f32_e64 v38, |v38|, s57
	v_exp_f32_e32 v38, v38
	s_nop 0
	v_add_f32_e32 v38, 1.0, v38
	v_cmp_gt_f32_e32 vcc, s97, v38
	s_nop 1
	v_cndmask_b32_e64 v39, 0, 32, vcc
	v_ldexp_f32 v38, v38, v39
	v_log_f32_e32 v38, v38
	s_nop 0
	v_mul_f32_e32 v39, 0x3f317217, v38
	v_fma_f32 v39, v38, s52, -v39
; __device__ __forceinline__ float logsig_f(float x) { return fminf(x, 0.f) - __logf(1.f + __expf(-fabsf(x))); }
;     __device__ __forceinline__ void operator()(const f32x4 (&acc)[2][2][4][2], const pg8::Unit& u, int wr, int wc, int fr, int fq) const {
;     ...
;         if (pn == 14) {
;             if (wc == 0 && fq == 0) {
;                 const f32x4 fb0 = *(const f32x4*)fbias, fb1 = *(const f32x4*)(fbias + 4);
; #pragma unroll
;                 for (int ai = 0; ai < 2; ++ai)
; #pragma unroll
;                     for (int m = 0; m < 4; ++m) {
;                         const int row = row0 + ai * 128 + m * 16;
;                         const f32x4 sv = *(const f32x4*)(ssq + (size_t)row * 16), sv1 = *(const f32x4*)(ssq + (size_t)row * 16 + 4), sv2 = *(const f32x4*)(ssq + (size_t)row * 16 + 8), sv3 = *(const f32x4*)(ssq + (size_t)row * 16 + 12);
;                         const float st = ((sv[0] + sv[1]) + (sv[2] + sv[3])) + ((sv1[0] + sv1[1]) + (sv1[2] + sv1[3])) + ((sv2[0] + sv2[1]) + (sv2[2] + sv2[3])) + ((sv3[0] + sv3[1]) + (sv3[2] + sv3[3]));
;                         const float rs = __builtin_amdgcn_rsqf(st * (1.f / DM) + EPS);
;                         f32x4 a = acc[ai][0][m][0] * rs, b = acc[ai][0][m][1] * rs;
; #pragma unroll
;                         for (int i = 0; i < 4; ++i) { a[i] = logsig_f(a[i] + fb0[i]) * LOG2E; b[i] = logsig_f(b[i] + fb1[i]) * LOG2E; }
;                         *(f32x4*)(FF + (size_t)row * 8) = a; *(f32x4*)(FF + (size_t)row * 8 + 4) = b;
;                         asm volatile("" ::: "memory");
;                     }
;             }
	v_fmac_f32_e32 v39, 0x3377d1cf, v38
	v_fmac_f32_e32 v39, 0x3f317217, v38
	v_cmp_lt_f32_e64 s[8:9], |v38|, s53
	s_nop 1
	v_cndmask_b32_e64 v38, v38, v39, s[8:9]
	v_cndmask_b32_e32 v39, 0, v216, vcc
	v_sub_f32_e32 v38, v38, v39
	v_add_f32_e32 v39, v69, v37
	v_min_f32_e32 v37, 0, v39
	v_mul_f32_e64 v39, |v39|, s57
	v_exp_f32_e32 v39, v39
	s_nop 0
	v_add_f32_e32 v39, 1.0, v39
	v_cmp_gt_f32_e32 vcc, s97, v39
	s_nop 1
	v_cndmask_b32_e64 v45, 0, 32, vcc
	v_ldexp_f32 v39, v39, v45
	v_log_f32_e32 v39, v39
	s_nop 0
	v_mul_f32_e32 v45, 0x3f317217, v39
	v_fma_f32 v45, v39, s52, -v45
	v_fmac_f32_e32 v45, 0x3377d1cf, v39
	v_fmac_f32_e32 v45, 0x3f317217, v39
	v_cmp_lt_f32_e64 s[8:9], |v39|, s53
	s_nop 1
	v_cndmask_b32_e64 v39, v39, v45, s[8:9]
	v_cndmask_b32_e32 v45, 0, v216, vcc
	v_sub_f32_e32 v45, v39, v45
	v_add_f32_e32 v39, v65, v33
	v_min_f32_e32 v33, 0, v39
	v_mul_f32_e64 v39, |v39|, s57
	v_exp_f32_e32 v39, v39
	v_pk_add_f32 v[36:37], v[36:37], v[44:45] neg_lo:[0,1] neg_hi:[0,1]
	v_add_f32_e32 v39, 1.0, v39
	v_cmp_gt_f32_e32 vcc, s97, v39
	s_nop 1
	v_cndmask_b32_e64 v46, 0, 32, vcc
	v_ldexp_f32 v39, v39, v46
	v_log_f32_e32 v39, v39
	s_nop 0
	v_mul_f32_e32 v46, 0x3f317217, v39
	v_fma_f32 v46, v39, s52, -v46
	v_fmac_f32_e32 v46, 0x3377d1cf, v39
	v_fmac_f32_e32 v46, 0x3f317217, v39
	v_cmp_lt_f32_e64 s[8:9], |v39|, s53
	s_nop 1
	v_cndmask_b32_e64 v39, v39, v46, s[8:9]
	v_cndmask_b32_e32 v46, 0, v216, vcc
	v_sub_f32_e32 v39, v39, v46
	v_add_f32_e32 v46, v70, v42
	v_min_f32_e32 v42, 0, v46
	v_mul_f32_e64 v46, |v46|, s57
	v_exp_f32_e32 v46, v46
	v_pk_add_f32 v[32:33], v[32:33], v[38:39] neg_lo:[0,1] neg_hi:[0,1]
	v_add_f32_e32 v46, 1.0, v46
	v_cmp_gt_f32_e32 vcc, s97, v46
	v_pk_mul_f32 v[32:33], v[32:33], s[2:3] op_sel_hi:[1,0]
	s_nop 0
	v_cndmask_b32_e64 v47, 0, 32, vcc
	v_ldexp_f32 v46, v46, v47
	v_log_f32_e32 v46, v46
	s_nop 0
	v_mul_f32_e32 v47, 0x3f317217, v46
	v_fma_f32 v47, v46, s52, -v47
	v_fmac_f32_e32 v47, 0x3377d1cf, v46
	v_fmac_f32_e32 v47, 0x3f317217, v46
	v_cmp_lt_f32_e64 s[8:9], |v46|, s53
	s_nop 1
	v_cndmask_b32_e64 v46, v46, v47, s[8:9]
	v_cndmask_b32_e32 v47, 0, v216, vcc
	v_sub_f32_e32 v46, v46, v47
	v_add_f32_e32 v47, v66, v34
	v_min_f32_e32 v34, 0, v47
	v_mul_f32_e64 v47, |v47|, s57
	v_exp_f32_e32 v47, v47
	s_nop 0
	v_add_f32_e32 v47, 1.0, v47
	v_cmp_gt_f32_e32 vcc, s97, v47
	s_nop 1
	v_cndmask_b32_e64 v48, 0, 32, vcc
	v_ldexp_f32 v47, v47, v48
	v_log_f32_e32 v47, v47
	s_nop 0
	v_mul_f32_e32 v48, 0x3f317217, v47
	v_fma_f32 v48, v47, s52, -v48
	v_fmac_f32_e32 v48, 0x3377d1cf, v47
	v_fmac_f32_e32 v48, 0x3f317217, v47
	v_cmp_lt_f32_e64 s[8:9], |v47|, s53
	s_nop 1
	v_cndmask_b32_e64 v47, v47, v48, s[8:9]
	v_cndmask_b32_e32 v48, 0, v216, vcc
	v_sub_f32_e32 v48, v47, v48
	v_add_f32_e32 v47, v71, v43
	v_min_f32_e32 v43, 0, v47
	v_mul_f32_e64 v47, |v47|, s57
	v_exp_f32_e32 v47, v47
	s_nop 0
	v_add_f32_e32 v47, 1.0, v47
	v_cmp_gt_f32_e32 vcc, s97, v47
	s_nop 1
	v_cndmask_b32_e64 v49, 0, 32, vcc
	v_ldexp_f32 v47, v47, v49
	v_log_f32_e32 v47, v47
	s_nop 0
	v_mul_f32_e32 v49, 0x3f317217, v47
	v_fma_f32 v49, v47, s52, -v49
	v_fmac_f32_e32 v49, 0x3377d1cf, v47
	v_fmac_f32_e32 v49, 0x3f317217, v47
	v_cmp_lt_f32_e64 s[8:9], |v47|, s53
	s_nop 1
	v_cndmask_b32_e64 v47, v47, v49, s[8:9]
	v_cndmask_b32_e32 v49, 0, v216, vcc
	v_sub_f32_e32 v47, v47, v49
	v_pk_add_f32 v[42:43], v[42:43], v[46:47] neg_lo:[0,1] neg_hi:[0,1]
	s_nop 0
	v_pk_mul_f32 v[44:45], v[42:43], s[2:3] op_sel_hi:[1,0]
	v_pk_mul_f32 v[42:43], v[36:37], s[2:3] op_sel_hi:[1,0]
	v_add_f32_e32 v36, v67, v35
	v_min_f32_e32 v35, 0, v36
	v_mul_f32_e64 v36, |v36|, s57
	v_exp_f32_e32 v36, v36
	s_nop 0
	v_add_f32_e32 v36, 1.0, v36
	v_cmp_gt_f32_e32 vcc, s97, v36
	s_nop 1
	v_cndmask_b32_e64 v37, 0, 32, vcc
	v_ldexp_f32 v36, v36, v37
	v_log_f32_e32 v36, v36
	s_nop 0
	v_mul_f32_e32 v37, 0x3f317217, v36
	v_fma_f32 v37, v36, s52, -v37
	v_fmac_f32_e32 v37, 0x3377d1cf, v36
	v_fmac_f32_e32 v37, 0x3f317217, v36
	v_cmp_lt_f32_e64 s[8:9], |v36|, s53
	s_nop 1
	v_cndmask_b32_e64 v36, v36, v37, s[8:9]
	v_cndmask_b32_e32 v37, 0, v216, vcc
	v_sub_f32_e32 v49, v36, v37
	v_lshlrev_b64 v[36:37], 5, v[40:41]
	v_pk_add_f32 v[34:35], v[34:35], v[48:49] neg_lo:[0,1] neg_hi:[0,1]
	v_lshl_add_u64 v[36:37], s[42:43], 0, v[36:37]
	v_pk_mul_f32 v[34:35], v[34:35], s[2:3] op_sel_hi:[1,0]
	flat_store_dwordx4 v[36:37], v[42:45] sc1
	flat_store_dwordx4 v[36:37], v[32:35] offset:16 sc1
	s_nop 1
	v_add_u32_e32 v32, 0x80, v166
	v_ashrrev_i32_e32 v33, 31, v32
	v_lshlrev_b64 v[34:35], 6, v[32:33]
	v_lshl_add_u64 v[46:47], s[82:83], 0, v[34:35]
	flat_load_dwordx4 v[34:37], v[46:47]
	flat_load_dwordx4 v[38:41], v[46:47] offset:16
	flat_load_dwordx4 v[42:45], v[46:47] offset:32
	s_nop 0
	flat_load_dwordx4 v[46:49], v[46:47] offset:48
	s_waitcnt vmcnt(0) lgkmcnt(0)
; __device__ __forceinline__ float logsig_f(float x) { return fminf(x, 0.f) - __logf(1.f + __expf(-fabsf(x))); }
;     __device__ __forceinline__ void operator()(const f32x4 (&acc)[2][2][4][2], const pg8::Unit& u, int wr, int wc, int fr, int fq) const {
;     ...
;         if (pn == 14) {
;             if (wc == 0 && fq == 0) {
;                 const f32x4 fb0 = *(const f32x4*)fbias, fb1 = *(const f32x4*)(fbias + 4);
; #pragma unroll
;                 for (int ai = 0; ai < 2; ++ai)
; #pragma unroll
;                     for (int m = 0; m < 4; ++m) {
;                         const int row = row0 + ai * 128 + m * 16;
;                         const f32x4 sv = *(const f32x4*)(ssq + (size_t)row * 16), sv1 = *(const f32x4*)(ssq + (size_t)row * 16 + 4), sv2 = *(const f32x4*)(ssq + (size_t)row * 16 + 8), sv3 = *(const f32x4*)(ssq + (size_t)row * 16 + 12);
;                         const float st = ((sv[0] + sv[1]) + (sv[2] + sv[3])) + ((sv1[0] + sv1[1]) + (sv1[2] + sv1[3])) + ((sv2[0] + sv2[1]) + (sv2[2] + sv2[3])) + ((sv3[0] + sv3[1]) + (sv3[2] + sv3[3]));
;                         const float rs = __builtin_amdgcn_rsqf(st * (1.f / DM) + EPS);
;                         f32x4 a = acc[ai][0][m][0] * rs, b = acc[ai][0][m][1] * rs;
; #pragma unroll
;                         for (int i = 0; i < 4; ++i) { a[i] = logsig_f(a[i] + fb0[i]) * LOG2E; b[i] = logsig_f(b[i] + fb1[i]) * LOG2E; }
;                         *(f32x4*)(FF + (size_t)row * 8) = a; *(f32x4*)(FF + (size_t)row * 8 + 4) = b;
;                         asm volatile("" ::: "memory");
;                     }
;             }
	v_mov_b32_e32 v50, v35
	v_mov_b32_e32 v51, v36
	v_mov_b32_e32 v35, v37
	v_mov_b32_e32 v36, v39
	v_mov_b32_e32 v37, v40
	v_mov_b32_e32 v39, v41
	v_pk_add_f32 v[34:35], v[50:51], v[34:35]
	v_pk_add_f32 v[36:37], v[36:37], v[38:39]
	v_pk_add_f32 v[34:35], v[34:35], v[34:35] op_sel:[0,1] op_sel_hi:[1,0]
	v_pk_add_f32 v[36:37], v[36:37], v[36:37] op_sel:[0,1] op_sel_hi:[1,0]
	v_add_f32_e32 v38, v42, v43
	v_add_f32_e32 v40, v44, v45
	v_mov_b32_e32 v35, v46
	v_mov_b32_e32 v37, v47
	v_mov_b32_e32 v39, v48
	v_mov_b32_e32 v41, v49
	v_pk_add_f32 v[34:35], v[34:35], v[36:37]
	v_pk_add_f32 v[36:37], v[38:39], v[40:41]
	s_nop 0
	v_pk_add_f32 v[34:35], v[34:35], v[36:37]
	s_nop 0
	v_add_f32_e32 v34, v34, v35
	v_fmamk_f32 v34, v34, 0x3a800000, v212
	v_rsq_f32_e32 v36, v34
	s_nop 0
	v_pk_mul_f32 v[28:29], v[28:29], v[36:37] op_sel_hi:[1,0]
	v_pk_mul_f32 v[34:35], v[30:31], v[36:37] op_sel_hi:[1,0]
	v_add_f32_e32 v30, v68, v28
	v_min_f32_e32 v28, 0, v30
	v_mul_f32_e64 v30, |v30|, s57
	v_exp_f32_e32 v30, v30
	v_pk_mul_f32 v[24:25], v[24:25], v[36:37] op_sel_hi:[1,0]
	v_pk_mul_f32 v[26:27], v[26:27], v[36:37] op_sel_hi:[1,0]
	v_add_f32_e32 v30, 1.0, v30
	v_cmp_gt_f32_e32 vcc, s97, v30
	s_nop 1
	v_cndmask_b32_e64 v31, 0, 32, vcc
	v_ldexp_f32 v30, v30, v31
	v_log_f32_e32 v30, v30
	s_nop 0
	v_mul_f32_e32 v31, 0x3f317217, v30
	v_fma_f32 v31, v30, s52, -v31
	v_fmac_f32_e32 v31, 0x3377d1cf, v30
	v_fmac_f32_e32 v31, 0x3f317217, v30
	v_cmp_lt_f32_e64 s[8:9], |v30|, s53
	s_nop 1
	v_cndmask_b32_e64 v30, v30, v31, s[8:9]
	v_cndmask_b32_e32 v31, 0, v216, vcc
	v_sub_f32_e32 v36, v30, v31
	v_add_f32_e32 v30, v64, v24
	v_min_f32_e32 v24, 0, v30
	v_mul_f32_e64 v30, |v30|, s57
	v_exp_f32_e32 v30, v30
	s_nop 0
	v_add_f32_e32 v30, 1.0, v30
	v_cmp_gt_f32_e32 vcc, s97, v30
	s_nop 1
	v_cndmask_b32_e64 v31, 0, 32, vcc
	v_ldexp_f32 v30, v30, v31
	v_log_f32_e32 v30, v30
	s_nop 0
	v_mul_f32_e32 v31, 0x3f317217, v30
	v_fma_f32 v31, v30, s52, -v31
	v_fmac_f32_e32 v31, 0x3377d1cf, v30
	v_fmac_f32_e32 v31, 0x3f317217, v30
	v_cmp_lt_f32_e64 s[8:9], |v30|, s53
	s_nop 1
	v_cndmask_b32_e64 v30, v30, v31, s[8:9]
	v_cndmask_b32_e32 v31, 0, v216, vcc
	v_sub_f32_e32 v30, v30, v31
	v_add_f32_e32 v31, v69, v29
	v_min_f32_e32 v29, 0, v31
	v_mul_f32_e64 v31, |v31|, s57
	v_exp_f32_e32 v31, v31
	s_nop 0
	v_add_f32_e32 v31, 1.0, v31
	v_cmp_gt_f32_e32 vcc, s97, v31
	s_nop 1
	v_cndmask_b32_e64 v37, 0, 32, vcc
	v_ldexp_f32 v31, v31, v37
	v_log_f32_e32 v31, v31
	s_nop 0
	v_mul_f32_e32 v37, 0x3f317217, v31
	v_fma_f32 v37, v31, s52, -v37
	v_fmac_f32_e32 v37, 0x3377d1cf, v31
	v_fmac_f32_e32 v37, 0x3f317217, v31
	v_cmp_lt_f32_e64 s[8:9], |v31|, s53
	s_nop 1
	v_cndmask_b32_e64 v31, v31, v37, s[8:9]
	v_cndmask_b32_e32 v37, 0, v216, vcc
	v_sub_f32_e32 v37, v31, v37
	v_add_f32_e32 v31, v65, v25
	v_min_f32_e32 v25, 0, v31
	v_mul_f32_e64 v31, |v31|, s57
	v_exp_f32_e32 v31, v31
	v_pk_add_f32 v[28:29], v[28:29], v[36:37] neg_lo:[0,1] neg_hi:[0,1]
	v_add_f32_e32 v31, 1.0, v31
	v_cmp_gt_f32_e32 vcc, s97, v31
	s_nop 1
	v_cndmask_b32_e64 v38, 0, 32, vcc
	v_ldexp_f32 v31, v31, v38
	v_log_f32_e32 v31, v31
	s_nop 0
	v_mul_f32_e32 v38, 0x3f317217, v31
	v_fma_f32 v38, v31, s52, -v38
	v_fmac_f32_e32 v38, 0x3377d1cf, v31
	v_fmac_f32_e32 v38, 0x3f317217, v31
	v_cmp_lt_f32_e64 s[8:9], |v31|, s53
	s_nop 1
	v_cndmask_b32_e64 v31, v31, v38, s[8:9]
	v_cndmask_b32_e32 v38, 0, v216, vcc
	v_sub_f32_e32 v31, v31, v38
	v_add_f32_e32 v38, v70, v34
	v_min_f32_e32 v34, 0, v38
	v_mul_f32_e64 v38, |v38|, s57
	v_exp_f32_e32 v38, v38
	v_pk_add_f32 v[24:25], v[24:25], v[30:31] neg_lo:[0,1] neg_hi:[0,1]
	v_add_f32_e32 v38, 1.0, v38
	v_cmp_gt_f32_e32 vcc, s97, v38
	v_pk_mul_f32 v[24:25], v[24:25], s[2:3] op_sel_hi:[1,0]
	s_nop 0
	v_cndmask_b32_e64 v39, 0, 32, vcc
	v_ldexp_f32 v38, v38, v39
	v_log_f32_e32 v38, v38
	s_nop 0
	v_mul_f32_e32 v39, 0x3f317217, v38
	v_fma_f32 v39, v38, s52, -v39
	v_fmac_f32_e32 v39, 0x3377d1cf, v38
	v_fmac_f32_e32 v39, 0x3f317217, v38
	v_cmp_lt_f32_e64 s[8:9], |v38|, s53
	s_nop 1
	v_cndmask_b32_e64 v38, v38, v39, s[8:9]
	v_cndmask_b32_e32 v39, 0, v216, vcc
	v_sub_f32_e32 v38, v38, v39
	v_add_f32_e32 v39, v66, v26
	v_min_f32_e32 v26, 0, v39
	v_mul_f32_e64 v39, |v39|, s57
	v_exp_f32_e32 v39, v39
	s_nop 0
	v_add_f32_e32 v39, 1.0, v39
	v_cmp_gt_f32_e32 vcc, s97, v39
	s_nop 1
	v_cndmask_b32_e64 v40, 0, 32, vcc
	v_ldexp_f32 v39, v39, v40
	v_log_f32_e32 v39, v39
	s_nop 0
	v_mul_f32_e32 v40, 0x3f317217, v39
	v_fma_f32 v40, v39, s52, -v40
	v_fmac_f32_e32 v40, 0x3377d1cf, v39
	v_fmac_f32_e32 v40, 0x3f317217, v39
	v_cmp_lt_f32_e64 s[8:9], |v39|, s53
	s_nop 1
	v_cndmask_b32_e64 v39, v39, v40, s[8:9]
	v_cndmask_b32_e32 v40, 0, v216, vcc
	v_sub_f32_e32 v40, v39, v40
	v_add_f32_e32 v39, v71, v35
	v_min_f32_e32 v35, 0, v39
	v_mul_f32_e64 v39, |v39|, s57
	v_exp_f32_e32 v39, v39
	s_nop 0
	v_add_f32_e32 v39, 1.0, v39
	v_cmp_gt_f32_e32 vcc, s97, v39
	s_nop 1
	v_cndmask_b32_e64 v41, 0, 32, vcc
	v_ldexp_f32 v39, v39, v41
	v_log_f32_e32 v39, v39
	s_nop 0
	v_mul_f32_e32 v41, 0x3f317217, v39
	v_fma_f32 v41, v39, s52, -v41
	v_fmac_f32_e32 v41, 0x3377d1cf, v39
	v_fmac_f32_e32 v41, 0x3f317217, v39
	v_cmp_lt_f32_e64 s[8:9], |v39|, s53
	s_nop 1
	v_cndmask_b32_e64 v39, v39, v41, s[8:9]
	v_cndmask_b32_e32 v41, 0, v216, vcc
	v_sub_f32_e32 v39, v39, v41
	v_pk_add_f32 v[34:35], v[34:35], v[38:39] neg_lo:[0,1] neg_hi:[0,1]
	s_nop 0
	v_pk_mul_f32 v[36:37], v[34:35], s[2:3] op_sel_hi:[1,0]
	v_pk_mul_f32 v[34:35], v[28:29], s[2:3] op_sel_hi:[1,0]
	v_add_f32_e32 v28, v67, v27
	v_min_f32_e32 v27, 0, v28
	v_mul_f32_e64 v28, |v28|, s57
	v_exp_f32_e32 v28, v28
	s_nop 0
	v_add_f32_e32 v28, 1.0, v28
	v_cmp_gt_f32_e32 vcc, s97, v28
	s_nop 1
	v_cndmask_b32_e64 v29, 0, 32, vcc
	v_ldexp_f32 v28, v28, v29
	v_log_f32_e32 v28, v28
	s_nop 0
	v_mul_f32_e32 v29, 0x3f317217, v28
	v_fma_f32 v29, v28, s52, -v29
	v_fmac_f32_e32 v29, 0x3377d1cf, v28
	v_fmac_f32_e32 v29, 0x3f317217, v28
	v_cmp_lt_f32_e64 s[8:9], |v28|, s53
	s_nop 1
	v_cndmask_b32_e64 v28, v28, v29, s[8:9]
	v_cndmask_b32_e32 v29, 0, v216, vcc
	v_sub_f32_e32 v41, v28, v29
	v_lshlrev_b64 v[28:29], 5, v[32:33]
	v_pk_add_f32 v[26:27], v[26:27], v[40:41] neg_lo:[0,1] neg_hi:[0,1]
	v_lshl_add_u64 v[28:29], s[42:43], 0, v[28:29]
	v_pk_mul_f32 v[26:27], v[26:27], s[2:3] op_sel_hi:[1,0]
	flat_store_dwordx4 v[28:29], v[34:37] sc1
	flat_store_dwordx4 v[28:29], v[24:27] offset:16 sc1
	s_nop 1
	v_add_u32_e32 v24, 0x90, v166
	v_ashrrev_i32_e32 v25, 31, v24
	v_lshlrev_b64 v[26:27], 6, v[24:25]
	v_lshl_add_u64 v[38:39], s[82:83], 0, v[26:27]
	flat_load_dwordx4 v[26:29], v[38:39]
	flat_load_dwordx4 v[30:33], v[38:39] offset:16
	flat_load_dwordx4 v[34:37], v[38:39] offset:32
	s_nop 0
	flat_load_dwordx4 v[38:41], v[38:39] offset:48
	s_waitcnt vmcnt(0) lgkmcnt(0)
; __device__ __forceinline__ float logsig_f(float x) { return fminf(x, 0.f) - __logf(1.f + __expf(-fabsf(x))); }
;     __device__ __forceinline__ void operator()(const f32x4 (&acc)[2][2][4][2], const pg8::Unit& u, int wr, int wc, int fr, int fq) const {
;     ...
;         if (pn == 14) {
;             if (wc == 0 && fq == 0) {
;                 const f32x4 fb0 = *(const f32x4*)fbias, fb1 = *(const f32x4*)(fbias + 4);
; #pragma unroll
;                 for (int ai = 0; ai < 2; ++ai)
; #pragma unroll
;                     for (int m = 0; m < 4; ++m) {
;                         const int row = row0 + ai * 128 + m * 16;
;                         const f32x4 sv = *(const f32x4*)(ssq + (size_t)row * 16), sv1 = *(const f32x4*)(ssq + (size_t)row * 16 + 4), sv2 = *(const f32x4*)(ssq + (size_t)row * 16 + 8), sv3 = *(const f32x4*)(ssq + (size_t)row * 16 + 12);
;                         const float st = ((sv[0] + sv[1]) + (sv[2] + sv[3])) + ((sv1[0] + sv1[1]) + (sv1[2] + sv1[3])) + ((sv2[0] + sv2[1]) + (sv2[2] + sv2[3])) + ((sv3[0] + sv3[1]) + (sv3[2] + sv3[3]));
;                         const float rs = __builtin_amdgcn_rsqf(st * (1.f / DM) + EPS);
;                         f32x4 a = acc[ai][0][m][0] * rs, b = acc[ai][0][m][1] * rs;
; #pragma unroll
;                         for (int i = 0; i < 4; ++i) { a[i] = logsig_f(a[i] + fb0[i]) * LOG2E; b[i] = logsig_f(b[i] + fb1[i]) * LOG2E; }
;                         *(f32x4*)(FF + (size_t)row * 8) = a; *(f32x4*)(FF + (size_t)row * 8 + 4) = b;
;                         asm volatile("" ::: "memory");
;                     }
;             }
	v_mov_b32_e32 v42, v27
	v_mov_b32_e32 v43, v28
	v_mov_b32_e32 v27, v29
	v_mov_b32_e32 v28, v31
	v_mov_b32_e32 v29, v32
	v_mov_b32_e32 v31, v33
	v_pk_add_f32 v[26:27], v[42:43], v[26:27]
	v_pk_add_f32 v[28:29], v[28:29], v[30:31]
	v_pk_add_f32 v[26:27], v[26:27], v[26:27] op_sel:[0,1] op_sel_hi:[1,0]
	v_pk_add_f32 v[28:29], v[28:29], v[28:29] op_sel:[0,1] op_sel_hi:[1,0]
	v_add_f32_e32 v30, v34, v35
	v_add_f32_e32 v32, v36, v37
	v_mov_b32_e32 v27, v38
	v_mov_b32_e32 v29, v39
	v_mov_b32_e32 v31, v40
	v_mov_b32_e32 v33, v41
	v_pk_add_f32 v[26:27], v[26:27], v[28:29]
	v_pk_add_f32 v[28:29], v[30:31], v[32:33]
	s_nop 0
	v_pk_add_f32 v[26:27], v[26:27], v[28:29]
	s_nop 0
	v_add_f32_e32 v26, v26, v27
	v_fmamk_f32 v26, v26, 0x3a800000, v212
	v_rsq_f32_e32 v28, v26
	s_nop 0
	v_pk_mul_f32 v[20:21], v[20:21], v[28:29] op_sel_hi:[1,0]
	v_pk_mul_f32 v[26:27], v[22:23], v[28:29] op_sel_hi:[1,0]
	v_add_f32_e32 v22, v68, v20
	v_min_f32_e32 v20, 0, v22
	v_mul_f32_e64 v22, |v22|, s57
	v_exp_f32_e32 v22, v22
	v_pk_mul_f32 v[16:17], v[16:17], v[28:29] op_sel_hi:[1,0]
	v_pk_mul_f32 v[18:19], v[18:19], v[28:29] op_sel_hi:[1,0]
	v_add_f32_e32 v22, 1.0, v22
	v_cmp_gt_f32_e32 vcc, s97, v22
	s_nop 1
	v_cndmask_b32_e64 v23, 0, 32, vcc
	v_ldexp_f32 v22, v22, v23
	v_log_f32_e32 v22, v22
	s_nop 0
	v_mul_f32_e32 v23, 0x3f317217, v22
	v_fma_f32 v23, v22, s52, -v23
	v_fmac_f32_e32 v23, 0x3377d1cf, v22
	v_fmac_f32_e32 v23, 0x3f317217, v22
	v_cmp_lt_f32_e64 s[8:9], |v22|, s53
	s_nop 1
	v_cndmask_b32_e64 v22, v22, v23, s[8:9]
	v_cndmask_b32_e32 v23, 0, v216, vcc
	v_sub_f32_e32 v28, v22, v23
	v_add_f32_e32 v22, v64, v16
	v_min_f32_e32 v16, 0, v22
	v_mul_f32_e64 v22, |v22|, s57
	v_exp_f32_e32 v22, v22
	s_nop 0
	v_add_f32_e32 v22, 1.0, v22
	v_cmp_gt_f32_e32 vcc, s97, v22
	s_nop 1
	v_cndmask_b32_e64 v23, 0, 32, vcc
	v_ldexp_f32 v22, v22, v23
	v_log_f32_e32 v22, v22
	s_nop 0
	v_mul_f32_e32 v23, 0x3f317217, v22
	v_fma_f32 v23, v22, s52, -v23
	v_fmac_f32_e32 v23, 0x3377d1cf, v22
	v_fmac_f32_e32 v23, 0x3f317217, v22
	v_cmp_lt_f32_e64 s[8:9], |v22|, s53
	s_nop 1
	v_cndmask_b32_e64 v22, v22, v23, s[8:9]
	v_cndmask_b32_e32 v23, 0, v216, vcc
	v_sub_f32_e32 v22, v22, v23
	v_add_f32_e32 v23, v69, v21
	v_min_f32_e32 v21, 0, v23
	v_mul_f32_e64 v23, |v23|, s57
	v_exp_f32_e32 v23, v23
	s_nop 0
	v_add_f32_e32 v23, 1.0, v23
	v_cmp_gt_f32_e32 vcc, s97, v23
	s_nop 1
	v_cndmask_b32_e64 v29, 0, 32, vcc
	v_ldexp_f32 v23, v23, v29
	v_log_f32_e32 v23, v23
	s_nop 0
	v_mul_f32_e32 v29, 0x3f317217, v23
	v_fma_f32 v29, v23, s52, -v29
	v_fmac_f32_e32 v29, 0x3377d1cf, v23
	v_fmac_f32_e32 v29, 0x3f317217, v23
	v_cmp_lt_f32_e64 s[8:9], |v23|, s53
	s_nop 1
	v_cndmask_b32_e64 v23, v23, v29, s[8:9]
	v_cndmask_b32_e32 v29, 0, v216, vcc
	v_sub_f32_e32 v29, v23, v29
	v_add_f32_e32 v23, v65, v17
	v_min_f32_e32 v17, 0, v23
	v_mul_f32_e64 v23, |v23|, s57
	v_exp_f32_e32 v23, v23
	v_pk_add_f32 v[20:21], v[20:21], v[28:29] neg_lo:[0,1] neg_hi:[0,1]
	v_add_f32_e32 v23, 1.0, v23
	v_cmp_gt_f32_e32 vcc, s97, v23
	s_nop 1
	v_cndmask_b32_e64 v30, 0, 32, vcc
	v_ldexp_f32 v23, v23, v30
	v_log_f32_e32 v23, v23
	s_nop 0
	v_mul_f32_e32 v30, 0x3f317217, v23
	v_fma_f32 v30, v23, s52, -v30
	v_fmac_f32_e32 v30, 0x3377d1cf, v23
	v_fmac_f32_e32 v30, 0x3f317217, v23
	v_cmp_lt_f32_e64 s[8:9], |v23|, s53
	s_nop 1
	v_cndmask_b32_e64 v23, v23, v30, s[8:9]
	v_cndmask_b32_e32 v30, 0, v216, vcc
	v_sub_f32_e32 v23, v23, v30
	v_add_f32_e32 v30, v70, v26
	v_min_f32_e32 v26, 0, v30
	v_mul_f32_e64 v30, |v30|, s57
	v_exp_f32_e32 v30, v30
	v_pk_add_f32 v[16:17], v[16:17], v[22:23] neg_lo:[0,1] neg_hi:[0,1]
	v_add_f32_e32 v30, 1.0, v30
	v_cmp_gt_f32_e32 vcc, s97, v30
	v_pk_mul_f32 v[16:17], v[16:17], s[2:3] op_sel_hi:[1,0]
	s_nop 0
	v_cndmask_b32_e64 v31, 0, 32, vcc
	v_ldexp_f32 v30, v30, v31
	v_log_f32_e32 v30, v30
	s_nop 0
	v_mul_f32_e32 v31, 0x3f317217, v30
	v_fma_f32 v31, v30, s52, -v31
	v_fmac_f32_e32 v31, 0x3377d1cf, v30
	v_fmac_f32_e32 v31, 0x3f317217, v30
	v_cmp_lt_f32_e64 s[8:9], |v30|, s53
	s_nop 1
	v_cndmask_b32_e64 v30, v30, v31, s[8:9]
	v_cndmask_b32_e32 v31, 0, v216, vcc
	v_sub_f32_e32 v30, v30, v31
	v_add_f32_e32 v31, v66, v18
	v_min_f32_e32 v18, 0, v31
	v_mul_f32_e64 v31, |v31|, s57
	v_exp_f32_e32 v31, v31
	s_nop 0
	v_add_f32_e32 v31, 1.0, v31
	v_cmp_gt_f32_e32 vcc, s97, v31
	s_nop 1
	v_cndmask_b32_e64 v32, 0, 32, vcc
	v_ldexp_f32 v31, v31, v32
	v_log_f32_e32 v31, v31
	s_nop 0
	v_mul_f32_e32 v32, 0x3f317217, v31
	v_fma_f32 v32, v31, s52, -v32
	v_fmac_f32_e32 v32, 0x3377d1cf, v31
	v_fmac_f32_e32 v32, 0x3f317217, v31
	v_cmp_lt_f32_e64 s[8:9], |v31|, s53
	s_nop 1
	v_cndmask_b32_e64 v31, v31, v32, s[8:9]
	v_cndmask_b32_e32 v32, 0, v216, vcc
	v_sub_f32_e32 v32, v31, v32
	v_add_f32_e32 v31, v71, v27
	v_min_f32_e32 v27, 0, v31
	v_mul_f32_e64 v31, |v31|, s57
	v_exp_f32_e32 v31, v31
	s_nop 0
	v_add_f32_e32 v31, 1.0, v31
	v_cmp_gt_f32_e32 vcc, s97, v31
	s_nop 1
	v_cndmask_b32_e64 v33, 0, 32, vcc
	v_ldexp_f32 v31, v31, v33
	v_log_f32_e32 v31, v31
	s_nop 0
	v_mul_f32_e32 v33, 0x3f317217, v31
	v_fma_f32 v33, v31, s52, -v33
	v_fmac_f32_e32 v33, 0x3377d1cf, v31
	v_fmac_f32_e32 v33, 0x3f317217, v31
	v_cmp_lt_f32_e64 s[8:9], |v31|, s53
	s_nop 1
	v_cndmask_b32_e64 v31, v31, v33, s[8:9]
	v_cndmask_b32_e32 v33, 0, v216, vcc
	v_sub_f32_e32 v31, v31, v33
	v_pk_add_f32 v[26:27], v[26:27], v[30:31] neg_lo:[0,1] neg_hi:[0,1]
	s_nop 0
	v_pk_mul_f32 v[28:29], v[26:27], s[2:3] op_sel_hi:[1,0]
	v_pk_mul_f32 v[26:27], v[20:21], s[2:3] op_sel_hi:[1,0]
	v_add_f32_e32 v20, v67, v19
	v_min_f32_e32 v19, 0, v20
	v_mul_f32_e64 v20, |v20|, s57
	v_exp_f32_e32 v20, v20
	s_nop 0
	v_add_f32_e32 v20, 1.0, v20
	v_cmp_gt_f32_e32 vcc, s97, v20
	s_nop 1
	v_cndmask_b32_e64 v21, 0, 32, vcc
	v_ldexp_f32 v20, v20, v21
	v_log_f32_e32 v20, v20
	s_nop 0
	v_mul_f32_e32 v21, 0x3f317217, v20
	v_fma_f32 v21, v20, s52, -v21
	v_fmac_f32_e32 v21, 0x3377d1cf, v20
	v_fmac_f32_e32 v21, 0x3f317217, v20
	v_cmp_lt_f32_e64 s[8:9], |v20|, s53
	s_nop 1
	v_cndmask_b32_e64 v20, v20, v21, s[8:9]
	v_cndmask_b32_e32 v21, 0, v216, vcc
	v_sub_f32_e32 v33, v20, v21
	v_lshlrev_b64 v[20:21], 5, v[24:25]
	v_pk_add_f32 v[18:19], v[18:19], v[32:33] neg_lo:[0,1] neg_hi:[0,1]
	v_lshl_add_u64 v[20:21], s[42:43], 0, v[20:21]
	v_pk_mul_f32 v[18:19], v[18:19], s[2:3] op_sel_hi:[1,0]
	flat_store_dwordx4 v[20:21], v[26:29] sc1
	flat_store_dwordx4 v[20:21], v[16:19] offset:16 sc1
	s_nop 1
	v_add_u32_e32 v16, 0xa0, v166
	v_ashrrev_i32_e32 v17, 31, v16
	v_lshlrev_b64 v[18:19], 6, v[16:17]
	v_lshl_add_u64 v[30:31], s[82:83], 0, v[18:19]
	flat_load_dwordx4 v[18:21], v[30:31]
	flat_load_dwordx4 v[22:25], v[30:31] offset:16
	flat_load_dwordx4 v[26:29], v[30:31] offset:32
	s_nop 0
	flat_load_dwordx4 v[30:33], v[30:31] offset:48
	s_waitcnt vmcnt(0) lgkmcnt(0)
; __device__ __forceinline__ float logsig_f(float x) { return fminf(x, 0.f) - __logf(1.f + __expf(-fabsf(x))); }
;     __device__ __forceinline__ void operator()(const f32x4 (&acc)[2][2][4][2], const pg8::Unit& u, int wr, int wc, int fr, int fq) const {
;     ...
;         if (pn == 14) {
;             if (wc == 0 && fq == 0) {
;                 const f32x4 fb0 = *(const f32x4*)fbias, fb1 = *(const f32x4*)(fbias + 4);
; #pragma unroll
;                 for (int ai = 0; ai < 2; ++ai)
; #pragma unroll
;                     for (int m = 0; m < 4; ++m) {
;                         const int row = row0 + ai * 128 + m * 16;
;                         const f32x4 sv = *(const f32x4*)(ssq + (size_t)row * 16), sv1 = *(const f32x4*)(ssq + (size_t)row * 16 + 4), sv2 = *(const f32x4*)(ssq + (size_t)row * 16 + 8), sv3 = *(const f32x4*)(ssq + (size_t)row * 16 + 12);
;                         const float st = ((sv[0] + sv[1]) + (sv[2] + sv[3])) + ((sv1[0] + sv1[1]) + (sv1[2] + sv1[3])) + ((sv2[0] + sv2[1]) + (sv2[2] + sv2[3])) + ((sv3[0] + sv3[1]) + (sv3[2] + sv3[3]));
;                         const float rs = __builtin_amdgcn_rsqf(st * (1.f / DM) + EPS);
;                         f32x4 a = acc[ai][0][m][0] * rs, b = acc[ai][0][m][1] * rs;
; #pragma unroll
;                         for (int i = 0; i < 4; ++i) { a[i] = logsig_f(a[i] + fb0[i]) * LOG2E; b[i] = logsig_f(b[i] + fb1[i]) * LOG2E; }
;                         *(f32x4*)(FF + (size_t)row * 8) = a; *(f32x4*)(FF + (size_t)row * 8 + 4) = b;
;                         asm volatile("" ::: "memory");
;                     }
;             }
;             return;
	v_mov_b32_e32 v34, v19
	v_mov_b32_e32 v35, v20
	v_mov_b32_e32 v19, v21
	v_mov_b32_e32 v20, v23
	v_mov_b32_e32 v21, v24
	v_mov_b32_e32 v23, v25
	v_pk_add_f32 v[18:19], v[34:35], v[18:19]
	v_pk_add_f32 v[20:21], v[20:21], v[22:23]
	v_pk_add_f32 v[18:19], v[18:19], v[18:19] op_sel:[0,1] op_sel_hi:[1,0]
	v_pk_add_f32 v[20:21], v[20:21], v[20:21] op_sel:[0,1] op_sel_hi:[1,0]
	v_add_f32_e32 v22, v26, v27
	v_add_f32_e32 v24, v28, v29
	v_mov_b32_e32 v19, v30
	v_mov_b32_e32 v21, v31
	v_mov_b32_e32 v23, v32
	v_mov_b32_e32 v25, v33
	v_pk_add_f32 v[18:19], v[18:19], v[20:21]
	v_pk_add_f32 v[20:21], v[22:23], v[24:25]
	s_nop 0
	v_pk_add_f32 v[18:19], v[18:19], v[20:21]
	s_nop 0
	v_add_f32_e32 v18, v18, v19
	v_fmamk_f32 v18, v18, 0x3a800000, v212
	v_rsq_f32_e32 v20, v18
	s_nop 0
	v_pk_mul_f32 v[12:13], v[12:13], v[20:21] op_sel_hi:[1,0]
	v_pk_mul_f32 v[18:19], v[14:15], v[20:21] op_sel_hi:[1,0]
	v_add_f32_e32 v14, v68, v12
	v_min_f32_e32 v12, 0, v14
	v_mul_f32_e64 v14, |v14|, s57
	v_exp_f32_e32 v14, v14
	v_pk_mul_f32 v[8:9], v[8:9], v[20:21] op_sel_hi:[1,0]
	v_pk_mul_f32 v[10:11], v[10:11], v[20:21] op_sel_hi:[1,0]
	v_add_f32_e32 v14, 1.0, v14
	v_cmp_gt_f32_e32 vcc, s97, v14
	s_nop 1
	v_cndmask_b32_e64 v15, 0, 32, vcc
	v_ldexp_f32 v14, v14, v15
	v_log_f32_e32 v14, v14
	s_nop 0
	v_mul_f32_e32 v15, 0x3f317217, v14
	v_fma_f32 v15, v14, s52, -v15
	v_fmac_f32_e32 v15, 0x3377d1cf, v14
	v_fmac_f32_e32 v15, 0x3f317217, v14
	v_cmp_lt_f32_e64 s[8:9], |v14|, s53
	s_nop 1
	v_cndmask_b32_e64 v14, v14, v15, s[8:9]
	v_cndmask_b32_e32 v15, 0, v216, vcc
	v_sub_f32_e32 v20, v14, v15
	v_add_f32_e32 v14, v64, v8
	v_min_f32_e32 v8, 0, v14
	v_mul_f32_e64 v14, |v14|, s57
	v_exp_f32_e32 v14, v14
	s_nop 0
	v_add_f32_e32 v14, 1.0, v14
	v_cmp_gt_f32_e32 vcc, s97, v14
	s_nop 1
	v_cndmask_b32_e64 v15, 0, 32, vcc
	v_ldexp_f32 v14, v14, v15
	v_log_f32_e32 v14, v14
	s_nop 0
	v_mul_f32_e32 v15, 0x3f317217, v14
	v_fma_f32 v15, v14, s52, -v15
	v_fmac_f32_e32 v15, 0x3377d1cf, v14
	v_fmac_f32_e32 v15, 0x3f317217, v14
	v_cmp_lt_f32_e64 s[8:9], |v14|, s53
	s_nop 1
	v_cndmask_b32_e64 v14, v14, v15, s[8:9]
	v_cndmask_b32_e32 v15, 0, v216, vcc
	v_sub_f32_e32 v14, v14, v15
	v_add_f32_e32 v15, v69, v13
	v_min_f32_e32 v13, 0, v15
	v_mul_f32_e64 v15, |v15|, s57
	v_exp_f32_e32 v15, v15
	s_nop 0
	v_add_f32_e32 v15, 1.0, v15
	v_cmp_gt_f32_e32 vcc, s97, v15
	s_nop 1
	v_cndmask_b32_e64 v21, 0, 32, vcc
	v_ldexp_f32 v15, v15, v21
	v_log_f32_e32 v15, v15
	s_nop 0
	v_mul_f32_e32 v21, 0x3f317217, v15
	v_fma_f32 v21, v15, s52, -v21
	v_fmac_f32_e32 v21, 0x3377d1cf, v15
	v_fmac_f32_e32 v21, 0x3f317217, v15
	v_cmp_lt_f32_e64 s[8:9], |v15|, s53
	s_nop 1
	v_cndmask_b32_e64 v15, v15, v21, s[8:9]
	v_cndmask_b32_e32 v21, 0, v216, vcc
	v_sub_f32_e32 v21, v15, v21
	v_add_f32_e32 v15, v65, v9
	v_min_f32_e32 v9, 0, v15
	v_mul_f32_e64 v15, |v15|, s57
	v_exp_f32_e32 v15, v15
	v_pk_add_f32 v[12:13], v[12:13], v[20:21] neg_lo:[0,1] neg_hi:[0,1]
	v_add_f32_e32 v15, 1.0, v15
	v_cmp_gt_f32_e32 vcc, s97, v15
	s_nop 1
	v_cndmask_b32_e64 v22, 0, 32, vcc
	v_ldexp_f32 v15, v15, v22
	v_log_f32_e32 v15, v15
	s_nop 0
	v_mul_f32_e32 v22, 0x3f317217, v15
	v_fma_f32 v22, v15, s52, -v22
	v_fmac_f32_e32 v22, 0x3377d1cf, v15
	v_fmac_f32_e32 v22, 0x3f317217, v15
	v_cmp_lt_f32_e64 s[8:9], |v15|, s53
	s_nop 1
	v_cndmask_b32_e64 v15, v15, v22, s[8:9]
	v_cndmask_b32_e32 v22, 0, v216, vcc
	v_sub_f32_e32 v15, v15, v22
	v_add_f32_e32 v22, v70, v18
	v_min_f32_e32 v18, 0, v22
	v_mul_f32_e64 v22, |v22|, s57
	v_exp_f32_e32 v22, v22
	v_pk_add_f32 v[8:9], v[8:9], v[14:15] neg_lo:[0,1] neg_hi:[0,1]
	v_add_f32_e32 v22, 1.0, v22
	v_cmp_gt_f32_e32 vcc, s97, v22
	v_pk_mul_f32 v[8:9], v[8:9], s[2:3] op_sel_hi:[1,0]
	s_nop 0
	v_cndmask_b32_e64 v23, 0, 32, vcc
	v_ldexp_f32 v22, v22, v23
	v_log_f32_e32 v22, v22
	s_nop 0
	v_mul_f32_e32 v23, 0x3f317217, v22
	v_fma_f32 v23, v22, s52, -v23
	v_fmac_f32_e32 v23, 0x3377d1cf, v22
	v_fmac_f32_e32 v23, 0x3f317217, v22
	v_cmp_lt_f32_e64 s[8:9], |v22|, s53
	s_nop 1
	v_cndmask_b32_e64 v22, v22, v23, s[8:9]
	v_cndmask_b32_e32 v23, 0, v216, vcc
	v_sub_f32_e32 v22, v22, v23
	v_add_f32_e32 v23, v66, v10
	v_min_f32_e32 v10, 0, v23
	v_mul_f32_e64 v23, |v23|, s57
	v_exp_f32_e32 v23, v23
	s_nop 0
	v_add_f32_e32 v23, 1.0, v23
	v_cmp_gt_f32_e32 vcc, s97, v23
	s_nop 1
	v_cndmask_b32_e64 v24, 0, 32, vcc
	v_ldexp_f32 v23, v23, v24
	v_log_f32_e32 v23, v23
	s_nop 0
	v_mul_f32_e32 v24, 0x3f317217, v23
	v_fma_f32 v24, v23, s52, -v24
	v_fmac_f32_e32 v24, 0x3377d1cf, v23
	v_fmac_f32_e32 v24, 0x3f317217, v23
	v_cmp_lt_f32_e64 s[8:9], |v23|, s53
	s_nop 1
	v_cndmask_b32_e64 v23, v23, v24, s[8:9]
	v_cndmask_b32_e32 v24, 0, v216, vcc
	v_sub_f32_e32 v24, v23, v24
	v_add_f32_e32 v23, v71, v19
	v_min_f32_e32 v19, 0, v23
	v_mul_f32_e64 v23, |v23|, s57
	v_exp_f32_e32 v23, v23
	s_nop 0
	v_add_f32_e32 v23, 1.0, v23
	v_cmp_gt_f32_e32 vcc, s97, v23
	s_nop 1
	v_cndmask_b32_e64 v25, 0, 32, vcc
	v_ldexp_f32 v23, v23, v25
	v_log_f32_e32 v23, v23
	s_nop 0
	v_mul_f32_e32 v25, 0x3f317217, v23
	v_fma_f32 v25, v23, s52, -v25
	v_fmac_f32_e32 v25, 0x3377d1cf, v23
	v_fmac_f32_e32 v25, 0x3f317217, v23
	v_cmp_lt_f32_e64 s[8:9], |v23|, s53
	s_nop 1
	v_cndmask_b32_e64 v23, v23, v25, s[8:9]
	v_cndmask_b32_e32 v25, 0, v216, vcc
	v_sub_f32_e32 v23, v23, v25
	v_pk_add_f32 v[18:19], v[18:19], v[22:23] neg_lo:[0,1] neg_hi:[0,1]
	s_nop 0
	v_pk_mul_f32 v[20:21], v[18:19], s[2:3] op_sel_hi:[1,0]
	v_pk_mul_f32 v[18:19], v[12:13], s[2:3] op_sel_hi:[1,0]
	v_add_f32_e32 v12, v67, v11
	v_min_f32_e32 v11, 0, v12
	v_mul_f32_e64 v12, |v12|, s57
	v_exp_f32_e32 v12, v12
	s_nop 0
	v_add_f32_e32 v12, 1.0, v12
	v_cmp_gt_f32_e32 vcc, s97, v12
	s_nop 1
	v_cndmask_b32_e64 v13, 0, 32, vcc
	v_ldexp_f32 v12, v12, v13
	v_log_f32_e32 v12, v12
	s_nop 0
	v_mul_f32_e32 v13, 0x3f317217, v12
	v_fma_f32 v13, v12, s52, -v13
	v_fmac_f32_e32 v13, 0x3377d1cf, v12
	v_fmac_f32_e32 v13, 0x3f317217, v12
	v_cmp_lt_f32_e64 s[8:9], |v12|, s53
	s_nop 1
	v_cndmask_b32_e64 v12, v12, v13, s[8:9]
	v_cndmask_b32_e32 v13, 0, v216, vcc
	v_sub_f32_e32 v25, v12, v13
	v_lshlrev_b64 v[12:13], 5, v[16:17]
	v_pk_add_f32 v[10:11], v[10:11], v[24:25] neg_lo:[0,1] neg_hi:[0,1]
	v_lshl_add_u64 v[12:13], s[42:43], 0, v[12:13]
	v_pk_mul_f32 v[10:11], v[10:11], s[2:3] op_sel_hi:[1,0]
	flat_store_dwordx4 v[12:13], v[18:21] sc1
	flat_store_dwordx4 v[12:13], v[8:11] offset:16 sc1
	s_nop 1
	v_add_u32_e32 v8, 0xb0, v166
	v_ashrrev_i32_e32 v9, 31, v8
	v_lshlrev_b64 v[10:11], 6, v[8:9]
	v_lshl_add_u64 v[22:23], s[82:83], 0, v[10:11]
	flat_load_dwordx4 v[10:13], v[22:23]
	flat_load_dwordx4 v[14:17], v[22:23] offset:16
	flat_load_dwordx4 v[18:21], v[22:23] offset:32
	s_nop 0
	flat_load_dwordx4 v[22:25], v[22:23] offset:48
	s_waitcnt vmcnt(0) lgkmcnt(0)
; __device__ __forceinline__ float logsig_f(float x) { return fminf(x, 0.f) - __logf(1.f + __expf(-fabsf(x))); }
;     __device__ __forceinline__ void operator()(const f32x4 (&acc)[2][2][4][2], const pg8::Unit& u, int wr, int wc, int fr, int fq) const {
;     ...
;         if (pn == 14) {
;             if (wc == 0 && fq == 0) {
;                 const f32x4 fb0 = *(const f32x4*)fbias, fb1 = *(const f32x4*)(fbias + 4);
; #pragma unroll
;                 for (int ai = 0; ai < 2; ++ai)
; #pragma unroll
;                     for (int m = 0; m < 4; ++m) {
;                         const int row = row0 + ai * 128 + m * 16;
;                         const f32x4 sv = *(const f32x4*)(ssq + (size_t)row * 16), sv1 = *(const f32x4*)(ssq + (size_t)row * 16 + 4), sv2 = *(const f32x4*)(ssq + (size_t)row * 16 + 8), sv3 = *(const f32x4*)(ssq + (size_t)row * 16 + 12);
;                         const float st = ((sv[0] + sv[1]) + (sv[2] + sv[3])) + ((sv1[0] + sv1[1]) + (sv1[2] + sv1[3])) + ((sv2[0] + sv2[1]) + (sv2[2] + sv2[3])) + ((sv3[0] + sv3[1]) + (sv3[2] + sv3[3]));
;                         const float rs = __builtin_amdgcn_rsqf(st * (1.f / DM) + EPS);
;                         f32x4 a = acc[ai][0][m][0] * rs, b = acc[ai][0][m][1] * rs;
; #pragma unroll
;                         for (int i = 0; i < 4; ++i) { a[i] = logsig_f(a[i] + fb0[i]) * LOG2E; b[i] = logsig_f(b[i] + fb1[i]) * LOG2E; }
;                         *(f32x4*)(FF + (size_t)row * 8) = a; *(f32x4*)(FF + (size_t)row * 8 + 4) = b;
;                         asm volatile("" ::: "memory");
;                     }
;             }
;             return;
	v_mov_b32_e32 v26, v11
	v_mov_b32_e32 v27, v12
	v_mov_b32_e32 v11, v13
	v_mov_b32_e32 v12, v15
	v_mov_b32_e32 v13, v16
	v_mov_b32_e32 v15, v17
	v_pk_add_f32 v[10:11], v[26:27], v[10:11]
	v_pk_add_f32 v[12:13], v[12:13], v[14:15]
	v_pk_add_f32 v[10:11], v[10:11], v[10:11] op_sel:[0,1] op_sel_hi:[1,0]
	v_pk_add_f32 v[12:13], v[12:13], v[12:13] op_sel:[0,1] op_sel_hi:[1,0]
	v_add_f32_e32 v14, v18, v19
	v_add_f32_e32 v16, v20, v21
	v_mov_b32_e32 v11, v22
	v_mov_b32_e32 v13, v23
	v_mov_b32_e32 v15, v24
	v_mov_b32_e32 v17, v25
	v_pk_add_f32 v[10:11], v[10:11], v[12:13]
	v_pk_add_f32 v[12:13], v[14:15], v[16:17]
	s_nop 0
	v_pk_add_f32 v[10:11], v[10:11], v[12:13]
	s_nop 0
	v_add_f32_e32 v10, v10, v11
	v_fmamk_f32 v10, v10, 0x3a800000, v212
	v_rsq_f32_e32 v12, v10
	s_nop 0
	v_pk_mul_f32 v[4:5], v[4:5], v[12:13] op_sel_hi:[1,0]
	v_pk_mul_f32 v[10:11], v[6:7], v[12:13] op_sel_hi:[1,0]
	v_add_f32_e32 v6, v68, v4
	v_min_f32_e32 v4, 0, v6
	v_mul_f32_e64 v6, |v6|, s57
	v_exp_f32_e32 v6, v6
	v_pk_mul_f32 v[0:1], v[0:1], v[12:13] op_sel_hi:[1,0]
	v_pk_mul_f32 v[2:3], v[2:3], v[12:13] op_sel_hi:[1,0]
	v_add_f32_e32 v6, 1.0, v6
	v_cmp_gt_f32_e32 vcc, s97, v6
	s_nop 1
	v_cndmask_b32_e64 v7, 0, 32, vcc
	v_ldexp_f32 v6, v6, v7
	v_log_f32_e32 v6, v6
	s_nop 0
	v_mul_f32_e32 v7, 0x3f317217, v6
	v_fma_f32 v7, v6, s52, -v7
	v_fmac_f32_e32 v7, 0x3377d1cf, v6
	v_fmac_f32_e32 v7, 0x3f317217, v6
	v_cmp_lt_f32_e64 s[8:9], |v6|, s53
	s_nop 1
	v_cndmask_b32_e64 v6, v6, v7, s[8:9]
	v_cndmask_b32_e32 v7, 0, v216, vcc
	v_sub_f32_e32 v12, v6, v7
	v_add_f32_e32 v6, v64, v0
	v_min_f32_e32 v0, 0, v6
	v_mul_f32_e64 v6, |v6|, s57
	v_exp_f32_e32 v6, v6
	s_nop 0
	v_add_f32_e32 v6, 1.0, v6
	v_cmp_gt_f32_e32 vcc, s97, v6
	s_nop 1
	v_cndmask_b32_e64 v7, 0, 32, vcc
	v_ldexp_f32 v6, v6, v7
	v_log_f32_e32 v6, v6
	s_nop 0
	v_mul_f32_e32 v7, 0x3f317217, v6
	v_fma_f32 v7, v6, s52, -v7
	v_fmac_f32_e32 v7, 0x3377d1cf, v6
	v_fmac_f32_e32 v7, 0x3f317217, v6
	v_cmp_lt_f32_e64 s[8:9], |v6|, s53
	s_nop 1
	v_cndmask_b32_e64 v6, v6, v7, s[8:9]
	v_cndmask_b32_e32 v7, 0, v216, vcc
	v_sub_f32_e32 v6, v6, v7
	v_add_f32_e32 v7, v69, v5
	v_min_f32_e32 v5, 0, v7
	v_mul_f32_e64 v7, |v7|, s57
	v_exp_f32_e32 v7, v7
	s_nop 0
	v_add_f32_e32 v7, 1.0, v7
	v_cmp_gt_f32_e32 vcc, s97, v7
	s_nop 1
	v_cndmask_b32_e64 v13, 0, 32, vcc
	v_ldexp_f32 v7, v7, v13
	v_log_f32_e32 v7, v7
	s_nop 0
	v_mul_f32_e32 v13, 0x3f317217, v7
	v_fma_f32 v13, v7, s52, -v13
	v_fmac_f32_e32 v13, 0x3377d1cf, v7
	v_fmac_f32_e32 v13, 0x3f317217, v7
	v_cmp_lt_f32_e64 s[8:9], |v7|, s53
	s_nop 1
	v_cndmask_b32_e64 v7, v7, v13, s[8:9]
	v_cndmask_b32_e32 v13, 0, v216, vcc
	v_sub_f32_e32 v13, v7, v13
	v_add_f32_e32 v7, v65, v1
	v_min_f32_e32 v1, 0, v7
	v_mul_f32_e64 v7, |v7|, s57
	v_exp_f32_e32 v7, v7
	v_pk_add_f32 v[4:5], v[4:5], v[12:13] neg_lo:[0,1] neg_hi:[0,1]
	v_add_f32_e32 v7, 1.0, v7
	v_cmp_gt_f32_e32 vcc, s97, v7
	s_nop 1
	v_cndmask_b32_e64 v14, 0, 32, vcc
	v_ldexp_f32 v7, v7, v14
	v_log_f32_e32 v7, v7
	s_nop 0
	v_mul_f32_e32 v14, 0x3f317217, v7
	v_fma_f32 v14, v7, s52, -v14
	v_fmac_f32_e32 v14, 0x3377d1cf, v7
	v_fmac_f32_e32 v14, 0x3f317217, v7
	v_cmp_lt_f32_e64 s[8:9], |v7|, s53
	s_nop 1
	v_cndmask_b32_e64 v7, v7, v14, s[8:9]
	v_cndmask_b32_e32 v14, 0, v216, vcc
	v_sub_f32_e32 v7, v7, v14
	v_add_f32_e32 v14, v70, v10
	v_min_f32_e32 v10, 0, v14
	v_mul_f32_e64 v14, |v14|, s57
	v_exp_f32_e32 v14, v14
	v_pk_add_f32 v[0:1], v[0:1], v[6:7] neg_lo:[0,1] neg_hi:[0,1]
	v_add_f32_e32 v14, 1.0, v14
	v_cmp_gt_f32_e32 vcc, s97, v14
	v_pk_mul_f32 v[0:1], v[0:1], s[2:3] op_sel_hi:[1,0]
	s_nop 0
	v_cndmask_b32_e64 v15, 0, 32, vcc
	v_ldexp_f32 v14, v14, v15
	v_log_f32_e32 v14, v14
	s_nop 0
	v_mul_f32_e32 v15, 0x3f317217, v14
	v_fma_f32 v15, v14, s52, -v15
	v_fmac_f32_e32 v15, 0x3377d1cf, v14
	v_fmac_f32_e32 v15, 0x3f317217, v14
	v_cmp_lt_f32_e64 s[8:9], |v14|, s53
	s_nop 1
	v_cndmask_b32_e64 v14, v14, v15, s[8:9]
	v_cndmask_b32_e32 v15, 0, v216, vcc
	v_sub_f32_e32 v14, v14, v15
	v_add_f32_e32 v15, v66, v2
	v_min_f32_e32 v2, 0, v15
	v_mul_f32_e64 v15, |v15|, s57
	v_exp_f32_e32 v15, v15
	s_nop 0
	v_add_f32_e32 v15, 1.0, v15
	v_cmp_gt_f32_e32 vcc, s97, v15
	s_nop 1
	v_cndmask_b32_e64 v16, 0, 32, vcc
	v_ldexp_f32 v15, v15, v16
	v_log_f32_e32 v15, v15
	s_nop 0
	v_mul_f32_e32 v16, 0x3f317217, v15
	v_fma_f32 v16, v15, s52, -v16
	v_fmac_f32_e32 v16, 0x3377d1cf, v15
	v_fmac_f32_e32 v16, 0x3f317217, v15
	v_cmp_lt_f32_e64 s[8:9], |v15|, s53
	s_nop 1
	v_cndmask_b32_e64 v15, v15, v16, s[8:9]
	v_cndmask_b32_e32 v16, 0, v216, vcc
	v_sub_f32_e32 v16, v15, v16
	v_add_f32_e32 v15, v71, v11
	v_min_f32_e32 v11, 0, v15
	v_mul_f32_e64 v15, |v15|, s57
	v_exp_f32_e32 v15, v15
	s_nop 0
	v_add_f32_e32 v15, 1.0, v15
	v_cmp_gt_f32_e32 vcc, s97, v15
	s_nop 1
	v_cndmask_b32_e64 v17, 0, 32, vcc
	v_ldexp_f32 v15, v15, v17
	v_log_f32_e32 v15, v15
	s_nop 0
	v_mul_f32_e32 v17, 0x3f317217, v15
	v_fma_f32 v17, v15, s52, -v17
	v_fmac_f32_e32 v17, 0x3377d1cf, v15
	v_fmac_f32_e32 v17, 0x3f317217, v15
	v_cmp_lt_f32_e64 s[8:9], |v15|, s53
	s_nop 1
	v_cndmask_b32_e64 v15, v15, v17, s[8:9]
	v_cndmask_b32_e32 v17, 0, v216, vcc
	v_sub_f32_e32 v15, v15, v17
	v_pk_add_f32 v[10:11], v[10:11], v[14:15] neg_lo:[0,1] neg_hi:[0,1]
	s_nop 0
	v_pk_mul_f32 v[12:13], v[10:11], s[2:3] op_sel_hi:[1,0]
	v_pk_mul_f32 v[10:11], v[4:5], s[2:3] op_sel_hi:[1,0]
	v_add_f32_e32 v4, v67, v3
	v_min_f32_e32 v3, 0, v4
	v_mul_f32_e64 v4, |v4|, s57
	v_exp_f32_e32 v4, v4
	s_nop 0
	v_add_f32_e32 v4, 1.0, v4
	v_cmp_gt_f32_e32 vcc, s97, v4
	s_nop 1
	v_cndmask_b32_e64 v5, 0, 32, vcc
	v_ldexp_f32 v4, v4, v5
	v_log_f32_e32 v4, v4
	s_nop 0
	v_mul_f32_e32 v5, 0x3f317217, v4
	v_fma_f32 v5, v4, s52, -v5
	v_fmac_f32_e32 v5, 0x3377d1cf, v4
	v_fmac_f32_e32 v5, 0x3f317217, v4
	v_cmp_lt_f32_e64 s[8:9], |v4|, s53
	s_nop 1
	v_cndmask_b32_e64 v4, v4, v5, s[8:9]
	v_cndmask_b32_e32 v5, 0, v216, vcc
	v_sub_f32_e32 v17, v4, v5
	v_lshlrev_b64 v[4:5], 5, v[8:9]
	v_pk_add_f32 v[2:3], v[2:3], v[16:17] neg_lo:[0,1] neg_hi:[0,1]
	v_lshl_add_u64 v[4:5], s[42:43], 0, v[4:5]
	v_pk_mul_f32 v[2:3], v[2:3], s[2:3] op_sel_hi:[1,0]
	flat_store_dwordx4 v[4:5], v[10:13] sc1
	flat_store_dwordx4 v[4:5], v[0:3] offset:16 sc1

; __device__ __forceinline__ v4u pack8(const f32x4 a, const f32x4 b) { v4u w; w.x = cvt_pk_bf16(a[0], a[1]); w.y = cvt_pk_bf16(a[2], a[3]); w.z = cvt_pk_bf16(b[0], b[1]); w.w = cvt_pk_bf16(b[2], b[3]); return w; }
;     __device__ __forceinline__ void operator()(const f32x4 (&acc)[2][2][4][2], const pg8::Unit& u, int wr, int wc, int fr, int fq) const {
;         const int hd = u.pm >> 3, b = (u.pm >> 2) & 1, q = u.pm & 3;
;         const int rowb = modeB ? q * 256 : b * 1024 + hd * 256, colb = modeB ? hd * 256 : q * 256; bf16* Ob = O + (modeB ? (size_t)b * 1024 * 1024 : 0);
; #pragma unroll
;         for (int ai = 0; ai < 2; ++ai)
; #pragma unroll
;             for (int m = 0; m < 4; ++m) { const int row = rowb + ai * 128 + wr * 64 + m * 16 + fr;
; #pragma unroll
;                 for (int bj = 0; bj < 2; ++bj) *(v4u*)(Ob + (size_t)row * 1024 + colb + bj * 128 + wc * 32 + 8 * fq) = pack8(acc[ai][bj][m][0] * scale, acc[ai][bj][m][1] * scale); }
.LBB0_435:
	s_lshl_b32 s2, s0, 8
	s_and_b32 s2, s2, 0x400
	s_or_b32 s2, s21, s2
	v_add_u32_e32 v24, s2, v129
	s_lshl_b32 s2, s0, 9
	s_and_b32 s2, s2, 0x600
	s_add_u32 s2, s4, s2
	s_addc_u32 s7, s5, 0
	s_lshl_b32 s6, s22, 1
	s_add_u32 s6, s2, s6
	s_addc_u32 s7, s7, 0
	v_mov_b32_e32 v129, v193
	v_lshl_add_u64 v[16:17], s[6:7], 0, v[128:129]
	s_mov_b64 s[6:7], 0xda00000
	v_ashrrev_i32_e32 v25, 31, v24
	v_lshl_add_u64 v[26:27], v[16:17], 0, s[6:7]
	v_lshlrev_b64 v[16:17], 11, v[24:25]
	v_lshl_add_u64 v[128:129], v[26:27], 0, v[16:17]
	v_cvt_pk_bf16_f32 v16, v124, v125
	v_cvt_pk_bf16_f32 v17, v126, v127
	v_cvt_pk_bf16_f32 v18, v120, v121
	v_cvt_pk_bf16_f32 v19, v122, v123
	flat_store_dwordx4 v[128:129], v[16:19] sc1
	s_mov_b64 s[6:7], 0x40000
	v_cvt_pk_bf16_f32 v4, v4, v5
	v_cvt_pk_bf16_f32 v16, v138, v139
	v_cvt_pk_bf16_f32 v17, v136, v137
	v_cvt_pk_bf16_f32 v18, v142, v143
	v_cvt_pk_bf16_f32 v19, v140, v141
	flat_store_dwordx4 v[128:129], v[16:19] offset:256 sc1
	v_cvt_pk_bf16_f32 v5, v6, v7
	v_cvt_pk_bf16_f32 v6, v0, v1
	v_or_b32_e32 v16, 16, v24
	v_ashrrev_i32_e32 v17, 31, v16
	v_lshlrev_b64 v[16:17], 11, v[16:17]
	v_lshl_add_u64 v[120:121], v[26:27], 0, v[16:17]
	v_cvt_pk_bf16_f32 v16, v102, v103
	v_cvt_pk_bf16_f32 v17, v100, v101
	v_cvt_pk_bf16_f32 v18, v110, v111
	v_cvt_pk_bf16_f32 v19, v108, v109
	flat_store_dwordx4 v[120:121], v[16:19] sc1
	v_cvt_pk_bf16_f32 v7, v2, v3
	s_nop 0
	v_cvt_pk_bf16_f32 v16, v114, v115
	v_cvt_pk_bf16_f32 v17, v112, v113
	v_cvt_pk_bf16_f32 v18, v118, v119
	v_cvt_pk_bf16_f32 v19, v116, v117
	flat_store_dwordx4 v[120:121], v[16:19] offset:256 sc1
	s_nop 1
	v_or_b32_e32 v16, 32, v24
	v_ashrrev_i32_e32 v17, 31, v16
	v_lshlrev_b64 v[16:17], 11, v[16:17]
	v_lshl_add_u64 v[100:101], v[26:27], 0, v[16:17]
	v_cvt_pk_bf16_f32 v16, v86, v87
	v_cvt_pk_bf16_f32 v17, v84, v85
	v_cvt_pk_bf16_f32 v18, v94, v95
	v_cvt_pk_bf16_f32 v19, v92, v93
	flat_store_dwordx4 v[100:101], v[16:19] sc1
	s_nop 1
	v_cvt_pk_bf16_f32 v16, v98, v99
	v_cvt_pk_bf16_f32 v17, v96, v97
	v_cvt_pk_bf16_f32 v18, v106, v107
	v_cvt_pk_bf16_f32 v19, v104, v105
	flat_store_dwordx4 v[100:101], v[16:19] offset:256 sc1
	s_nop 1
	v_or_b32_e32 v16, 48, v24
	v_ashrrev_i32_e32 v17, 31, v16
	v_lshlrev_b64 v[16:17], 11, v[16:17]
	v_lshl_add_u64 v[24:25], v[26:27], 0, v[16:17]
	v_cvt_pk_bf16_f32 v16, v74, v75
	v_cvt_pk_bf16_f32 v17, v72, v73
	v_cvt_pk_bf16_f32 v18, v78, v79
	v_cvt_pk_bf16_f32 v19, v76, v77
	flat_store_dwordx4 v[24:25], v[16:19] sc1
	v_add_co_u32_e32 v26, vcc, s54, v128
	s_nop 0
	v_cvt_pk_bf16_f32 v16, v68, v69
	v_cvt_pk_bf16_f32 v17, v70, v71
	v_cvt_pk_bf16_f32 v18, v64, v65
	v_cvt_pk_bf16_f32 v19, v66, v67
	flat_store_dwordx4 v[24:25], v[16:19] offset:256 sc1
	v_addc_co_u32_e32 v27, vcc, 0, v129, vcc
	s_nop 0
	v_cvt_pk_bf16_f32 v16, v60, v61
	v_cvt_pk_bf16_f32 v17, v62, v63
	v_cvt_pk_bf16_f32 v18, v56, v57
	v_cvt_pk_bf16_f32 v19, v58, v59
	v_lshl_add_u64 v[24:25], v[128:129], 0, s[6:7]
	flat_store_dwordx4 v[26:27], v[16:19] sc1
	v_add_co_u32_e32 v26, vcc, s55, v128
	s_nop 0
	v_cvt_pk_bf16_f32 v16, v82, v83
	v_cvt_pk_bf16_f32 v17, v80, v81
	v_cvt_pk_bf16_f32 v18, v90, v91
	v_cvt_pk_bf16_f32 v19, v88, v89
	flat_store_dwordx4 v[24:25], v[16:19] offset:256 sc1
	s_mov_b64 s[6:7], 0x48000
	v_addc_co_u32_e32 v27, vcc, 0, v129, vcc
	v_cvt_pk_bf16_f32 v16, v38, v39
	v_cvt_pk_bf16_f32 v17, v36, v37
	v_cvt_pk_bf16_f32 v18, v46, v47
	v_cvt_pk_bf16_f32 v19, v44, v45
	v_lshl_add_u64 v[24:25], v[128:129], 0, s[6:7]
	flat_store_dwordx4 v[26:27], v[16:19] sc1
	s_mov_b64 s[6:7], 0x50000
	s_nop 0
	v_cvt_pk_bf16_f32 v16, v50, v51
	v_cvt_pk_bf16_f32 v17, v48, v49
	v_cvt_pk_bf16_f32 v18, v54, v55
	v_cvt_pk_bf16_f32 v19, v52, v53
	flat_store_dwordx4 v[24:25], v[16:19] offset:256 sc1
	v_lshl_add_u64 v[24:25], v[128:129], 0, s[6:7]
	s_mov_b64 s[6:7], 0x58000
	v_cvt_pk_bf16_f32 v17, v20, v21
	v_add_co_u32_e32 v20, vcc, s86, v128
	v_cvt_pk_bf16_f32 v16, v22, v23
	v_cvt_pk_bf16_f32 v18, v30, v31
	v_cvt_pk_bf16_f32 v19, v28, v29
	v_addc_co_u32_e32 v21, vcc, 0, v129, vcc
	flat_store_dwordx4 v[20:21], v[16:19] sc1
	v_lshl_add_u64 v[20:21], v[128:129], 0, s[6:7]
	flat_store_dwordx4 v[20:21], v[4:7] offset:256 sc1
	v_cvt_pk_bf16_f32 v16, v34, v35
	v_cvt_pk_bf16_f32 v17, v32, v33
	v_cvt_pk_bf16_f32 v18, v42, v43
	v_cvt_pk_bf16_f32 v19, v40, v41
	flat_store_dwordx4 v[24:25], v[16:19] offset:256 sc1
	s_nop 1
	v_cvt_pk_bf16_f32 v17, v8, v9
	v_add_co_u32_e32 v8, vcc, s87, v128
	v_cvt_pk_bf16_f32 v16, v10, v11
	v_cvt_pk_bf16_f32 v18, v14, v15
	v_cvt_pk_bf16_f32 v19, v12, v13
	v_addc_co_u32_e32 v9, vcc, 0, v129, vcc
	flat_store_dwordx4 v[8:9], v[16:19] sc1
	s_waitcnt vmcnt(0)
	s_barrier

; __device__ __forceinline__ v4u pack8(const f32x4 a, const f32x4 b) { v4u w; w.x = cvt_pk_bf16(a[0], a[1]); w.y = cvt_pk_bf16(a[2], a[3]); w.z = cvt_pk_bf16(b[0], b[1]); w.w = cvt_pk_bf16(b[2], b[3]); return w; }
;     __device__ __forceinline__ void operator()(const f32x4 (&acc)[2][2][4][2], const pg8::Unit& u, int wr, int wc, int fr, int fq) const {
;         const int hd = u.pm >> 3, b = (u.pm >> 2) & 1, q = u.pm & 3;
;         const int rowb = modeB ? q * 256 : b * 1024 + hd * 256, colb = modeB ? hd * 256 : q * 256; bf16* Ob = O + (modeB ? (size_t)b * 1024 * 1024 : 0);
; #pragma unroll
;         for (int ai = 0; ai < 2; ++ai)
; #pragma unroll
;             for (int m = 0; m < 4; ++m) { const int row = rowb + ai * 128 + wr * 64 + m * 16 + fr;
; #pragma unroll
;                 for (int bj = 0; bj < 2; ++bj) *(v4u*)(Ob + (size_t)row * 1024 + colb + bj * 128 + wc * 32 + 8 * fq) = pack8(acc[ai][bj][m][0] * scale, acc[ai][bj][m][1] * scale); }
.LBB0_444:
	s_lshl_b32 s1, s0, 8
	s_lshl_b32 s0, s0, 19
	s_and_b32 s1, s1, 0x300
	s_and_b32 s0, s0, 0x200000
	s_add_u32 s0, s4, s0
	s_addc_u32 s2, s5, 0
	v_add_u32_e32 v130, s1, v129
	s_lshl_b32 s1, s21, 1
	s_add_u32 s0, s0, s1
	s_addc_u32 s1, s2, 0
	s_lshl_b32 s2, s18, 1
	s_add_u32 s0, s0, s2
	s_addc_u32 s1, s1, 0
	v_mov_b32_e32 v129, v193
	v_lshl_add_u64 v[128:129], s[0:1], 0, v[128:129]
	s_mov_b64 s[0:1], 0xde00000
	v_ashrrev_i32_e32 v131, 31, v130
	v_lshl_add_u64 v[128:129], v[128:129], 0, s[0:1]
	v_lshlrev_b64 v[132:133], 11, v[130:131]
	v_lshl_add_u64 v[132:133], v[128:129], 0, v[132:133]
	v_cvt_pk_bf16_f32 v60, v60, v61
	v_cvt_pk_bf16_f32 v61, v62, v63
	v_cvt_pk_bf16_f32 v62, v56, v57
	v_add_co_u32_e32 v56, vcc, s54, v132
	v_cvt_pk_bf16_f32 v44, v44, v45
	s_nop 0
	v_addc_co_u32_e32 v57, vcc, 0, v133, vcc
	v_cvt_pk_bf16_f32 v45, v46, v47
	v_cvt_pk_bf16_f32 v46, v40, v41
	v_add_co_u32_e32 v40, vcc, s55, v132
	s_mov_b64 s[0:1], 0x40000
	s_nop 0
	v_addc_co_u32_e32 v41, vcc, 0, v133, vcc
	v_cvt_pk_bf16_f32 v116, v116, v117
	v_cvt_pk_bf16_f32 v117, v118, v119
	v_cvt_pk_bf16_f32 v118, v112, v113
	v_or_b32_e32 v112, 16, v130
	v_cvt_pk_bf16_f32 v100, v100, v101
	v_cvt_pk_bf16_f32 v101, v102, v103
	v_cvt_pk_bf16_f32 v102, v96, v97
	v_or_b32_e32 v96, 32, v130
	v_cvt_pk_bf16_f32 v84, v84, v85
	v_cvt_pk_bf16_f32 v85, v86, v87
	v_cvt_pk_bf16_f32 v86, v80, v81
	v_or_b32_e32 v80, 48, v130
	v_cvt_pk_bf16_f32 v68, v68, v69
	v_cvt_pk_bf16_f32 v69, v70, v71
	v_cvt_pk_bf16_f32 v70, v64, v65
	v_lshl_add_u64 v[64:65], v[132:133], 0, s[0:1]
	s_mov_b64 s[0:1], 0x48000
	v_cvt_pk_bf16_f32 v28, v28, v29
	v_cvt_pk_bf16_f32 v29, v30, v31
	v_cvt_pk_bf16_f32 v30, v24, v25
	v_add_co_u32_e32 v24, vcc, s86, v132
	v_ashrrev_i32_e32 v113, 31, v112
	v_ashrrev_i32_e32 v97, 31, v96
	v_ashrrev_i32_e32 v81, 31, v80
	v_cvt_pk_bf16_f32 v52, v52, v53
	v_cvt_pk_bf16_f32 v53, v54, v55
	v_cvt_pk_bf16_f32 v54, v48, v49
	v_lshl_add_u64 v[48:49], v[132:133], 0, s[0:1]
	s_mov_b64 s[0:1], 0x50000
	v_addc_co_u32_e32 v25, vcc, 0, v133, vcc
	v_lshlrev_b64 v[112:113], 11, v[112:113]
	v_lshlrev_b64 v[96:97], 11, v[96:97]
	v_lshlrev_b64 v[80:81], 11, v[80:81]
	v_cvt_pk_bf16_f32 v36, v36, v37
	v_cvt_pk_bf16_f32 v37, v38, v39
	v_cvt_pk_bf16_f32 v38, v32, v33
	v_lshl_add_u64 v[32:33], v[132:133], 0, s[0:1]
	s_mov_b64 s[0:1], 0x58000
	v_cvt_pk_bf16_f32 v12, v12, v13
	v_cvt_pk_bf16_f32 v13, v14, v15
	v_cvt_pk_bf16_f32 v14, v8, v9
	v_add_co_u32_e32 v8, vcc, s87, v132
	v_cvt_pk_bf16_f32 v120, v120, v121
	v_cvt_pk_bf16_f32 v121, v122, v123
	v_cvt_pk_bf16_f32 v122, v124, v125
	v_cvt_pk_bf16_f32 v123, v126, v127
	v_cvt_pk_bf16_f32 v119, v114, v115
	v_lshl_add_u64 v[112:113], v[128:129], 0, v[112:113]
	v_cvt_pk_bf16_f32 v108, v108, v109
	v_cvt_pk_bf16_f32 v109, v110, v111
	v_cvt_pk_bf16_f32 v110, v104, v105
	v_cvt_pk_bf16_f32 v111, v106, v107
	v_cvt_pk_bf16_f32 v103, v98, v99
	v_lshl_add_u64 v[96:97], v[128:129], 0, v[96:97]
	v_cvt_pk_bf16_f32 v92, v92, v93
	v_cvt_pk_bf16_f32 v93, v94, v95
	v_cvt_pk_bf16_f32 v94, v88, v89
	v_cvt_pk_bf16_f32 v95, v90, v91
	v_cvt_pk_bf16_f32 v87, v82, v83
	v_lshl_add_u64 v[80:81], v[128:129], 0, v[80:81]
	v_cvt_pk_bf16_f32 v76, v76, v77
	v_cvt_pk_bf16_f32 v77, v78, v79
	v_cvt_pk_bf16_f32 v78, v72, v73
	v_cvt_pk_bf16_f32 v79, v74, v75
	v_cvt_pk_bf16_f32 v71, v66, v67
	v_cvt_pk_bf16_f32 v63, v58, v59
	v_cvt_pk_bf16_f32 v55, v50, v51
	v_cvt_pk_bf16_f32 v47, v42, v43
	v_cvt_pk_bf16_f32 v39, v34, v35
	v_cvt_pk_bf16_f32 v31, v26, v27
	v_cvt_pk_bf16_f32 v20, v20, v21
	v_cvt_pk_bf16_f32 v21, v22, v23
	v_cvt_pk_bf16_f32 v22, v16, v17
	v_cvt_pk_bf16_f32 v23, v18, v19
	v_lshl_add_u64 v[16:17], v[132:133], 0, s[0:1]
	v_cvt_pk_bf16_f32 v15, v10, v11
	v_addc_co_u32_e32 v9, vcc, 0, v133, vcc
	v_cvt_pk_bf16_f32 v4, v4, v5
	v_cvt_pk_bf16_f32 v5, v6, v7
	v_cvt_pk_bf16_f32 v6, v0, v1
	v_cvt_pk_bf16_f32 v7, v2, v3
	flat_store_dwordx4 v[132:133], v[120:123] sc1
	flat_store_dwordx4 v[132:133], v[116:119] offset:256 sc1
	flat_store_dwordx4 v[112:113], v[108:111] sc1
	flat_store_dwordx4 v[112:113], v[100:103] offset:256 sc1
	flat_store_dwordx4 v[96:97], v[92:95] sc1
	flat_store_dwordx4 v[96:97], v[84:87] offset:256 sc1
	flat_store_dwordx4 v[80:81], v[76:79] sc1
	flat_store_dwordx4 v[80:81], v[68:71] offset:256 sc1
	flat_store_dwordx4 v[56:57], v[60:63] sc1
	flat_store_dwordx4 v[64:65], v[52:55] offset:256 sc1
	flat_store_dwordx4 v[40:41], v[44:47] sc1
	flat_store_dwordx4 v[48:49], v[36:39] offset:256 sc1
	flat_store_dwordx4 v[24:25], v[28:31] sc1
	flat_store_dwordx4 v[32:33], v[20:23] offset:256 sc1
	flat_store_dwordx4 v[8:9], v[12:15] sc1
	flat_store_dwordx4 v[16:17], v[4:7] offset:256 sc1
	s_waitcnt vmcnt(0)
	s_barrier

; __device__ __forceinline__ int crow(int r,int hi){return (r&3)+8*(r>>2)+4*hi;}
; template<int THRL> __device__ __forceinline__ void attn_unit(int b,int h,int qb,const bf16*Q,const bf16*__restrict__ K,const bf16*__restrict__ V,bf16*O,const float*__restrict__ CK,const float*__restrict__ KMX,const float*__restrict__ QSV,char*shm){
;     ...
;   float rli[16];
;   #pragma unroll
;   for(int r=0;r<16;++r)rli[r]=__builtin_amdgcn_rcpf(wsf[32+crow(r,hi)]);
;   bf16*Ow=O+(rowbase+q0+wid*QBLK)*QP+h*D;
;   { bf16*stg=(bf16*)(shm+LDS_OST)+wid*2048;
;     #pragma unroll
;     for(int r=0;r<16;++r){const int orow=crow(r,hi);
;       #pragma unroll
;       for(int d0=0;d0<2;++d0)stg[orow*64+d0*32+r32]=__float2bfloat16(o[d0][r]*rli[r]);}
;     asm volatile("s_waitcnt lgkmcnt(0)":::"memory");
;     #pragma unroll
;     for(int i=0;i<4;++i){const int row=i*8+(lane>>3),ch=lane&7; const u32x4 v=*(const u32x4*)(stg+row*64+ch*8); ATTN_STORE16(Ow+(long)row*QP+ch*8,v);} }
;   asm volatile("s_waitcnt lgkmcnt(0)\n\ts_barrier":::"memory");
.LBB0_700:
	s_or_b64 exec, exec, s[4:5]
	s_waitcnt lgkmcnt(0)
	v_add_u32_e32 v32, 0xc080, v225
	ds_read2_b32 v[32:33], v32 offset1:1
	s_lshl_b32 s2, s13, 12
	s_add_i32 s2, s28, s2
	v_lshlrev_b32_e32 v49, 9, v221
	v_lshlrev_b32_e32 v50, 1, v220
	s_waitcnt lgkmcnt(0)
	v_rcp_f32_e32 v34, v32
	v_add_u32_e32 v32, 0xc088, v225
	v_rcp_f32_e32 v35, v33
	ds_read2_b32 v[32:33], v32 offset1:1
	v_mul_f32_e32 v0, v0, v34
	v_mul_f32_e32 v16, v16, v34
	v_add3_u32 v49, s2, v49, v50
	v_cvt_pk_bf16_f32 v0, v0, s0
	s_waitcnt lgkmcnt(0)
	v_rcp_f32_e32 v36, v32
	v_add_u32_e32 v32, 0xc0a0, v225
	v_rcp_f32_e32 v37, v33
	ds_read2_b32 v[32:33], v32 offset1:1
	v_lshlrev_b32_e32 v48, 7, v222
	v_cvt_pk_bf16_f32 v16, v16, s0
	s_add_i32 s45, s45, 1
	s_mov_b64 s[4:5], 0
	s_waitcnt lgkmcnt(0)
	v_rcp_f32_e32 v38, v32
	v_add_u32_e32 v32, 0xc0a8, v225
	v_rcp_f32_e32 v39, v33
	ds_read2_b32 v[32:33], v32 offset1:1
	s_waitcnt lgkmcnt(0)
	v_rcp_f32_e32 v40, v32
	v_add_u32_e32 v32, 0xc0c0, v225
	v_rcp_f32_e32 v41, v33
	ds_read2_b32 v[32:33], v32 offset1:1
	s_waitcnt lgkmcnt(0)
	v_rcp_f32_e32 v42, v32
	v_add_u32_e32 v32, 0xc0c8, v225
	v_rcp_f32_e32 v43, v33
	ds_read2_b32 v[32:33], v32 offset1:1
	s_waitcnt lgkmcnt(0)
	v_rcp_f32_e32 v44, v32
	v_add_u32_e32 v32, 0xc0e0, v225
	v_rcp_f32_e32 v45, v33
	ds_read2_b32 v[32:33], v32 offset1:1
	s_waitcnt lgkmcnt(0)
	v_rcp_f32_e32 v46, v32
	v_add_u32_e32 v32, 0xc0e8, v225
	v_rcp_f32_e32 v47, v33
	ds_read2_b32 v[32:33], v32 offset1:1
	ds_write_b16 v49, v0 offset:51264
	v_mul_f32_e32 v0, v17, v35
	ds_write_b16 v49, v16 offset:51200
	v_cvt_pk_bf16_f32 v0, v0, s0
	v_add3_u32 v16, s2, v48, v50
	ds_write_b16 v16, v0 offset:51328
	v_mul_f32_e32 v0, v1, v35
	v_cvt_pk_bf16_f32 v0, v0, s0
	ds_write_b16 v16, v0 offset:51392
	v_mul_f32_e32 v0, v18, v36
	v_cvt_pk_bf16_f32 v0, v0, s0
	ds_write_b16 v16, v0 offset:51456
	v_mul_f32_e32 v0, v2, v36
	v_cvt_pk_bf16_f32 v0, v0, s0
	ds_write_b16 v16, v0 offset:51520
	v_mul_f32_e32 v0, v19, v37
	v_cvt_pk_bf16_f32 v0, v0, s0
	ds_write_b16 v16, v0 offset:51584
	v_mul_f32_e32 v0, v3, v37
	v_cvt_pk_bf16_f32 v0, v0, s0
	ds_write_b16 v16, v0 offset:51648
	v_mul_f32_e32 v0, v20, v38
	v_cvt_pk_bf16_f32 v0, v0, s0
	ds_write_b16 v16, v0 offset:52224
	v_mul_f32_e32 v0, v4, v38
	v_cvt_pk_bf16_f32 v0, v0, s0
	ds_write_b16 v16, v0 offset:52288
	v_mul_f32_e32 v0, v21, v39
	v_cvt_pk_bf16_f32 v0, v0, s0
	ds_write_b16 v16, v0 offset:52352
	v_mul_f32_e32 v0, v5, v39
	v_cvt_pk_bf16_f32 v0, v0, s0
	ds_write_b16 v16, v0 offset:52416
	v_mul_f32_e32 v0, v22, v40
	v_cvt_pk_bf16_f32 v0, v0, s0
	ds_write_b16 v16, v0 offset:52480
	v_mul_f32_e32 v0, v6, v40
	v_cvt_pk_bf16_f32 v0, v0, s0
	ds_write_b16 v16, v0 offset:52544
	v_mul_f32_e32 v0, v23, v41
	v_cvt_pk_bf16_f32 v0, v0, s0
	ds_write_b16 v16, v0 offset:52608
	v_mul_f32_e32 v0, v7, v41
	v_cvt_pk_bf16_f32 v0, v0, s0
	ds_write_b16 v16, v0 offset:52672
	v_mul_f32_e32 v0, v24, v42
	v_cvt_pk_bf16_f32 v0, v0, s0
	ds_write_b16 v16, v0 offset:53248
	v_mul_f32_e32 v0, v8, v42
	v_cvt_pk_bf16_f32 v0, v0, s0
	ds_write_b16 v16, v0 offset:53312
	v_mul_f32_e32 v0, v25, v43
	v_cvt_pk_bf16_f32 v0, v0, s0
	ds_write_b16 v16, v0 offset:53376
	v_mul_f32_e32 v0, v9, v43
	v_cvt_pk_bf16_f32 v0, v0, s0
	ds_write_b16 v16, v0 offset:53440
	v_mul_f32_e32 v0, v26, v44
	v_cvt_pk_bf16_f32 v0, v0, s0
	ds_write_b16 v16, v0 offset:53504
	v_mul_f32_e32 v0, v10, v44
	v_cvt_pk_bf16_f32 v0, v0, s0
	ds_write_b16 v16, v0 offset:53568
	v_mul_f32_e32 v0, v27, v45
	v_cvt_pk_bf16_f32 v0, v0, s0
	ds_write_b16 v16, v0 offset:53632
	v_mul_f32_e32 v0, v11, v45
	v_cvt_pk_bf16_f32 v0, v0, s0
	ds_write_b16 v16, v0 offset:53696
	v_mul_f32_e32 v0, v28, v46
	v_cvt_pk_bf16_f32 v0, v0, s0
	ds_write_b16 v16, v0 offset:54272
	v_mul_f32_e32 v0, v12, v46
	v_cvt_pk_bf16_f32 v0, v0, s0
	s_waitcnt lgkmcnt(14)
	v_rcp_f32_e32 v32, v32
	ds_write_b16 v16, v0 offset:54336
	v_mul_f32_e32 v0, v29, v47
	v_cvt_pk_bf16_f32 v0, v0, s0
	ds_write_b16 v16, v0 offset:54400
	v_mul_f32_e32 v0, v13, v47
	v_cvt_pk_bf16_f32 v0, v0, s0
	v_rcp_f32_e32 v33, v33
	ds_write_b16 v16, v0 offset:54464
	v_mul_f32_e32 v0, v30, v32
	v_cvt_pk_bf16_f32 v0, v0, s0
	ds_write_b16 v16, v0 offset:54528
	v_mul_f32_e32 v0, v14, v32
	v_cvt_pk_bf16_f32 v0, v0, s0
	ds_write_b16 v16, v0 offset:54592
	v_mul_f32_e32 v0, v31, v33
	v_cvt_pk_bf16_f32 v0, v0, s0
	ds_write_b16 v16, v0 offset:54656
	v_mul_f32_e32 v0, v15, v33
	v_cvt_pk_bf16_f32 v0, v0, s0
	ds_write_b16 v16, v0 offset:54720
	v_lshlrev_b32_e32 v0, 1, v219
	v_and_b32_e32 v192, 0x70, v0
	v_lshrrev_b32_e32 v8, 3, v218
	v_add_u32_e32 v9, s2, v192
	s_waitcnt lgkmcnt(0)
	v_lshl_add_u32 v0, v8, 7, v9
	ds_read_b128 v[0:3], v0 offset:51200
	v_lshl_add_u64 v[4:5], s[14:15], 0, v[192:193]
	v_lshlrev_b32_e32 v192, 11, v8
	v_lshl_add_u64 v[6:7], v[4:5], 0, v[192:193]
	s_waitcnt lgkmcnt(0)
	flat_store_dwordx4 v[6:7], v[0:3] sc1
	v_or_b32_e32 v6, 8, v8
	s_nop 0
	v_lshl_add_u32 v0, v6, 7, v9
	ds_read_b128 v[0:3], v0 offset:51200
	v_lshlrev_b32_e32 v192, 11, v6
	v_lshl_add_u64 v[6:7], v[4:5], 0, v[192:193]
	s_waitcnt lgkmcnt(0)
	flat_store_dwordx4 v[6:7], v[0:3] sc1
	v_or_b32_e32 v6, 16, v8
	s_nop 0
	v_lshl_add_u32 v0, v6, 7, v9
	ds_read_b128 v[0:3], v0 offset:51200
	v_lshlrev_b32_e32 v192, 11, v6
	v_lshl_add_u64 v[6:7], v[4:5], 0, v[192:193]
	s_waitcnt lgkmcnt(0)
	flat_store_dwordx4 v[6:7], v[0:3] sc1
	v_or_b32_e32 v6, 24, v8
	s_nop 0
	v_lshl_add_u32 v0, v6, 7, v9
	ds_read_b128 v[0:3], v0 offset:51200
	v_lshlrev_b32_e32 v192, 11, v6
	v_lshl_add_u64 v[4:5], v[4:5], 0, v[192:193]
	s_waitcnt lgkmcnt(0)
	flat_store_dwordx4 v[4:5], v[0:3] sc1
	s_waitcnt lgkmcnt(0)
	s_barrier
